# final RMSNorm phase: next row pair prefetched one iteration ahead into staging VGPRs (counted vmcnt)
# baseline (speedup 1.0000x reference)
; #define PG8_STAGE(bufoff, gbase, voff) do { _Pragma("unroll") for (int _i = 0; _i < 2; ++_i) \
;         __builtin_amdgcn_global_load_lds((const unsigned*)((const char*)(gbase) + (voff)[_i]), (LAS unsigned*)(lds + (bufoff) + ldsw + _i * 8192), 16, 0, 0); } while (0)
; #define PG8_LDA(dst, b, h) do { _Pragma("unroll") for (int m = 0; m < 4; ++m) _Pragma("unroll") for (int k = 0; k < 2; ++k) dst[m][k] = *(const LAS bf16x8*)(lds + PG8_SA(b, h) + aoff + m * 2048 + k * 1024); } while (0)
; #define PG8_LDB(dst, b, h) do { _Pragma("unroll") for (int n = 0; n < 2; ++n) _Pragma("unroll") for (int k = 0; k < 2; ++k) dst[n][k] = *(const LAS bf16x8*)(lds + PG8_SB(b, h) + boff + n * 2048 + k * 1024); } while (0)
; #define PG8_MMA(ai, bj, At, Bt) do { __builtin_amdgcn_s_setprio(1); _Pragma("unroll") for (int m = 0; m < 4; ++m) _Pragma("unroll") for (int n = 0; n < 2; ++n) _Pragma("unroll") for (int k = 0; k < 2; ++k) \
;         acc[ai][bj][m][n] = __builtin_amdgcn_mfma_f32_16x16x32_bf16(Bt[n][k], At[m][k], acc[ai][bj][m][n], 0, 0, 0); __builtin_amdgcn_s_setprio(0); } while (0)
; #define PG8_WAIT_V(n) asm volatile("s_waitcnt vmcnt(" #n ")" ::: "memory")
; #define PG8_WAIT_L(n) asm volatile("s_waitcnt lgkmcnt(" #n ")" ::: "memory")
; #define PG8_BAR __builtin_amdgcn_s_barrier()
; #define PG8_SCHED __builtin_amdgcn_sched_barrier(0)
; #define PG8_STAGE(bufoff, gbase, voff) do { _Pragma("unroll") for (int _i = 0; _i < 2; ++_i) \
;         __builtin_amdgcn_global_load_lds((const unsigned*)((const char*)(gbase) + (voff)[_i]), (LAS unsigned*)(lds + (bufoff) + ldsw + _i * 8192), 16, 0, 0); } while (0)
; #define PG8_BAR __builtin_amdgcn_s_barrier()
; template <class Epi>
; DI void gemm_phase(LAS unsigned char* lds, const Gemm g, const StaticOrder S, const Epi E) {
;     ...
;             PG8_LDB(B0, 0, 0); PG8_SCHED; PG8_LDA(At, 0, 0); PG8_STAGE(PG8_SA(1, 1), a1 + hstep, voffA);
;             PG8_WAIT_L(8); PG8_BAR; PG8_WAIT_L(0); PG8_MMA(0, 0, At, B0); PG8_BAR; PG8_SCHED;
;             PG8_LDB(B1, 0, 1); PG8_STAGE(PG8_SB(0, 0), b2, voffB);
;             PG8_BAR; PG8_WAIT_L(0); PG8_MMA(0, 1, At, B1); PG8_BAR;
;             PG8_LDA(At, 0, 1); PG8_STAGE(PG8_SA(0, 0), a2, voffA);
;             PG8_BAR; PG8_WAIT_L(0); PG8_MMA(1, 0, At, B0); PG8_BAR; PG8_SCHED;
;             PG8_STAGE(PG8_SB(0, 1), b2 + hstep, voffB);
;             PG8_WAIT_V(6); PG8_BAR; PG8_MMA(1, 1, At, B1); PG8_BAR;
.LBB0_107:
	ds_read_b128 v[152:155], v149
	ds_read_b128 v[156:159], v149 offset:1024
	ds_read_b128 v[160:163], v149 offset:2048
	ds_read_b128 v[164:167], v149 offset:3072
	s_add_u32 s14, s76, 0xfffc0080
	s_addc_u32 s15, s77, -1
	s_cmp_eq_u32 s97, 12
	s_cselect_b32 s81, s11, s15
	s_cselect_b32 s80, s93, s14
	s_cselect_b32 s79, s9, s96
	s_cselect_b32 s78, s94, s95
	v_lshl_add_u64 v[144:145], s[76:77], 0, v[136:137]
	s_add_i32 m0, s29, 0xc000
	ds_read_b128 v[168:171], v150
	ds_read_b128 v[172:175], v150 offset:1024
	ds_read_b128 v[176:179], v150 offset:2048
	ds_read_b128 v[180:183], v150 offset:3072
	ds_read_b128 v[184:187], v150 offset:4096
	ds_read_b128 v[188:191], v150 offset:5120
	ds_read_b128 v[192:195], v150 offset:6144
	ds_read_b128 v[196:199], v150 offset:7168
	global_load_lds_dwordx4 v[144:145], off
	v_lshl_add_u64 v[144:145], s[76:77], 0, v[138:139]
	s_add_i32 m0, s29, 0xe000
	s_nop 0
	global_load_lds_dwordx4 v[144:145], off
	s_waitcnt lgkmcnt(8)
	s_barrier
	s_waitcnt lgkmcnt(0)
	s_setprio 1
	s_waitcnt lgkmcnt(0)
	v_mfma_f32_16x16x32_bf16 v[124:127], v[152:155], v[168:171], v[124:127]
	v_mfma_f32_16x16x32_bf16 v[116:119], v[160:163], v[168:171], v[116:119]
	v_mfma_f32_16x16x32_bf16 v[108:111], v[152:155], v[176:179], v[108:111]
	v_mfma_f32_16x16x32_bf16 v[100:103], v[160:163], v[176:179], v[100:103]
	v_mfma_f32_16x16x32_bf16 v[92:95], v[152:155], v[184:187], v[92:95]
	v_mfma_f32_16x16x32_bf16 v[84:87], v[160:163], v[184:187], v[84:87]
	v_mfma_f32_16x16x32_bf16 v[76:79], v[152:155], v[192:195], v[76:79]
	v_mfma_f32_16x16x32_bf16 v[68:71], v[160:163], v[192:195], v[68:71]
	v_mfma_f32_16x16x32_bf16 v[124:127], v[156:159], v[172:175], v[124:127]
	v_mfma_f32_16x16x32_bf16 v[116:119], v[164:167], v[172:175], v[116:119]
	v_mfma_f32_16x16x32_bf16 v[108:111], v[156:159], v[180:183], v[108:111]
	v_mfma_f32_16x16x32_bf16 v[100:103], v[164:167], v[180:183], v[100:103]
	v_mfma_f32_16x16x32_bf16 v[92:95], v[156:159], v[188:191], v[92:95]
	v_mfma_f32_16x16x32_bf16 v[84:87], v[164:167], v[188:191], v[84:87]
	v_mfma_f32_16x16x32_bf16 v[76:79], v[156:159], v[196:199], v[76:79]
	v_mfma_f32_16x16x32_bf16 v[68:71], v[164:167], v[196:199], v[68:71]
	s_setprio 0
	s_barrier
	s_add_i32 s14, s89, s7
	v_lshl_add_u64 v[144:145], s[78:79], 0, v[132:133]
	s_mov_b32 m0, s14
	ds_read_b128 v[200:203], v151
	ds_read_b128 v[204:207], v151 offset:1024
	ds_read_b128 v[208:211], v151 offset:2048
	ds_read_b128 v[212:215], v151 offset:3072
	global_load_lds_dwordx4 v[144:145], off
	v_lshl_add_u64 v[216:217], s[78:79], 0, v[128:129]
	s_add_i32 m0, s14, 0x2000
	s_nop 0
	global_load_lds_dwordx4 v[216:217], off
	s_barrier
	s_waitcnt lgkmcnt(0)
	s_setprio 1
	s_waitcnt lgkmcnt(0)
	v_mfma_f32_16x16x32_bf16 v[120:123], v[200:203], v[168:171], v[120:123]
	v_mfma_f32_16x16x32_bf16 v[112:115], v[208:211], v[168:171], v[112:115]
	v_mfma_f32_16x16x32_bf16 v[104:107], v[200:203], v[176:179], v[104:107]
	v_mfma_f32_16x16x32_bf16 v[96:99], v[208:211], v[176:179], v[96:99]
	v_mfma_f32_16x16x32_bf16 v[88:91], v[200:203], v[184:187], v[88:91]
	v_mfma_f32_16x16x32_bf16 v[80:83], v[208:211], v[184:187], v[80:83]
	v_mfma_f32_16x16x32_bf16 v[72:75], v[200:203], v[192:195], v[72:75]
	v_mfma_f32_16x16x32_bf16 v[64:67], v[208:211], v[192:195], v[64:67]
	v_mfma_f32_16x16x32_bf16 v[120:123], v[204:207], v[172:175], v[120:123]
	v_mfma_f32_16x16x32_bf16 v[112:115], v[212:215], v[172:175], v[112:115]
	v_mfma_f32_16x16x32_bf16 v[104:107], v[204:207], v[180:183], v[104:107]
	v_mfma_f32_16x16x32_bf16 v[96:99], v[212:215], v[180:183], v[96:99]
	v_mfma_f32_16x16x32_bf16 v[88:91], v[204:207], v[188:191], v[88:91]
	v_mfma_f32_16x16x32_bf16 v[80:83], v[212:215], v[188:191], v[80:83]
	v_mfma_f32_16x16x32_bf16 v[72:75], v[204:207], v[196:199], v[72:75]
	v_mfma_f32_16x16x32_bf16 v[64:67], v[212:215], v[196:199], v[64:67]
	s_setprio 0
	s_mov_b32 m0, s29
	v_lshl_add_u64 v[218:219], s[80:81], 0, v[134:135]
	s_barrier
	ds_read_b128 v[168:171], v150 offset:16384
	ds_read_b128 v[172:175], v150 offset:17408
	ds_read_b128 v[176:179], v150 offset:18432
	ds_read_b128 v[180:183], v150 offset:19456
	ds_read_b128 v[184:187], v150 offset:20480
	ds_read_b128 v[188:191], v150 offset:21504
	ds_read_b128 v[192:195], v150 offset:22528
	ds_read_b128 v[196:199], v150 offset:23552
	global_load_lds_dwordx4 v[218:219], off
	v_lshl_add_u64 v[220:221], s[80:81], 0, v[130:131]
	s_mov_b32 m0, s59
	s_nop 0
	global_load_lds_dwordx4 v[220:221], off
	s_barrier
	s_waitcnt lgkmcnt(0)
	s_setprio 1
	s_waitcnt lgkmcnt(0)
	v_mfma_f32_16x16x32_bf16 v[60:63], v[152:155], v[168:171], v[60:63]
	v_mfma_f32_16x16x32_bf16 v[52:55], v[160:163], v[168:171], v[52:55]
	v_mfma_f32_16x16x32_bf16 v[44:47], v[152:155], v[176:179], v[44:47]
	v_mfma_f32_16x16x32_bf16 v[36:39], v[160:163], v[176:179], v[36:39]
	v_mfma_f32_16x16x32_bf16 v[28:31], v[152:155], v[184:187], v[28:31]
	v_mfma_f32_16x16x32_bf16 v[20:23], v[160:163], v[184:187], v[20:23]
	v_mfma_f32_16x16x32_bf16 v[12:15], v[152:155], v[192:195], v[12:15]
	v_mfma_f32_16x16x32_bf16 v[4:7], v[160:163], v[192:195], v[4:7]
	v_mfma_f32_16x16x32_bf16 v[60:63], v[156:159], v[172:175], v[60:63]
	v_mfma_f32_16x16x32_bf16 v[52:55], v[164:167], v[172:175], v[52:55]
	v_mfma_f32_16x16x32_bf16 v[44:47], v[156:159], v[180:183], v[44:47]
	v_mfma_f32_16x16x32_bf16 v[36:39], v[164:167], v[180:183], v[36:39]
	v_mfma_f32_16x16x32_bf16 v[28:31], v[156:159], v[188:191], v[28:31]
	v_mfma_f32_16x16x32_bf16 v[20:23], v[164:167], v[188:191], v[20:23]
	v_mfma_f32_16x16x32_bf16 v[12:15], v[156:159], v[196:199], v[12:15]
	v_mfma_f32_16x16x32_bf16 v[4:7], v[164:167], v[196:199], v[4:7]
	s_setprio 0
	s_barrier
; #define PG8_STAGE(bufoff, gbase, voff) do { _Pragma("unroll") for (int _i = 0; _i < 2; ++_i) \
;         __builtin_amdgcn_global_load_lds((const unsigned*)((const char*)(gbase) + (voff)[_i]), (LAS unsigned*)(lds + (bufoff) + ldsw + _i * 8192), 16, 0, 0); } while (0)
; #define PG8_LDA(dst, b, h) do { _Pragma("unroll") for (int m = 0; m < 4; ++m) _Pragma("unroll") for (int k = 0; k < 2; ++k) dst[m][k] = *(const LAS bf16x8*)(lds + PG8_SA(b, h) + aoff + m * 2048 + k * 1024); } while (0)
; #define PG8_LDB(dst, b, h) do { _Pragma("unroll") for (int n = 0; n < 2; ++n) _Pragma("unroll") for (int k = 0; k < 2; ++k) dst[n][k] = *(const LAS bf16x8*)(lds + PG8_SB(b, h) + boff + n * 2048 + k * 1024); } while (0)
; #define PG8_MMA(ai, bj, At, Bt) do { __builtin_amdgcn_s_setprio(1); _Pragma("unroll") for (int m = 0; m < 4; ++m) _Pragma("unroll") for (int n = 0; n < 2; ++n) _Pragma("unroll") for (int k = 0; k < 2; ++k) \
;         acc[ai][bj][m][n] = __builtin_amdgcn_mfma_f32_16x16x32_bf16(Bt[n][k], At[m][k], acc[ai][bj][m][n], 0, 0, 0); __builtin_amdgcn_s_setprio(0); } while (0)
; #define PG8_WAIT_V(n) asm volatile("s_waitcnt vmcnt(" #n ")" ::: "memory")
; #define PG8_WAIT_L(n) asm volatile("s_waitcnt lgkmcnt(" #n ")" ::: "memory")
; #define PG8_BAR __builtin_amdgcn_s_barrier()
; #define PG8_SCHED __builtin_amdgcn_sched_barrier(0)
; #define PG8_STAGE(bufoff, gbase, voff) do { _Pragma("unroll") for (int _i = 0; _i < 2; ++_i) \
;         __builtin_amdgcn_global_load_lds((const unsigned*)((const char*)(gbase) + (voff)[_i]), (LAS unsigned*)(lds + (bufoff) + ldsw + _i * 8192), 16, 0, 0); } while (0)
; #define PG8_BAR __builtin_amdgcn_s_barrier()
; template <class Epi>
; DI void gemm_phase(LAS unsigned char* lds, const Gemm g, const StaticOrder S, const Epi E) {
;     ...
;             PG8_STAGE(PG8_SB(0, 1), b2 + hstep, voffB);
;             PG8_WAIT_V(6); PG8_BAR; PG8_MMA(1, 1, At, B1); PG8_BAR;
;             PG8_LDB(B0, 1, 0); PG8_SCHED; PG8_LDA(At, 1, 0); PG8_STAGE(PG8_SA(0, 1), a2 + hstep, voffA);
;             PG8_WAIT_L(8); PG8_BAR; PG8_WAIT_L(0); PG8_MMA(0, 0, At, B0); PG8_BAR; PG8_SCHED;
;             PG8_LDB(B1, 1, 1); PG8_STAGE(PG8_SB(1, 0), b3, voffB);
;             PG8_BAR; PG8_WAIT_L(0); PG8_MMA(0, 1, At, B1); PG8_BAR;
;             PG8_LDA(At, 1, 1); PG8_STAGE(PG8_SA(1, 0), a3, voffA);
;             PG8_BAR; PG8_WAIT_L(0); PG8_MMA(1, 0, At, B0); PG8_BAR; PG8_SCHED;
	s_add_u32 s14, s78, 0x40000
	s_addc_u32 s15, s79, 0
	s_add_i32 s35, s90, s7
	v_lshl_add_u64 v[152:153], s[14:15], 0, v[132:133]
	s_mov_b32 m0, s35
	s_nop 0
	global_load_lds_dwordx4 v[152:153], off
	v_lshl_add_u64 v[152:153], s[14:15], 0, v[128:129]
	s_add_i32 m0, s35, 0x2000
	s_nop 0
	global_load_lds_dwordx4 v[152:153], off
	s_waitcnt vmcnt(6)
	s_barrier
	s_setprio 1
	v_mfma_f32_16x16x32_bf16 v[56:59], v[200:203], v[168:171], v[56:59]
	v_mfma_f32_16x16x32_bf16 v[48:51], v[208:211], v[168:171], v[48:51]
	v_mfma_f32_16x16x32_bf16 v[40:43], v[200:203], v[176:179], v[40:43]
	v_mfma_f32_16x16x32_bf16 v[32:35], v[208:211], v[176:179], v[32:35]
	v_mfma_f32_16x16x32_bf16 v[24:27], v[200:203], v[184:187], v[24:27]
	v_mfma_f32_16x16x32_bf16 v[16:19], v[208:211], v[184:187], v[16:19]
	v_mfma_f32_16x16x32_bf16 v[8:11], v[200:203], v[192:195], v[8:11]
	v_mfma_f32_16x16x32_bf16 v[0:3], v[208:211], v[192:195], v[0:3]
	v_mfma_f32_16x16x32_bf16 v[56:59], v[204:207], v[172:175], v[56:59]
	v_mfma_f32_16x16x32_bf16 v[48:51], v[212:215], v[172:175], v[48:51]
	v_mfma_f32_16x16x32_bf16 v[40:43], v[204:207], v[180:183], v[40:43]
	v_mfma_f32_16x16x32_bf16 v[32:35], v[212:215], v[180:183], v[32:35]
	v_mfma_f32_16x16x32_bf16 v[24:27], v[204:207], v[188:191], v[24:27]
	v_mfma_f32_16x16x32_bf16 v[16:19], v[212:215], v[188:191], v[16:19]
	v_mfma_f32_16x16x32_bf16 v[8:11], v[204:207], v[196:199], v[8:11]
	v_mfma_f32_16x16x32_bf16 v[0:3], v[212:215], v[196:199], v[0:3]
	s_setprio 0
	s_add_i32 s35, 0, 0x18000
	v_add_u32_e32 v164, s35, v147
	s_barrier
	ds_read_b128 v[152:155], v164
	ds_read_b128 v[156:159], v164 offset:1024
	ds_read_b128 v[160:163], v164 offset:2048
	ds_read_b128 v[164:167], v164 offset:3072
	s_add_u32 s14, s80, 0x40000
	s_addc_u32 s15, s81, 0
	s_mov_b32 m0, s82
	v_lshl_add_u64 v[200:201], s[14:15], 0, v[134:135]
	ds_read_b128 v[168:171], v150 offset:32768
	ds_read_b128 v[172:175], v150 offset:33792
	ds_read_b128 v[176:179], v150 offset:34816
	ds_read_b128 v[180:183], v150 offset:35840
	ds_read_b128 v[184:187], v150 offset:36864
	ds_read_b128 v[188:191], v150 offset:37888
	ds_read_b128 v[192:195], v150 offset:38912
	ds_read_b128 v[196:199], v150 offset:39936
	global_load_lds_dwordx4 v[200:201], off
	v_lshl_add_u64 v[200:201], s[14:15], 0, v[130:131]
	s_mov_b32 m0, s83
	s_nop 0
	global_load_lds_dwordx4 v[200:201], off
	s_waitcnt lgkmcnt(8)
	s_barrier
	s_waitcnt lgkmcnt(0)
	s_setprio 1
	s_waitcnt lgkmcnt(0)
	v_mfma_f32_16x16x32_bf16 v[124:127], v[152:155], v[168:171], v[124:127]
	v_mfma_f32_16x16x32_bf16 v[116:119], v[160:163], v[168:171], v[116:119]
	v_mfma_f32_16x16x32_bf16 v[108:111], v[152:155], v[176:179], v[108:111]
	v_mfma_f32_16x16x32_bf16 v[100:103], v[160:163], v[176:179], v[100:103]
	v_mfma_f32_16x16x32_bf16 v[92:95], v[152:155], v[184:187], v[92:95]
	v_mfma_f32_16x16x32_bf16 v[84:87], v[160:163], v[184:187], v[84:87]
	v_mfma_f32_16x16x32_bf16 v[76:79], v[152:155], v[192:195], v[76:79]
	v_mfma_f32_16x16x32_bf16 v[68:71], v[160:163], v[192:195], v[68:71]
	v_mfma_f32_16x16x32_bf16 v[124:127], v[156:159], v[172:175], v[124:127]
	v_mfma_f32_16x16x32_bf16 v[116:119], v[164:167], v[172:175], v[116:119]
	v_mfma_f32_16x16x32_bf16 v[108:111], v[156:159], v[180:183], v[108:111]
	v_mfma_f32_16x16x32_bf16 v[100:103], v[164:167], v[180:183], v[100:103]
	v_mfma_f32_16x16x32_bf16 v[92:95], v[156:159], v[188:191], v[92:95]
	v_mfma_f32_16x16x32_bf16 v[84:87], v[164:167], v[188:191], v[84:87]
	v_mfma_f32_16x16x32_bf16 v[76:79], v[156:159], v[196:199], v[76:79]
	v_mfma_f32_16x16x32_bf16 v[68:71], v[164:167], v[196:199], v[68:71]
	s_setprio 0
	s_barrier
	s_add_i32 s80, 0, 0x1c000
	s_add_i32 s14, s35, s7
	v_add_u32_e32 v212, s80, v147
	v_lshl_add_u64 v[144:145], v[144:145], 0, s[4:5]
	s_mov_b32 m0, s14
	ds_read_b128 v[200:203], v212
	ds_read_b128 v[204:207], v212 offset:1024
	ds_read_b128 v[208:211], v212 offset:2048
	ds_read_b128 v[212:215], v212 offset:3072
	global_load_lds_dwordx4 v[144:145], off
	v_lshl_add_u64 v[144:145], v[216:217], 0, s[4:5]
	s_add_i32 m0, s14, 0x2000
	s_nop 0
	global_load_lds_dwordx4 v[144:145], off
	s_barrier
	s_waitcnt lgkmcnt(0)
	s_setprio 1
	s_waitcnt lgkmcnt(0)
	v_mfma_f32_16x16x32_bf16 v[120:123], v[200:203], v[168:171], v[120:123]
	v_mfma_f32_16x16x32_bf16 v[112:115], v[208:211], v[168:171], v[112:115]
	v_mfma_f32_16x16x32_bf16 v[104:107], v[200:203], v[176:179], v[104:107]
	v_mfma_f32_16x16x32_bf16 v[96:99], v[208:211], v[176:179], v[96:99]
	v_mfma_f32_16x16x32_bf16 v[88:91], v[200:203], v[184:187], v[88:91]
	v_mfma_f32_16x16x32_bf16 v[80:83], v[208:211], v[184:187], v[80:83]
	v_mfma_f32_16x16x32_bf16 v[72:75], v[200:203], v[192:195], v[72:75]
	v_mfma_f32_16x16x32_bf16 v[64:67], v[208:211], v[192:195], v[64:67]
	v_mfma_f32_16x16x32_bf16 v[120:123], v[204:207], v[172:175], v[120:123]
	v_mfma_f32_16x16x32_bf16 v[112:115], v[212:215], v[172:175], v[112:115]
	v_mfma_f32_16x16x32_bf16 v[104:107], v[204:207], v[180:183], v[104:107]
	v_mfma_f32_16x16x32_bf16 v[96:99], v[212:215], v[180:183], v[96:99]
	v_mfma_f32_16x16x32_bf16 v[88:91], v[204:207], v[188:191], v[88:91]
	v_mfma_f32_16x16x32_bf16 v[80:83], v[212:215], v[188:191], v[80:83]
	v_mfma_f32_16x16x32_bf16 v[72:75], v[204:207], v[196:199], v[72:75]
	v_mfma_f32_16x16x32_bf16 v[64:67], v[212:215], v[196:199], v[64:67]
	s_setprio 0
	s_mov_b32 m0, s85
	v_lshl_add_u64 v[144:145], v[218:219], 0, s[4:5]
	s_barrier
	ds_read_b128 v[168:171], v150 offset:49152
	ds_read_b128 v[172:175], v150 offset:50176
	ds_read_b128 v[176:179], v150 offset:51200
	ds_read_b128 v[180:183], v150 offset:52224
	ds_read_b128 v[184:187], v150 offset:53248
	ds_read_b128 v[188:191], v150 offset:54272
	ds_read_b128 v[192:195], v150 offset:55296
	ds_read_b128 v[196:199], v150 offset:56320
	global_load_lds_dwordx4 v[144:145], off
	v_lshl_add_u64 v[144:145], v[220:221], 0, s[4:5]
	s_mov_b32 m0, s86
	s_nop 0
	global_load_lds_dwordx4 v[144:145], off
	s_barrier
; DI unsigned pk_bf16(float lo, float hi) { f32x2 v = {lo, hi}; return __builtin_bit_cast(unsigned, __builtin_convertvector(v, bf16v2)); }
; DI float fast_silu(float x) { return x * fast_sigmoid(x); }
; #define PG8_STAGE(bufoff, gbase, voff) do { _Pragma("unroll") for (int _i = 0; _i < 2; ++_i) \
;         __builtin_amdgcn_global_load_lds((const unsigned*)((const char*)(gbase) + (voff)[_i]), (LAS unsigned*)(lds + (bufoff) + ldsw + _i * 8192), 16, 0, 0); } while (0)
; #define PG8_MMA(ai, bj, At, Bt) do { __builtin_amdgcn_s_setprio(1); _Pragma("unroll") for (int m = 0; m < 4; ++m) _Pragma("unroll") for (int n = 0; n < 2; ++n) _Pragma("unroll") for (int k = 0; k < 2; ++k) \
;         acc[ai][bj][m][n] = __builtin_amdgcn_mfma_f32_16x16x32_bf16(Bt[n][k], At[m][k], acc[ai][bj][m][n], 0, 0, 0); __builtin_amdgcn_s_setprio(0); } while (0)
; #define PG8_WAIT_V(n) asm volatile("s_waitcnt vmcnt(" #n ")" ::: "memory")
; #define PG8_WAIT_L(n) asm volatile("s_waitcnt lgkmcnt(" #n ")" ::: "memory")
; #define PG8_BAR __builtin_amdgcn_s_barrier()
; #define PG8_SCHED __builtin_amdgcn_sched_barrier(0)
; #define PG8_WAIT_V(n) asm volatile("s_waitcnt vmcnt(" #n ")" ::: "memory")
; #define PG8_WAIT_L(n) asm volatile("s_waitcnt lgkmcnt(" #n ")" ::: "memory")
; template <class Epi>
; DI void gemm_phase(LAS unsigned char* lds, const Gemm g, const StaticOrder S, const Epi E) {
;     ...
;             PG8_BAR; PG8_WAIT_L(0); PG8_MMA(1, 0, At, B0); PG8_BAR; PG8_SCHED;
;             PG8_STAGE(PG8_SB(1, 1), b3 + hstep, voffB);
;             PG8_WAIT_V(6); PG8_BAR; PG8_MMA(1, 1, At, B1); PG8_BAR;
;     DI void operator()(AccRef acc, const Unit& u, int wr, int wc, int fr, int fq) const {
;     ...
;             for (int m = 0; m < 4; ++m) {
;                 const int row = row0 + ai * 128 + m * 16;
;                 const float r = RS ? rsc.r[ai][m] : 1.0f;
;                 const f32x4 a0 = acc[ai][0][m][0] * r, a1 = acc[ai][0][m][1] * r, b0 = acc[ai][1][m][0] * r, b1 = acc[ai][1][m][1] * r;
;                 u32x4 w;
;                 w.x = pk_bf16(fast_silu(a0[0]) * b0[0], fast_silu(a0[1]) * b0[1]); w.y = pk_bf16(fast_silu(a0[2]) * b0[2], fast_silu(a0[3]) * b0[3]);
;                 w.z = pk_bf16(fast_silu(a1[0]) * b1[0], fast_silu(a1[1]) * b1[1]); w.w = pk_bf16(fast_silu(a1[2]) * b1[2], fast_silu(a1[3]) * b1[3]);
;                 *(u32x4*)(G + (size_t)row * DFF + col) = w;
	s_waitcnt lgkmcnt(0)
	s_setprio 1
	s_waitcnt lgkmcnt(0)
	v_mfma_f32_16x16x32_bf16 v[60:63], v[152:155], v[168:171], v[60:63]
	v_mfma_f32_16x16x32_bf16 v[52:55], v[160:163], v[168:171], v[52:55]
	v_mfma_f32_16x16x32_bf16 v[44:47], v[152:155], v[176:179], v[44:47]
	v_mfma_f32_16x16x32_bf16 v[36:39], v[160:163], v[176:179], v[36:39]
	v_mfma_f32_16x16x32_bf16 v[28:31], v[152:155], v[184:187], v[28:31]
	v_mfma_f32_16x16x32_bf16 v[20:23], v[160:163], v[184:187], v[20:23]
	v_mfma_f32_16x16x32_bf16 v[12:15], v[152:155], v[192:195], v[12:15]
	v_mfma_f32_16x16x32_bf16 v[4:7], v[160:163], v[192:195], v[4:7]
	v_mfma_f32_16x16x32_bf16 v[60:63], v[156:159], v[172:175], v[60:63]
	v_mfma_f32_16x16x32_bf16 v[52:55], v[164:167], v[172:175], v[52:55]
	v_mfma_f32_16x16x32_bf16 v[44:47], v[156:159], v[180:183], v[44:47]
	v_mfma_f32_16x16x32_bf16 v[36:39], v[164:167], v[180:183], v[36:39]
	v_mfma_f32_16x16x32_bf16 v[28:31], v[156:159], v[188:191], v[28:31]
	v_mfma_f32_16x16x32_bf16 v[20:23], v[164:167], v[188:191], v[20:23]
	v_mfma_f32_16x16x32_bf16 v[12:15], v[156:159], v[196:199], v[12:15]
	v_mfma_f32_16x16x32_bf16 v[4:7], v[164:167], v[196:199], v[4:7]
	s_setprio 0
	s_barrier
	s_add_u32 s14, s78, 0x40080
	s_addc_u32 s15, s79, 0
	s_add_i32 s35, s80, s7
	v_lshl_add_u64 v[144:145], s[14:15], 0, v[132:133]
	s_mov_b32 m0, s35
	s_nop 0
	global_load_lds_dwordx4 v[144:145], off
	v_lshl_add_u64 v[144:145], s[14:15], 0, v[128:129]
	s_add_i32 m0, s35, 0x2000
	s_nop 0
	global_load_lds_dwordx4 v[144:145], off
	s_waitcnt vmcnt(6)
	s_barrier
	s_setprio 1
	v_mfma_f32_16x16x32_bf16 v[56:59], v[200:203], v[168:171], v[56:59]
	v_mfma_f32_16x16x32_bf16 v[48:51], v[208:211], v[168:171], v[48:51]
	v_mfma_f32_16x16x32_bf16 v[40:43], v[200:203], v[176:179], v[40:43]
	v_mfma_f32_16x16x32_bf16 v[32:35], v[208:211], v[176:179], v[32:35]
	v_mfma_f32_16x16x32_bf16 v[24:27], v[200:203], v[184:187], v[24:27]
	v_mfma_f32_16x16x32_bf16 v[16:19], v[208:211], v[184:187], v[16:19]
	v_mfma_f32_16x16x32_bf16 v[8:11], v[200:203], v[192:195], v[8:11]
	v_mfma_f32_16x16x32_bf16 v[0:3], v[208:211], v[192:195], v[0:3]
	v_mfma_f32_16x16x32_bf16 v[56:59], v[204:207], v[172:175], v[56:59]
	v_mfma_f32_16x16x32_bf16 v[48:51], v[212:215], v[172:175], v[48:51]
	v_mfma_f32_16x16x32_bf16 v[40:43], v[204:207], v[180:183], v[40:43]
	v_mfma_f32_16x16x32_bf16 v[32:35], v[212:215], v[180:183], v[32:35]
	v_mfma_f32_16x16x32_bf16 v[24:27], v[204:207], v[188:191], v[24:27]
	v_mfma_f32_16x16x32_bf16 v[16:19], v[212:215], v[188:191], v[16:19]
	v_mfma_f32_16x16x32_bf16 v[8:11], v[204:207], v[196:199], v[8:11]
	v_mfma_f32_16x16x32_bf16 v[0:3], v[212:215], v[196:199], v[0:3]
	s_setprio 0
	s_add_i32 s97, s97, 2
	s_add_u32 s76, s76, 0x100
	s_addc_u32 s77, s77, 0
	s_add_u32 s95, s95, 0x100
	s_addc_u32 s96, s96, 0
	s_cmp_gt_u32 s97, 13
	s_barrier
	s_cbranch_scc0 .LBB0_107
	v_mul_f32_e32 v153, 0xbfb8aa3b, v124
	v_exp_f32_e32 v153, v153
	v_mul_f32_e32 v154, 0xbfb8aa3b, v125
	v_exp_f32_e32 v155, v154
	v_lshl_or_b32 v144, s92, 7, v148
	v_add_f32_e32 v153, 1.0, v153
	v_rcp_f32_e32 v154, v153
	v_add_f32_e32 v153, 1.0, v155
	v_mul_f32_e32 v155, 0xbfb8aa3b, v126
	v_exp_f32_e32 v156, v155
	v_mul_f32_e32 v155, 0xbfb8aa3b, v127
	v_exp_f32_e32 v157, v155
	v_rcp_f32_e32 v155, v153
	v_add_f32_e32 v153, 1.0, v156
	v_rcp_f32_e32 v156, v153
	v_add_f32_e32 v153, 1.0, v157
	v_rcp_f32_e32 v157, v153
	v_pk_mul_f32 v[124:125], v[124:125], v[154:155]
	v_ashrrev_i32_e32 v145, 31, v144
	v_pk_mul_f32 v[120:121], v[124:125], v[120:121]
	v_pk_mul_f32 v[124:125], v[126:127], v[156:157]
	v_cvt_pk_bf16_f32 v120, v120, v121
	v_mul_f32_e32 v121, 0xbfb8aa3b, v116
	v_pk_mul_f32 v[122:123], v[124:125], v[122:123]
	v_exp_f32_e32 v124, v121
	v_mul_f32_e32 v121, 0xbfb8aa3b, v117
	v_exp_f32_e32 v125, v121
	v_cvt_pk_bf16_f32 v121, v122, v123
	v_add_f32_e32 v122, 1.0, v124
	v_mul_f32_e32 v124, 0xbfb8aa3b, v118
	v_add_f32_e32 v123, 1.0, v125
	v_mul_f32_e32 v125, 0xbfb8aa3b, v119
	v_exp_f32_e32 v124, v124
	v_exp_f32_e32 v125, v125
	v_rcp_f32_e32 v122, v122
	v_rcp_f32_e32 v123, v123
	v_add_f32_e32 v124, 1.0, v124
	v_add_f32_e32 v125, 1.0, v125
	v_rcp_f32_e32 v124, v124
	v_rcp_f32_e32 v125, v125
	v_pk_mul_f32 v[116:117], v[116:117], v[122:123]
	v_lshl_add_u32 v152, s28, 8, v146
	v_pk_mul_f32 v[112:113], v[116:117], v[112:113]
	v_lshl_add_u64 v[144:145], v[144:145], 1, s[54:55]
	v_cvt_pk_bf16_f32 v122, v112, v113
	v_pk_mul_f32 v[112:113], v[118:119], v[124:125]
	v_or_b32_e32 v116, 16, v152
	v_pk_mul_f32 v[112:113], v[112:113], v[114:115]
	v_mul_f32_e32 v114, 0xbfb8aa3b, v110
	v_cvt_pk_bf16_f32 v123, v112, v113
	v_mad_i64_i32 v[112:113], s[14:15], v152, s91, v[144:145]
	global_store_dwordx4 v[112:113], v[120:123], off
	v_mul_f32_e32 v112, 0xbfb8aa3b, v108
	v_mul_f32_e32 v113, 0xbfb8aa3b, v109
	v_exp_f32_e32 v112, v112
	v_exp_f32_e32 v113, v113
	v_mul_f32_e32 v115, 0xbfb8aa3b, v111
	v_exp_f32_e32 v114, v114
	v_exp_f32_e32 v115, v115
	v_add_f32_e32 v112, 1.0, v112
	v_add_f32_e32 v113, 1.0, v113
	v_rcp_f32_e32 v112, v112
	v_rcp_f32_e32 v113, v113
	v_add_f32_e32 v114, 1.0, v114
	v_add_f32_e32 v115, 1.0, v115
	v_rcp_f32_e32 v114, v114
	v_rcp_f32_e32 v115, v115
	v_pk_mul_f32 v[108:109], v[108:109], v[112:113]
	s_and_b64 vcc, exec, s[0:1]
	v_pk_mul_f32 v[104:105], v[108:109], v[104:105]
	v_pk_mul_f32 v[108:109], v[110:111], v[114:115]
	v_cvt_pk_bf16_f32 v104, v104, v105
	v_mul_f32_e32 v105, 0xbfb8aa3b, v100
	v_pk_mul_f32 v[106:107], v[108:109], v[106:107]
	v_exp_f32_e32 v108, v105
	v_mul_f32_e32 v105, 0xbfb8aa3b, v101
	v_exp_f32_e32 v109, v105
	v_cvt_pk_bf16_f32 v105, v106, v107
	v_add_f32_e32 v106, 1.0, v108
	v_mul_f32_e32 v108, 0xbfb8aa3b, v102
	v_add_f32_e32 v107, 1.0, v109
; DI unsigned pk_bf16(float lo, float hi) { f32x2 v = {lo, hi}; return __builtin_bit_cast(unsigned, __builtin_convertvector(v, bf16v2)); }
; DI float fast_silu(float x) { return x * fast_sigmoid(x); }
;     DI void operator()(AccRef acc, const Unit& u, int wr, int wc, int fr, int fq) const {
;     ...
;             for (int m = 0; m < 4; ++m) {
;                 const int row = row0 + ai * 128 + m * 16;
;                 const float r = RS ? rsc.r[ai][m] : 1.0f;
;                 const f32x4 a0 = acc[ai][0][m][0] * r, a1 = acc[ai][0][m][1] * r, b0 = acc[ai][1][m][0] * r, b1 = acc[ai][1][m][1] * r;
;                 u32x4 w;
;                 w.x = pk_bf16(fast_silu(a0[0]) * b0[0], fast_silu(a0[1]) * b0[1]); w.y = pk_bf16(fast_silu(a0[2]) * b0[2], fast_silu(a0[3]) * b0[3]);
;                 w.z = pk_bf16(fast_silu(a1[0]) * b1[0], fast_silu(a1[1]) * b1[1]); w.w = pk_bf16(fast_silu(a1[2]) * b1[2], fast_silu(a1[3]) * b1[3]);
;                 *(u32x4*)(G + (size_t)row * DFF + col) = w;
	v_mul_f32_e32 v109, 0xbfb8aa3b, v103
	v_exp_f32_e32 v108, v108
	v_exp_f32_e32 v109, v109
	v_rcp_f32_e32 v106, v106
	v_rcp_f32_e32 v107, v107
	v_add_f32_e32 v108, 1.0, v108
	v_add_f32_e32 v109, 1.0, v109
	v_rcp_f32_e32 v108, v108
	v_rcp_f32_e32 v109, v109
	v_pk_mul_f32 v[100:101], v[100:101], v[106:107]
	s_mov_b32 s92, s8
	v_pk_mul_f32 v[96:97], v[100:101], v[96:97]
	v_or_b32_e32 v100, 32, v152
	v_cvt_pk_bf16_f32 v106, v96, v97
	v_pk_mul_f32 v[96:97], v[102:103], v[108:109]
	s_mov_b32 s28, s10
	v_pk_mul_f32 v[96:97], v[96:97], v[98:99]
	v_mul_f32_e32 v98, 0xbfb8aa3b, v94
	v_cvt_pk_bf16_f32 v107, v96, v97
	v_mad_i64_i32 v[96:97], s[14:15], v116, s91, v[144:145]
	global_store_dwordx4 v[96:97], v[104:107], off
	v_mul_f32_e32 v96, 0xbfb8aa3b, v92
	v_mul_f32_e32 v97, 0xbfb8aa3b, v93
	v_exp_f32_e32 v96, v96
	v_exp_f32_e32 v97, v97
	v_mul_f32_e32 v99, 0xbfb8aa3b, v95
	v_exp_f32_e32 v98, v98
	v_exp_f32_e32 v99, v99
	v_add_f32_e32 v96, 1.0, v96
	v_add_f32_e32 v97, 1.0, v97
	v_rcp_f32_e32 v96, v96
	v_rcp_f32_e32 v97, v97
	v_add_f32_e32 v98, 1.0, v98
	v_add_f32_e32 v99, 1.0, v99
	v_rcp_f32_e32 v98, v98
	v_rcp_f32_e32 v99, v99
	v_pk_mul_f32 v[92:93], v[92:93], v[96:97]
	s_mov_b64 s[78:79], s[26:27]
	v_pk_mul_f32 v[88:89], v[92:93], v[88:89]
	v_pk_mul_f32 v[92:93], v[94:95], v[98:99]
	v_cvt_pk_bf16_f32 v88, v88, v89
	v_mul_f32_e32 v89, 0xbfb8aa3b, v84
	v_pk_mul_f32 v[90:91], v[92:93], v[90:91]
	v_exp_f32_e32 v92, v89
	v_mul_f32_e32 v89, 0xbfb8aa3b, v85
	v_exp_f32_e32 v93, v89
	v_cvt_pk_bf16_f32 v89, v90, v91
	v_add_f32_e32 v90, 1.0, v92
	v_mul_f32_e32 v92, 0xbfb8aa3b, v86
	v_add_f32_e32 v91, 1.0, v93
	v_mul_f32_e32 v93, 0xbfb8aa3b, v87
	v_exp_f32_e32 v92, v92
	v_exp_f32_e32 v93, v93
	v_rcp_f32_e32 v90, v90
	v_rcp_f32_e32 v91, v91
	v_add_f32_e32 v92, 1.0, v92
	v_add_f32_e32 v93, 1.0, v93
	v_rcp_f32_e32 v92, v92
	v_rcp_f32_e32 v93, v93
	v_pk_mul_f32 v[84:85], v[84:85], v[90:91]
	s_mov_b64 s[76:77], s[24:25]
	v_pk_mul_f32 v[80:81], v[84:85], v[80:81]
	v_or_b32_e32 v84, 48, v152
	v_cvt_pk_bf16_f32 v90, v80, v81
	v_pk_mul_f32 v[80:81], v[86:87], v[92:93]
	s_nop 0
	v_pk_mul_f32 v[80:81], v[80:81], v[82:83]
	v_mul_f32_e32 v82, 0xbfb8aa3b, v78
	v_cvt_pk_bf16_f32 v91, v80, v81
	v_mad_i64_i32 v[80:81], s[14:15], v100, s91, v[144:145]
	global_store_dwordx4 v[80:81], v[88:91], off
	v_mul_f32_e32 v80, 0xbfb8aa3b, v76
	v_mul_f32_e32 v81, 0xbfb8aa3b, v77
	v_exp_f32_e32 v80, v80
	v_exp_f32_e32 v81, v81
	v_mul_f32_e32 v83, 0xbfb8aa3b, v79
	v_exp_f32_e32 v82, v82
	v_exp_f32_e32 v83, v83
	v_add_f32_e32 v80, 1.0, v80
	v_add_f32_e32 v81, 1.0, v81
	v_rcp_f32_e32 v80, v80
	v_rcp_f32_e32 v81, v81
	v_add_f32_e32 v82, 1.0, v82
	v_add_f32_e32 v83, 1.0, v83
	v_rcp_f32_e32 v82, v82
	v_rcp_f32_e32 v83, v83
	v_pk_mul_f32 v[76:77], v[76:77], v[80:81]
	s_nop 0
	v_pk_mul_f32 v[72:73], v[76:77], v[72:73]
	v_pk_mul_f32 v[76:77], v[78:79], v[82:83]
	v_cvt_pk_bf16_f32 v72, v72, v73
	v_mul_f32_e32 v73, 0xbfb8aa3b, v68
	v_pk_mul_f32 v[74:75], v[76:77], v[74:75]
	v_exp_f32_e32 v76, v73
	v_mul_f32_e32 v73, 0xbfb8aa3b, v69
	v_exp_f32_e32 v77, v73
	v_cvt_pk_bf16_f32 v73, v74, v75
	v_add_f32_e32 v74, 1.0, v76
	v_mul_f32_e32 v76, 0xbfb8aa3b, v70
	v_add_f32_e32 v75, 1.0, v77
	v_mul_f32_e32 v77, 0xbfb8aa3b, v71
	v_exp_f32_e32 v76, v76
	v_exp_f32_e32 v77, v77
	v_rcp_f32_e32 v74, v74
	v_rcp_f32_e32 v75, v75
	v_add_f32_e32 v76, 1.0, v76
	v_add_f32_e32 v77, 1.0, v77
	v_rcp_f32_e32 v76, v76
	v_rcp_f32_e32 v77, v77
	v_pk_mul_f32 v[68:69], v[68:69], v[74:75]
	s_nop 0
	v_pk_mul_f32 v[64:65], v[68:69], v[64:65]
	v_add_u32_e32 v68, 0x80, v152
	v_cvt_pk_bf16_f32 v74, v64, v65
	v_pk_mul_f32 v[64:65], v[70:71], v[76:77]
	s_nop 0
	v_pk_mul_f32 v[64:65], v[64:65], v[66:67]
	v_mul_f32_e32 v66, 0xbfb8aa3b, v62
	v_cvt_pk_bf16_f32 v75, v64, v65
	v_mad_i64_i32 v[64:65], s[14:15], v84, s91, v[144:145]
	global_store_dwordx4 v[64:65], v[72:75], off
	v_mul_f32_e32 v64, 0xbfb8aa3b, v60
	v_mul_f32_e32 v65, 0xbfb8aa3b, v61
	v_exp_f32_e32 v64, v64
	v_exp_f32_e32 v65, v65
	v_mul_f32_e32 v67, 0xbfb8aa3b, v63
	v_exp_f32_e32 v66, v66
	v_exp_f32_e32 v67, v67
	v_add_f32_e32 v64, 1.0, v64
	v_add_f32_e32 v65, 1.0, v65
	v_rcp_f32_e32 v64, v64
	v_rcp_f32_e32 v65, v65
	v_add_f32_e32 v66, 1.0, v66
	v_add_f32_e32 v67, 1.0, v67
	v_rcp_f32_e32 v66, v66
	v_rcp_f32_e32 v67, v67
	v_pk_mul_f32 v[60:61], v[60:61], v[64:65]
	s_nop 0
	v_pk_mul_f32 v[56:57], v[60:61], v[56:57]
	v_pk_mul_f32 v[60:61], v[62:63], v[66:67]
	v_cvt_pk_bf16_f32 v56, v56, v57
	v_mul_f32_e32 v57, 0xbfb8aa3b, v52
	v_pk_mul_f32 v[58:59], v[60:61], v[58:59]
	v_exp_f32_e32 v60, v57
	v_mul_f32_e32 v57, 0xbfb8aa3b, v53
	v_exp_f32_e32 v61, v57
	v_cvt_pk_bf16_f32 v57, v58, v59
	v_add_f32_e32 v58, 1.0, v60
	v_mul_f32_e32 v60, 0xbfb8aa3b, v54
	v_add_f32_e32 v59, 1.0, v61
	v_mul_f32_e32 v61, 0xbfb8aa3b, v55
	v_exp_f32_e32 v60, v60
	v_exp_f32_e32 v61, v61
	v_rcp_f32_e32 v58, v58
	v_rcp_f32_e32 v59, v59
	v_add_f32_e32 v60, 1.0, v60
	v_add_f32_e32 v61, 1.0, v61
	v_rcp_f32_e32 v60, v60
	v_rcp_f32_e32 v61, v61
	v_pk_mul_f32 v[52:53], v[52:53], v[58:59]
	s_nop 0
	v_pk_mul_f32 v[48:49], v[52:53], v[48:49]
; DI unsigned pk_bf16(float lo, float hi) { f32x2 v = {lo, hi}; return __builtin_bit_cast(unsigned, __builtin_convertvector(v, bf16v2)); }
; DI float fast_silu(float x) { return x * fast_sigmoid(x); }
; #define PG8_WAIT_V(n) asm volatile("s_waitcnt vmcnt(" #n ")" ::: "memory")
; #define PG8_BAR __builtin_amdgcn_s_barrier()
; #define PG8_WAIT_V(n) asm volatile("s_waitcnt vmcnt(" #n ")" ::: "memory")
; #define PG8_BAR __builtin_amdgcn_s_barrier()
; template <class Epi>
; DI void gemm_phase(LAS unsigned char* lds, const Gemm g, const StaticOrder S, const Epi E) {
;     ...
;         E(acc, cur, wr, wc, fr, fq);
;         if (!has_next) break;
; #pragma unroll
;         for (int a = 0; a < 2; ++a)
; #pragma unroll
;             for (int b = 0; b < 2; ++b)
; #pragma unroll
;                 for (int m = 0; m < 4; ++m)
; #pragma unroll
;                     for (int n = 0; n < 2; ++n) acc[a][b][m][n] = (f32x4){0.f, 0.f, 0.f, 0.f};
;         cur = nxt; cA = nA; cB = nB; ++ui;
;     }
;     PG8_WAIT_V(0);
;     if (wr == 0) PG8_BAR;
;     PG8_BAR;
;     DI void operator()(AccRef acc, const Unit& u, int wr, int wc, int fr, int fq) const {
;     ...
;             for (int m = 0; m < 4; ++m) {
;                 const int row = row0 + ai * 128 + m * 16;
;                 const float r = RS ? rsc.r[ai][m] : 1.0f;
;                 const f32x4 a0 = acc[ai][0][m][0] * r, a1 = acc[ai][0][m][1] * r, b0 = acc[ai][1][m][0] * r, b1 = acc[ai][1][m][1] * r;
;                 u32x4 w;
;                 w.x = pk_bf16(fast_silu(a0[0]) * b0[0], fast_silu(a0[1]) * b0[1]); w.y = pk_bf16(fast_silu(a0[2]) * b0[2], fast_silu(a0[3]) * b0[3]);
;                 w.z = pk_bf16(fast_silu(a1[0]) * b1[0], fast_silu(a1[1]) * b1[1]); w.w = pk_bf16(fast_silu(a1[2]) * b1[2], fast_silu(a1[3]) * b1[3]);
;                 *(u32x4*)(G + (size_t)row * DFF + col) = w;
	v_add_u32_e32 v52, 0x90, v152
	v_cvt_pk_bf16_f32 v58, v48, v49
	v_pk_mul_f32 v[48:49], v[54:55], v[60:61]
	s_nop 0
	v_pk_mul_f32 v[48:49], v[48:49], v[50:51]
	v_mul_f32_e32 v50, 0xbfb8aa3b, v46
	v_cvt_pk_bf16_f32 v59, v48, v49
	v_mad_i64_i32 v[48:49], s[14:15], v68, s91, v[144:145]
	global_store_dwordx4 v[48:49], v[56:59], off
	v_mul_f32_e32 v48, 0xbfb8aa3b, v44
	v_mul_f32_e32 v49, 0xbfb8aa3b, v45
	v_exp_f32_e32 v48, v48
	v_exp_f32_e32 v49, v49
	v_mul_f32_e32 v51, 0xbfb8aa3b, v47
	v_exp_f32_e32 v50, v50
	v_exp_f32_e32 v51, v51
	v_add_f32_e32 v48, 1.0, v48
	v_add_f32_e32 v49, 1.0, v49
	v_rcp_f32_e32 v48, v48
	v_rcp_f32_e32 v49, v49
	v_add_f32_e32 v50, 1.0, v50
	v_add_f32_e32 v51, 1.0, v51
	v_rcp_f32_e32 v50, v50
	v_rcp_f32_e32 v51, v51
	v_pk_mul_f32 v[44:45], v[44:45], v[48:49]
	s_nop 0
	v_pk_mul_f32 v[40:41], v[44:45], v[40:41]
	v_pk_mul_f32 v[44:45], v[46:47], v[50:51]
	v_cvt_pk_bf16_f32 v40, v40, v41
	v_mul_f32_e32 v41, 0xbfb8aa3b, v36
	v_pk_mul_f32 v[42:43], v[44:45], v[42:43]
	v_exp_f32_e32 v44, v41
	v_mul_f32_e32 v41, 0xbfb8aa3b, v37
	v_exp_f32_e32 v45, v41
	v_cvt_pk_bf16_f32 v41, v42, v43
	v_add_f32_e32 v42, 1.0, v44
	v_mul_f32_e32 v44, 0xbfb8aa3b, v38
	v_add_f32_e32 v43, 1.0, v45
	v_mul_f32_e32 v45, 0xbfb8aa3b, v39
	v_exp_f32_e32 v44, v44
	v_exp_f32_e32 v45, v45
	v_rcp_f32_e32 v42, v42
	v_rcp_f32_e32 v43, v43
	v_add_f32_e32 v44, 1.0, v44
	v_add_f32_e32 v45, 1.0, v45
	v_rcp_f32_e32 v44, v44
	v_rcp_f32_e32 v45, v45
	v_pk_mul_f32 v[36:37], v[36:37], v[42:43]
	s_nop 0
	v_pk_mul_f32 v[32:33], v[36:37], v[32:33]
	v_add_u32_e32 v36, 0xa0, v152
	v_cvt_pk_bf16_f32 v42, v32, v33
	v_pk_mul_f32 v[32:33], v[38:39], v[44:45]
	s_nop 0
	v_pk_mul_f32 v[32:33], v[32:33], v[34:35]
	v_mul_f32_e32 v34, 0xbfb8aa3b, v30
	v_cvt_pk_bf16_f32 v43, v32, v33
	v_mad_i64_i32 v[32:33], s[14:15], v52, s91, v[144:145]
	global_store_dwordx4 v[32:33], v[40:43], off
	v_mul_f32_e32 v32, 0xbfb8aa3b, v28
	v_mul_f32_e32 v33, 0xbfb8aa3b, v29
	v_exp_f32_e32 v32, v32
	v_exp_f32_e32 v33, v33
	v_mul_f32_e32 v35, 0xbfb8aa3b, v31
	v_exp_f32_e32 v34, v34
	v_exp_f32_e32 v35, v35
	v_add_f32_e32 v32, 1.0, v32
	v_add_f32_e32 v33, 1.0, v33
	v_rcp_f32_e32 v32, v32
	v_rcp_f32_e32 v33, v33
	v_add_f32_e32 v34, 1.0, v34
	v_add_f32_e32 v35, 1.0, v35
	v_rcp_f32_e32 v34, v34
	v_rcp_f32_e32 v35, v35
	v_pk_mul_f32 v[28:29], v[28:29], v[32:33]
	s_nop 0
	v_pk_mul_f32 v[24:25], v[28:29], v[24:25]
	v_pk_mul_f32 v[28:29], v[30:31], v[34:35]
	v_cvt_pk_bf16_f32 v24, v24, v25
	v_mul_f32_e32 v25, 0xbfb8aa3b, v20
	v_pk_mul_f32 v[26:27], v[28:29], v[26:27]
	v_exp_f32_e32 v28, v25
	v_mul_f32_e32 v25, 0xbfb8aa3b, v21
	v_exp_f32_e32 v29, v25
	v_cvt_pk_bf16_f32 v25, v26, v27
	v_add_f32_e32 v26, 1.0, v28
	v_mul_f32_e32 v28, 0xbfb8aa3b, v22
	v_add_f32_e32 v27, 1.0, v29
	v_mul_f32_e32 v29, 0xbfb8aa3b, v23
	v_exp_f32_e32 v28, v28
	v_exp_f32_e32 v29, v29
	v_rcp_f32_e32 v26, v26
	v_rcp_f32_e32 v27, v27
	v_add_f32_e32 v28, 1.0, v28
	v_add_f32_e32 v29, 1.0, v29
	v_rcp_f32_e32 v28, v28
	v_rcp_f32_e32 v29, v29
	v_pk_mul_f32 v[20:21], v[20:21], v[26:27]
	s_nop 0
	v_pk_mul_f32 v[16:17], v[20:21], v[16:17]
	v_add_u32_e32 v20, 0xb0, v152
	v_cvt_pk_bf16_f32 v26, v16, v17
	v_pk_mul_f32 v[16:17], v[22:23], v[28:29]
	s_nop 0
	v_pk_mul_f32 v[16:17], v[16:17], v[18:19]
	v_mul_f32_e32 v18, 0xbfb8aa3b, v14
	v_cvt_pk_bf16_f32 v27, v16, v17
	v_mad_i64_i32 v[16:17], s[14:15], v36, s91, v[144:145]
	global_store_dwordx4 v[16:17], v[24:27], off
	v_mul_f32_e32 v16, 0xbfb8aa3b, v12
	v_mul_f32_e32 v17, 0xbfb8aa3b, v13
	v_exp_f32_e32 v16, v16
	v_exp_f32_e32 v17, v17
	v_mul_f32_e32 v19, 0xbfb8aa3b, v15
	v_exp_f32_e32 v18, v18
	v_exp_f32_e32 v19, v19
	v_add_f32_e32 v16, 1.0, v16
	v_add_f32_e32 v17, 1.0, v17
	v_rcp_f32_e32 v16, v16
	v_rcp_f32_e32 v17, v17
	v_add_f32_e32 v18, 1.0, v18
	v_add_f32_e32 v19, 1.0, v19
	v_rcp_f32_e32 v18, v18
	v_rcp_f32_e32 v19, v19
	v_pk_mul_f32 v[12:13], v[12:13], v[16:17]
	s_nop 0
	v_pk_mul_f32 v[8:9], v[12:13], v[8:9]
	v_pk_mul_f32 v[12:13], v[14:15], v[18:19]
	v_cvt_pk_bf16_f32 v8, v8, v9
	v_mul_f32_e32 v9, 0xbfb8aa3b, v4
	v_pk_mul_f32 v[10:11], v[12:13], v[10:11]
	v_exp_f32_e32 v12, v9
	v_mul_f32_e32 v9, 0xbfb8aa3b, v5
	v_exp_f32_e32 v13, v9
	v_cvt_pk_bf16_f32 v9, v10, v11
	v_add_f32_e32 v10, 1.0, v12
	v_mul_f32_e32 v12, 0xbfb8aa3b, v6
	v_add_f32_e32 v11, 1.0, v13
	v_mul_f32_e32 v13, 0xbfb8aa3b, v7
	v_exp_f32_e32 v12, v12
	v_exp_f32_e32 v13, v13
	v_rcp_f32_e32 v10, v10
	v_rcp_f32_e32 v11, v11
	v_add_f32_e32 v12, 1.0, v12
	v_add_f32_e32 v13, 1.0, v13
	v_rcp_f32_e32 v12, v12
	v_rcp_f32_e32 v13, v13
	v_pk_mul_f32 v[4:5], v[4:5], v[10:11]
	s_nop 0
	v_pk_mul_f32 v[0:1], v[4:5], v[0:1]
	s_nop 0
	v_cvt_pk_bf16_f32 v10, v0, v1
	v_pk_mul_f32 v[0:1], v[6:7], v[12:13]
	s_nop 0
	v_pk_mul_f32 v[0:1], v[0:1], v[2:3]
	s_nop 0
	v_cvt_pk_bf16_f32 v11, v0, v1
	v_mad_i64_i32 v[0:1], s[14:15], v20, s91, v[144:145]
	global_store_dwordx4 v[0:1], v[8:11], off
	s_cbranch_vccz .LBB0_104
	s_waitcnt vmcnt(0)
	v_readlane_b32 s92, v243, 8
	s_cmpk_gt_u32 s6, 0xff
	v_readlane_b32 s93, v243, 9
	s_cbranch_scc1 .LBB0_111
	s_barrier

; #define PG8_STAGE(bufoff, gbase, voff) do { _Pragma("unroll") for (int _i = 0; _i < 2; ++_i) \
;         __builtin_amdgcn_global_load_lds((const unsigned*)((const char*)(gbase) + (voff)[_i]), (LAS unsigned*)(lds + (bufoff) + ldsw + _i * 8192), 16, 0, 0); } while (0)
; #define PG8_LDA(dst, b, h) do { _Pragma("unroll") for (int m = 0; m < 4; ++m) _Pragma("unroll") for (int k = 0; k < 2; ++k) dst[m][k] = *(const LAS bf16x8*)(lds + PG8_SA(b, h) + aoff + m * 2048 + k * 1024); } while (0)
; #define PG8_LDB(dst, b, h) do { _Pragma("unroll") for (int n = 0; n < 2; ++n) _Pragma("unroll") for (int k = 0; k < 2; ++k) dst[n][k] = *(const LAS bf16x8*)(lds + PG8_SB(b, h) + boff + n * 2048 + k * 1024); } while (0)
; #define PG8_MMA(ai, bj, At, Bt) do { __builtin_amdgcn_s_setprio(1); _Pragma("unroll") for (int m = 0; m < 4; ++m) _Pragma("unroll") for (int n = 0; n < 2; ++n) _Pragma("unroll") for (int k = 0; k < 2; ++k) \
;         acc[ai][bj][m][n] = __builtin_amdgcn_mfma_f32_16x16x32_bf16(Bt[n][k], At[m][k], acc[ai][bj][m][n], 0, 0, 0); __builtin_amdgcn_s_setprio(0); } while (0)
; #define PG8_WAIT_V(n) asm volatile("s_waitcnt vmcnt(" #n ")" ::: "memory")
; #define PG8_WAIT_L(n) asm volatile("s_waitcnt lgkmcnt(" #n ")" ::: "memory")
; #define PG8_BAR __builtin_amdgcn_s_barrier()
; #define PG8_SCHED __builtin_amdgcn_sched_barrier(0)
; #define PG8_STAGE(bufoff, gbase, voff) do { _Pragma("unroll") for (int _i = 0; _i < 2; ++_i) \
;         __builtin_amdgcn_global_load_lds((const unsigned*)((const char*)(gbase) + (voff)[_i]), (LAS unsigned*)(lds + (bufoff) + ldsw + _i * 8192), 16, 0, 0); } while (0)
; #define PG8_BAR __builtin_amdgcn_s_barrier()
; template <class Epi>
; DI void gemm_phase(LAS unsigned char* lds, const Gemm g, const StaticOrder S, const Epi E) {
;     ...
;             PG8_LDB(B0, 0, 0); PG8_SCHED; PG8_LDA(At, 0, 0); PG8_STAGE(PG8_SA(1, 1), a1 + hstep, voffA);
;             PG8_WAIT_L(8); PG8_BAR; PG8_WAIT_L(0); PG8_MMA(0, 0, At, B0); PG8_BAR; PG8_SCHED;
;             PG8_LDB(B1, 0, 1); PG8_STAGE(PG8_SB(0, 0), b2, voffB);
;             PG8_BAR; PG8_WAIT_L(0); PG8_MMA(0, 1, At, B1); PG8_BAR;
;             PG8_LDA(At, 0, 1); PG8_STAGE(PG8_SA(0, 0), a2, voffA);
;             PG8_BAR; PG8_WAIT_L(0); PG8_MMA(1, 0, At, B0); PG8_BAR; PG8_SCHED;
;             PG8_STAGE(PG8_SB(0, 1), b2 + hstep, voffB);
;             PG8_WAIT_V(6); PG8_BAR; PG8_MMA(1, 1, At, B1); PG8_BAR;
.LBB0_186:
	ds_read_b128 v[128:131], v207
	ds_read_b128 v[132:135], v207 offset:1024
	ds_read_b128 v[136:139], v207 offset:2048
	ds_read_b128 v[140:143], v207 offset:3072
	s_add_u32 s76, s28, 0x100
	s_addc_u32 s77, s29, 0
	s_cmp_eq_u32 s97, 40
	s_cselect_b32 s81, s9, s77
	s_cselect_b32 s80, s8, s76
	s_cselect_b32 s79, s11, s7
	s_cselect_b32 s78, s10, s6
	v_lshl_add_u64 v[192:193], s[28:29], 0, v[184:185]
	s_add_i32 m0, s82, 0xc000
	ds_read_b128 v[144:147], v208
	ds_read_b128 v[148:151], v208 offset:1024
	ds_read_b128 v[152:155], v208 offset:2048
	ds_read_b128 v[156:159], v208 offset:3072
	ds_read_b128 v[160:163], v208 offset:4096
	ds_read_b128 v[164:167], v208 offset:5120
	ds_read_b128 v[168:171], v208 offset:6144
	ds_read_b128 v[172:175], v208 offset:7168
	global_load_lds_dwordx4 v[192:193], off
	v_lshl_add_u64 v[192:193], s[28:29], 0, v[186:187]
	s_add_i32 m0, s82, 0xe000
	s_nop 0
	global_load_lds_dwordx4 v[192:193], off
	s_waitcnt lgkmcnt(8)
	s_barrier
	s_waitcnt lgkmcnt(0)
	s_setprio 1
	s_waitcnt lgkmcnt(0)
	v_mfma_f32_16x16x32_bf16 v[124:127], v[128:131], v[144:147], v[124:127]
	v_mfma_f32_16x16x32_bf16 v[120:123], v[136:139], v[144:147], v[120:123]
	v_mfma_f32_16x16x32_bf16 v[108:111], v[128:131], v[152:155], v[108:111]
	v_mfma_f32_16x16x32_bf16 v[104:107], v[136:139], v[152:155], v[104:107]
	v_mfma_f32_16x16x32_bf16 v[92:95], v[128:131], v[160:163], v[92:95]
	v_mfma_f32_16x16x32_bf16 v[88:91], v[136:139], v[160:163], v[88:91]
	v_mfma_f32_16x16x32_bf16 v[76:79], v[128:131], v[168:171], v[76:79]
	v_mfma_f32_16x16x32_bf16 v[72:75], v[136:139], v[168:171], v[72:75]
	v_mfma_f32_16x16x32_bf16 v[124:127], v[132:135], v[148:151], v[124:127]
	v_mfma_f32_16x16x32_bf16 v[120:123], v[140:143], v[148:151], v[120:123]
	v_mfma_f32_16x16x32_bf16 v[108:111], v[132:135], v[156:159], v[108:111]
	v_mfma_f32_16x16x32_bf16 v[104:107], v[140:143], v[156:159], v[104:107]
	v_mfma_f32_16x16x32_bf16 v[92:95], v[132:135], v[164:167], v[92:95]
	v_mfma_f32_16x16x32_bf16 v[88:91], v[140:143], v[164:167], v[88:91]
	v_mfma_f32_16x16x32_bf16 v[76:79], v[132:135], v[172:175], v[76:79]
	v_mfma_f32_16x16x32_bf16 v[72:75], v[140:143], v[172:175], v[72:75]
	s_setprio 0
	s_barrier
	s_add_i32 s14, s91, s59
	v_lshl_add_u64 v[216:217], s[78:79], 0, v[178:179]
	s_mov_b32 m0, s14
	ds_read_b128 v[192:195], v209
	ds_read_b128 v[196:199], v209 offset:1024
	ds_read_b128 v[200:203], v209 offset:2048
	ds_read_b128 v[212:215], v209 offset:3072
	global_load_lds_dwordx4 v[216:217], off
	v_lshl_add_u64 v[218:219], s[78:79], 0, v[182:183]
	s_add_i32 m0, s14, 0x2000
	s_nop 0
	global_load_lds_dwordx4 v[218:219], off
	s_barrier
	s_waitcnt lgkmcnt(0)
	s_setprio 1
	s_waitcnt lgkmcnt(0)
	v_mfma_f32_16x16x32_bf16 v[116:119], v[192:195], v[144:147], v[116:119]
	v_mfma_f32_16x16x32_bf16 v[112:115], v[200:203], v[144:147], v[112:115]
	v_mfma_f32_16x16x32_bf16 v[100:103], v[192:195], v[152:155], v[100:103]
	v_mfma_f32_16x16x32_bf16 v[96:99], v[200:203], v[152:155], v[96:99]
	v_mfma_f32_16x16x32_bf16 v[84:87], v[192:195], v[160:163], v[84:87]
	v_mfma_f32_16x16x32_bf16 v[80:83], v[200:203], v[160:163], v[80:83]
	v_mfma_f32_16x16x32_bf16 v[68:71], v[192:195], v[168:171], v[68:71]
	v_mfma_f32_16x16x32_bf16 v[64:67], v[200:203], v[168:171], v[64:67]
	v_mfma_f32_16x16x32_bf16 v[116:119], v[196:199], v[148:151], v[116:119]
	v_mfma_f32_16x16x32_bf16 v[112:115], v[212:215], v[148:151], v[112:115]
	v_mfma_f32_16x16x32_bf16 v[100:103], v[196:199], v[156:159], v[100:103]
	v_mfma_f32_16x16x32_bf16 v[96:99], v[212:215], v[156:159], v[96:99]
	v_mfma_f32_16x16x32_bf16 v[84:87], v[196:199], v[164:167], v[84:87]
	v_mfma_f32_16x16x32_bf16 v[80:83], v[212:215], v[164:167], v[80:83]
	v_mfma_f32_16x16x32_bf16 v[68:71], v[196:199], v[172:175], v[68:71]
	v_mfma_f32_16x16x32_bf16 v[64:67], v[212:215], v[172:175], v[64:67]
	s_setprio 0
	s_mov_b32 m0, s82
	v_lshl_add_u64 v[220:221], s[80:81], 0, v[176:177]
	s_barrier
	ds_read_b128 v[144:147], v208 offset:16384
	ds_read_b128 v[148:151], v208 offset:17408
	ds_read_b128 v[152:155], v208 offset:18432
	ds_read_b128 v[156:159], v208 offset:19456
	ds_read_b128 v[160:163], v208 offset:20480
	ds_read_b128 v[164:167], v208 offset:21504
	ds_read_b128 v[168:171], v208 offset:22528
	ds_read_b128 v[172:175], v208 offset:23552
	global_load_lds_dwordx4 v[220:221], off
	v_lshl_add_u64 v[224:225], s[80:81], 0, v[180:181]
	s_mov_b32 m0, s83
	s_nop 0
	global_load_lds_dwordx4 v[224:225], off
	s_barrier
	s_waitcnt lgkmcnt(0)
	s_setprio 1
	s_waitcnt lgkmcnt(0)
	v_mfma_f32_16x16x32_bf16 v[60:63], v[128:131], v[144:147], v[60:63]
	v_mfma_f32_16x16x32_bf16 v[56:59], v[136:139], v[144:147], v[56:59]
	v_mfma_f32_16x16x32_bf16 v[44:47], v[128:131], v[152:155], v[44:47]
	v_mfma_f32_16x16x32_bf16 v[40:43], v[136:139], v[152:155], v[40:43]
	v_mfma_f32_16x16x32_bf16 v[28:31], v[128:131], v[160:163], v[28:31]
	v_mfma_f32_16x16x32_bf16 v[24:27], v[136:139], v[160:163], v[24:27]
	v_mfma_f32_16x16x32_bf16 v[12:15], v[128:131], v[168:171], v[12:15]
	v_mfma_f32_16x16x32_bf16 v[8:11], v[136:139], v[168:171], v[8:11]
	v_mfma_f32_16x16x32_bf16 v[60:63], v[132:135], v[148:151], v[60:63]
	v_mfma_f32_16x16x32_bf16 v[56:59], v[140:143], v[148:151], v[56:59]
	v_mfma_f32_16x16x32_bf16 v[44:47], v[132:135], v[156:159], v[44:47]
	v_mfma_f32_16x16x32_bf16 v[40:43], v[140:143], v[156:159], v[40:43]
	v_mfma_f32_16x16x32_bf16 v[28:31], v[132:135], v[164:167], v[28:31]
	v_mfma_f32_16x16x32_bf16 v[24:27], v[140:143], v[164:167], v[24:27]
	v_mfma_f32_16x16x32_bf16 v[12:15], v[132:135], v[172:175], v[12:15]
	v_mfma_f32_16x16x32_bf16 v[8:11], v[140:143], v[172:175], v[8:11]
	s_setprio 0
	s_barrier
; #define PG8_STAGE(bufoff, gbase, voff) do { _Pragma("unroll") for (int _i = 0; _i < 2; ++_i) \
;         __builtin_amdgcn_global_load_lds((const unsigned*)((const char*)(gbase) + (voff)[_i]), (LAS unsigned*)(lds + (bufoff) + ldsw + _i * 8192), 16, 0, 0); } while (0)
; #define PG8_LDA(dst, b, h) do { _Pragma("unroll") for (int m = 0; m < 4; ++m) _Pragma("unroll") for (int k = 0; k < 2; ++k) dst[m][k] = *(const LAS bf16x8*)(lds + PG8_SA(b, h) + aoff + m * 2048 + k * 1024); } while (0)
; #define PG8_LDB(dst, b, h) do { _Pragma("unroll") for (int n = 0; n < 2; ++n) _Pragma("unroll") for (int k = 0; k < 2; ++k) dst[n][k] = *(const LAS bf16x8*)(lds + PG8_SB(b, h) + boff + n * 2048 + k * 1024); } while (0)
; #define PG8_MMA(ai, bj, At, Bt) do { __builtin_amdgcn_s_setprio(1); _Pragma("unroll") for (int m = 0; m < 4; ++m) _Pragma("unroll") for (int n = 0; n < 2; ++n) _Pragma("unroll") for (int k = 0; k < 2; ++k) \
;         acc[ai][bj][m][n] = __builtin_amdgcn_mfma_f32_16x16x32_bf16(Bt[n][k], At[m][k], acc[ai][bj][m][n], 0, 0, 0); __builtin_amdgcn_s_setprio(0); } while (0)
; #define PG8_WAIT_V(n) asm volatile("s_waitcnt vmcnt(" #n ")" ::: "memory")
; #define PG8_WAIT_L(n) asm volatile("s_waitcnt lgkmcnt(" #n ")" ::: "memory")
; #define PG8_BAR __builtin_amdgcn_s_barrier()
; #define PG8_SCHED __builtin_amdgcn_sched_barrier(0)
; #define PG8_STAGE(bufoff, gbase, voff) do { _Pragma("unroll") for (int _i = 0; _i < 2; ++_i) \
;         __builtin_amdgcn_global_load_lds((const unsigned*)((const char*)(gbase) + (voff)[_i]), (LAS unsigned*)(lds + (bufoff) + ldsw + _i * 8192), 16, 0, 0); } while (0)
; #define PG8_BAR __builtin_amdgcn_s_barrier()
; template <class Epi>
; DI void gemm_phase(LAS unsigned char* lds, const Gemm g, const StaticOrder S, const Epi E) {
;     ...
;             PG8_STAGE(PG8_SB(0, 1), b2 + hstep, voffB);
;             PG8_WAIT_V(6); PG8_BAR; PG8_MMA(1, 1, At, B1); PG8_BAR;
;             PG8_LDB(B0, 1, 0); PG8_SCHED; PG8_LDA(At, 1, 0); PG8_STAGE(PG8_SA(0, 1), a2 + hstep, voffA);
;             PG8_WAIT_L(8); PG8_BAR; PG8_WAIT_L(0); PG8_MMA(0, 0, At, B0); PG8_BAR; PG8_SCHED;
;             PG8_LDB(B1, 1, 1); PG8_STAGE(PG8_SB(1, 0), b3, voffB);
;             PG8_BAR; PG8_WAIT_L(0); PG8_MMA(0, 1, At, B1); PG8_BAR;
;             PG8_LDA(At, 1, 1); PG8_STAGE(PG8_SA(1, 0), a3, voffA);
;             PG8_BAR; PG8_WAIT_L(0); PG8_MMA(1, 0, At, B0); PG8_BAR; PG8_SCHED;
	s_add_u32 s14, s78, 0xb0000
	s_addc_u32 s15, s79, 0
	s_add_i32 s28, s92, s59
	v_lshl_add_u64 v[128:129], s[14:15], 0, v[178:179]
	s_mov_b32 m0, s28
	s_nop 0
	global_load_lds_dwordx4 v[128:129], off
	v_lshl_add_u64 v[128:129], s[14:15], 0, v[182:183]
	s_add_i32 m0, s28, 0x2000
	s_nop 0
	global_load_lds_dwordx4 v[128:129], off
	s_waitcnt vmcnt(6)
	s_barrier
	s_setprio 1
	v_mfma_f32_16x16x32_bf16 v[52:55], v[192:195], v[144:147], v[52:55]
	v_mfma_f32_16x16x32_bf16 v[48:51], v[200:203], v[144:147], v[48:51]
	v_mfma_f32_16x16x32_bf16 v[36:39], v[192:195], v[152:155], v[36:39]
	v_mfma_f32_16x16x32_bf16 v[32:35], v[200:203], v[152:155], v[32:35]
	v_mfma_f32_16x16x32_bf16 v[20:23], v[192:195], v[160:163], v[20:23]
	v_mfma_f32_16x16x32_bf16 v[16:19], v[200:203], v[160:163], v[16:19]
	v_mfma_f32_16x16x32_bf16 v[4:7], v[192:195], v[168:171], v[4:7]
	v_mfma_f32_16x16x32_bf16 v[0:3], v[200:203], v[168:171], v[0:3]
	v_mfma_f32_16x16x32_bf16 v[52:55], v[196:199], v[148:151], v[52:55]
	v_mfma_f32_16x16x32_bf16 v[48:51], v[212:215], v[148:151], v[48:51]
	v_mfma_f32_16x16x32_bf16 v[36:39], v[196:199], v[156:159], v[36:39]
	v_mfma_f32_16x16x32_bf16 v[32:35], v[212:215], v[156:159], v[32:35]
	v_mfma_f32_16x16x32_bf16 v[20:23], v[196:199], v[164:167], v[20:23]
	v_mfma_f32_16x16x32_bf16 v[16:19], v[212:215], v[164:167], v[16:19]
	v_mfma_f32_16x16x32_bf16 v[4:7], v[196:199], v[172:175], v[4:7]
	v_mfma_f32_16x16x32_bf16 v[0:3], v[212:215], v[172:175], v[0:3]
	s_setprio 0
	s_add_i32 s28, 0, 0x18000
	v_add_u32_e32 v140, s28, v205
	s_barrier
	ds_read_b128 v[128:131], v140
	ds_read_b128 v[132:135], v140 offset:1024
	ds_read_b128 v[136:139], v140 offset:2048
	ds_read_b128 v[140:143], v140 offset:3072
	s_add_u32 s14, s80, 0xb0000
	s_addc_u32 s15, s81, 0
	s_mov_b32 m0, s84
	v_lshl_add_u64 v[192:193], s[14:15], 0, v[176:177]
	ds_read_b128 v[144:147], v208 offset:32768
	ds_read_b128 v[148:151], v208 offset:33792
	ds_read_b128 v[152:155], v208 offset:34816
	ds_read_b128 v[156:159], v208 offset:35840
	ds_read_b128 v[160:163], v208 offset:36864
	ds_read_b128 v[164:167], v208 offset:37888
	ds_read_b128 v[168:171], v208 offset:38912
	ds_read_b128 v[172:175], v208 offset:39936
	global_load_lds_dwordx4 v[192:193], off
	v_lshl_add_u64 v[192:193], s[14:15], 0, v[180:181]
	s_mov_b32 m0, s85
	s_nop 0
	global_load_lds_dwordx4 v[192:193], off
	s_waitcnt lgkmcnt(8)
	s_barrier
	s_waitcnt lgkmcnt(0)
	s_setprio 1
	s_waitcnt lgkmcnt(0)
	v_mfma_f32_16x16x32_bf16 v[124:127], v[128:131], v[144:147], v[124:127]
	v_mfma_f32_16x16x32_bf16 v[120:123], v[136:139], v[144:147], v[120:123]
	v_mfma_f32_16x16x32_bf16 v[108:111], v[128:131], v[152:155], v[108:111]
	v_mfma_f32_16x16x32_bf16 v[104:107], v[136:139], v[152:155], v[104:107]
	v_mfma_f32_16x16x32_bf16 v[92:95], v[128:131], v[160:163], v[92:95]
	v_mfma_f32_16x16x32_bf16 v[88:91], v[136:139], v[160:163], v[88:91]
	v_mfma_f32_16x16x32_bf16 v[76:79], v[128:131], v[168:171], v[76:79]
	v_mfma_f32_16x16x32_bf16 v[72:75], v[136:139], v[168:171], v[72:75]
	v_mfma_f32_16x16x32_bf16 v[124:127], v[132:135], v[148:151], v[124:127]
	v_mfma_f32_16x16x32_bf16 v[120:123], v[140:143], v[148:151], v[120:123]
	v_mfma_f32_16x16x32_bf16 v[108:111], v[132:135], v[156:159], v[108:111]
	v_mfma_f32_16x16x32_bf16 v[104:107], v[140:143], v[156:159], v[104:107]
	v_mfma_f32_16x16x32_bf16 v[92:95], v[132:135], v[164:167], v[92:95]
	v_mfma_f32_16x16x32_bf16 v[88:91], v[140:143], v[164:167], v[88:91]
	v_mfma_f32_16x16x32_bf16 v[76:79], v[132:135], v[172:175], v[76:79]
	v_mfma_f32_16x16x32_bf16 v[72:75], v[140:143], v[172:175], v[72:75]
	s_setprio 0
	s_barrier
	s_add_i32 s29, 0, 0x1c000
	s_add_i32 s14, s28, s59
	v_add_u32_e32 v211, s29, v205
	v_lshl_add_u64 v[216:217], v[216:217], 0, s[24:25]
	s_mov_b32 m0, s14
	ds_read_b128 v[192:195], v211
	ds_read_b128 v[196:199], v211 offset:1024
	ds_read_b128 v[200:203], v211 offset:2048
	ds_read_b128 v[212:215], v211 offset:3072
	global_load_lds_dwordx4 v[216:217], off
	v_lshl_add_u64 v[216:217], v[218:219], 0, s[24:25]
	s_add_i32 m0, s14, 0x2000
	s_nop 0
	global_load_lds_dwordx4 v[216:217], off
	s_barrier
	s_waitcnt lgkmcnt(0)
	s_setprio 1
	s_waitcnt lgkmcnt(0)
	v_mfma_f32_16x16x32_bf16 v[116:119], v[192:195], v[144:147], v[116:119]
	v_mfma_f32_16x16x32_bf16 v[112:115], v[200:203], v[144:147], v[112:115]
	v_mfma_f32_16x16x32_bf16 v[100:103], v[192:195], v[152:155], v[100:103]
	v_mfma_f32_16x16x32_bf16 v[96:99], v[200:203], v[152:155], v[96:99]
	v_mfma_f32_16x16x32_bf16 v[84:87], v[192:195], v[160:163], v[84:87]
	v_mfma_f32_16x16x32_bf16 v[80:83], v[200:203], v[160:163], v[80:83]
	v_mfma_f32_16x16x32_bf16 v[68:71], v[192:195], v[168:171], v[68:71]
	v_mfma_f32_16x16x32_bf16 v[64:67], v[200:203], v[168:171], v[64:67]
	v_mfma_f32_16x16x32_bf16 v[116:119], v[196:199], v[148:151], v[116:119]
	v_mfma_f32_16x16x32_bf16 v[112:115], v[212:215], v[148:151], v[112:115]
	v_mfma_f32_16x16x32_bf16 v[100:103], v[196:199], v[156:159], v[100:103]
	v_mfma_f32_16x16x32_bf16 v[96:99], v[212:215], v[156:159], v[96:99]
	v_mfma_f32_16x16x32_bf16 v[84:87], v[196:199], v[164:167], v[84:87]
	v_mfma_f32_16x16x32_bf16 v[80:83], v[212:215], v[164:167], v[80:83]
	v_mfma_f32_16x16x32_bf16 v[68:71], v[196:199], v[172:175], v[68:71]
	v_mfma_f32_16x16x32_bf16 v[64:67], v[212:215], v[172:175], v[64:67]
	s_setprio 0
	s_mov_b32 m0, s87
	v_lshl_add_u64 v[216:217], v[220:221], 0, s[24:25]
	s_barrier
	ds_read_b128 v[144:147], v208 offset:49152
	ds_read_b128 v[148:151], v208 offset:50176
	ds_read_b128 v[152:155], v208 offset:51200
	ds_read_b128 v[156:159], v208 offset:52224
	ds_read_b128 v[160:163], v208 offset:53248
	ds_read_b128 v[164:167], v208 offset:54272
	ds_read_b128 v[168:171], v208 offset:55296
	ds_read_b128 v[172:175], v208 offset:56320
	global_load_lds_dwordx4 v[216:217], off
	v_lshl_add_u64 v[216:217], v[224:225], 0, s[24:25]
	s_mov_b32 m0, s88
	s_nop 0
	global_load_lds_dwordx4 v[216:217], off
	s_barrier
; DI unsigned pk_bf16(float lo, float hi) { f32x2 v = {lo, hi}; return __builtin_bit_cast(unsigned, __builtin_convertvector(v, bf16v2)); }
; DI f32x4 bf_lo4(u32x4 w) { f32x4 r; r[0] = bf_lo(w.x); r[1] = bf_hi(w.x); r[2] = bf_lo(w.y); r[3] = bf_hi(w.y); return r; }
; DI f32x4 bf_hi4(u32x4 w) { f32x4 r; r[0] = bf_lo(w.z); r[1] = bf_hi(w.z); r[2] = bf_lo(w.w); r[3] = bf_hi(w.w); return r; }
; #define PG8_WAIT_V(n) asm volatile("s_waitcnt vmcnt(" #n ")" ::: "memory")
; template <class Epi>
; DI void gemm_phase(LAS unsigned char* lds, const Gemm g, const StaticOrder S, const Epi E) {
;     ...
;             PG8_BAR; PG8_WAIT_L(0); PG8_MMA(1, 0, At, B0); PG8_BAR; PG8_SCHED;
;             PG8_STAGE(PG8_SB(1, 1), b3 + hstep, voffB);
;             PG8_WAIT_V(6); PG8_BAR; PG8_MMA(1, 1, At, B1); PG8_BAR;
;     DI void operator()(AccRef acc, const Unit& u, int wr, int wc, int fr, int fq) const {
;     ...
;         for (int ai = 0; ai < 2; ++ai) {
;             f32x4 bv[4][2][2];
; #pragma unroll
;             for (int m = 0; m < 4; ++m)
; #pragma unroll
;                 for (int bj = 0; bj < 2; ++bj) {
;                     const size_t o = (size_t)(row0 + ai * 128 + m * 16) * DM + col0 + bj * 128;
;                     if (BASEF32) { bv[m][bj][0] = *(const f32x4*)(basef + o); bv[m][bj][1] = *(const f32x4*)(basef + o + 4); }
;                     else { const u32x4 h = *(const u32x4*)(xnb + o); bv[m][bj][0] = bf_lo4(h); bv[m][bj][1] = bf_hi4(h); }
;                 }
; #pragma unroll
;             for (int m = 0; m < 4; ++m) {
;                 const int row = row0 + ai * 128 + m * 16;
;                 float q = 0.f;
; #pragma unroll
;                 for (int bj = 0; bj < 2; ++bj) {
;                     const size_t o = (size_t)row * DM + col0 + bj * 128;
;                     const f32x4 r0 = bv[m][bj][0] + scale * acc[ai][bj][m][0], r1 = bv[m][bj][1] + scale * acc[ai][bj][m][1];
;                     u32x4 w; w.x = pk_bf16(r0[0], r0[1]); w.y = pk_bf16(r0[2], r0[3]); w.z = pk_bf16(r1[0], r1[1]); w.w = pk_bf16(r1[2], r1[3]);
;                     *(u32x4*)(xnb + o) = w;
;                     if (STATS) q += r0[0] * r0[0] + r0[1] * r0[1] + r0[2] * r0[2] + r0[3] * r0[3] + r1[0] * r1[0] + r1[1] * r1[1] + r1[2] * r1[2] + r1[3] * r1[3];
;                 }
;                 if (STATS) { q += __shfl_xor(q, 16); q += __shfl_xor(q, 32); if (fq == 0) atomicAdd(ss + row, q); }
	s_waitcnt lgkmcnt(0)
	s_setprio 1
	s_waitcnt lgkmcnt(0)
	v_mfma_f32_16x16x32_bf16 v[60:63], v[128:131], v[144:147], v[60:63]
	v_mfma_f32_16x16x32_bf16 v[56:59], v[136:139], v[144:147], v[56:59]
	v_mfma_f32_16x16x32_bf16 v[44:47], v[128:131], v[152:155], v[44:47]
	v_mfma_f32_16x16x32_bf16 v[40:43], v[136:139], v[152:155], v[40:43]
	v_mfma_f32_16x16x32_bf16 v[28:31], v[128:131], v[160:163], v[28:31]
	v_mfma_f32_16x16x32_bf16 v[24:27], v[136:139], v[160:163], v[24:27]
	v_mfma_f32_16x16x32_bf16 v[12:15], v[128:131], v[168:171], v[12:15]
	v_mfma_f32_16x16x32_bf16 v[8:11], v[136:139], v[168:171], v[8:11]
	v_mfma_f32_16x16x32_bf16 v[60:63], v[132:135], v[148:151], v[60:63]
	v_mfma_f32_16x16x32_bf16 v[56:59], v[140:143], v[148:151], v[56:59]
	v_mfma_f32_16x16x32_bf16 v[44:47], v[132:135], v[156:159], v[44:47]
	v_mfma_f32_16x16x32_bf16 v[40:43], v[140:143], v[156:159], v[40:43]
	v_mfma_f32_16x16x32_bf16 v[28:31], v[132:135], v[164:167], v[28:31]
	v_mfma_f32_16x16x32_bf16 v[24:27], v[140:143], v[164:167], v[24:27]
	v_mfma_f32_16x16x32_bf16 v[12:15], v[132:135], v[172:175], v[12:15]
	v_mfma_f32_16x16x32_bf16 v[8:11], v[140:143], v[172:175], v[8:11]
	s_setprio 0
	s_barrier
	s_add_u32 s14, s78, 0xb0080
	s_addc_u32 s15, s79, 0
	s_add_i32 s28, s29, s59
	v_lshl_add_u64 v[128:129], s[14:15], 0, v[178:179]
	s_mov_b32 m0, s28
	s_nop 0
	global_load_lds_dwordx4 v[128:129], off
	v_lshl_add_u64 v[128:129], s[14:15], 0, v[182:183]
	s_add_i32 m0, s28, 0x2000
	s_nop 0
	global_load_lds_dwordx4 v[128:129], off
	s_waitcnt vmcnt(6)
	s_barrier
	s_setprio 1
	v_mfma_f32_16x16x32_bf16 v[52:55], v[192:195], v[144:147], v[52:55]
	v_mfma_f32_16x16x32_bf16 v[48:51], v[200:203], v[144:147], v[48:51]
	v_mfma_f32_16x16x32_bf16 v[36:39], v[192:195], v[152:155], v[36:39]
	v_mfma_f32_16x16x32_bf16 v[32:35], v[200:203], v[152:155], v[32:35]
	v_mfma_f32_16x16x32_bf16 v[20:23], v[192:195], v[160:163], v[20:23]
	v_mfma_f32_16x16x32_bf16 v[16:19], v[200:203], v[160:163], v[16:19]
	v_mfma_f32_16x16x32_bf16 v[4:7], v[192:195], v[168:171], v[4:7]
	v_mfma_f32_16x16x32_bf16 v[0:3], v[200:203], v[168:171], v[0:3]
	v_mfma_f32_16x16x32_bf16 v[52:55], v[196:199], v[148:151], v[52:55]
	v_mfma_f32_16x16x32_bf16 v[48:51], v[212:215], v[148:151], v[48:51]
	v_mfma_f32_16x16x32_bf16 v[36:39], v[196:199], v[156:159], v[36:39]
	v_mfma_f32_16x16x32_bf16 v[32:35], v[212:215], v[156:159], v[32:35]
	v_mfma_f32_16x16x32_bf16 v[20:23], v[196:199], v[164:167], v[20:23]
	v_mfma_f32_16x16x32_bf16 v[16:19], v[212:215], v[164:167], v[16:19]
	v_mfma_f32_16x16x32_bf16 v[4:7], v[196:199], v[172:175], v[4:7]
	v_mfma_f32_16x16x32_bf16 v[0:3], v[212:215], v[172:175], v[0:3]
	s_setprio 0
	s_add_i32 s97, s97, 2
	s_add_u32 s6, s6, 0x100
	s_addc_u32 s7, s7, 0
	s_cmp_gt_u32 s97, 41
	s_mov_b64 s[28:29], s[76:77]
	s_barrier
	s_cbranch_scc0 .LBB0_186
	v_lshl_add_u32 v194, s96, 8, v204
	v_lshl_or_b32 v192, s95, 8, v206
	v_ashrrev_i32_e32 v193, 31, v192
	v_ashrrev_i32_e32 v195, 31, v194
	v_lshl_add_u64 v[196:197], v[192:193], 2, s[52:53]
	v_lshlrev_b64 v[128:129], 12, v[194:195]
	v_lshl_add_u64 v[128:129], v[196:197], 0, v[128:129]
	global_load_dwordx4 v[214:217], v[128:129], off
	global_load_dwordx4 v[218:221], v[128:129], off offset:16
	global_load_dwordx4 v[224:227], v[128:129], off offset:512
	global_load_dwordx4 v[228:231], v[128:129], off offset:528
	v_or_b32_e32 v202, 16, v194
	v_or_b32_e32 v200, 32, v194
	v_or_b32_e32 v198, 48, v194
	v_ashrrev_i32_e32 v203, 31, v202
	v_ashrrev_i32_e32 v201, 31, v200
	v_ashrrev_i32_e32 v199, 31, v198
	v_lshlrev_b64 v[128:129], 12, v[202:203]
	v_lshlrev_b64 v[130:131], 12, v[200:201]
	v_lshlrev_b64 v[132:133], 12, v[198:199]
	v_lshl_add_u64 v[128:129], v[196:197], 0, v[128:129]
	v_lshl_add_u64 v[130:131], v[196:197], 0, v[130:131]
	v_lshl_add_u64 v[132:133], v[196:197], 0, v[132:133]
	global_load_dwordx4 v[168:171], v[128:129], off offset:16
	global_load_dwordx4 v[172:175], v[128:129], off
	global_load_dwordx4 v[160:163], v[128:129], off offset:528
	global_load_dwordx4 v[164:167], v[128:129], off offset:512
	global_load_dwordx4 v[152:155], v[130:131], off offset:16
	global_load_dwordx4 v[156:159], v[130:131], off
	global_load_dwordx4 v[144:147], v[130:131], off offset:528
	global_load_dwordx4 v[148:151], v[130:131], off offset:512
	global_load_dwordx4 v[136:139], v[132:133], off offset:16
	global_load_dwordx4 v[140:143], v[132:133], off
	s_nop 0
	global_load_dwordx4 v[128:131], v[132:133], off offset:528
	s_nop 0
	global_load_dwordx4 v[132:135], v[132:133], off offset:512
	v_and_b32_e32 v212, 64, v210
	v_xor_b32_e32 v211, 16, v210
	v_add_u32_e32 v212, 64, v212
	v_xor_b32_e32 v213, 32, v210
	v_cmp_lt_i32_e32 vcc, v211, v212
	v_lshlrev_b64 v[232:233], 11, v[194:195]
	s_waitcnt vmcnt(0)
	v_pk_fma_f32 v[124:125], v[124:125], 0.5, v[214:215] op_sel_hi:[1,0,1]
	v_cndmask_b32_e32 v211, v210, v211, vcc
	v_cmp_lt_i32_e32 vcc, v213, v212
	v_pk_fma_f32 v[116:117], v[116:117], 0.5, v[224:225] op_sel_hi:[1,0,1]
	v_lshlrev_b32_e32 v212, 2, v211
	v_cndmask_b32_e32 v213, v210, v213, vcc
	v_lshlrev_b32_e32 v211, 2, v213
	v_pk_fma_f32 v[126:127], v[126:127], 0.5, v[216:217] op_sel_hi:[1,0,1]
	v_pk_fma_f32 v[216:217], v[112:113], 0.5, v[228:229] op_sel_hi:[1,0,1]
	v_cvt_pk_bf16_f32 v112, v124, v125
	v_mul_f32_e32 v125, v125, v125
	v_mul_f32_e32 v213, v117, v117
	v_pk_fma_f32 v[118:119], v[118:119], 0.5, v[226:227] op_sel_hi:[1,0,1]
	v_fmac_f32_e32 v125, v124, v124
	v_fmac_f32_e32 v213, v116, v116
	v_fmac_f32_e32 v125, v126, v126
	v_fmac_f32_e32 v213, v118, v118
	v_pk_fma_f32 v[120:121], v[120:121], 0.5, v[218:219] op_sel_hi:[1,0,1]
	v_fmac_f32_e32 v125, v127, v127
	v_fmac_f32_e32 v213, v119, v119
	v_fmac_f32_e32 v125, v120, v120
	v_fmac_f32_e32 v213, v216, v216
	v_pk_fma_f32 v[122:123], v[122:123], 0.5, v[220:221] op_sel_hi:[1,0,1]
	v_pk_fma_f32 v[214:215], v[114:115], 0.5, v[230:231] op_sel_hi:[1,0,1]
	v_fmac_f32_e32 v125, v121, v121
	v_fmac_f32_e32 v213, v217, v217
	v_fmac_f32_e32 v125, v122, v122
	v_fmac_f32_e32 v213, v214, v214
	v_fmac_f32_e32 v125, v123, v123
	v_fmac_f32_e32 v213, v215, v215
	v_cvt_pk_bf16_f32 v115, v122, v123
	v_add_f32_e32 v122, v125, v213
	ds_bpermute_b32 v123, v212, v122
	v_cvt_pk_bf16_f32 v114, v120, v121
	v_lshl_add_u64 v[120:121], s[56:57], 0, v[232:233]
	v_cvt_pk_bf16_f32 v113, v126, v127
	v_lshl_add_u64 v[120:121], v[192:193], 1, v[120:121]
	global_store_dwordx4 v[120:121], v[112:115], off
	s_waitcnt lgkmcnt(0)
	s_nop 0
	v_add_f32_e32 v112, v122, v123
	ds_bpermute_b32 v113, v211, v112
	v_cvt_pk_bf16_f32 v114, v116, v117
	v_cvt_pk_bf16_f32 v115, v118, v119
	v_cvt_pk_bf16_f32 v116, v216, v217
	v_cvt_pk_bf16_f32 v117, v214, v215
	global_store_dwordx4 v[120:121], v[114:117], off offset:256
	s_and_saveexec_b64 s[6:7], s[0:1]
	s_cbranch_execz .LBB0_189
	v_lshl_add_u64 v[114:115], v[194:195], 2, s[60:61]
	s_waitcnt lgkmcnt(0)
	v_add_f32_e32 v112, v112, v113
	global_atomic_add_f32 v[114:115], v112, off

; #define PG8_STAGE(bufoff, gbase, voff) do { _Pragma("unroll") for (int _i = 0; _i < 2; ++_i) \
;         __builtin_amdgcn_global_load_lds((const unsigned*)((const char*)(gbase) + (voff)[_i]), (LAS unsigned*)(lds + (bufoff) + ldsw + _i * 8192), 16, 0, 0); } while (0)
; #define PG8_LDA(dst, b, h) do { _Pragma("unroll") for (int m = 0; m < 4; ++m) _Pragma("unroll") for (int k = 0; k < 2; ++k) dst[m][k] = *(const LAS bf16x8*)(lds + PG8_SA(b, h) + aoff + m * 2048 + k * 1024); } while (0)
; #define PG8_LDB(dst, b, h) do { _Pragma("unroll") for (int n = 0; n < 2; ++n) _Pragma("unroll") for (int k = 0; k < 2; ++k) dst[n][k] = *(const LAS bf16x8*)(lds + PG8_SB(b, h) + boff + n * 2048 + k * 1024); } while (0)
; #define PG8_MMA(ai, bj, At, Bt) do { __builtin_amdgcn_s_setprio(1); _Pragma("unroll") for (int m = 0; m < 4; ++m) _Pragma("unroll") for (int n = 0; n < 2; ++n) _Pragma("unroll") for (int k = 0; k < 2; ++k) \
;         acc[ai][bj][m][n] = __builtin_amdgcn_mfma_f32_16x16x32_bf16(Bt[n][k], At[m][k], acc[ai][bj][m][n], 0, 0, 0); __builtin_amdgcn_s_setprio(0); } while (0)
; #define PG8_WAIT_V(n) asm volatile("s_waitcnt vmcnt(" #n ")" ::: "memory")
; #define PG8_WAIT_L(n) asm volatile("s_waitcnt lgkmcnt(" #n ")" ::: "memory")
; #define PG8_BAR __builtin_amdgcn_s_barrier()
; #define PG8_SCHED __builtin_amdgcn_sched_barrier(0)
; #define PG8_STAGE(bufoff, gbase, voff) do { _Pragma("unroll") for (int _i = 0; _i < 2; ++_i) \
;         __builtin_amdgcn_global_load_lds((const unsigned*)((const char*)(gbase) + (voff)[_i]), (LAS unsigned*)(lds + (bufoff) + ldsw + _i * 8192), 16, 0, 0); } while (0)
; #define PG8_BAR __builtin_amdgcn_s_barrier()
; template <class Epi>
; DI void gemm_phase(LAS unsigned char* lds, const Gemm g, const StaticOrder S, const Epi E) {
;     ...
;             PG8_LDB(B0, 0, 0); PG8_SCHED; PG8_LDA(At, 0, 0); PG8_STAGE(PG8_SA(1, 1), a1 + hstep, voffA);
;             PG8_WAIT_L(8); PG8_BAR; PG8_WAIT_L(0); PG8_MMA(0, 0, At, B0); PG8_BAR; PG8_SCHED;
;             PG8_LDB(B1, 0, 1); PG8_STAGE(PG8_SB(0, 0), b2, voffB);
;             PG8_BAR; PG8_WAIT_L(0); PG8_MMA(0, 1, At, B1); PG8_BAR;
;             PG8_LDA(At, 0, 1); PG8_STAGE(PG8_SA(0, 0), a2, voffA);
;             PG8_BAR; PG8_WAIT_L(0); PG8_MMA(1, 0, At, B0); PG8_BAR; PG8_SCHED;
;             PG8_STAGE(PG8_SB(0, 1), b2 + hstep, voffB);
;             PG8_WAIT_V(6); PG8_BAR; PG8_MMA(1, 1, At, B1); PG8_BAR;
.LBB0_274:
	ds_read_b128 v[100:103], v227
	ds_read_b128 v[134:137], v227 offset:1024
	ds_read_b128 v[138:141], v227 offset:2048
	ds_read_b128 v[142:145], v227 offset:3072
	s_add_u32 s14, s8, 0xfffc0080
	s_addc_u32 s15, s9, -1
	s_cmp_eq_u32 s95, 12
	s_cselect_b32 s77, s1, s15
	s_cselect_b32 s76, s6, s14
	s_cselect_b32 s53, s7, s94
	s_cselect_b32 s52, s21, s23
	v_lshl_add_u64 v[104:105], s[8:9], 0, v[212:213]
	s_add_i32 m0, s78, 0xc000
	ds_read_b128 v[146:149], v228
	ds_read_b128 v[150:153], v228 offset:1024
	ds_read_b128 v[154:157], v228 offset:2048
	ds_read_b128 v[158:161], v228 offset:3072
	ds_read_b128 v[162:165], v228 offset:4096
	ds_read_b128 v[166:169], v228 offset:5120
	ds_read_b128 v[170:173], v228 offset:6144
	ds_read_b128 v[174:177], v228 offset:7168
	global_load_lds_dwordx4 v[104:105], off
	v_lshl_add_u64 v[104:105], s[8:9], 0, v[214:215]
	s_add_i32 m0, s78, 0xe000
	s_nop 0
	global_load_lds_dwordx4 v[104:105], off
	s_waitcnt lgkmcnt(8)
	s_barrier
	s_waitcnt lgkmcnt(0)
	s_setprio 1
	s_waitcnt lgkmcnt(0)
	v_mfma_f32_16x16x32_bf16 v[130:133], v[100:103], v[146:149], v[130:133]
	v_mfma_f32_16x16x32_bf16 v[126:129], v[138:141], v[146:149], v[126:129]
	v_mfma_f32_16x16x32_bf16 v[114:117], v[100:103], v[154:157], v[114:117]
	v_mfma_f32_16x16x32_bf16 v[110:113], v[138:141], v[154:157], v[110:113]
	v_mfma_f32_16x16x32_bf16 v[92:95], v[100:103], v[162:165], v[92:95]
	v_mfma_f32_16x16x32_bf16 v[88:91], v[138:141], v[162:165], v[88:91]
	v_mfma_f32_16x16x32_bf16 v[76:79], v[100:103], v[170:173], v[76:79]
	v_mfma_f32_16x16x32_bf16 v[72:75], v[138:141], v[170:173], v[72:75]
	v_mfma_f32_16x16x32_bf16 v[130:133], v[134:137], v[150:153], v[130:133]
	v_mfma_f32_16x16x32_bf16 v[126:129], v[142:145], v[150:153], v[126:129]
	v_mfma_f32_16x16x32_bf16 v[114:117], v[134:137], v[158:161], v[114:117]
	v_mfma_f32_16x16x32_bf16 v[110:113], v[142:145], v[158:161], v[110:113]
	v_mfma_f32_16x16x32_bf16 v[92:95], v[134:137], v[166:169], v[92:95]
	v_mfma_f32_16x16x32_bf16 v[88:91], v[142:145], v[166:169], v[88:91]
	v_mfma_f32_16x16x32_bf16 v[76:79], v[134:137], v[174:177], v[76:79]
	v_mfma_f32_16x16x32_bf16 v[72:75], v[142:145], v[174:177], v[72:75]
	s_setprio 0
	s_barrier
	s_add_i32 s14, s87, s59
	v_lshl_add_u64 v[194:195], s[52:53], 0, v[200:201]
	s_mov_b32 m0, s14
	ds_read_b128 v[178:181], v229
	ds_read_b128 v[182:185], v229 offset:1024
	ds_read_b128 v[186:189], v229 offset:2048
	ds_read_b128 v[190:193], v229 offset:3072
	global_load_lds_dwordx4 v[194:195], off
	v_lshl_add_u64 v[196:197], s[52:53], 0, v[204:205]
	s_add_i32 m0, s14, 0x2000
	s_nop 0
	global_load_lds_dwordx4 v[196:197], off
	s_barrier
	s_waitcnt lgkmcnt(0)
	s_setprio 1
	s_waitcnt lgkmcnt(0)
	v_mfma_f32_16x16x32_bf16 v[122:125], v[178:181], v[146:149], v[122:125]
	v_mfma_f32_16x16x32_bf16 v[118:121], v[186:189], v[146:149], v[118:121]
	v_mfma_f32_16x16x32_bf16 v[104:107], v[178:181], v[154:157], v[106:109]
	v_mfma_f32_16x16x32_bf16 v[96:99], v[186:189], v[154:157], v[96:99]
	v_mfma_f32_16x16x32_bf16 v[84:87], v[178:181], v[162:165], v[84:87]
	v_mfma_f32_16x16x32_bf16 v[80:83], v[186:189], v[162:165], v[80:83]
	v_mfma_f32_16x16x32_bf16 v[68:71], v[178:181], v[170:173], v[68:71]
	v_mfma_f32_16x16x32_bf16 v[64:67], v[186:189], v[170:173], v[64:67]
	v_mfma_f32_16x16x32_bf16 v[122:125], v[182:185], v[150:153], v[122:125]
	v_mfma_f32_16x16x32_bf16 v[118:121], v[190:193], v[150:153], v[118:121]
	v_mfma_f32_16x16x32_bf16 v[104:107], v[182:185], v[158:161], v[104:107]
	v_mfma_f32_16x16x32_bf16 v[96:99], v[190:193], v[158:161], v[96:99]
	v_mfma_f32_16x16x32_bf16 v[84:87], v[182:185], v[166:169], v[84:87]
	v_mfma_f32_16x16x32_bf16 v[80:83], v[190:193], v[166:169], v[80:83]
	v_mfma_f32_16x16x32_bf16 v[68:71], v[182:185], v[174:177], v[68:71]
	v_mfma_f32_16x16x32_bf16 v[64:67], v[190:193], v[174:177], v[64:67]
	s_setprio 0
	s_mov_b32 m0, s78
	v_lshl_add_u64 v[220:221], s[76:77], 0, v[198:199]
	s_barrier
	ds_read_b128 v[146:149], v228 offset:16384
	ds_read_b128 v[150:153], v228 offset:17408
	ds_read_b128 v[154:157], v228 offset:18432
	ds_read_b128 v[158:161], v228 offset:19456
	ds_read_b128 v[162:165], v228 offset:20480
	ds_read_b128 v[166:169], v228 offset:21504
	ds_read_b128 v[170:173], v228 offset:22528
	ds_read_b128 v[174:177], v228 offset:23552
	global_load_lds_dwordx4 v[220:221], off
	v_lshl_add_u64 v[232:233], s[76:77], 0, v[202:203]
	s_mov_b32 m0, s79
	s_nop 0
	global_load_lds_dwordx4 v[232:233], off
	s_barrier
	s_waitcnt lgkmcnt(0)
	s_setprio 1
	s_waitcnt lgkmcnt(0)
	v_mfma_f32_16x16x32_bf16 v[60:63], v[100:103], v[146:149], v[60:63]
	v_mfma_f32_16x16x32_bf16 v[56:59], v[138:141], v[146:149], v[56:59]
	v_mfma_f32_16x16x32_bf16 v[44:47], v[100:103], v[154:157], v[44:47]
	v_mfma_f32_16x16x32_bf16 v[40:43], v[138:141], v[154:157], v[40:43]
	v_mfma_f32_16x16x32_bf16 v[28:31], v[100:103], v[162:165], v[28:31]
	v_mfma_f32_16x16x32_bf16 v[24:27], v[138:141], v[162:165], v[24:27]
	v_mfma_f32_16x16x32_bf16 v[12:15], v[100:103], v[170:173], v[12:15]
	v_mfma_f32_16x16x32_bf16 v[8:11], v[138:141], v[170:173], v[8:11]
	v_mfma_f32_16x16x32_bf16 v[60:63], v[134:137], v[150:153], v[60:63]
	v_mfma_f32_16x16x32_bf16 v[56:59], v[142:145], v[150:153], v[56:59]
	v_mfma_f32_16x16x32_bf16 v[44:47], v[134:137], v[158:161], v[44:47]
	v_mfma_f32_16x16x32_bf16 v[40:43], v[142:145], v[158:161], v[40:43]
	v_mfma_f32_16x16x32_bf16 v[28:31], v[134:137], v[166:169], v[28:31]
	v_mfma_f32_16x16x32_bf16 v[24:27], v[142:145], v[166:169], v[24:27]
	v_mfma_f32_16x16x32_bf16 v[12:15], v[134:137], v[174:177], v[12:15]
	v_mfma_f32_16x16x32_bf16 v[8:11], v[142:145], v[174:177], v[8:11]
	s_setprio 0
	s_barrier
; #define PG8_STAGE(bufoff, gbase, voff) do { _Pragma("unroll") for (int _i = 0; _i < 2; ++_i) \
;         __builtin_amdgcn_global_load_lds((const unsigned*)((const char*)(gbase) + (voff)[_i]), (LAS unsigned*)(lds + (bufoff) + ldsw + _i * 8192), 16, 0, 0); } while (0)
; #define PG8_LDA(dst, b, h) do { _Pragma("unroll") for (int m = 0; m < 4; ++m) _Pragma("unroll") for (int k = 0; k < 2; ++k) dst[m][k] = *(const LAS bf16x8*)(lds + PG8_SA(b, h) + aoff + m * 2048 + k * 1024); } while (0)
; #define PG8_LDB(dst, b, h) do { _Pragma("unroll") for (int n = 0; n < 2; ++n) _Pragma("unroll") for (int k = 0; k < 2; ++k) dst[n][k] = *(const LAS bf16x8*)(lds + PG8_SB(b, h) + boff + n * 2048 + k * 1024); } while (0)
; #define PG8_MMA(ai, bj, At, Bt) do { __builtin_amdgcn_s_setprio(1); _Pragma("unroll") for (int m = 0; m < 4; ++m) _Pragma("unroll") for (int n = 0; n < 2; ++n) _Pragma("unroll") for (int k = 0; k < 2; ++k) \
;         acc[ai][bj][m][n] = __builtin_amdgcn_mfma_f32_16x16x32_bf16(Bt[n][k], At[m][k], acc[ai][bj][m][n], 0, 0, 0); __builtin_amdgcn_s_setprio(0); } while (0)
; #define PG8_WAIT_V(n) asm volatile("s_waitcnt vmcnt(" #n ")" ::: "memory")
; #define PG8_WAIT_L(n) asm volatile("s_waitcnt lgkmcnt(" #n ")" ::: "memory")
; #define PG8_BAR __builtin_amdgcn_s_barrier()
; #define PG8_SCHED __builtin_amdgcn_sched_barrier(0)
; #define PG8_STAGE(bufoff, gbase, voff) do { _Pragma("unroll") for (int _i = 0; _i < 2; ++_i) \
;         __builtin_amdgcn_global_load_lds((const unsigned*)((const char*)(gbase) + (voff)[_i]), (LAS unsigned*)(lds + (bufoff) + ldsw + _i * 8192), 16, 0, 0); } while (0)
; #define PG8_BAR __builtin_amdgcn_s_barrier()
; template <class Epi>
; DI void gemm_phase(LAS unsigned char* lds, const Gemm g, const StaticOrder S, const Epi E) {
;     ...
;             PG8_STAGE(PG8_SB(0, 1), b2 + hstep, voffB);
;             PG8_WAIT_V(6); PG8_BAR; PG8_MMA(1, 1, At, B1); PG8_BAR;
;             PG8_LDB(B0, 1, 0); PG8_SCHED; PG8_LDA(At, 1, 0); PG8_STAGE(PG8_SA(0, 1), a2 + hstep, voffA);
;             PG8_WAIT_L(8); PG8_BAR; PG8_WAIT_L(0); PG8_MMA(0, 0, At, B0); PG8_BAR; PG8_SCHED;
;             PG8_LDB(B1, 1, 1); PG8_STAGE(PG8_SB(1, 0), b3, voffB);
;             PG8_BAR; PG8_WAIT_L(0); PG8_MMA(0, 1, At, B1); PG8_BAR;
;             PG8_LDA(At, 1, 1); PG8_STAGE(PG8_SA(1, 0), a3, voffA);
;             PG8_BAR; PG8_WAIT_L(0); PG8_MMA(1, 0, At, B0); PG8_BAR; PG8_SCHED;
	s_add_u32 s14, s52, 0x40000
	s_addc_u32 s15, s53, 0
	s_add_i32 s35, s90, s59
	v_lshl_add_u64 v[100:101], s[14:15], 0, v[200:201]
	s_mov_b32 m0, s35
	s_nop 0
	global_load_lds_dwordx4 v[100:101], off
	v_lshl_add_u64 v[100:101], s[14:15], 0, v[204:205]
	s_add_i32 m0, s35, 0x2000
	s_nop 0
	global_load_lds_dwordx4 v[100:101], off
	s_waitcnt vmcnt(6)
	s_barrier
	s_setprio 1
	v_mfma_f32_16x16x32_bf16 v[52:55], v[178:181], v[146:149], v[52:55]
	v_mfma_f32_16x16x32_bf16 v[48:51], v[186:189], v[146:149], v[48:51]
	v_mfma_f32_16x16x32_bf16 v[36:39], v[178:181], v[154:157], v[36:39]
	v_mfma_f32_16x16x32_bf16 v[32:35], v[186:189], v[154:157], v[32:35]
	v_mfma_f32_16x16x32_bf16 v[20:23], v[178:181], v[162:165], v[20:23]
	v_mfma_f32_16x16x32_bf16 v[16:19], v[186:189], v[162:165], v[16:19]
	v_mfma_f32_16x16x32_bf16 v[4:7], v[178:181], v[170:173], v[4:7]
	v_mfma_f32_16x16x32_bf16 v[0:3], v[186:189], v[170:173], v[0:3]
	v_mfma_f32_16x16x32_bf16 v[52:55], v[182:185], v[150:153], v[52:55]
	v_mfma_f32_16x16x32_bf16 v[48:51], v[190:193], v[150:153], v[48:51]
	v_mfma_f32_16x16x32_bf16 v[36:39], v[182:185], v[158:161], v[36:39]
	v_mfma_f32_16x16x32_bf16 v[32:35], v[190:193], v[158:161], v[32:35]
	v_mfma_f32_16x16x32_bf16 v[20:23], v[182:185], v[166:169], v[20:23]
	v_mfma_f32_16x16x32_bf16 v[16:19], v[190:193], v[166:169], v[16:19]
	v_mfma_f32_16x16x32_bf16 v[4:7], v[182:185], v[174:177], v[4:7]
	v_mfma_f32_16x16x32_bf16 v[0:3], v[190:193], v[174:177], v[0:3]
	s_setprio 0
	s_add_i32 s35, 0, 0x18000
	v_add_u32_e32 v108, s35, v225
	s_barrier
	ds_read_b128 v[100:103], v108
	ds_read_b128 v[134:137], v108 offset:1024
	ds_read_b128 v[138:141], v108 offset:2048
	ds_read_b128 v[142:145], v108 offset:3072
	s_add_u32 s14, s76, 0x40000
	s_addc_u32 s15, s77, 0
	s_mov_b32 m0, s80
	v_lshl_add_u64 v[108:109], s[14:15], 0, v[198:199]
	ds_read_b128 v[146:149], v228 offset:32768
	ds_read_b128 v[150:153], v228 offset:33792
	ds_read_b128 v[154:157], v228 offset:34816
	ds_read_b128 v[158:161], v228 offset:35840
	ds_read_b128 v[162:165], v228 offset:36864
	ds_read_b128 v[166:169], v228 offset:37888
	ds_read_b128 v[170:173], v228 offset:38912
	ds_read_b128 v[174:177], v228 offset:39936
	global_load_lds_dwordx4 v[108:109], off
	v_lshl_add_u64 v[108:109], s[14:15], 0, v[202:203]
	s_mov_b32 m0, s81
	s_nop 0
	global_load_lds_dwordx4 v[108:109], off
	s_waitcnt lgkmcnt(8)
	s_barrier
	s_waitcnt lgkmcnt(0)
	s_setprio 1
	s_waitcnt lgkmcnt(0)
	v_mfma_f32_16x16x32_bf16 v[130:133], v[100:103], v[146:149], v[130:133]
	v_mfma_f32_16x16x32_bf16 v[126:129], v[138:141], v[146:149], v[126:129]
	v_mfma_f32_16x16x32_bf16 v[114:117], v[100:103], v[154:157], v[114:117]
	v_mfma_f32_16x16x32_bf16 v[108:111], v[138:141], v[154:157], v[110:113]
	v_mfma_f32_16x16x32_bf16 v[92:95], v[100:103], v[162:165], v[92:95]
	v_mfma_f32_16x16x32_bf16 v[88:91], v[138:141], v[162:165], v[88:91]
	v_mfma_f32_16x16x32_bf16 v[76:79], v[100:103], v[170:173], v[76:79]
	v_mfma_f32_16x16x32_bf16 v[72:75], v[138:141], v[170:173], v[72:75]
	v_mfma_f32_16x16x32_bf16 v[130:133], v[134:137], v[150:153], v[130:133]
	v_mfma_f32_16x16x32_bf16 v[126:129], v[142:145], v[150:153], v[126:129]
	v_mfma_f32_16x16x32_bf16 v[114:117], v[134:137], v[158:161], v[114:117]
	v_mfma_f32_16x16x32_bf16 v[110:113], v[142:145], v[158:161], v[108:111]
	v_mfma_f32_16x16x32_bf16 v[92:95], v[134:137], v[166:169], v[92:95]
	v_mfma_f32_16x16x32_bf16 v[88:91], v[142:145], v[166:169], v[88:91]
	v_mfma_f32_16x16x32_bf16 v[76:79], v[134:137], v[174:177], v[76:79]
	v_mfma_f32_16x16x32_bf16 v[72:75], v[142:145], v[174:177], v[72:75]
	s_setprio 0
	s_barrier
	s_add_i32 s76, 0, 0x1c000
	v_add_u32_e32 v108, s76, v225
	s_add_i32 s14, s35, s59
	ds_read_b128 v[178:181], v108
	ds_read_b128 v[182:185], v108 offset:1024
	ds_read_b128 v[186:189], v108 offset:2048
	ds_read_b128 v[190:193], v108 offset:3072
	v_lshl_add_u64 v[108:109], v[194:195], 0, s[18:19]
	s_mov_b32 m0, s14
	s_nop 0
	global_load_lds_dwordx4 v[108:109], off
	v_lshl_add_u64 v[108:109], v[196:197], 0, s[18:19]
	s_add_i32 m0, s14, 0x2000
	s_nop 0
	global_load_lds_dwordx4 v[108:109], off
	s_barrier
	s_waitcnt lgkmcnt(0)
	s_setprio 1
	s_waitcnt lgkmcnt(0)
	v_mfma_f32_16x16x32_bf16 v[122:125], v[178:181], v[146:149], v[122:125]
	v_mfma_f32_16x16x32_bf16 v[118:121], v[186:189], v[146:149], v[118:121]
	v_mfma_f32_16x16x32_bf16 v[104:107], v[178:181], v[154:157], v[104:107]
	v_mfma_f32_16x16x32_bf16 v[96:99], v[186:189], v[154:157], v[96:99]
	v_mfma_f32_16x16x32_bf16 v[84:87], v[178:181], v[162:165], v[84:87]
	v_mfma_f32_16x16x32_bf16 v[80:83], v[186:189], v[162:165], v[80:83]
	v_mfma_f32_16x16x32_bf16 v[68:71], v[178:181], v[170:173], v[68:71]
	v_mfma_f32_16x16x32_bf16 v[64:67], v[186:189], v[170:173], v[64:67]
	v_mfma_f32_16x16x32_bf16 v[122:125], v[182:185], v[150:153], v[122:125]
	v_mfma_f32_16x16x32_bf16 v[118:121], v[190:193], v[150:153], v[118:121]
	v_mfma_f32_16x16x32_bf16 v[106:109], v[182:185], v[158:161], v[104:107]
	v_mfma_f32_16x16x32_bf16 v[96:99], v[190:193], v[158:161], v[96:99]
	v_mfma_f32_16x16x32_bf16 v[84:87], v[182:185], v[166:169], v[84:87]
	v_mfma_f32_16x16x32_bf16 v[80:83], v[190:193], v[166:169], v[80:83]
	v_mfma_f32_16x16x32_bf16 v[68:71], v[182:185], v[174:177], v[68:71]
	v_mfma_f32_16x16x32_bf16 v[64:67], v[190:193], v[174:177], v[64:67]
	s_setprio 0
	s_mov_b32 m0, s83
	v_lshl_add_u64 v[104:105], v[220:221], 0, s[18:19]
	s_barrier
	ds_read_b128 v[146:149], v228 offset:49152
	ds_read_b128 v[150:153], v228 offset:50176
	ds_read_b128 v[154:157], v228 offset:51200
	ds_read_b128 v[158:161], v228 offset:52224
	ds_read_b128 v[162:165], v228 offset:53248
	ds_read_b128 v[166:169], v228 offset:54272
	ds_read_b128 v[170:173], v228 offset:55296
	ds_read_b128 v[174:177], v228 offset:56320
	global_load_lds_dwordx4 v[104:105], off
	v_lshl_add_u64 v[104:105], v[232:233], 0, s[18:19]
	s_mov_b32 m0, s84
	s_nop 0
	global_load_lds_dwordx4 v[104:105], off
	s_barrier
; #define PG8_STAGE(bufoff, gbase, voff) do { _Pragma("unroll") for (int _i = 0; _i < 2; ++_i) \
;         __builtin_amdgcn_global_load_lds((const unsigned*)((const char*)(gbase) + (voff)[_i]), (LAS unsigned*)(lds + (bufoff) + ldsw + _i * 8192), 16, 0, 0); } while (0)
; #define PG8_MMA(ai, bj, At, Bt) do { __builtin_amdgcn_s_setprio(1); _Pragma("unroll") for (int m = 0; m < 4; ++m) _Pragma("unroll") for (int n = 0; n < 2; ++n) _Pragma("unroll") for (int k = 0; k < 2; ++k) \
;         acc[ai][bj][m][n] = __builtin_amdgcn_mfma_f32_16x16x32_bf16(Bt[n][k], At[m][k], acc[ai][bj][m][n], 0, 0, 0); __builtin_amdgcn_s_setprio(0); } while (0)
; #define PG8_WAIT_V(n) asm volatile("s_waitcnt vmcnt(" #n ")" ::: "memory")
; #define PG8_WAIT_L(n) asm volatile("s_waitcnt lgkmcnt(" #n ")" ::: "memory")
; #define PG8_BAR __builtin_amdgcn_s_barrier()
; #define PG8_BAR __builtin_amdgcn_s_barrier()
; template <class Epi>
; DI void gemm_phase(LAS unsigned char* lds, const Gemm g, const StaticOrder S, const Epi E) {
;     ...
;             PG8_BAR; PG8_WAIT_L(0); PG8_MMA(1, 0, At, B0); PG8_BAR; PG8_SCHED;
;             PG8_STAGE(PG8_SB(1, 1), b3 + hstep, voffB);
;             PG8_WAIT_V(6); PG8_BAR; PG8_MMA(1, 1, At, B1); PG8_BAR;
;     DI void operator()(AccRef acc, const Unit& u, int wr, int wc, int fr, int fq) const {
;         const int X = u.pn >> 2, h = u.pn & 3, isk = wc >> 1, i0 = (wc & 1) * 32 + 8 * fq;
;         bf16_t* dst = (X ? qkoB : qkoA) + h * 256 + isk * 128 + i0;
;         const float qs0 = isk ? 1.0f : 0.08838834764831845f;
;         const int row0 = u.pm * 256 + wr * 64 + fr;
;         const RowScales rsc = load_rowscales(ss, row0);
; #pragma unroll
;         for (int ai = 0; ai < 2; ++ai) {
;             f32x4 cs[4][2], sn[4][2];
;             if (X == 0) {
; #pragma unroll
;                 for (int m = 0; m < 4; ++m) {
;                     const int pos = (row0 + ai * 128 + m * 16) & (SEQ - 1);
;                     cs[m][0] = *(const f32x4*)(cosT + pos * 64 + i0); cs[m][1] = *(const f32x4*)(cosT + pos * 64 + i0 + 4);
;                     sn[m][0] = *(const f32x4*)(sinT + pos * 64 + i0); sn[m][1] = *(const f32x4*)(sinT + pos * 64 + i0 + 4);
;                 }
;             } else {
; #pragma unroll
;                 for (int m = 0; m < 4; ++m) { cs[m][0] = cs[m][1] = (f32x4){1.f, 1.f, 1.f, 1.f}; sn[m][0] = sn[m][1] = (f32x4){0.f, 0.f, 0.f, 0.f}; }
;             }
	s_waitcnt lgkmcnt(0)
	s_setprio 1
	s_waitcnt lgkmcnt(0)
	v_mfma_f32_16x16x32_bf16 v[60:63], v[100:103], v[146:149], v[60:63]
	v_mfma_f32_16x16x32_bf16 v[56:59], v[138:141], v[146:149], v[56:59]
	v_mfma_f32_16x16x32_bf16 v[44:47], v[100:103], v[154:157], v[44:47]
	v_mfma_f32_16x16x32_bf16 v[40:43], v[138:141], v[154:157], v[40:43]
	v_mfma_f32_16x16x32_bf16 v[28:31], v[100:103], v[162:165], v[28:31]
	v_mfma_f32_16x16x32_bf16 v[24:27], v[138:141], v[162:165], v[24:27]
	v_mfma_f32_16x16x32_bf16 v[12:15], v[100:103], v[170:173], v[12:15]
	v_mfma_f32_16x16x32_bf16 v[8:11], v[138:141], v[170:173], v[8:11]
	v_mfma_f32_16x16x32_bf16 v[60:63], v[134:137], v[150:153], v[60:63]
	v_mfma_f32_16x16x32_bf16 v[56:59], v[142:145], v[150:153], v[56:59]
	v_mfma_f32_16x16x32_bf16 v[44:47], v[134:137], v[158:161], v[44:47]
	v_mfma_f32_16x16x32_bf16 v[40:43], v[142:145], v[158:161], v[40:43]
	v_mfma_f32_16x16x32_bf16 v[28:31], v[134:137], v[166:169], v[28:31]
	v_mfma_f32_16x16x32_bf16 v[24:27], v[142:145], v[166:169], v[24:27]
	v_mfma_f32_16x16x32_bf16 v[12:15], v[134:137], v[174:177], v[12:15]
	v_mfma_f32_16x16x32_bf16 v[8:11], v[142:145], v[174:177], v[8:11]
	s_setprio 0
	s_barrier
	s_add_u32 s14, s52, 0x40080
	s_addc_u32 s15, s53, 0
	s_add_i32 s35, s76, s59
	v_lshl_add_u64 v[100:101], s[14:15], 0, v[200:201]
	s_mov_b32 m0, s35
	s_nop 0
	global_load_lds_dwordx4 v[100:101], off
	v_lshl_add_u64 v[100:101], s[14:15], 0, v[204:205]
	s_add_i32 m0, s35, 0x2000
	s_nop 0
	global_load_lds_dwordx4 v[100:101], off
	s_waitcnt vmcnt(6)
	s_barrier
	s_setprio 1
	v_mfma_f32_16x16x32_bf16 v[52:55], v[178:181], v[146:149], v[52:55]
	v_mfma_f32_16x16x32_bf16 v[48:51], v[186:189], v[146:149], v[48:51]
	v_mfma_f32_16x16x32_bf16 v[36:39], v[178:181], v[154:157], v[36:39]
	v_mfma_f32_16x16x32_bf16 v[32:35], v[186:189], v[154:157], v[32:35]
	v_mfma_f32_16x16x32_bf16 v[20:23], v[178:181], v[162:165], v[20:23]
	v_mfma_f32_16x16x32_bf16 v[16:19], v[186:189], v[162:165], v[16:19]
	v_mfma_f32_16x16x32_bf16 v[4:7], v[178:181], v[170:173], v[4:7]
	v_mfma_f32_16x16x32_bf16 v[0:3], v[186:189], v[170:173], v[0:3]
	v_mfma_f32_16x16x32_bf16 v[52:55], v[182:185], v[150:153], v[52:55]
	v_mfma_f32_16x16x32_bf16 v[48:51], v[190:193], v[150:153], v[48:51]
	v_mfma_f32_16x16x32_bf16 v[36:39], v[182:185], v[158:161], v[36:39]
	v_mfma_f32_16x16x32_bf16 v[32:35], v[190:193], v[158:161], v[32:35]
	v_mfma_f32_16x16x32_bf16 v[20:23], v[182:185], v[166:169], v[20:23]
	v_mfma_f32_16x16x32_bf16 v[16:19], v[190:193], v[166:169], v[16:19]
	v_mfma_f32_16x16x32_bf16 v[4:7], v[182:185], v[174:177], v[4:7]
	v_mfma_f32_16x16x32_bf16 v[0:3], v[190:193], v[174:177], v[0:3]
	s_setprio 0
	s_add_i32 s95, s95, 2
	s_add_u32 s8, s8, 0x100
	s_addc_u32 s9, s9, 0
	s_add_u32 s23, s23, 0x100
	s_addc_u32 s94, s94, 0
	s_cmp_gt_u32 s95, 13
	s_barrier
	s_cbranch_scc0 .LBB0_274
	v_lshl_add_u32 v102, s0, 8, v224
	v_ashrrev_i32_e32 v103, 31, v102
	v_lshl_add_u64 v[134:135], v[102:103], 2, s[60:61]
	global_load_dword v237, v[134:135], off
	global_load_dword v236, v[134:135], off offset:64
	global_load_dword v105, v[134:135], off offset:128
	global_load_dword v101, v[134:135], off offset:192
	global_load_dword v231, v[134:135], off offset:512
	global_load_dword v232, v[134:135], off offset:576
	global_load_dword v233, v[134:135], off offset:640
	global_load_dword v234, v[134:135], off offset:704
	s_cmp_lt_u32 s93, 4
	s_cselect_b64 s[0:1], -1, 0
	s_cmp_gt_u32 s93, 3
	v_lshlrev_b32_e32 v235, 6, v102
	v_mov_b32_e32 v100, 1.0
	v_mov_b32_e32 v104, 0
	v_mov_b32_e32 v134, 0
	v_mov_b32_e32 v135, 0
	v_mov_b32_e32 v136, 0
	v_mov_b32_e32 v137, 0
	v_mov_b32_e32 v142, 0
	v_mov_b32_e32 v143, 0
	v_mov_b32_e32 v144, 0
	v_mov_b32_e32 v145, 0
	v_mov_b32_e32 v146, 0
	v_mov_b32_e32 v147, 0
	v_mov_b32_e32 v148, 0
	v_mov_b32_e32 v149, 0
	v_mov_b32_e32 v154, 0
	v_mov_b32_e32 v155, 0
	v_mov_b32_e32 v156, 0
	v_mov_b32_e32 v157, 0
	v_mov_b32_e32 v162, 0
	v_mov_b32_e32 v163, 0
	v_mov_b32_e32 v164, 0
	v_mov_b32_e32 v165, 0
	v_mov_b32_e32 v174, 0
	v_mov_b32_e32 v175, 0
	v_mov_b32_e32 v176, 0
	v_mov_b32_e32 v177, 0
	v_mov_b32_e32 v182, 0
	v_mov_b32_e32 v183, 0
	v_mov_b32_e32 v184, 0
	v_mov_b32_e32 v185, 0
	v_mov_b32_e32 v194, 0
	v_mov_b32_e32 v195, 0
	v_mov_b32_e32 v196, 0
	v_mov_b32_e32 v197, 0
	v_mov_b32_e32 v138, 1.0
	v_mov_b32_e32 v139, 1.0
	v_mov_b32_e32 v140, 1.0
	v_mov_b32_e32 v141, 1.0
	v_mov_b32_e32 v190, 1.0
	v_mov_b32_e32 v191, 1.0
	v_mov_b32_e32 v192, 1.0
	v_mov_b32_e32 v193, 1.0
	v_mov_b32_e32 v186, 1.0
	v_mov_b32_e32 v187, 1.0
	v_mov_b32_e32 v188, 1.0
	v_mov_b32_e32 v189, 1.0
	v_mov_b32_e32 v178, 1.0
	v_mov_b32_e32 v179, 1.0
	v_mov_b32_e32 v180, 1.0
	v_mov_b32_e32 v181, 1.0
	v_mov_b32_e32 v170, 1.0
	v_mov_b32_e32 v171, 1.0
	v_mov_b32_e32 v172, 1.0
	v_mov_b32_e32 v173, 1.0
	v_mov_b32_e32 v166, 1.0
	v_mov_b32_e32 v167, 1.0
	v_mov_b32_e32 v168, 1.0
	v_mov_b32_e32 v169, 1.0
	v_mov_b32_e32 v158, 1.0
	v_mov_b32_e32 v159, 1.0
	v_mov_b32_e32 v160, 1.0
	v_mov_b32_e32 v161, 1.0
	v_mov_b32_e32 v150, 1.0
	v_mov_b32_e32 v151, 1.0
	v_mov_b32_e32 v152, 1.0
	v_mov_b32_e32 v153, 1.0
	s_cbranch_scc1 .LBB0_277
	v_lshlrev_b32_e32 v134, 2, v235
	v_and_b32_e32 v134, 0x1fcf00, v134
	v_mov_b32_e32 v135, v207
	v_lshl_add_u64 v[136:137], v[208:209], 0, v[134:135]
	global_load_dwordx4 v[190:193], v[136:137], off
	global_load_dwordx4 v[186:189], v[136:137], off offset:16
	v_lshl_add_u64 v[136:137], v[210:211], 0, v[134:135]
	global_load_dwordx4 v[182:185], v[136:137], off offset:16
	global_load_dwordx4 v[194:197], v[136:137], off
	v_or_b32_e32 v136, 0x1000, v134
	v_mov_b32_e32 v137, v207
	v_lshl_add_u64 v[138:139], v[208:209], 0, v[136:137]
	v_lshl_add_u64 v[136:137], v[210:211], 0, v[136:137]
	global_load_dwordx4 v[178:181], v[138:139], off
	global_load_dwordx4 v[170:173], v[138:139], off offset:16
	global_load_dwordx4 v[162:165], v[136:137], off offset:16
	global_load_dwordx4 v[174:177], v[136:137], off
	v_or_b32_e32 v136, 0x2000, v134
	v_mov_b32_e32 v137, v207
	v_lshl_add_u64 v[138:139], v[208:209], 0, v[136:137]
	v_lshl_add_u64 v[136:137], v[210:211], 0, v[136:137]
	v_or_b32_e32 v134, 0x3000, v134
	global_load_dwordx4 v[166:169], v[138:139], off
	global_load_dwordx4 v[158:161], v[138:139], off offset:16
	global_load_dwordx4 v[146:149], v[136:137], off offset:16
	global_load_dwordx4 v[154:157], v[136:137], off
	v_lshl_add_u64 v[136:137], v[208:209], 0, v[134:135]
	v_lshl_add_u64 v[142:143], v[210:211], 0, v[134:135]
	global_load_dwordx4 v[138:141], v[136:137], off offset:16
	global_load_dwordx4 v[150:153], v[136:137], off
	s_nop 0
	global_load_dwordx4 v[134:137], v[142:143], off offset:16
	s_nop 0
	global_load_dwordx4 v[142:145], v[142:143], off

; #define PG8_STAGE(bufoff, gbase, voff) do { _Pragma("unroll") for (int _i = 0; _i < 2; ++_i) \
;         __builtin_amdgcn_global_load_lds((const unsigned*)((const char*)(gbase) + (voff)[_i]), (LAS unsigned*)(lds + (bufoff) + ldsw + _i * 8192), 16, 0, 0); } while (0)
; #define PG8_LDA(dst, b, h) do { _Pragma("unroll") for (int m = 0; m < 4; ++m) _Pragma("unroll") for (int k = 0; k < 2; ++k) dst[m][k] = *(const LAS bf16x8*)(lds + PG8_SA(b, h) + aoff + m * 2048 + k * 1024); } while (0)
; #define PG8_LDB(dst, b, h) do { _Pragma("unroll") for (int n = 0; n < 2; ++n) _Pragma("unroll") for (int k = 0; k < 2; ++k) dst[n][k] = *(const LAS bf16x8*)(lds + PG8_SB(b, h) + boff + n * 2048 + k * 1024); } while (0)
; #define PG8_MMA(ai, bj, At, Bt) do { __builtin_amdgcn_s_setprio(1); _Pragma("unroll") for (int m = 0; m < 4; ++m) _Pragma("unroll") for (int n = 0; n < 2; ++n) _Pragma("unroll") for (int k = 0; k < 2; ++k) \
;         acc[ai][bj][m][n] = __builtin_amdgcn_mfma_f32_16x16x32_bf16(Bt[n][k], At[m][k], acc[ai][bj][m][n], 0, 0, 0); __builtin_amdgcn_s_setprio(0); } while (0)
; #define PG8_WAIT_V(n) asm volatile("s_waitcnt vmcnt(" #n ")" ::: "memory")
; #define PG8_WAIT_L(n) asm volatile("s_waitcnt lgkmcnt(" #n ")" ::: "memory")
; #define PG8_BAR __builtin_amdgcn_s_barrier()
; #define PG8_SCHED __builtin_amdgcn_sched_barrier(0)
; #define PG8_STAGE(bufoff, gbase, voff) do { _Pragma("unroll") for (int _i = 0; _i < 2; ++_i) \
;         __builtin_amdgcn_global_load_lds((const unsigned*)((const char*)(gbase) + (voff)[_i]), (LAS unsigned*)(lds + (bufoff) + ldsw + _i * 8192), 16, 0, 0); } while (0)
; #define PG8_BAR __builtin_amdgcn_s_barrier()
; template <class Epi>
; DI void gemm_phase(LAS unsigned char* lds, const Gemm g, const StaticOrder S, const Epi E) {
;     ...
;             PG8_LDB(B0, 0, 0); PG8_SCHED; PG8_LDA(At, 0, 0); PG8_STAGE(PG8_SA(1, 1), a1 + hstep, voffA);
;             PG8_WAIT_L(8); PG8_BAR; PG8_WAIT_L(0); PG8_MMA(0, 0, At, B0); PG8_BAR; PG8_SCHED;
;             PG8_LDB(B1, 0, 1); PG8_STAGE(PG8_SB(0, 0), b2, voffB);
;             PG8_BAR; PG8_WAIT_L(0); PG8_MMA(0, 1, At, B1); PG8_BAR;
;             PG8_LDA(At, 0, 1); PG8_STAGE(PG8_SA(0, 0), a2, voffA);
;             PG8_BAR; PG8_WAIT_L(0); PG8_MMA(1, 0, At, B0); PG8_BAR; PG8_SCHED;
;             PG8_STAGE(PG8_SB(0, 1), b2 + hstep, voffB);
;             PG8_WAIT_V(6); PG8_BAR; PG8_MMA(1, 1, At, B1); PG8_BAR;
.LBB0_298:
	ds_read_b128 v[128:131], v168
	ds_read_b128 v[132:135], v168 offset:1024
	ds_read_b128 v[154:157], v168 offset:2048
	ds_read_b128 v[158:161], v168 offset:3072
	s_add_u32 s5, s8, 0xfffc0080
	s_addc_u32 s14, s9, -1
	s_cmp_eq_u32 s4, 12
	s_cselect_b32 s81, s6, s14
	s_cselect_b32 s80, s7, s5
	s_cselect_b32 s79, s21, vcc_hi
	s_cselect_b32 s78, s23, vcc_lo
	v_lshl_add_u64 v[162:163], s[8:9], 0, v[146:147]
	s_add_i32 m0, s58, 0xc000
	ds_read_b128 v[172:175], v169
	ds_read_b128 v[176:179], v169 offset:1024
	ds_read_b128 v[180:183], v169 offset:2048
	ds_read_b128 v[184:187], v169 offset:3072
	ds_read_b128 v[188:191], v169 offset:4096
	ds_read_b128 v[192:195], v169 offset:5120
	ds_read_b128 v[196:199], v169 offset:6144
	ds_read_b128 v[200:203], v169 offset:7168
	global_load_lds_dwordx4 v[162:163], off
	v_lshl_add_u64 v[162:163], s[8:9], 0, v[148:149]
	s_add_i32 m0, s58, 0xe000
	s_nop 0
	global_load_lds_dwordx4 v[162:163], off
	s_waitcnt lgkmcnt(8)
	s_barrier
	s_waitcnt lgkmcnt(0)
	s_setprio 1
	s_waitcnt lgkmcnt(0)
	v_mfma_f32_16x16x32_bf16 v[124:127], v[128:131], v[172:175], v[124:127]
	v_mfma_f32_16x16x32_bf16 v[120:123], v[154:157], v[172:175], v[120:123]
	v_mfma_f32_16x16x32_bf16 v[112:115], v[128:131], v[180:183], v[112:115]
	v_mfma_f32_16x16x32_bf16 v[104:107], v[154:157], v[180:183], v[104:107]
	v_mfma_f32_16x16x32_bf16 v[96:99], v[128:131], v[188:191], v[96:99]
	v_mfma_f32_16x16x32_bf16 v[88:91], v[154:157], v[188:191], v[88:91]
	v_mfma_f32_16x16x32_bf16 v[80:83], v[128:131], v[196:199], v[80:83]
	v_mfma_f32_16x16x32_bf16 v[72:75], v[154:157], v[196:199], v[72:75]
	v_mfma_f32_16x16x32_bf16 v[124:127], v[132:135], v[176:179], v[124:127]
	v_mfma_f32_16x16x32_bf16 v[120:123], v[158:161], v[176:179], v[120:123]
	v_mfma_f32_16x16x32_bf16 v[112:115], v[132:135], v[184:187], v[112:115]
	v_mfma_f32_16x16x32_bf16 v[104:107], v[158:161], v[184:187], v[104:107]
	v_mfma_f32_16x16x32_bf16 v[96:99], v[132:135], v[192:195], v[96:99]
	v_mfma_f32_16x16x32_bf16 v[88:91], v[158:161], v[192:195], v[88:91]
	v_mfma_f32_16x16x32_bf16 v[80:83], v[132:135], v[200:203], v[80:83]
	v_mfma_f32_16x16x32_bf16 v[72:75], v[158:161], v[200:203], v[72:75]
	s_setprio 0
	s_barrier
	s_add_i32 s5, s94, s19
	v_lshl_add_u64 v[162:163], s[78:79], 0, v[138:139]
	s_mov_b32 m0, s5
	ds_read_b128 v[204:207], v170
	ds_read_b128 v[208:211], v170 offset:1024
	ds_read_b128 v[212:215], v170 offset:2048
	ds_read_b128 v[216:219], v170 offset:3072
	global_load_lds_dwordx4 v[162:163], off
	v_lshl_add_u64 v[220:221], s[78:79], 0, v[142:143]
	s_add_i32 m0, s5, 0x2000
	s_nop 0
	global_load_lds_dwordx4 v[220:221], off
	s_barrier
	s_waitcnt lgkmcnt(0)
	s_setprio 1
	s_waitcnt lgkmcnt(0)
	v_mfma_f32_16x16x32_bf16 v[116:119], v[204:207], v[172:175], v[116:119]
	v_mfma_f32_16x16x32_bf16 v[108:111], v[212:215], v[172:175], v[108:111]
	v_mfma_f32_16x16x32_bf16 v[100:103], v[204:207], v[180:183], v[100:103]
	v_mfma_f32_16x16x32_bf16 v[92:95], v[212:215], v[180:183], v[92:95]
	v_mfma_f32_16x16x32_bf16 v[84:87], v[204:207], v[188:191], v[84:87]
	v_mfma_f32_16x16x32_bf16 v[76:79], v[212:215], v[188:191], v[76:79]
	v_mfma_f32_16x16x32_bf16 v[68:71], v[204:207], v[196:199], v[68:71]
	v_mfma_f32_16x16x32_bf16 v[64:67], v[212:215], v[196:199], v[64:67]
	v_mfma_f32_16x16x32_bf16 v[116:119], v[208:211], v[176:179], v[116:119]
	v_mfma_f32_16x16x32_bf16 v[108:111], v[216:219], v[176:179], v[108:111]
	v_mfma_f32_16x16x32_bf16 v[100:103], v[208:211], v[184:187], v[100:103]
	v_mfma_f32_16x16x32_bf16 v[92:95], v[216:219], v[184:187], v[92:95]
	v_mfma_f32_16x16x32_bf16 v[84:87], v[208:211], v[192:195], v[84:87]
	v_mfma_f32_16x16x32_bf16 v[76:79], v[216:219], v[192:195], v[76:79]
	v_mfma_f32_16x16x32_bf16 v[68:71], v[208:211], v[200:203], v[68:71]
	v_mfma_f32_16x16x32_bf16 v[64:67], v[216:219], v[200:203], v[64:67]
	s_setprio 0
	s_mov_b32 m0, s58
	v_lshl_add_u64 v[224:225], s[80:81], 0, v[136:137]
	s_barrier
	ds_read_b128 v[172:175], v169 offset:16384
	ds_read_b128 v[176:179], v169 offset:17408
	ds_read_b128 v[180:183], v169 offset:18432
	ds_read_b128 v[184:187], v169 offset:19456
	ds_read_b128 v[188:191], v169 offset:20480
	ds_read_b128 v[192:195], v169 offset:21504
	ds_read_b128 v[196:199], v169 offset:22528
	ds_read_b128 v[200:203], v169 offset:23552
	global_load_lds_dwordx4 v[224:225], off
	v_lshl_add_u64 v[226:227], s[80:81], 0, v[140:141]
	s_mov_b32 m0, s59
	s_nop 0
	global_load_lds_dwordx4 v[226:227], off
	s_barrier
	s_waitcnt lgkmcnt(0)
	s_setprio 1
	s_waitcnt lgkmcnt(0)
	v_mfma_f32_16x16x32_bf16 v[60:63], v[128:131], v[172:175], v[60:63]
	v_mfma_f32_16x16x32_bf16 v[56:59], v[154:157], v[172:175], v[56:59]
	v_mfma_f32_16x16x32_bf16 v[48:51], v[128:131], v[180:183], v[48:51]
	v_mfma_f32_16x16x32_bf16 v[40:43], v[154:157], v[180:183], v[40:43]
	v_mfma_f32_16x16x32_bf16 v[32:35], v[128:131], v[188:191], v[32:35]
	v_mfma_f32_16x16x32_bf16 v[24:27], v[154:157], v[188:191], v[24:27]
	v_mfma_f32_16x16x32_bf16 v[16:19], v[128:131], v[196:199], v[16:19]
	v_mfma_f32_16x16x32_bf16 v[8:11], v[154:157], v[196:199], v[8:11]
	v_mfma_f32_16x16x32_bf16 v[60:63], v[132:135], v[176:179], v[60:63]
	v_mfma_f32_16x16x32_bf16 v[56:59], v[158:161], v[176:179], v[56:59]
	v_mfma_f32_16x16x32_bf16 v[48:51], v[132:135], v[184:187], v[48:51]
	v_mfma_f32_16x16x32_bf16 v[40:43], v[158:161], v[184:187], v[40:43]
	v_mfma_f32_16x16x32_bf16 v[32:35], v[132:135], v[192:195], v[32:35]
	v_mfma_f32_16x16x32_bf16 v[24:27], v[158:161], v[192:195], v[24:27]
	v_mfma_f32_16x16x32_bf16 v[16:19], v[132:135], v[200:203], v[16:19]
	v_mfma_f32_16x16x32_bf16 v[8:11], v[158:161], v[200:203], v[8:11]
	s_setprio 0
	s_barrier
; #define PG8_STAGE(bufoff, gbase, voff) do { _Pragma("unroll") for (int _i = 0; _i < 2; ++_i) \
;         __builtin_amdgcn_global_load_lds((const unsigned*)((const char*)(gbase) + (voff)[_i]), (LAS unsigned*)(lds + (bufoff) + ldsw + _i * 8192), 16, 0, 0); } while (0)
; #define PG8_LDA(dst, b, h) do { _Pragma("unroll") for (int m = 0; m < 4; ++m) _Pragma("unroll") for (int k = 0; k < 2; ++k) dst[m][k] = *(const LAS bf16x8*)(lds + PG8_SA(b, h) + aoff + m * 2048 + k * 1024); } while (0)
; #define PG8_LDB(dst, b, h) do { _Pragma("unroll") for (int n = 0; n < 2; ++n) _Pragma("unroll") for (int k = 0; k < 2; ++k) dst[n][k] = *(const LAS bf16x8*)(lds + PG8_SB(b, h) + boff + n * 2048 + k * 1024); } while (0)
; #define PG8_MMA(ai, bj, At, Bt) do { __builtin_amdgcn_s_setprio(1); _Pragma("unroll") for (int m = 0; m < 4; ++m) _Pragma("unroll") for (int n = 0; n < 2; ++n) _Pragma("unroll") for (int k = 0; k < 2; ++k) \
;         acc[ai][bj][m][n] = __builtin_amdgcn_mfma_f32_16x16x32_bf16(Bt[n][k], At[m][k], acc[ai][bj][m][n], 0, 0, 0); __builtin_amdgcn_s_setprio(0); } while (0)
; #define PG8_WAIT_V(n) asm volatile("s_waitcnt vmcnt(" #n ")" ::: "memory")
; #define PG8_WAIT_L(n) asm volatile("s_waitcnt lgkmcnt(" #n ")" ::: "memory")
; #define PG8_BAR __builtin_amdgcn_s_barrier()
; #define PG8_SCHED __builtin_amdgcn_sched_barrier(0)
; #define PG8_STAGE(bufoff, gbase, voff) do { _Pragma("unroll") for (int _i = 0; _i < 2; ++_i) \
;         __builtin_amdgcn_global_load_lds((const unsigned*)((const char*)(gbase) + (voff)[_i]), (LAS unsigned*)(lds + (bufoff) + ldsw + _i * 8192), 16, 0, 0); } while (0)
; #define PG8_BAR __builtin_amdgcn_s_barrier()
; template <class Epi>
; DI void gemm_phase(LAS unsigned char* lds, const Gemm g, const StaticOrder S, const Epi E) {
;     ...
;             PG8_STAGE(PG8_SB(0, 1), b2 + hstep, voffB);
;             PG8_WAIT_V(6); PG8_BAR; PG8_MMA(1, 1, At, B1); PG8_BAR;
;             PG8_LDB(B0, 1, 0); PG8_SCHED; PG8_LDA(At, 1, 0); PG8_STAGE(PG8_SA(0, 1), a2 + hstep, voffA);
;             PG8_WAIT_L(8); PG8_BAR; PG8_WAIT_L(0); PG8_MMA(0, 0, At, B0); PG8_BAR; PG8_SCHED;
;             PG8_LDB(B1, 1, 1); PG8_STAGE(PG8_SB(1, 0), b3, voffB);
;             PG8_BAR; PG8_WAIT_L(0); PG8_MMA(0, 1, At, B1); PG8_BAR;
;             PG8_LDA(At, 1, 1); PG8_STAGE(PG8_SA(1, 0), a3, voffA);
;             PG8_BAR; PG8_WAIT_L(0); PG8_MMA(1, 0, At, B0); PG8_BAR; PG8_SCHED;
	s_add_u32 s14, s78, 0x40000
	s_addc_u32 s15, s79, 0
	s_add_i32 s5, s95, s19
	v_lshl_add_u64 v[128:129], s[14:15], 0, v[138:139]
	s_mov_b32 m0, s5
	s_nop 0
	global_load_lds_dwordx4 v[128:129], off
	v_lshl_add_u64 v[128:129], s[14:15], 0, v[142:143]
	s_add_i32 m0, s5, 0x2000
	s_nop 0
	global_load_lds_dwordx4 v[128:129], off
	s_waitcnt vmcnt(6)
	s_barrier
	s_setprio 1
	v_mfma_f32_16x16x32_bf16 v[52:55], v[204:207], v[172:175], v[52:55]
	v_mfma_f32_16x16x32_bf16 v[44:47], v[212:215], v[172:175], v[44:47]
	v_mfma_f32_16x16x32_bf16 v[36:39], v[204:207], v[180:183], v[36:39]
	v_mfma_f32_16x16x32_bf16 v[28:31], v[212:215], v[180:183], v[28:31]
	v_mfma_f32_16x16x32_bf16 v[20:23], v[204:207], v[188:191], v[20:23]
	v_mfma_f32_16x16x32_bf16 v[12:15], v[212:215], v[188:191], v[12:15]
	v_mfma_f32_16x16x32_bf16 v[4:7], v[204:207], v[196:199], v[4:7]
	v_mfma_f32_16x16x32_bf16 v[0:3], v[212:215], v[196:199], v[0:3]
	v_mfma_f32_16x16x32_bf16 v[52:55], v[208:211], v[176:179], v[52:55]
	v_mfma_f32_16x16x32_bf16 v[44:47], v[216:219], v[176:179], v[44:47]
	v_mfma_f32_16x16x32_bf16 v[36:39], v[208:211], v[184:187], v[36:39]
	v_mfma_f32_16x16x32_bf16 v[28:31], v[216:219], v[184:187], v[28:31]
	v_mfma_f32_16x16x32_bf16 v[20:23], v[208:211], v[192:195], v[20:23]
	v_mfma_f32_16x16x32_bf16 v[12:15], v[216:219], v[192:195], v[12:15]
	v_mfma_f32_16x16x32_bf16 v[4:7], v[208:211], v[200:203], v[4:7]
	v_mfma_f32_16x16x32_bf16 v[0:3], v[216:219], v[200:203], v[0:3]
	s_setprio 0
	s_add_i32 s5, 0, 0x18000
	v_add_u32_e32 v158, s5, v165
	s_barrier
	ds_read_b128 v[128:131], v158
	ds_read_b128 v[132:135], v158 offset:1024
	ds_read_b128 v[154:157], v158 offset:2048
	ds_read_b128 v[158:161], v158 offset:3072
	s_add_u32 s14, s80, 0x40000
	s_addc_u32 s15, s81, 0
	s_mov_b32 m0, s77
	v_lshl_add_u64 v[204:205], s[14:15], 0, v[136:137]
	ds_read_b128 v[172:175], v169 offset:32768
	ds_read_b128 v[176:179], v169 offset:33792
	ds_read_b128 v[180:183], v169 offset:34816
	ds_read_b128 v[184:187], v169 offset:35840
	ds_read_b128 v[188:191], v169 offset:36864
	ds_read_b128 v[192:195], v169 offset:37888
	ds_read_b128 v[196:199], v169 offset:38912
	ds_read_b128 v[200:203], v169 offset:39936
	global_load_lds_dwordx4 v[204:205], off
	v_lshl_add_u64 v[204:205], s[14:15], 0, v[140:141]
	s_mov_b32 m0, s82
	s_nop 0
	global_load_lds_dwordx4 v[204:205], off
	s_waitcnt lgkmcnt(8)
	s_barrier
	s_waitcnt lgkmcnt(0)
	s_setprio 1
	s_waitcnt lgkmcnt(0)
	v_mfma_f32_16x16x32_bf16 v[124:127], v[128:131], v[172:175], v[124:127]
	v_mfma_f32_16x16x32_bf16 v[120:123], v[154:157], v[172:175], v[120:123]
	v_mfma_f32_16x16x32_bf16 v[112:115], v[128:131], v[180:183], v[112:115]
	v_mfma_f32_16x16x32_bf16 v[104:107], v[154:157], v[180:183], v[104:107]
	v_mfma_f32_16x16x32_bf16 v[96:99], v[128:131], v[188:191], v[96:99]
	v_mfma_f32_16x16x32_bf16 v[88:91], v[154:157], v[188:191], v[88:91]
	v_mfma_f32_16x16x32_bf16 v[80:83], v[128:131], v[196:199], v[80:83]
	v_mfma_f32_16x16x32_bf16 v[72:75], v[154:157], v[196:199], v[72:75]
	v_mfma_f32_16x16x32_bf16 v[124:127], v[132:135], v[176:179], v[124:127]
	v_mfma_f32_16x16x32_bf16 v[120:123], v[158:161], v[176:179], v[120:123]
	v_mfma_f32_16x16x32_bf16 v[112:115], v[132:135], v[184:187], v[112:115]
	v_mfma_f32_16x16x32_bf16 v[104:107], v[158:161], v[184:187], v[104:107]
	v_mfma_f32_16x16x32_bf16 v[96:99], v[132:135], v[192:195], v[96:99]
	v_mfma_f32_16x16x32_bf16 v[88:91], v[158:161], v[192:195], v[88:91]
	v_mfma_f32_16x16x32_bf16 v[80:83], v[132:135], v[200:203], v[80:83]
	v_mfma_f32_16x16x32_bf16 v[72:75], v[158:161], v[200:203], v[72:75]
	s_setprio 0
	s_barrier
	s_add_i32 s35, 0, 0x1c000
	s_add_i32 s5, s5, s19
	v_add_u32_e32 v171, s35, v165
	v_lshl_add_u64 v[162:163], v[162:163], 0, s[10:11]
	s_mov_b32 m0, s5
	ds_read_b128 v[204:207], v171
	ds_read_b128 v[208:211], v171 offset:1024
	ds_read_b128 v[212:215], v171 offset:2048
	ds_read_b128 v[216:219], v171 offset:3072
	global_load_lds_dwordx4 v[162:163], off
	v_lshl_add_u64 v[162:163], v[220:221], 0, s[10:11]
	s_add_i32 m0, s5, 0x2000
	s_nop 0
	global_load_lds_dwordx4 v[162:163], off
	s_barrier
	s_waitcnt lgkmcnt(0)
	s_setprio 1
	s_waitcnt lgkmcnt(0)
	v_mfma_f32_16x16x32_bf16 v[116:119], v[204:207], v[172:175], v[116:119]
	v_mfma_f32_16x16x32_bf16 v[108:111], v[212:215], v[172:175], v[108:111]
	v_mfma_f32_16x16x32_bf16 v[100:103], v[204:207], v[180:183], v[100:103]
	v_mfma_f32_16x16x32_bf16 v[92:95], v[212:215], v[180:183], v[92:95]
	v_mfma_f32_16x16x32_bf16 v[84:87], v[204:207], v[188:191], v[84:87]
	v_mfma_f32_16x16x32_bf16 v[76:79], v[212:215], v[188:191], v[76:79]
	v_mfma_f32_16x16x32_bf16 v[68:71], v[204:207], v[196:199], v[68:71]
	v_mfma_f32_16x16x32_bf16 v[64:67], v[212:215], v[196:199], v[64:67]
	v_mfma_f32_16x16x32_bf16 v[116:119], v[208:211], v[176:179], v[116:119]
	v_mfma_f32_16x16x32_bf16 v[108:111], v[216:219], v[176:179], v[108:111]
	v_mfma_f32_16x16x32_bf16 v[100:103], v[208:211], v[184:187], v[100:103]
	v_mfma_f32_16x16x32_bf16 v[92:95], v[216:219], v[184:187], v[92:95]
	v_mfma_f32_16x16x32_bf16 v[84:87], v[208:211], v[192:195], v[84:87]
	v_mfma_f32_16x16x32_bf16 v[76:79], v[216:219], v[192:195], v[76:79]
	v_mfma_f32_16x16x32_bf16 v[68:71], v[208:211], v[200:203], v[68:71]
	v_mfma_f32_16x16x32_bf16 v[64:67], v[216:219], v[200:203], v[64:67]
	s_setprio 0
	s_mov_b32 m0, s86
	v_lshl_add_u64 v[162:163], v[224:225], 0, s[10:11]
	s_barrier
	ds_read_b128 v[172:175], v169 offset:49152
	ds_read_b128 v[176:179], v169 offset:50176
	ds_read_b128 v[180:183], v169 offset:51200
	ds_read_b128 v[184:187], v169 offset:52224
	ds_read_b128 v[188:191], v169 offset:53248
	ds_read_b128 v[192:195], v169 offset:54272
	ds_read_b128 v[196:199], v169 offset:55296
	ds_read_b128 v[200:203], v169 offset:56320
	global_load_lds_dwordx4 v[162:163], off
	v_lshl_add_u64 v[162:163], v[226:227], 0, s[10:11]
	s_mov_b32 m0, s87
	s_nop 0
	global_load_lds_dwordx4 v[162:163], off
	s_barrier
; #define PG8_STAGE(bufoff, gbase, voff) do { _Pragma("unroll") for (int _i = 0; _i < 2; ++_i) \
;         __builtin_amdgcn_global_load_lds((const unsigned*)((const char*)(gbase) + (voff)[_i]), (LAS unsigned*)(lds + (bufoff) + ldsw + _i * 8192), 16, 0, 0); } while (0)
; #define PG8_MMA(ai, bj, At, Bt) do { __builtin_amdgcn_s_setprio(1); _Pragma("unroll") for (int m = 0; m < 4; ++m) _Pragma("unroll") for (int n = 0; n < 2; ++n) _Pragma("unroll") for (int k = 0; k < 2; ++k) \
;         acc[ai][bj][m][n] = __builtin_amdgcn_mfma_f32_16x16x32_bf16(Bt[n][k], At[m][k], acc[ai][bj][m][n], 0, 0, 0); __builtin_amdgcn_s_setprio(0); } while (0)
; #define PG8_WAIT_V(n) asm volatile("s_waitcnt vmcnt(" #n ")" ::: "memory")
; #define PG8_WAIT_L(n) asm volatile("s_waitcnt lgkmcnt(" #n ")" ::: "memory")
; #define PG8_BAR __builtin_amdgcn_s_barrier()
; #define PG8_SCHED __builtin_amdgcn_sched_barrier(0)
; #define PG8_STAGE(bufoff, gbase, voff) do { _Pragma("unroll") for (int _i = 0; _i < 2; ++_i) \
;         __builtin_amdgcn_global_load_lds((const unsigned*)((const char*)(gbase) + (voff)[_i]), (LAS unsigned*)(lds + (bufoff) + ldsw + _i * 8192), 16, 0, 0); } while (0)
; #define PG8_WAIT_V(n) asm volatile("s_waitcnt vmcnt(" #n ")" ::: "memory")
; #define PG8_WAIT_L(n) asm volatile("s_waitcnt lgkmcnt(" #n ")" ::: "memory")
; #define PG8_BAR __builtin_amdgcn_s_barrier()
; #define PG8_SCHED __builtin_amdgcn_sched_barrier(0)
; template <class Epi>
; DI void gemm_phase(LAS unsigned char* lds, const Gemm g, const StaticOrder S, const Epi E) {
;     ...
;             PG8_BAR; PG8_WAIT_L(0); PG8_MMA(1, 0, At, B0); PG8_BAR; PG8_SCHED;
;             PG8_STAGE(PG8_SB(1, 1), b3 + hstep, voffB);
;             PG8_WAIT_V(6); PG8_BAR; PG8_MMA(1, 1, At, B1); PG8_BAR;
;     DI void operator()(AccRef acc, const Unit& u, int wr, int wc, int fr, int fq) const {
;         f32x4 ts[2][2];
; #pragma unroll
;         for (int bj = 0; bj < 2; ++bj) { const int tok = u.pn * 256 + bj * 128 + wc * 32 + 8 * fq; ts[bj][0] = *(const f32x4*)(ss + tok); ts[bj][1] = *(const f32x4*)(ss + tok + 4); }
; #pragma unroll
;         for (int bj = 0; bj < 2; ++bj)
; #pragma unroll
;             for (int n = 0; n < 2; ++n)
; #pragma unroll
;                 for (int e = 0; e < 4; ++e) ts[bj][n][e] = rsqrtf(ts[bj][n][e] * (1.0f / 1024.0f) + 1e-6f);
	s_waitcnt lgkmcnt(0)
	s_setprio 1
	s_waitcnt lgkmcnt(0)
	v_mfma_f32_16x16x32_bf16 v[60:63], v[128:131], v[172:175], v[60:63]
	v_mfma_f32_16x16x32_bf16 v[56:59], v[154:157], v[172:175], v[56:59]
	v_mfma_f32_16x16x32_bf16 v[48:51], v[128:131], v[180:183], v[48:51]
	v_mfma_f32_16x16x32_bf16 v[40:43], v[154:157], v[180:183], v[40:43]
	v_mfma_f32_16x16x32_bf16 v[32:35], v[128:131], v[188:191], v[32:35]
	v_mfma_f32_16x16x32_bf16 v[24:27], v[154:157], v[188:191], v[24:27]
	v_mfma_f32_16x16x32_bf16 v[16:19], v[128:131], v[196:199], v[16:19]
	v_mfma_f32_16x16x32_bf16 v[8:11], v[154:157], v[196:199], v[8:11]
	v_mfma_f32_16x16x32_bf16 v[60:63], v[132:135], v[176:179], v[60:63]
	v_mfma_f32_16x16x32_bf16 v[56:59], v[158:161], v[176:179], v[56:59]
	v_mfma_f32_16x16x32_bf16 v[48:51], v[132:135], v[184:187], v[48:51]
	v_mfma_f32_16x16x32_bf16 v[40:43], v[158:161], v[184:187], v[40:43]
	v_mfma_f32_16x16x32_bf16 v[32:35], v[132:135], v[192:195], v[32:35]
	v_mfma_f32_16x16x32_bf16 v[24:27], v[158:161], v[192:195], v[24:27]
	v_mfma_f32_16x16x32_bf16 v[16:19], v[132:135], v[200:203], v[16:19]
	v_mfma_f32_16x16x32_bf16 v[8:11], v[158:161], v[200:203], v[8:11]
	s_setprio 0
	s_barrier
	s_add_u32 s14, s78, 0x40080
	s_addc_u32 s15, s79, 0
	s_add_i32 s5, s35, s19
	v_lshl_add_u64 v[128:129], s[14:15], 0, v[138:139]
	s_mov_b32 m0, s5
	s_nop 0
	global_load_lds_dwordx4 v[128:129], off
	v_lshl_add_u64 v[128:129], s[14:15], 0, v[142:143]
	s_add_i32 m0, s5, 0x2000
	s_nop 0
	global_load_lds_dwordx4 v[128:129], off
	s_waitcnt vmcnt(6)
	s_barrier
	s_setprio 1
	v_mfma_f32_16x16x32_bf16 v[52:55], v[204:207], v[172:175], v[52:55]
	v_mfma_f32_16x16x32_bf16 v[44:47], v[212:215], v[172:175], v[44:47]
	v_mfma_f32_16x16x32_bf16 v[36:39], v[204:207], v[180:183], v[36:39]
	v_mfma_f32_16x16x32_bf16 v[28:31], v[212:215], v[180:183], v[28:31]
	v_mfma_f32_16x16x32_bf16 v[20:23], v[204:207], v[188:191], v[20:23]
	v_mfma_f32_16x16x32_bf16 v[12:15], v[212:215], v[188:191], v[12:15]
	v_mfma_f32_16x16x32_bf16 v[4:7], v[204:207], v[196:199], v[4:7]
	v_mfma_f32_16x16x32_bf16 v[0:3], v[212:215], v[196:199], v[0:3]
	v_mfma_f32_16x16x32_bf16 v[52:55], v[208:211], v[176:179], v[52:55]
	v_mfma_f32_16x16x32_bf16 v[44:47], v[216:219], v[176:179], v[44:47]
	v_mfma_f32_16x16x32_bf16 v[36:39], v[208:211], v[184:187], v[36:39]
	v_mfma_f32_16x16x32_bf16 v[28:31], v[216:219], v[184:187], v[28:31]
	v_mfma_f32_16x16x32_bf16 v[20:23], v[208:211], v[192:195], v[20:23]
	v_mfma_f32_16x16x32_bf16 v[12:15], v[216:219], v[192:195], v[12:15]
	v_mfma_f32_16x16x32_bf16 v[4:7], v[208:211], v[200:203], v[4:7]
	v_mfma_f32_16x16x32_bf16 v[0:3], v[216:219], v[200:203], v[0:3]
	s_setprio 0
	s_add_i32 s4, s4, 2
	s_add_u32 s8, s8, 0x100
	s_addc_u32 s9, s9, 0
	s_add_u32 vcc_lo, vcc_lo, 0x100
	s_addc_u32 vcc_hi, vcc_hi, 0
	s_cmp_gt_u32 s4, 13
	s_barrier
	s_cbranch_scc0 .LBB0_298
	s_lshl_b32 s4, s97, 8
	v_or_b32_e32 v128, s4, v166
	v_ashrrev_i32_e32 v129, 31, v128
	v_lshl_add_u64 v[132:133], v[128:129], 2, s[60:61]
	global_load_dwordx4 v[158:161], v[132:133], off offset:16
	global_load_dwordx4 v[154:157], v[132:133], off
	global_load_dwordx4 v[128:131], v[132:133], off offset:528
	s_nop 0
	global_load_dwordx4 v[132:135], v[132:133], off offset:512
	s_mov_b32 s6, 0x358637bd
	v_mov_b64_e32 v[162:163], s[6:7]
	s_lshl_b32 s6, s76, 8
	s_add_i32 s6, s6, s84
	s_lshr_b32 s5, s97, 3
	s_and_b32 s7, s5, 0x1fffc
	s_bfe_u32 s5, s6, 0x20008
	s_or_b32 s4, s4, s85
	s_or_b32 s5, s5, s7
	s_cmpk_lt_u32 s6, 0x400
	s_mov_b32 s97, s20
	s_mov_b32 s76, s22
	s_mov_b64 s[78:79], s[28:29]
	s_waitcnt vmcnt(0)
	v_pk_fma_f32 v[158:159], v[158:159], s[16:17], v[162:163] op_sel_hi:[1,0,0]
	v_pk_fma_f32 v[154:155], v[154:155], s[16:17], v[162:163] op_sel_hi:[1,0,0]
	v_pk_fma_f32 v[156:157], v[156:157], s[16:17], v[162:163] op_sel_hi:[1,0,0]
	v_mul_f32_e32 v171, 0x4b800000, v154
	v_cmp_gt_f32_e64 s[8:9], s96, v154
	v_cmp_gt_f32_e32 vcc, s96, v155
	v_pk_fma_f32 v[160:161], v[160:161], s[16:17], v[162:163] op_sel_hi:[1,0,0]
	v_cndmask_b32_e64 v154, v154, v171, s[8:9]
	v_mul_f32_e32 v171, 0x4b800000, v155
	v_cndmask_b32_e32 v155, v155, v171, vcc
	v_rsq_f32_e32 v154, v154
	v_rsq_f32_e32 v155, v155
	v_mul_f32_e32 v171, 0x4b800000, v156
	v_pk_fma_f32 v[132:133], v[132:133], s[16:17], v[162:163] op_sel_hi:[1,0,0]
	v_pk_fma_f32 v[134:135], v[134:135], s[16:17], v[162:163] op_sel_hi:[1,0,0]
	v_pk_mul_f32 v[172:173], v[154:155], s[18:19] op_sel_hi:[1,0]
	v_pk_fma_f32 v[128:129], v[128:129], s[16:17], v[162:163] op_sel_hi:[1,0,0]
	v_cndmask_b32_e64 v154, v154, v172, s[8:9]
	v_cmp_gt_f32_e64 s[8:9], s96, v156
	v_cndmask_b32_e32 v155, v155, v173, vcc
	v_cmp_gt_f32_e32 vcc, s96, v157
	v_cndmask_b32_e64 v156, v156, v171, s[8:9]
	v_mul_f32_e32 v171, 0x4b800000, v157
	v_cndmask_b32_e32 v157, v157, v171, vcc
	v_rsq_f32_e32 v156, v156
	v_rsq_f32_e32 v157, v157
	v_mul_f32_e32 v171, 0x4b800000, v158
	v_pk_fma_f32 v[130:131], v[130:131], s[16:17], v[162:163] op_sel_hi:[1,0,0]
	v_pk_mul_f32 v[124:125], v[124:125], v[154:155]
	v_pk_mul_f32 v[172:173], v[156:157], s[18:19] op_sel_hi:[1,0]
	v_mul_f32_e32 v162, 0x4b800000, v130
	v_cndmask_b32_e64 v156, v156, v172, s[8:9]
	v_cmp_gt_f32_e64 s[8:9], s96, v158
	v_cndmask_b32_e32 v157, v157, v173, vcc
	v_cmp_gt_f32_e32 vcc, s96, v159
	v_cndmask_b32_e64 v158, v158, v171, s[8:9]
	v_mul_f32_e32 v171, 0x4b800000, v159
	v_cndmask_b32_e32 v159, v159, v171, vcc
	v_rsq_f32_e32 v158, v158
	v_rsq_f32_e32 v159, v159
	v_mul_f32_e32 v171, 0x4b800000, v160
	v_pk_mul_f32 v[126:127], v[126:127], v[156:157]
	v_pk_mul_f32 v[112:113], v[112:113], v[154:155]
	v_pk_mul_f32 v[172:173], v[158:159], s[18:19] op_sel_hi:[1,0]
	v_pk_mul_f32 v[96:97], v[96:97], v[154:155]
; DI unsigned pk_bf16(float lo, float hi) { f32x2 v = {lo, hi}; return __builtin_bit_cast(unsigned, __builtin_convertvector(v, bf16v2)); }
;     DI void operator()(AccRef acc, const Unit& u, int wr, int wc, int fr, int fq) const {
;     ...
;                 for (int e = 0; e < 4; ++e) ts[bj][n][e] = rsqrtf(ts[bj][n][e] * (1.0f / 1024.0f) + 1e-6f);
; #pragma unroll
;         for (int ai = 0; ai < 2; ++ai)
; #pragma unroll
;             for (int m = 0; m < 4; ++m) {
;                 const int R = u.pm * 256 + ai * 128 + wr * 64 + m * 16 + fr, X = R >> 10, hv = R & 1023;
; #pragma unroll
;                 for (int bj = 0; bj < 2; ++bj) {
;                     const int tok = u.pn * 256 + bj * 128 + wc * 32 + 8 * fq, b = tok >> 13, s = tok & (SEQ - 1);
;                     bf16_t* dst = (X ? vtB : vtA) + ((size_t)(((b * 4 + (hv >> 8)) * 128 + (s >> 6)) * 256 + (hv & 255))) * 64 + (s & 63);
;                     const f32x4 v0 = acc[ai][bj][m][0] * ts[bj][0], v1 = acc[ai][bj][m][1] * ts[bj][1];
;                     u32x4 w; w.x = pk_bf16(v0[0], v0[1]); w.y = pk_bf16(v0[2], v0[3]); w.z = pk_bf16(v1[0], v1[1]); w.w = pk_bf16(v1[2], v1[3]);
;                     *(u32x4*)dst = w;
	v_cndmask_b32_e64 v158, v158, v172, s[8:9]
	v_cmp_gt_f32_e64 s[8:9], s96, v160
	v_cndmask_b32_e32 v159, v159, v173, vcc
	v_cmp_gt_f32_e32 vcc, s96, v161
	v_cndmask_b32_e64 v160, v160, v171, s[8:9]
	v_mul_f32_e32 v171, 0x4b800000, v161
	v_cndmask_b32_e32 v161, v161, v171, vcc
	v_rsq_f32_e32 v160, v160
	v_rsq_f32_e32 v161, v161
	v_mul_f32_e32 v171, 0x4b800000, v132
	v_pk_mul_f32 v[80:81], v[80:81], v[154:155]
	v_pk_mul_f32 v[62:63], v[62:63], v[156:157]
	v_pk_mul_f32 v[172:173], v[160:161], s[18:19] op_sel_hi:[1,0]
	v_pk_mul_f32 v[60:61], v[60:61], v[154:155]
	v_cndmask_b32_e64 v160, v160, v172, s[8:9]
	v_cmp_gt_f32_e64 s[8:9], s96, v132
	v_cndmask_b32_e32 v161, v161, v173, vcc
	v_cmp_gt_f32_e32 vcc, s96, v133
	v_cndmask_b32_e64 v132, v132, v171, s[8:9]
	v_mul_f32_e32 v171, 0x4b800000, v133
	v_cndmask_b32_e32 v133, v133, v171, vcc
	v_rsq_f32_e32 v132, v132
	v_rsq_f32_e32 v133, v133
	v_mul_f32_e32 v171, 0x4b800000, v134
	v_pk_mul_f32 v[48:49], v[48:49], v[154:155]
	v_pk_mul_f32 v[32:33], v[32:33], v[154:155]
	v_pk_mul_f32 v[172:173], v[132:133], s[18:19] op_sel_hi:[1,0]
	v_pk_mul_f32 v[16:17], v[16:17], v[154:155]
	v_cndmask_b32_e64 v132, v132, v172, s[8:9]
	v_cmp_gt_f32_e64 s[8:9], s96, v134
	v_cndmask_b32_e32 v133, v133, v173, vcc
	v_cmp_gt_f32_e32 vcc, s96, v135
	v_cndmask_b32_e64 v134, v134, v171, s[8:9]
	v_mul_f32_e32 v171, 0x4b800000, v135
	v_cndmask_b32_e32 v135, v135, v171, vcc
	v_rsq_f32_e32 v134, v134
	v_rsq_f32_e32 v135, v135
	v_mul_f32_e32 v171, 0x4b800000, v128
	v_pk_mul_f32 v[116:117], v[116:117], v[132:133]
	v_pk_mul_f32 v[100:101], v[100:101], v[132:133]
	v_pk_mul_f32 v[172:173], v[134:135], s[18:19] op_sel_hi:[1,0]
	v_pk_mul_f32 v[84:85], v[84:85], v[132:133]
	v_cndmask_b32_e64 v134, v134, v172, s[8:9]
	v_cmp_gt_f32_e64 s[8:9], s96, v128
	v_cndmask_b32_e32 v135, v135, v173, vcc
	v_cmp_gt_f32_e32 vcc, s96, v129
	v_cndmask_b32_e64 v128, v128, v171, s[8:9]
	v_mul_f32_e32 v171, 0x4b800000, v129
	v_cndmask_b32_e32 v129, v129, v171, vcc
	v_rsq_f32_e32 v128, v128
	v_rsq_f32_e32 v129, v129
	v_lshl_or_b32 v171, s5, 15, v167
	v_pk_mul_f32 v[118:119], v[118:119], v[134:135]
	v_pk_mul_f32 v[102:103], v[102:103], v[134:135]
	v_pk_mul_f32 v[172:173], v[128:129], s[18:19] op_sel_hi:[1,0]
	v_pk_mul_f32 v[86:87], v[86:87], v[134:135]
	v_cndmask_b32_e64 v128, v128, v172, s[8:9]
	v_cmp_gt_f32_e64 s[8:9], s96, v130
	v_cndmask_b32_e32 v129, v129, v173, vcc
	v_cmp_gt_f32_e32 vcc, s96, v131
	v_cndmask_b32_e64 v130, v130, v162, s[8:9]
	v_mul_f32_e32 v162, 0x4b800000, v131
	v_cndmask_b32_e32 v131, v131, v162, vcc
	v_rsq_f32_e32 v130, v130
	v_rsq_f32_e32 v131, v131
	v_pk_mul_f32 v[172:173], v[122:123], v[160:161]
	v_pk_mul_f32 v[122:123], v[120:121], v[158:159]
	v_cvt_pk_bf16_f32 v120, v124, v125
	v_pk_mul_f32 v[162:163], v[130:131], s[18:19] op_sel_hi:[1,0]
	v_cvt_pk_bf16_f32 v121, v126, v127
	v_cndmask_b32_e64 v130, v130, v162, s[8:9]
	s_cselect_b32 s9, s53, s91
	s_cselect_b32 s8, s52, s90
	s_lshl_b32 s4, s4, 2
	s_and_b32 s4, s4, 0x7d00
	v_or_b32_e32 v162, s4, v171
	v_cndmask_b32_e32 v131, v131, v163, vcc
	v_ashrrev_i32_e32 v163, 31, v162
	v_lshlrev_b64 v[162:163], 7, v[162:163]
	v_lshl_add_u64 v[162:163], s[8:9], 0, v[162:163]
	v_lshl_add_u64 v[162:163], v[162:163], 0, v[144:145]
	v_cvt_pk_bf16_f32 v122, v122, v123
	v_cvt_pk_bf16_f32 v123, v172, v173
	s_or_b32 s5, s4, 0x200
	global_store_dwordx4 v[162:163], v[120:123], off
	s_addk_i32 s6, 0x80
	v_pk_mul_f32 v[70:71], v[70:71], v[134:135]
	v_or_b32_e32 v120, s5, v171
	v_ashrrev_i32_e32 v121, 31, v120
	v_lshlrev_b64 v[120:121], 7, v[120:121]
	v_lshl_add_u64 v[120:121], s[8:9], 0, v[120:121]
	v_pk_mul_f32 v[122:123], v[110:111], v[130:131]
	v_pk_mul_f32 v[110:111], v[108:109], v[128:129]
	v_lshl_add_u64 v[120:121], v[120:121], 0, v[144:145]
	v_cvt_pk_bf16_f32 v108, v116, v117
	v_cvt_pk_bf16_f32 v109, v118, v119
	v_cvt_pk_bf16_f32 v110, v110, v111
	v_cvt_pk_bf16_f32 v111, v122, v123
	v_or_b32_e32 v116, 16, v171
	global_store_dwordx4 v[120:121], v[108:111], off
	v_pk_mul_f32 v[68:69], v[68:69], v[132:133]
	v_pk_mul_f32 v[54:55], v[54:55], v[134:135]
	v_or_b32_e32 v108, s4, v116
	v_ashrrev_i32_e32 v109, 31, v108
	v_lshlrev_b64 v[108:109], 7, v[108:109]
	v_lshl_add_u64 v[108:109], s[8:9], 0, v[108:109]
	v_pk_mul_f32 v[110:111], v[114:115], v[156:157]
	v_pk_mul_f32 v[114:115], v[106:107], v[160:161]
	v_pk_mul_f32 v[106:107], v[104:105], v[158:159]
	v_lshl_add_u64 v[108:109], v[108:109], 0, v[144:145]
	v_cvt_pk_bf16_f32 v104, v112, v113
	v_cvt_pk_bf16_f32 v105, v110, v111
	v_cvt_pk_bf16_f32 v106, v106, v107
	v_cvt_pk_bf16_f32 v107, v114, v115
	global_store_dwordx4 v[108:109], v[104:107], off
	v_pk_mul_f32 v[52:53], v[52:53], v[132:133]
	v_pk_mul_f32 v[38:39], v[38:39], v[134:135]
	v_or_b32_e32 v104, s5, v116
	v_ashrrev_i32_e32 v105, 31, v104
	v_lshlrev_b64 v[104:105], 7, v[104:105]
	v_lshl_add_u64 v[104:105], s[8:9], 0, v[104:105]
	v_pk_mul_f32 v[106:107], v[94:95], v[130:131]
	v_pk_mul_f32 v[94:95], v[92:93], v[128:129]
	v_lshl_add_u64 v[104:105], v[104:105], 0, v[144:145]
	v_cvt_pk_bf16_f32 v92, v100, v101
	v_cvt_pk_bf16_f32 v93, v102, v103
	v_cvt_pk_bf16_f32 v94, v94, v95
	v_cvt_pk_bf16_f32 v95, v106, v107
	v_or_b32_e32 v100, 32, v171
	global_store_dwordx4 v[104:105], v[92:95], off
	v_pk_mul_f32 v[36:37], v[36:37], v[132:133]
	v_pk_mul_f32 v[22:23], v[22:23], v[134:135]
	v_or_b32_e32 v92, s4, v100
	v_ashrrev_i32_e32 v93, 31, v92
	v_lshlrev_b64 v[92:93], 7, v[92:93]
	v_lshl_add_u64 v[92:93], s[8:9], 0, v[92:93]
	v_pk_mul_f32 v[94:95], v[98:99], v[156:157]
	v_pk_mul_f32 v[98:99], v[90:91], v[160:161]
	v_pk_mul_f32 v[90:91], v[88:89], v[158:159]
	v_lshl_add_u64 v[92:93], v[92:93], 0, v[144:145]
; DI unsigned pk_bf16(float lo, float hi) { f32x2 v = {lo, hi}; return __builtin_bit_cast(unsigned, __builtin_convertvector(v, bf16v2)); }
; #define PG8_WAIT_V(n) asm volatile("s_waitcnt vmcnt(" #n ")" ::: "memory")
; #define PG8_BAR __builtin_amdgcn_s_barrier()
; #define PG8_WAIT_V(n) asm volatile("s_waitcnt vmcnt(" #n ")" ::: "memory")
; #define PG8_BAR __builtin_amdgcn_s_barrier()
; template <class Epi>
; DI void gemm_phase(LAS unsigned char* lds, const Gemm g, const StaticOrder S, const Epi E) {
;     ...
;         E(acc, cur, wr, wc, fr, fq);
;         if (!has_next) break;
; #pragma unroll
;         for (int a = 0; a < 2; ++a)
; #pragma unroll
;             for (int b = 0; b < 2; ++b)
; #pragma unroll
;                 for (int m = 0; m < 4; ++m)
; #pragma unroll
;                     for (int n = 0; n < 2; ++n) acc[a][b][m][n] = (f32x4){0.f, 0.f, 0.f, 0.f};
;         cur = nxt; cA = nA; cB = nB; ++ui;
;     }
;     PG8_WAIT_V(0);
;     if (wr == 0) PG8_BAR;
;     PG8_BAR;
;     DI void operator()(AccRef acc, const Unit& u, int wr, int wc, int fr, int fq) const {
;     ...
;         for (int ai = 0; ai < 2; ++ai)
; #pragma unroll
;             for (int m = 0; m < 4; ++m) {
;                 const int R = u.pm * 256 + ai * 128 + wr * 64 + m * 16 + fr, X = R >> 10, hv = R & 1023;
; #pragma unroll
;                 for (int bj = 0; bj < 2; ++bj) {
;                     const int tok = u.pn * 256 + bj * 128 + wc * 32 + 8 * fq, b = tok >> 13, s = tok & (SEQ - 1);
;                     bf16_t* dst = (X ? vtB : vtA) + ((size_t)(((b * 4 + (hv >> 8)) * 128 + (s >> 6)) * 256 + (hv & 255))) * 64 + (s & 63);
;                     const f32x4 v0 = acc[ai][bj][m][0] * ts[bj][0], v1 = acc[ai][bj][m][1] * ts[bj][1];
;                     u32x4 w; w.x = pk_bf16(v0[0], v0[1]); w.y = pk_bf16(v0[2], v0[3]); w.z = pk_bf16(v1[0], v1[1]); w.w = pk_bf16(v1[2], v1[3]);
;                     *(u32x4*)dst = w;
	v_cvt_pk_bf16_f32 v88, v96, v97
	v_cvt_pk_bf16_f32 v89, v94, v95
	v_cvt_pk_bf16_f32 v90, v90, v91
	v_cvt_pk_bf16_f32 v91, v98, v99
	global_store_dwordx4 v[92:93], v[88:91], off
	v_pk_mul_f32 v[20:21], v[20:21], v[132:133]
	v_pk_mul_f32 v[6:7], v[6:7], v[134:135]
	v_or_b32_e32 v88, s5, v100
	v_ashrrev_i32_e32 v89, 31, v88
	v_lshlrev_b64 v[88:89], 7, v[88:89]
	v_lshl_add_u64 v[88:89], s[8:9], 0, v[88:89]
	v_pk_mul_f32 v[90:91], v[78:79], v[130:131]
	v_pk_mul_f32 v[78:79], v[76:77], v[128:129]
	v_lshl_add_u64 v[88:89], v[88:89], 0, v[144:145]
	v_cvt_pk_bf16_f32 v76, v84, v85
	v_cvt_pk_bf16_f32 v77, v86, v87
	v_cvt_pk_bf16_f32 v78, v78, v79
	v_cvt_pk_bf16_f32 v79, v90, v91
	v_or_b32_e32 v84, 48, v171
	global_store_dwordx4 v[88:89], v[76:79], off
	v_pk_mul_f32 v[4:5], v[4:5], v[132:133]
	s_nop 0
	v_or_b32_e32 v76, s4, v84
	v_ashrrev_i32_e32 v77, 31, v76
	v_lshlrev_b64 v[76:77], 7, v[76:77]
	v_lshl_add_u64 v[76:77], s[8:9], 0, v[76:77]
	v_pk_mul_f32 v[78:79], v[82:83], v[156:157]
	v_pk_mul_f32 v[82:83], v[74:75], v[160:161]
	v_pk_mul_f32 v[74:75], v[72:73], v[158:159]
	v_lshl_add_u64 v[76:77], v[76:77], 0, v[144:145]
	v_cvt_pk_bf16_f32 v72, v80, v81
	v_cvt_pk_bf16_f32 v73, v78, v79
	v_cvt_pk_bf16_f32 v74, v74, v75
	v_cvt_pk_bf16_f32 v75, v82, v83
	global_store_dwordx4 v[76:77], v[72:75], off
	s_nop 1
	v_or_b32_e32 v72, s5, v84
	v_ashrrev_i32_e32 v73, 31, v72
	v_lshlrev_b64 v[72:73], 7, v[72:73]
	v_lshl_add_u64 v[72:73], s[8:9], 0, v[72:73]
	s_bfe_u32 s8, s6, 0x20008
	s_or_b32 s7, s8, s7
	s_lshl_b32 s7, s7, 15
	s_and_b32 s8, s6, 0xc0
	v_pk_mul_f32 v[74:75], v[66:67], v[130:131]
	v_pk_mul_f32 v[66:67], v[64:65], v[128:129]
	s_or_b32 s7, s7, s8
	v_lshl_add_u64 v[72:73], v[72:73], 0, v[144:145]
	v_cvt_pk_bf16_f32 v64, v68, v69
	v_cvt_pk_bf16_f32 v65, v70, v71
	v_cvt_pk_bf16_f32 v66, v66, v67
	v_cvt_pk_bf16_f32 v67, v74, v75
	v_or_b32_e32 v68, s7, v164
	global_store_dwordx4 v[72:73], v[64:67], off
	s_cmpk_lt_u32 s6, 0x400
	s_cselect_b32 s9, s53, s91
	v_or_b32_e32 v64, s4, v68
	v_ashrrev_i32_e32 v65, 31, v64
	s_cselect_b32 s8, s52, s90
	v_lshlrev_b64 v[64:65], 7, v[64:65]
	v_lshl_add_u64 v[64:65], s[8:9], 0, v[64:65]
	v_pk_mul_f32 v[66:67], v[58:59], v[160:161]
	v_pk_mul_f32 v[58:59], v[56:57], v[158:159]
	v_lshl_add_u64 v[64:65], v[64:65], 0, v[144:145]
	v_cvt_pk_bf16_f32 v56, v60, v61
	v_cvt_pk_bf16_f32 v57, v62, v63
	v_cvt_pk_bf16_f32 v58, v58, v59
	v_cvt_pk_bf16_f32 v59, v66, v67
	global_store_dwordx4 v[64:65], v[56:59], off
	s_and_b64 vcc, exec, s[0:1]
	s_nop 0
	v_or_b32_e32 v56, s5, v68
	v_ashrrev_i32_e32 v57, 31, v56
	v_lshlrev_b64 v[56:57], 7, v[56:57]
	v_lshl_add_u64 v[56:57], s[8:9], 0, v[56:57]
	v_pk_mul_f32 v[58:59], v[46:47], v[130:131]
	v_pk_mul_f32 v[46:47], v[44:45], v[128:129]
	v_lshl_add_u64 v[56:57], v[56:57], 0, v[144:145]
	v_cvt_pk_bf16_f32 v44, v52, v53
	v_cvt_pk_bf16_f32 v45, v54, v55
	v_cvt_pk_bf16_f32 v46, v46, v47
	v_cvt_pk_bf16_f32 v47, v58, v59
	v_or_b32_e32 v52, 16, v68
	global_store_dwordx4 v[56:57], v[44:47], off
	s_nop 1
	v_or_b32_e32 v44, s4, v52
	v_ashrrev_i32_e32 v45, 31, v44
	v_lshlrev_b64 v[44:45], 7, v[44:45]
	v_lshl_add_u64 v[44:45], s[8:9], 0, v[44:45]
	v_pk_mul_f32 v[46:47], v[50:51], v[156:157]
	v_pk_mul_f32 v[50:51], v[42:43], v[160:161]
	v_pk_mul_f32 v[42:43], v[40:41], v[158:159]
	v_lshl_add_u64 v[44:45], v[44:45], 0, v[144:145]
	v_cvt_pk_bf16_f32 v40, v48, v49
	v_cvt_pk_bf16_f32 v41, v46, v47
	v_cvt_pk_bf16_f32 v42, v42, v43
	v_cvt_pk_bf16_f32 v43, v50, v51
	global_store_dwordx4 v[44:45], v[40:43], off
	s_nop 1
	v_or_b32_e32 v40, s5, v52
	v_ashrrev_i32_e32 v41, 31, v40
	v_lshlrev_b64 v[40:41], 7, v[40:41]
	v_lshl_add_u64 v[40:41], s[8:9], 0, v[40:41]
	v_pk_mul_f32 v[42:43], v[30:31], v[130:131]
	v_pk_mul_f32 v[30:31], v[28:29], v[128:129]
	v_lshl_add_u64 v[40:41], v[40:41], 0, v[144:145]
	v_cvt_pk_bf16_f32 v28, v36, v37
	v_cvt_pk_bf16_f32 v29, v38, v39
	v_cvt_pk_bf16_f32 v30, v30, v31
	v_cvt_pk_bf16_f32 v31, v42, v43
	v_or_b32_e32 v36, 32, v68
	global_store_dwordx4 v[40:41], v[28:31], off
	s_nop 1
	v_or_b32_e32 v28, s4, v36
	v_ashrrev_i32_e32 v29, 31, v28
	v_lshlrev_b64 v[28:29], 7, v[28:29]
	v_lshl_add_u64 v[28:29], s[8:9], 0, v[28:29]
	v_pk_mul_f32 v[30:31], v[34:35], v[156:157]
	v_pk_mul_f32 v[34:35], v[26:27], v[160:161]
	v_pk_mul_f32 v[26:27], v[24:25], v[158:159]
	v_lshl_add_u64 v[28:29], v[28:29], 0, v[144:145]
	v_cvt_pk_bf16_f32 v24, v32, v33
	v_cvt_pk_bf16_f32 v25, v30, v31
	v_cvt_pk_bf16_f32 v26, v26, v27
	v_cvt_pk_bf16_f32 v27, v34, v35
	global_store_dwordx4 v[28:29], v[24:27], off
	s_nop 1
	v_or_b32_e32 v24, s5, v36
	v_ashrrev_i32_e32 v25, 31, v24
	v_lshlrev_b64 v[24:25], 7, v[24:25]
	v_lshl_add_u64 v[24:25], s[8:9], 0, v[24:25]
	v_pk_mul_f32 v[26:27], v[14:15], v[130:131]
	v_pk_mul_f32 v[14:15], v[12:13], v[128:129]
	v_lshl_add_u64 v[24:25], v[24:25], 0, v[144:145]
	v_cvt_pk_bf16_f32 v12, v20, v21
	v_cvt_pk_bf16_f32 v13, v22, v23
	v_cvt_pk_bf16_f32 v14, v14, v15
	v_cvt_pk_bf16_f32 v15, v26, v27
	v_or_b32_e32 v20, 48, v68
	global_store_dwordx4 v[24:25], v[12:15], off
	s_nop 1
	v_or_b32_e32 v12, s4, v20
	v_ashrrev_i32_e32 v13, 31, v12
	v_lshlrev_b64 v[12:13], 7, v[12:13]
	v_lshl_add_u64 v[12:13], s[8:9], 0, v[12:13]
	v_pk_mul_f32 v[14:15], v[18:19], v[156:157]
	v_pk_mul_f32 v[18:19], v[10:11], v[160:161]
	v_pk_mul_f32 v[10:11], v[8:9], v[158:159]
	v_lshl_add_u64 v[12:13], v[12:13], 0, v[144:145]
	v_cvt_pk_bf16_f32 v8, v16, v17
	v_cvt_pk_bf16_f32 v9, v14, v15
	v_cvt_pk_bf16_f32 v10, v10, v11
	v_cvt_pk_bf16_f32 v11, v18, v19
	global_store_dwordx4 v[12:13], v[8:11], off
	s_nop 1
	v_or_b32_e32 v8, s5, v20
	v_ashrrev_i32_e32 v9, 31, v8
	v_lshlrev_b64 v[8:9], 7, v[8:9]
	v_lshl_add_u64 v[8:9], s[8:9], 0, v[8:9]
	v_pk_mul_f32 v[10:11], v[2:3], v[130:131]
	v_pk_mul_f32 v[2:3], v[0:1], v[128:129]
	v_lshl_add_u64 v[8:9], v[8:9], 0, v[144:145]
	v_cvt_pk_bf16_f32 v0, v4, v5
	v_cvt_pk_bf16_f32 v1, v6, v7
	v_cvt_pk_bf16_f32 v2, v2, v3
	v_cvt_pk_bf16_f32 v3, v10, v11
	s_mov_b64 s[8:9], s[24:25]
	global_store_dwordx4 v[8:9], v[0:3], off
	s_cbranch_vccz .LBB0_291
	s_waitcnt vmcnt(0)
	s_cmpk_gt_u32 s17, 0xff
	s_cbranch_scc1 .LBB0_302
	s_barrier

; #define PG8_STAGE(bufoff, gbase, voff) do { _Pragma("unroll") for (int _i = 0; _i < 2; ++_i) \
;         __builtin_amdgcn_global_load_lds((const unsigned*)((const char*)(gbase) + (voff)[_i]), (LAS unsigned*)(lds + (bufoff) + ldsw + _i * 8192), 16, 0, 0); } while (0)
; #define PG8_LDA(dst, b, h) do { _Pragma("unroll") for (int m = 0; m < 4; ++m) _Pragma("unroll") for (int k = 0; k < 2; ++k) dst[m][k] = *(const LAS bf16x8*)(lds + PG8_SA(b, h) + aoff + m * 2048 + k * 1024); } while (0)
; #define PG8_LDB(dst, b, h) do { _Pragma("unroll") for (int n = 0; n < 2; ++n) _Pragma("unroll") for (int k = 0; k < 2; ++k) dst[n][k] = *(const LAS bf16x8*)(lds + PG8_SB(b, h) + boff + n * 2048 + k * 1024); } while (0)
; #define PG8_MMA(ai, bj, At, Bt) do { __builtin_amdgcn_s_setprio(1); _Pragma("unroll") for (int m = 0; m < 4; ++m) _Pragma("unroll") for (int n = 0; n < 2; ++n) _Pragma("unroll") for (int k = 0; k < 2; ++k) \
;         acc[ai][bj][m][n] = __builtin_amdgcn_mfma_f32_16x16x32_bf16(Bt[n][k], At[m][k], acc[ai][bj][m][n], 0, 0, 0); __builtin_amdgcn_s_setprio(0); } while (0)
; #define PG8_WAIT_V(n) asm volatile("s_waitcnt vmcnt(" #n ")" ::: "memory")
; #define PG8_WAIT_L(n) asm volatile("s_waitcnt lgkmcnt(" #n ")" ::: "memory")
; #define PG8_BAR __builtin_amdgcn_s_barrier()
; #define PG8_SCHED __builtin_amdgcn_sched_barrier(0)
; #define PG8_STAGE(bufoff, gbase, voff) do { _Pragma("unroll") for (int _i = 0; _i < 2; ++_i) \
;         __builtin_amdgcn_global_load_lds((const unsigned*)((const char*)(gbase) + (voff)[_i]), (LAS unsigned*)(lds + (bufoff) + ldsw + _i * 8192), 16, 0, 0); } while (0)
; template <class Epi0, class Epi1>
; DI void gemm_phase_dual(LAS unsigned char* lds, const Gemm g, const Gemm g1, const StaticOrder S, const Epi0 E0, const Epi1 E1) {
;     ...
;             PG8_LDB(B0, 0, 0); PG8_SCHED; PG8_LDA(At, 0, 0); PG8_STAGE(PG8_SA(1, 1), a1 + hstep, voffA);
;             PG8_WAIT_L(8); PG8_BAR; PG8_WAIT_L(0); PG8_MMA(0, 0, At, B0); PG8_BAR; PG8_SCHED;
;             PG8_LDB(B1, 0, 1); PG8_STAGE(PG8_SB(0, 0), b2, voffB);
;             PG8_BAR; PG8_WAIT_L(0); PG8_MMA(0, 1, At, B1); PG8_BAR;
;             PG8_LDA(At, 0, 1); PG8_STAGE(PG8_SA(0, 0), a2, voffA);
;             PG8_BAR; PG8_WAIT_L(0); PG8_MMA(1, 0, At, B0); PG8_BAR; PG8_SCHED;
;             PG8_STAGE(PG8_SB(0, 1), b2 + hstep, voffB);
;             PG8_WAIT_V(6); PG8_BAR; PG8_MMA(1, 1, At, B1); PG8_BAR;
.LBB0_632:
	ds_read_b128 v[128:131], v181
	ds_read_b128 v[132:135], v181 offset:1024
	ds_read_b128 v[136:139], v181 offset:2048
	ds_read_b128 v[140:143], v181 offset:3072
	s_add_u32 s12, s10, 0xfffc0080
	s_addc_u32 s13, s11, -1
	s_cmp_eq_u32 s19, 12
	s_cselect_b32 s15, s1, s13
	s_cselect_b32 s14, s6, s12
	s_cselect_b32 s13, s7, s18
	s_cselect_b32 s12, s16, s17
	v_lshl_add_u64 v[190:191], s[10:11], 0, v[168:169]
	s_add_i32 m0, s49, 0xc000
	ds_read_b128 v[144:147], v183
	ds_read_b128 v[148:151], v183 offset:1024
	ds_read_b128 v[152:155], v183 offset:2048
	ds_read_b128 v[184:187], v183 offset:3072
	ds_read_b128 v[194:197], v183 offset:4096
	ds_read_b128 v[198:201], v183 offset:5120
	ds_read_b128 v[202:205], v183 offset:6144
	ds_read_b128 v[206:209], v183 offset:7168
	global_load_lds_dwordx4 v[190:191], off
	v_lshl_add_u64 v[190:191], s[10:11], 0, v[170:171]
	s_add_i32 m0, s49, 0xe000
	s_nop 0
	global_load_lds_dwordx4 v[190:191], off
	s_waitcnt lgkmcnt(8)
	s_barrier
	s_waitcnt lgkmcnt(0)
	s_setprio 1
	s_waitcnt lgkmcnt(0)
	v_mfma_f32_16x16x32_bf16 v[124:127], v[128:131], v[144:147], v[124:127]
	v_mfma_f32_16x16x32_bf16 v[120:123], v[136:139], v[144:147], v[120:123]
	v_mfma_f32_16x16x32_bf16 v[108:111], v[128:131], v[152:155], v[108:111]
	v_mfma_f32_16x16x32_bf16 v[104:107], v[136:139], v[152:155], v[104:107]
	v_mfma_f32_16x16x32_bf16 v[92:95], v[128:131], v[194:197], v[92:95]
	v_mfma_f32_16x16x32_bf16 v[88:91], v[136:139], v[194:197], v[88:91]
	v_mfma_f32_16x16x32_bf16 v[76:79], v[128:131], v[202:205], v[76:79]
	v_mfma_f32_16x16x32_bf16 v[72:75], v[136:139], v[202:205], v[72:75]
	v_mfma_f32_16x16x32_bf16 v[124:127], v[132:135], v[148:151], v[124:127]
	v_mfma_f32_16x16x32_bf16 v[120:123], v[140:143], v[148:151], v[120:123]
	v_mfma_f32_16x16x32_bf16 v[108:111], v[132:135], v[184:187], v[108:111]
	v_mfma_f32_16x16x32_bf16 v[104:107], v[140:143], v[184:187], v[104:107]
	v_mfma_f32_16x16x32_bf16 v[92:95], v[132:135], v[198:201], v[92:95]
	v_mfma_f32_16x16x32_bf16 v[88:91], v[140:143], v[198:201], v[88:91]
	v_mfma_f32_16x16x32_bf16 v[76:79], v[132:135], v[206:209], v[76:79]
	v_mfma_f32_16x16x32_bf16 v[72:75], v[140:143], v[206:209], v[72:75]
	s_setprio 0
	s_barrier
	s_add_i32 s41, s78, s48
	v_lshl_add_u64 v[190:191], s[12:13], 0, v[158:159]
	s_mov_b32 m0, s41
	ds_read_b128 v[210:213], v189
	ds_read_b128 v[214:217], v189 offset:1024
	ds_read_b128 v[218:221], v189 offset:2048
	ds_read_b128 v[224:227], v189 offset:3072
	global_load_lds_dwordx4 v[190:191], off
	v_lshl_add_u64 v[228:229], s[12:13], 0, v[162:163]
	s_add_i32 m0, s41, 0x2000
	s_nop 0
	global_load_lds_dwordx4 v[228:229], off
	s_barrier
	s_waitcnt lgkmcnt(0)
	s_setprio 1
	s_waitcnt lgkmcnt(0)
	v_mfma_f32_16x16x32_bf16 v[116:119], v[210:213], v[144:147], v[116:119]
	v_mfma_f32_16x16x32_bf16 v[112:115], v[218:221], v[144:147], v[112:115]
	v_mfma_f32_16x16x32_bf16 v[100:103], v[210:213], v[152:155], v[100:103]
	v_mfma_f32_16x16x32_bf16 v[96:99], v[218:221], v[152:155], v[96:99]
	v_mfma_f32_16x16x32_bf16 v[84:87], v[210:213], v[194:197], v[84:87]
	v_mfma_f32_16x16x32_bf16 v[80:83], v[218:221], v[194:197], v[80:83]
	v_mfma_f32_16x16x32_bf16 v[68:71], v[210:213], v[202:205], v[68:71]
	v_mfma_f32_16x16x32_bf16 v[64:67], v[218:221], v[202:205], v[64:67]
	v_mfma_f32_16x16x32_bf16 v[116:119], v[214:217], v[148:151], v[116:119]
	v_mfma_f32_16x16x32_bf16 v[112:115], v[224:227], v[148:151], v[112:115]
	v_mfma_f32_16x16x32_bf16 v[100:103], v[214:217], v[184:187], v[100:103]
	v_mfma_f32_16x16x32_bf16 v[96:99], v[224:227], v[184:187], v[96:99]
	v_mfma_f32_16x16x32_bf16 v[84:87], v[214:217], v[198:201], v[84:87]
	v_mfma_f32_16x16x32_bf16 v[80:83], v[224:227], v[198:201], v[80:83]
	v_mfma_f32_16x16x32_bf16 v[68:71], v[214:217], v[206:209], v[68:71]
	v_mfma_f32_16x16x32_bf16 v[64:67], v[224:227], v[206:209], v[64:67]
	s_setprio 0
	s_mov_b32 m0, s49
	v_lshl_add_u64 v[230:231], s[14:15], 0, v[156:157]
	s_barrier
	ds_read_b128 v[144:147], v183 offset:16384
	ds_read_b128 v[148:151], v183 offset:17408
	ds_read_b128 v[152:155], v183 offset:18432
	ds_read_b128 v[184:187], v183 offset:19456
	ds_read_b128 v[194:197], v183 offset:20480
	ds_read_b128 v[198:201], v183 offset:21504
	ds_read_b128 v[202:205], v183 offset:22528
	ds_read_b128 v[206:209], v183 offset:23552
	global_load_lds_dwordx4 v[230:231], off
	v_lshl_add_u64 v[232:233], s[14:15], 0, v[160:161]
	s_mov_b32 m0, s50
	s_nop 0
	global_load_lds_dwordx4 v[232:233], off
	s_barrier
	s_waitcnt lgkmcnt(0)
	s_setprio 1
	s_waitcnt lgkmcnt(0)
	v_mfma_f32_16x16x32_bf16 v[60:63], v[128:131], v[144:147], v[60:63]
	v_mfma_f32_16x16x32_bf16 v[56:59], v[136:139], v[144:147], v[56:59]
	v_mfma_f32_16x16x32_bf16 v[44:47], v[128:131], v[152:155], v[44:47]
	v_mfma_f32_16x16x32_bf16 v[40:43], v[136:139], v[152:155], v[40:43]
	v_mfma_f32_16x16x32_bf16 v[28:31], v[128:131], v[194:197], v[28:31]
	v_mfma_f32_16x16x32_bf16 v[24:27], v[136:139], v[194:197], v[24:27]
	v_mfma_f32_16x16x32_bf16 v[12:15], v[128:131], v[202:205], v[12:15]
	v_mfma_f32_16x16x32_bf16 v[8:11], v[136:139], v[202:205], v[8:11]
	v_mfma_f32_16x16x32_bf16 v[60:63], v[132:135], v[148:151], v[60:63]
	v_mfma_f32_16x16x32_bf16 v[56:59], v[140:143], v[148:151], v[56:59]
	v_mfma_f32_16x16x32_bf16 v[44:47], v[132:135], v[184:187], v[44:47]
	v_mfma_f32_16x16x32_bf16 v[40:43], v[140:143], v[184:187], v[40:43]
	v_mfma_f32_16x16x32_bf16 v[28:31], v[132:135], v[198:201], v[28:31]
	v_mfma_f32_16x16x32_bf16 v[24:27], v[140:143], v[198:201], v[24:27]
	v_mfma_f32_16x16x32_bf16 v[12:15], v[132:135], v[206:209], v[12:15]
	v_mfma_f32_16x16x32_bf16 v[8:11], v[140:143], v[206:209], v[8:11]
	s_setprio 0
	s_barrier
; #define PG8_STAGE(bufoff, gbase, voff) do { _Pragma("unroll") for (int _i = 0; _i < 2; ++_i) \
;         __builtin_amdgcn_global_load_lds((const unsigned*)((const char*)(gbase) + (voff)[_i]), (LAS unsigned*)(lds + (bufoff) + ldsw + _i * 8192), 16, 0, 0); } while (0)
; #define PG8_LDA(dst, b, h) do { _Pragma("unroll") for (int m = 0; m < 4; ++m) _Pragma("unroll") for (int k = 0; k < 2; ++k) dst[m][k] = *(const LAS bf16x8*)(lds + PG8_SA(b, h) + aoff + m * 2048 + k * 1024); } while (0)
; #define PG8_LDB(dst, b, h) do { _Pragma("unroll") for (int n = 0; n < 2; ++n) _Pragma("unroll") for (int k = 0; k < 2; ++k) dst[n][k] = *(const LAS bf16x8*)(lds + PG8_SB(b, h) + boff + n * 2048 + k * 1024); } while (0)
; #define PG8_MMA(ai, bj, At, Bt) do { __builtin_amdgcn_s_setprio(1); _Pragma("unroll") for (int m = 0; m < 4; ++m) _Pragma("unroll") for (int n = 0; n < 2; ++n) _Pragma("unroll") for (int k = 0; k < 2; ++k) \
;         acc[ai][bj][m][n] = __builtin_amdgcn_mfma_f32_16x16x32_bf16(Bt[n][k], At[m][k], acc[ai][bj][m][n], 0, 0, 0); __builtin_amdgcn_s_setprio(0); } while (0)
; #define PG8_WAIT_V(n) asm volatile("s_waitcnt vmcnt(" #n ")" ::: "memory")
; #define PG8_WAIT_L(n) asm volatile("s_waitcnt lgkmcnt(" #n ")" ::: "memory")
; #define PG8_BAR __builtin_amdgcn_s_barrier()
; #define PG8_SCHED __builtin_amdgcn_sched_barrier(0)
; #define PG8_STAGE(bufoff, gbase, voff) do { _Pragma("unroll") for (int _i = 0; _i < 2; ++_i) \
;         __builtin_amdgcn_global_load_lds((const unsigned*)((const char*)(gbase) + (voff)[_i]), (LAS unsigned*)(lds + (bufoff) + ldsw + _i * 8192), 16, 0, 0); } while (0)
; template <class Epi0, class Epi1>
; DI void gemm_phase_dual(LAS unsigned char* lds, const Gemm g, const Gemm g1, const StaticOrder S, const Epi0 E0, const Epi1 E1) {
;     ...
;             PG8_STAGE(PG8_SB(0, 1), b2 + hstep, voffB);
;             PG8_WAIT_V(6); PG8_BAR; PG8_MMA(1, 1, At, B1); PG8_BAR;
;             PG8_LDB(B0, 1, 0); PG8_SCHED; PG8_LDA(At, 1, 0); PG8_STAGE(PG8_SA(0, 1), a2 + hstep, voffA);
;             PG8_WAIT_L(8); PG8_BAR; PG8_WAIT_L(0); PG8_MMA(0, 0, At, B0); PG8_BAR; PG8_SCHED;
;             PG8_LDB(B1, 1, 1); PG8_STAGE(PG8_SB(1, 0), b3, voffB);
;             PG8_BAR; PG8_WAIT_L(0); PG8_MMA(0, 1, At, B1); PG8_BAR;
;             PG8_LDA(At, 1, 1); PG8_STAGE(PG8_SA(1, 0), a3, voffA);
;             PG8_BAR; PG8_WAIT_L(0); PG8_MMA(1, 0, At, B0); PG8_BAR; PG8_SCHED;
	s_add_u32 s90, s12, 0x40000
	s_addc_u32 s91, s13, 0
	s_add_i32 s41, s79, s48
	v_lshl_add_u64 v[128:129], s[90:91], 0, v[158:159]
	s_mov_b32 m0, s41
	s_nop 0
	global_load_lds_dwordx4 v[128:129], off
	v_lshl_add_u64 v[128:129], s[90:91], 0, v[162:163]
	s_add_i32 m0, s41, 0x2000
	s_nop 0
	global_load_lds_dwordx4 v[128:129], off
	s_waitcnt vmcnt(6)
	s_barrier
	s_setprio 1
	v_mfma_f32_16x16x32_bf16 v[52:55], v[210:213], v[144:147], v[52:55]
	v_mfma_f32_16x16x32_bf16 v[48:51], v[218:221], v[144:147], v[48:51]
	v_mfma_f32_16x16x32_bf16 v[36:39], v[210:213], v[152:155], v[36:39]
	v_mfma_f32_16x16x32_bf16 v[32:35], v[218:221], v[152:155], v[32:35]
	v_mfma_f32_16x16x32_bf16 v[20:23], v[210:213], v[194:197], v[20:23]
	v_mfma_f32_16x16x32_bf16 v[16:19], v[218:221], v[194:197], v[16:19]
	v_mfma_f32_16x16x32_bf16 v[4:7], v[210:213], v[202:205], v[4:7]
	v_mfma_f32_16x16x32_bf16 v[0:3], v[218:221], v[202:205], v[0:3]
	v_mfma_f32_16x16x32_bf16 v[52:55], v[214:217], v[148:151], v[52:55]
	v_mfma_f32_16x16x32_bf16 v[48:51], v[224:227], v[148:151], v[48:51]
	v_mfma_f32_16x16x32_bf16 v[36:39], v[214:217], v[184:187], v[36:39]
	v_mfma_f32_16x16x32_bf16 v[32:35], v[224:227], v[184:187], v[32:35]
	v_mfma_f32_16x16x32_bf16 v[20:23], v[214:217], v[198:201], v[20:23]
	v_mfma_f32_16x16x32_bf16 v[16:19], v[224:227], v[198:201], v[16:19]
	v_mfma_f32_16x16x32_bf16 v[4:7], v[214:217], v[206:209], v[4:7]
	v_mfma_f32_16x16x32_bf16 v[0:3], v[224:227], v[206:209], v[0:3]
	s_setprio 0
	s_add_i32 s41, 0, 0x18000
	v_add_u32_e32 v140, s41, v179
	s_barrier
	ds_read_b128 v[128:131], v140
	ds_read_b128 v[132:135], v140 offset:1024
	ds_read_b128 v[136:139], v140 offset:2048
	ds_read_b128 v[140:143], v140 offset:3072
	s_add_u32 s14, s14, 0x40000
	s_addc_u32 s15, s15, 0
	s_mov_b32 m0, s51
	v_lshl_add_u64 v[210:211], s[14:15], 0, v[156:157]
	ds_read_b128 v[144:147], v183 offset:32768
	ds_read_b128 v[148:151], v183 offset:33792
	ds_read_b128 v[152:155], v183 offset:34816
	ds_read_b128 v[184:187], v183 offset:35840
	ds_read_b128 v[194:197], v183 offset:36864
	ds_read_b128 v[198:201], v183 offset:37888
	ds_read_b128 v[202:205], v183 offset:38912
	ds_read_b128 v[206:209], v183 offset:39936
	global_load_lds_dwordx4 v[210:211], off
	v_lshl_add_u64 v[210:211], s[14:15], 0, v[160:161]
	s_mov_b32 m0, s58
	s_nop 0
	global_load_lds_dwordx4 v[210:211], off
	s_waitcnt lgkmcnt(8)
	s_barrier
	s_waitcnt lgkmcnt(0)
	s_setprio 1
	s_waitcnt lgkmcnt(0)
	v_mfma_f32_16x16x32_bf16 v[124:127], v[128:131], v[144:147], v[124:127]
	v_mfma_f32_16x16x32_bf16 v[120:123], v[136:139], v[144:147], v[120:123]
	v_mfma_f32_16x16x32_bf16 v[108:111], v[128:131], v[152:155], v[108:111]
	v_mfma_f32_16x16x32_bf16 v[104:107], v[136:139], v[152:155], v[104:107]
	v_mfma_f32_16x16x32_bf16 v[92:95], v[128:131], v[194:197], v[92:95]
	v_mfma_f32_16x16x32_bf16 v[88:91], v[136:139], v[194:197], v[88:91]
	v_mfma_f32_16x16x32_bf16 v[76:79], v[128:131], v[202:205], v[76:79]
	v_mfma_f32_16x16x32_bf16 v[72:75], v[136:139], v[202:205], v[72:75]
	v_mfma_f32_16x16x32_bf16 v[124:127], v[132:135], v[148:151], v[124:127]
	v_mfma_f32_16x16x32_bf16 v[120:123], v[140:143], v[148:151], v[120:123]
	v_mfma_f32_16x16x32_bf16 v[108:111], v[132:135], v[184:187], v[108:111]
	v_mfma_f32_16x16x32_bf16 v[104:107], v[140:143], v[184:187], v[104:107]
	v_mfma_f32_16x16x32_bf16 v[92:95], v[132:135], v[198:201], v[92:95]
	v_mfma_f32_16x16x32_bf16 v[88:91], v[140:143], v[198:201], v[88:91]
	v_mfma_f32_16x16x32_bf16 v[76:79], v[132:135], v[206:209], v[76:79]
	v_mfma_f32_16x16x32_bf16 v[72:75], v[140:143], v[206:209], v[72:75]
	s_setprio 0
	s_barrier
	s_add_i32 s14, 0, 0x1c000
	s_add_i32 s15, s41, s48
	v_add_u32_e32 v176, s14, v179
	v_lshl_add_u64 v[190:191], v[190:191], 0, s[22:23]
	s_mov_b32 m0, s15
	ds_read_b128 v[210:213], v176
	ds_read_b128 v[214:217], v176 offset:1024
	ds_read_b128 v[218:221], v176 offset:2048
	ds_read_b128 v[224:227], v176 offset:3072
	global_load_lds_dwordx4 v[190:191], off
	v_lshl_add_u64 v[190:191], v[228:229], 0, s[22:23]
	s_add_i32 m0, s15, 0x2000
	s_nop 0
	global_load_lds_dwordx4 v[190:191], off
	s_barrier
	s_waitcnt lgkmcnt(0)
	s_setprio 1
	s_waitcnt lgkmcnt(0)
	v_mfma_f32_16x16x32_bf16 v[116:119], v[210:213], v[144:147], v[116:119]
	v_mfma_f32_16x16x32_bf16 v[112:115], v[218:221], v[144:147], v[112:115]
	v_mfma_f32_16x16x32_bf16 v[100:103], v[210:213], v[152:155], v[100:103]
	v_mfma_f32_16x16x32_bf16 v[96:99], v[218:221], v[152:155], v[96:99]
	v_mfma_f32_16x16x32_bf16 v[84:87], v[210:213], v[194:197], v[84:87]
	v_mfma_f32_16x16x32_bf16 v[80:83], v[218:221], v[194:197], v[80:83]
	v_mfma_f32_16x16x32_bf16 v[68:71], v[210:213], v[202:205], v[68:71]
	v_mfma_f32_16x16x32_bf16 v[64:67], v[218:221], v[202:205], v[64:67]
	v_mfma_f32_16x16x32_bf16 v[116:119], v[214:217], v[148:151], v[116:119]
	v_mfma_f32_16x16x32_bf16 v[112:115], v[224:227], v[148:151], v[112:115]
	v_mfma_f32_16x16x32_bf16 v[100:103], v[214:217], v[184:187], v[100:103]
	v_mfma_f32_16x16x32_bf16 v[96:99], v[224:227], v[184:187], v[96:99]
	v_mfma_f32_16x16x32_bf16 v[84:87], v[214:217], v[198:201], v[84:87]
	v_mfma_f32_16x16x32_bf16 v[80:83], v[224:227], v[198:201], v[80:83]
	v_mfma_f32_16x16x32_bf16 v[68:71], v[214:217], v[206:209], v[68:71]
	v_mfma_f32_16x16x32_bf16 v[64:67], v[224:227], v[206:209], v[64:67]
	s_setprio 0
	s_mov_b32 m0, s76
	v_lshl_add_u64 v[190:191], v[230:231], 0, s[22:23]
	s_barrier
	ds_read_b128 v[144:147], v183 offset:49152
	ds_read_b128 v[148:151], v183 offset:50176
	ds_read_b128 v[152:155], v183 offset:51200
	ds_read_b128 v[184:187], v183 offset:52224
	ds_read_b128 v[194:197], v183 offset:53248
	ds_read_b128 v[198:201], v183 offset:54272
	ds_read_b128 v[202:205], v183 offset:55296
	ds_read_b128 v[206:209], v183 offset:56320
	global_load_lds_dwordx4 v[190:191], off
	v_lshl_add_u64 v[190:191], v[232:233], 0, s[22:23]
	s_mov_b32 m0, s77
	s_nop 0
	global_load_lds_dwordx4 v[190:191], off
	s_barrier
; DI unsigned pk_bf16(float lo, float hi) { f32x2 v = {lo, hi}; return __builtin_bit_cast(unsigned, __builtin_convertvector(v, bf16v2)); }
; DI float fast_sigmoid(float x) { return __builtin_amdgcn_rcpf(1.0f + __expf(-x)); }
; #define PG8_STAGE(bufoff, gbase, voff) do { _Pragma("unroll") for (int _i = 0; _i < 2; ++_i) \
;         __builtin_amdgcn_global_load_lds((const unsigned*)((const char*)(gbase) + (voff)[_i]), (LAS unsigned*)(lds + (bufoff) + ldsw + _i * 8192), 16, 0, 0); } while (0)
; #define PG8_MMA(ai, bj, At, Bt) do { __builtin_amdgcn_s_setprio(1); _Pragma("unroll") for (int m = 0; m < 4; ++m) _Pragma("unroll") for (int n = 0; n < 2; ++n) _Pragma("unroll") for (int k = 0; k < 2; ++k) \
;         acc[ai][bj][m][n] = __builtin_amdgcn_mfma_f32_16x16x32_bf16(Bt[n][k], At[m][k], acc[ai][bj][m][n], 0, 0, 0); __builtin_amdgcn_s_setprio(0); } while (0)
; template <class Epi0, class Epi1>
; DI void gemm_phase_dual(LAS unsigned char* lds, const Gemm g, const Gemm g1, const StaticOrder S, const Epi0 E0, const Epi1 E1) {
;     ...
;             PG8_BAR; PG8_WAIT_L(0); PG8_MMA(1, 0, At, B0); PG8_BAR; PG8_SCHED;
;             PG8_STAGE(PG8_SB(1, 1), b3 + hstep, voffB);
;             PG8_WAIT_V(6); PG8_BAR; PG8_MMA(1, 1, At, B1); PG8_BAR;
;         }
;         if (ui & 1) E1(acc, cur, wr, wc, fr, fq); else E0(acc, cur, wr, wc, fr, fq);
;     DI void operator()(AccRef acc, const Unit& u, int wr, int wc, int fr, int fq) const {
;         const int row0 = u.pm * 256 + wr * 64 + fr;
;         bf16_t* Gp = gab + (size_t)(u.pm * 8 + u.pn) * 65536 + (wr * 64 + fr) * 256 + wc * 32 + 8 * fq;
;         const RowScales rsc = load_rowscales(ss, row0);
; #pragma unroll
;         for (int ai = 0; ai < 2; ++ai)
; #pragma unroll
;             for (int m = 0; m < 4; ++m)
; #pragma unroll
;                 for (int bj = 0; bj < 2; ++bj) {
;                     const float rs = rsc.r[ai][m];
;                     const f32x4 r0 = acc[ai][bj][m][0] * rs, r1 = acc[ai][bj][m][1] * rs;
;                     u32x4 w;
;                     w.x = pk_bf16(fast_sigmoid(r0[0]), fast_sigmoid(r0[1])); w.y = pk_bf16(fast_sigmoid(r0[2]), fast_sigmoid(r0[3]));
;                     w.z = pk_bf16(fast_sigmoid(r1[0]), fast_sigmoid(r1[1])); w.w = pk_bf16(fast_sigmoid(r1[2]), fast_sigmoid(r1[3]));
;                     *(u32x4*)(Gp + (ai * 128 + m * 16) * 256 + bj * 128) = w;
	s_waitcnt lgkmcnt(0)
	s_setprio 1
	s_waitcnt lgkmcnt(0)
	v_mfma_f32_16x16x32_bf16 v[60:63], v[128:131], v[144:147], v[60:63]
	v_mfma_f32_16x16x32_bf16 v[56:59], v[136:139], v[144:147], v[56:59]
	v_mfma_f32_16x16x32_bf16 v[44:47], v[128:131], v[152:155], v[44:47]
	v_mfma_f32_16x16x32_bf16 v[40:43], v[136:139], v[152:155], v[40:43]
	v_mfma_f32_16x16x32_bf16 v[28:31], v[128:131], v[194:197], v[28:31]
	v_mfma_f32_16x16x32_bf16 v[24:27], v[136:139], v[194:197], v[24:27]
	v_mfma_f32_16x16x32_bf16 v[12:15], v[128:131], v[202:205], v[12:15]
	v_mfma_f32_16x16x32_bf16 v[8:11], v[136:139], v[202:205], v[8:11]
	v_mfma_f32_16x16x32_bf16 v[60:63], v[132:135], v[148:151], v[60:63]
	v_mfma_f32_16x16x32_bf16 v[56:59], v[140:143], v[148:151], v[56:59]
	v_mfma_f32_16x16x32_bf16 v[44:47], v[132:135], v[184:187], v[44:47]
	v_mfma_f32_16x16x32_bf16 v[40:43], v[140:143], v[184:187], v[40:43]
	v_mfma_f32_16x16x32_bf16 v[28:31], v[132:135], v[198:201], v[28:31]
	v_mfma_f32_16x16x32_bf16 v[24:27], v[140:143], v[198:201], v[24:27]
	v_mfma_f32_16x16x32_bf16 v[12:15], v[132:135], v[206:209], v[12:15]
	v_mfma_f32_16x16x32_bf16 v[8:11], v[140:143], v[206:209], v[8:11]
	s_setprio 0
	s_barrier
	s_add_u32 s12, s12, 0x40080
	s_addc_u32 s13, s13, 0
	s_add_i32 s14, s14, s48
	v_lshl_add_u64 v[128:129], s[12:13], 0, v[158:159]
	s_mov_b32 m0, s14
	s_nop 0
	global_load_lds_dwordx4 v[128:129], off
	v_lshl_add_u64 v[128:129], s[12:13], 0, v[162:163]
	s_add_i32 m0, s14, 0x2000
	s_nop 0
	global_load_lds_dwordx4 v[128:129], off
	s_waitcnt vmcnt(6)
	s_barrier
	s_setprio 1
	v_mfma_f32_16x16x32_bf16 v[52:55], v[210:213], v[144:147], v[52:55]
	v_mfma_f32_16x16x32_bf16 v[48:51], v[218:221], v[144:147], v[48:51]
	v_mfma_f32_16x16x32_bf16 v[36:39], v[210:213], v[152:155], v[36:39]
	v_mfma_f32_16x16x32_bf16 v[32:35], v[218:221], v[152:155], v[32:35]
	v_mfma_f32_16x16x32_bf16 v[20:23], v[210:213], v[194:197], v[20:23]
	v_mfma_f32_16x16x32_bf16 v[16:19], v[218:221], v[194:197], v[16:19]
	v_mfma_f32_16x16x32_bf16 v[4:7], v[210:213], v[202:205], v[4:7]
	v_mfma_f32_16x16x32_bf16 v[0:3], v[218:221], v[202:205], v[0:3]
	v_mfma_f32_16x16x32_bf16 v[52:55], v[214:217], v[148:151], v[52:55]
	v_mfma_f32_16x16x32_bf16 v[48:51], v[224:227], v[148:151], v[48:51]
	v_mfma_f32_16x16x32_bf16 v[36:39], v[214:217], v[184:187], v[36:39]
	v_mfma_f32_16x16x32_bf16 v[32:35], v[224:227], v[184:187], v[32:35]
	v_mfma_f32_16x16x32_bf16 v[20:23], v[214:217], v[198:201], v[20:23]
	v_mfma_f32_16x16x32_bf16 v[16:19], v[224:227], v[198:201], v[16:19]
	v_mfma_f32_16x16x32_bf16 v[4:7], v[214:217], v[206:209], v[4:7]
	v_mfma_f32_16x16x32_bf16 v[0:3], v[224:227], v[206:209], v[0:3]
	s_setprio 0
	s_add_i32 s19, s19, 2
	s_add_u32 s10, s10, 0x100
	s_addc_u32 s11, s11, 0
	s_add_u32 s17, s17, 0x100
	s_addc_u32 s18, s18, 0
	s_cmp_gt_u32 s19, 13
	s_barrier
	s_cbranch_scc0 .LBB0_632
	v_lshl_add_u32 v128, s0, 8, v177
	s_mov_b64 s[6:7], -1
	s_and_b64 vcc, exec, s[8:9]
	v_ashrrev_i32_e32 v129, 31, v128
	s_cbranch_vccz .LBB0_635
	v_lshl_add_u64 v[130:131], v[128:129], 2, s[60:61]
	global_load_dword v132, v[130:131], off
	global_load_dword v133, v[130:131], off offset:64
	global_load_dword v134, v[130:131], off offset:128
	global_load_dword v135, v[130:131], off offset:192
	global_load_dword v136, v[130:131], off offset:512
	global_load_dword v137, v[130:131], off offset:576
	global_load_dword v138, v[130:131], off offset:640
	global_load_dword v139, v[130:131], off offset:704
	s_lshl_b32 s0, s0, 3
	s_add_i32 s0, s0, s87
	s_ashr_i32 s1, s0, 31
	s_lshl_b64 s[0:1], s[0:1], 17
	v_lshl_add_u64 v[130:131], v[166:167], 0, s[0:1]
	s_mov_b64 s[6:7], 0
	s_waitcnt vmcnt(0)
	v_fmamk_f32 v132, v132, 0x3a800000, v193
	v_mul_f32_e32 v140, 0x4b800000, v132
	v_cmp_gt_f32_e32 vcc, s80, v132
	v_fmamk_f32 v134, v134, 0x3a800000, v193
	v_fmamk_f32 v136, v136, 0x3a800000, v193
	v_fmamk_f32 v137, v137, 0x3a800000, v193
	v_fmamk_f32 v138, v138, 0x3a800000, v193
	v_fmamk_f32 v139, v139, 0x3a800000, v193
	v_mul_f32_e32 v144, 0x4b800000, v136
	v_mul_f32_e32 v145, 0x4b800000, v137
	v_cndmask_b32_e32 v132, v132, v140, vcc
	v_cmp_gt_f32_e64 s[12:13], s80, v136
	v_cmp_gt_f32_e64 s[14:15], s80, v137
	v_fmamk_f32 v133, v133, 0x3a800000, v193
	v_fmamk_f32 v135, v135, 0x3a800000, v193
	v_mul_f32_e32 v142, 0x4b800000, v134
	v_mul_f32_e32 v146, 0x4b800000, v138
	v_mul_f32_e32 v147, 0x4b800000, v139
	v_cmp_gt_f32_e64 s[8:9], s80, v134
	v_cndmask_b32_e64 v136, v136, v144, s[12:13]
	v_cndmask_b32_e64 v137, v137, v145, s[14:15]
	v_cmp_gt_f32_e64 s[16:17], s80, v138
	v_cmp_gt_f32_e64 s[18:19], s80, v139
	v_rsq_f32_e32 v132, v132
	v_mul_f32_e32 v141, 0x4b800000, v133
	v_mul_f32_e32 v143, 0x4b800000, v135
	v_cmp_gt_f32_e64 s[0:1], s80, v133
	v_cndmask_b32_e64 v134, v134, v142, s[8:9]
	v_cmp_gt_f32_e64 s[10:11], s80, v135
	v_cndmask_b32_e64 v138, v138, v146, s[16:17]
	v_cndmask_b32_e64 v139, v139, v147, s[18:19]
	v_rsq_f32_e32 v136, v136
	v_rsq_f32_e32 v137, v137
	v_cndmask_b32_e64 v133, v133, v141, s[0:1]
	v_cndmask_b32_e64 v135, v135, v143, s[10:11]
	v_rsq_f32_e32 v134, v134
	v_rsq_f32_e32 v141, v138
	v_rsq_f32_e32 v139, v139
	v_rsq_f32_e32 v133, v133
	v_rsq_f32_e32 v135, v135
	v_mul_f32_e32 v138, 0x45800000, v132
	v_mul_f32_e32 v144, 0x45800000, v136
	v_mul_f32_e32 v145, 0x45800000, v137
	v_cndmask_b32_e32 v148, v132, v138, vcc
	v_mul_f32_e32 v142, 0x45800000, v134
	v_mul_f32_e32 v146, 0x45800000, v141
	v_mul_f32_e32 v147, 0x45800000, v139
	v_cndmask_b32_e64 v138, v136, v144, s[12:13]
	v_cndmask_b32_e64 v136, v137, v145, s[14:15]
	v_pk_mul_f32 v[144:145], v[126:127], v[148:149] op_sel_hi:[1,0]
	v_pk_mul_f32 v[152:153], v[122:123], v[148:149] op_sel_hi:[1,0]
; DI unsigned pk_bf16(float lo, float hi) { f32x2 v = {lo, hi}; return __builtin_bit_cast(unsigned, __builtin_convertvector(v, bf16v2)); }
; DI float fast_sigmoid(float x) { return __builtin_amdgcn_rcpf(1.0f + __expf(-x)); }
;     DI void operator()(AccRef acc, const Unit& u, int wr, int wc, int fr, int fq) const {
;     ...
;         for (int ai = 0; ai < 2; ++ai)
; #pragma unroll
;             for (int m = 0; m < 4; ++m)
; #pragma unroll
;                 for (int bj = 0; bj < 2; ++bj) {
;                     const float rs = rsc.r[ai][m];
;                     const f32x4 r0 = acc[ai][bj][m][0] * rs, r1 = acc[ai][bj][m][1] * rs;
;                     u32x4 w;
;                     w.x = pk_bf16(fast_sigmoid(r0[0]), fast_sigmoid(r0[1])); w.y = pk_bf16(fast_sigmoid(r0[2]), fast_sigmoid(r0[3]));
;                     w.z = pk_bf16(fast_sigmoid(r1[0]), fast_sigmoid(r1[1])); w.w = pk_bf16(fast_sigmoid(r1[2]), fast_sigmoid(r1[3]));
;                     *(u32x4*)(Gp + (ai * 128 + m * 16) * 256 + bj * 128) = w;
;                 }
	v_mul_f32_e32 v140, 0x45800000, v133
	v_mul_f32_e32 v143, 0x45800000, v135
	v_cndmask_b32_e64 v142, v134, v142, s[8:9]
	v_cndmask_b32_e64 v134, v141, v146, s[16:17]
	v_cndmask_b32_e64 v132, v139, v147, s[18:19]
	v_pk_mul_f32 v[146:147], v[124:125], v[148:149] op_sel_hi:[1,0]
	v_pk_mul_f32 v[154:155], v[120:121], v[148:149] op_sel_hi:[1,0]
	v_mul_f32_e32 v137, 0xbfb8aa3b, v144
	v_mul_f32_e32 v144, 0xbfb8aa3b, v152
	v_cndmask_b32_e64 v150, v133, v140, s[0:1]
	v_cndmask_b32_e64 v140, v135, v143, s[10:11]
	v_mul_f32_e32 v133, 0xbfb8aa3b, v146
	v_mul_f32_e32 v135, 0xbfb8aa3b, v147
	v_mul_f32_e32 v139, 0xbfb8aa3b, v145
	v_mul_f32_e32 v141, 0xbfb8aa3b, v154
	v_mul_f32_e32 v143, 0xbfb8aa3b, v155
	v_exp_f32_e32 v144, v144
	v_mul_f32_e32 v145, 0xbfb8aa3b, v153
	v_exp_f32_e32 v133, v133
	v_exp_f32_e32 v135, v135
	v_exp_f32_e32 v137, v137
	v_exp_f32_e32 v139, v139
	v_exp_f32_e32 v141, v141
	v_exp_f32_e32 v143, v143
	v_exp_f32_e32 v145, v145
	v_add_f32_e32 v144, 1.0, v144
	v_add_f32_e32 v133, 1.0, v133
	v_add_f32_e32 v135, 1.0, v135
	v_add_f32_e32 v137, 1.0, v137
	v_add_f32_e32 v139, 1.0, v139
	v_add_f32_e32 v141, 1.0, v141
	v_add_f32_e32 v143, 1.0, v143
	v_rcp_f32_e32 v147, v144
	v_add_f32_e32 v144, 1.0, v145
	v_rcp_f32_e32 v133, v133
	v_rcp_f32_e32 v135, v135
	v_rcp_f32_e32 v137, v137
	v_rcp_f32_e32 v139, v139
	v_rcp_f32_e32 v141, v141
	v_rcp_f32_e32 v143, v143
	v_rcp_f32_e32 v149, v144
	v_cvt_pk_bf16_f32 v144, v133, v135
	v_cvt_pk_bf16_f32 v145, v137, v139
	v_cvt_pk_bf16_f32 v146, v141, v143
	v_cvt_pk_bf16_f32 v147, v147, v149
	global_store_dwordx4 v[130:131], v[144:147], off
	v_pk_mul_f32 v[152:153], v[114:115], v[148:149] op_sel_hi:[1,0]
	s_nop 0
	v_pk_mul_f32 v[144:145], v[118:119], v[148:149] op_sel_hi:[1,0]
	v_pk_mul_f32 v[146:147], v[116:117], v[148:149] op_sel_hi:[1,0]
	v_mul_f32_e32 v137, 0xbfb8aa3b, v144
	v_mul_f32_e32 v133, 0xbfb8aa3b, v146
	v_mul_f32_e32 v135, 0xbfb8aa3b, v147
	v_pk_mul_f32 v[146:147], v[112:113], v[148:149] op_sel_hi:[1,0]
	v_mul_f32_e32 v144, 0xbfb8aa3b, v152
	v_mul_f32_e32 v139, 0xbfb8aa3b, v145
	v_mul_f32_e32 v141, 0xbfb8aa3b, v146
	v_mul_f32_e32 v143, 0xbfb8aa3b, v147
	v_exp_f32_e32 v144, v144
	v_mul_f32_e32 v145, 0xbfb8aa3b, v153
	v_exp_f32_e32 v133, v133
	v_exp_f32_e32 v135, v135
	v_exp_f32_e32 v137, v137
	v_exp_f32_e32 v139, v139
	v_exp_f32_e32 v141, v141
	v_exp_f32_e32 v143, v143
	v_exp_f32_e32 v145, v145
	v_add_f32_e32 v144, 1.0, v144
	v_add_f32_e32 v133, 1.0, v133
	v_add_f32_e32 v135, 1.0, v135
	v_add_f32_e32 v137, 1.0, v137
	v_add_f32_e32 v139, 1.0, v139
	v_add_f32_e32 v141, 1.0, v141
	v_add_f32_e32 v143, 1.0, v143
	v_rcp_f32_e32 v147, v144
	v_add_f32_e32 v144, 1.0, v145
	v_rcp_f32_e32 v133, v133
	v_rcp_f32_e32 v135, v135
	v_rcp_f32_e32 v137, v137
	v_rcp_f32_e32 v139, v139
	v_rcp_f32_e32 v141, v141
	v_rcp_f32_e32 v143, v143
	v_rcp_f32_e32 v148, v144
	v_cvt_pk_bf16_f32 v144, v133, v135
	v_cvt_pk_bf16_f32 v145, v137, v139
	v_cvt_pk_bf16_f32 v146, v141, v143
	v_cvt_pk_bf16_f32 v147, v147, v148
	global_store_dwordx4 v[130:131], v[144:147], off offset:256
	v_pk_mul_f32 v[148:149], v[106:107], v[150:151] op_sel_hi:[1,0]
	v_pk_mul_f32 v[152:153], v[98:99], v[150:151] op_sel_hi:[1,0]
	v_pk_mul_f32 v[144:145], v[110:111], v[150:151] op_sel_hi:[1,0]
	v_pk_mul_f32 v[146:147], v[108:109], v[150:151] op_sel_hi:[1,0]
	v_mul_f32_e32 v137, 0xbfb8aa3b, v144
	v_mul_f32_e32 v144, 0xbfb8aa3b, v148
	v_mul_f32_e32 v133, 0xbfb8aa3b, v146
	v_mul_f32_e32 v135, 0xbfb8aa3b, v147
	v_pk_mul_f32 v[146:147], v[104:105], v[150:151] op_sel_hi:[1,0]
	v_mul_f32_e32 v139, 0xbfb8aa3b, v145
	v_exp_f32_e32 v144, v144
	v_mul_f32_e32 v145, 0xbfb8aa3b, v149
	v_mul_f32_e32 v141, 0xbfb8aa3b, v146
	v_mul_f32_e32 v143, 0xbfb8aa3b, v147
	v_exp_f32_e32 v145, v145
	v_exp_f32_e32 v133, v133
	v_exp_f32_e32 v135, v135
	v_exp_f32_e32 v137, v137
	v_exp_f32_e32 v139, v139
	v_exp_f32_e32 v141, v141
	v_exp_f32_e32 v143, v143
	v_add_f32_e32 v144, 1.0, v144
	v_rcp_f32_e32 v147, v144
	v_add_f32_e32 v144, 1.0, v145
	v_add_f32_e32 v133, 1.0, v133
	v_add_f32_e32 v135, 1.0, v135
	v_add_f32_e32 v137, 1.0, v137
	v_add_f32_e32 v139, 1.0, v139
	v_add_f32_e32 v141, 1.0, v141
	v_add_f32_e32 v143, 1.0, v143
	v_rcp_f32_e32 v148, v144
	v_rcp_f32_e32 v133, v133
	v_rcp_f32_e32 v135, v135
	v_rcp_f32_e32 v137, v137
	v_rcp_f32_e32 v139, v139
	v_rcp_f32_e32 v141, v141
	v_rcp_f32_e32 v143, v143
	v_cvt_pk_bf16_f32 v147, v147, v148
	v_add_co_u32_e32 v148, vcc, s59, v130
	v_cvt_pk_bf16_f32 v144, v133, v135
	v_cvt_pk_bf16_f32 v145, v137, v139
	v_cvt_pk_bf16_f32 v146, v141, v143
	v_addc_co_u32_e32 v149, vcc, 0, v131, vcc
	global_store_dwordx4 v[148:149], v[144:147], off
	s_nop 1
	v_pk_mul_f32 v[144:145], v[102:103], v[150:151] op_sel_hi:[1,0]
	v_pk_mul_f32 v[146:147], v[100:101], v[150:151] op_sel_hi:[1,0]
	v_mul_f32_e32 v137, 0xbfb8aa3b, v144
	v_mul_f32_e32 v133, 0xbfb8aa3b, v146
	v_mul_f32_e32 v135, 0xbfb8aa3b, v147
	v_pk_mul_f32 v[146:147], v[96:97], v[150:151] op_sel_hi:[1,0]
	v_mul_f32_e32 v144, 0xbfb8aa3b, v152
	v_mul_f32_e32 v139, 0xbfb8aa3b, v145
	v_mul_f32_e32 v141, 0xbfb8aa3b, v146
	v_mul_f32_e32 v143, 0xbfb8aa3b, v147
	v_exp_f32_e32 v144, v144
	v_mul_f32_e32 v145, 0xbfb8aa3b, v153
	v_exp_f32_e32 v133, v133
	v_exp_f32_e32 v135, v135
	v_exp_f32_e32 v137, v137
	v_exp_f32_e32 v139, v139
	v_exp_f32_e32 v141, v141
	v_exp_f32_e32 v143, v143
	v_exp_f32_e32 v145, v145
	v_add_f32_e32 v144, 1.0, v144
	v_add_f32_e32 v133, 1.0, v133
	v_add_f32_e32 v135, 1.0, v135
	v_add_f32_e32 v137, 1.0, v137
	v_add_f32_e32 v139, 1.0, v139
	v_add_f32_e32 v141, 1.0, v141
	v_add_f32_e32 v143, 1.0, v143
	v_rcp_f32_e32 v147, v144
	v_add_f32_e32 v144, 1.0, v145
	v_rcp_f32_e32 v133, v133
	v_rcp_f32_e32 v135, v135
; DI unsigned pk_bf16(float lo, float hi) { f32x2 v = {lo, hi}; return __builtin_bit_cast(unsigned, __builtin_convertvector(v, bf16v2)); }
; DI float fast_sigmoid(float x) { return __builtin_amdgcn_rcpf(1.0f + __expf(-x)); }
;     DI void operator()(AccRef acc, const Unit& u, int wr, int wc, int fr, int fq) const {
;     ...
;         for (int ai = 0; ai < 2; ++ai)
; #pragma unroll
;             for (int m = 0; m < 4; ++m)
; #pragma unroll
;                 for (int bj = 0; bj < 2; ++bj) {
;                     const float rs = rsc.r[ai][m];
;                     const f32x4 r0 = acc[ai][bj][m][0] * rs, r1 = acc[ai][bj][m][1] * rs;
;                     u32x4 w;
;                     w.x = pk_bf16(fast_sigmoid(r0[0]), fast_sigmoid(r0[1])); w.y = pk_bf16(fast_sigmoid(r0[2]), fast_sigmoid(r0[3]));
;                     w.z = pk_bf16(fast_sigmoid(r1[0]), fast_sigmoid(r1[1])); w.w = pk_bf16(fast_sigmoid(r1[2]), fast_sigmoid(r1[3]));
;                     *(u32x4*)(Gp + (ai * 128 + m * 16) * 256 + bj * 128) = w;
	v_rcp_f32_e32 v137, v137
	v_rcp_f32_e32 v139, v139
	v_rcp_f32_e32 v141, v141
	v_rcp_f32_e32 v143, v143
	v_rcp_f32_e32 v150, v144
	v_cvt_pk_bf16_f32 v144, v133, v135
	v_cvt_pk_bf16_f32 v145, v137, v139
	v_cvt_pk_bf16_f32 v146, v141, v143
	v_cvt_pk_bf16_f32 v147, v147, v150
	global_store_dwordx4 v[148:149], v[144:147], off offset:256
	v_pk_mul_f32 v[148:149], v[90:91], v[142:143] op_sel_hi:[1,0]
	s_nop 0
	v_pk_mul_f32 v[144:145], v[94:95], v[142:143] op_sel_hi:[1,0]
	v_pk_mul_f32 v[146:147], v[92:93], v[142:143] op_sel_hi:[1,0]
	v_mul_f32_e32 v137, 0xbfb8aa3b, v144
	v_mul_f32_e32 v144, 0xbfb8aa3b, v148
	v_mul_f32_e32 v133, 0xbfb8aa3b, v146
	v_mul_f32_e32 v135, 0xbfb8aa3b, v147
	v_pk_mul_f32 v[146:147], v[88:89], v[142:143] op_sel_hi:[1,0]
	v_mul_f32_e32 v139, 0xbfb8aa3b, v145
	v_exp_f32_e32 v144, v144
	v_mul_f32_e32 v145, 0xbfb8aa3b, v149
	v_mul_f32_e32 v141, 0xbfb8aa3b, v146
	v_mul_f32_e32 v143, 0xbfb8aa3b, v147
	v_exp_f32_e32 v145, v145
	v_exp_f32_e32 v133, v133
	v_exp_f32_e32 v135, v135
	v_exp_f32_e32 v137, v137
	v_exp_f32_e32 v139, v139
	v_exp_f32_e32 v141, v141
	v_exp_f32_e32 v143, v143
	v_add_f32_e32 v144, 1.0, v144
	v_rcp_f32_e32 v147, v144
	v_add_f32_e32 v144, 1.0, v145
	v_add_f32_e32 v133, 1.0, v133
	v_add_f32_e32 v135, 1.0, v135
	v_add_f32_e32 v137, 1.0, v137
	v_add_f32_e32 v139, 1.0, v139
	v_add_f32_e32 v141, 1.0, v141
	v_add_f32_e32 v143, 1.0, v143
	v_rcp_f32_e32 v148, v144
	v_rcp_f32_e32 v133, v133
	v_rcp_f32_e32 v135, v135
	v_rcp_f32_e32 v137, v137
	v_rcp_f32_e32 v139, v139
	v_rcp_f32_e32 v141, v141
	v_rcp_f32_e32 v143, v143
	v_cvt_pk_bf16_f32 v147, v147, v148
	v_add_co_u32_e32 v148, vcc, s66, v130
	v_cvt_pk_bf16_f32 v144, v133, v135
	v_cvt_pk_bf16_f32 v145, v137, v139
	v_cvt_pk_bf16_f32 v146, v141, v143
	v_addc_co_u32_e32 v149, vcc, 0, v131, vcc
	global_store_dwordx4 v[148:149], v[144:147], off
	v_pk_mul_f32 v[150:151], v[82:83], v[142:143] op_sel_hi:[1,0]
	s_nop 0
	v_pk_mul_f32 v[144:145], v[86:87], v[142:143] op_sel_hi:[1,0]
	v_pk_mul_f32 v[146:147], v[84:85], v[142:143] op_sel_hi:[1,0]
	v_pk_mul_f32 v[142:143], v[80:81], v[142:143] op_sel_hi:[1,0]
	v_mul_f32_e32 v133, 0xbfb8aa3b, v146
	v_mul_f32_e32 v141, 0xbfb8aa3b, v142
	v_mul_f32_e32 v142, 0xbfb8aa3b, v143
	v_exp_f32_e32 v142, v142
	v_mul_f32_e32 v143, 0xbfb8aa3b, v150
	v_mul_f32_e32 v135, 0xbfb8aa3b, v147
	v_mul_f32_e32 v137, 0xbfb8aa3b, v144
	v_mul_f32_e32 v139, 0xbfb8aa3b, v145
	v_exp_f32_e32 v143, v143
	v_mul_f32_e32 v144, 0xbfb8aa3b, v151
	v_exp_f32_e32 v133, v133
	v_exp_f32_e32 v135, v135
	v_exp_f32_e32 v137, v137
	v_exp_f32_e32 v139, v139
	v_exp_f32_e32 v141, v141
	v_exp_f32_e32 v144, v144
	v_add_f32_e32 v142, 1.0, v142
	v_rcp_f32_e32 v145, v142
	v_add_f32_e32 v142, 1.0, v143
	v_add_f32_e32 v133, 1.0, v133
	v_add_f32_e32 v135, 1.0, v135
	v_add_f32_e32 v137, 1.0, v137
	v_add_f32_e32 v139, 1.0, v139
	v_add_f32_e32 v141, 1.0, v141
	v_rcp_f32_e32 v146, v142
	v_add_f32_e32 v142, 1.0, v144
	v_rcp_f32_e32 v133, v133
	v_rcp_f32_e32 v135, v135
	v_rcp_f32_e32 v137, v137
	v_rcp_f32_e32 v139, v139
	v_rcp_f32_e32 v141, v141
	v_rcp_f32_e32 v147, v142
	v_cvt_pk_bf16_f32 v142, v133, v135
	v_cvt_pk_bf16_f32 v143, v137, v139
	v_cvt_pk_bf16_f32 v144, v141, v145
	v_cvt_pk_bf16_f32 v145, v146, v147
	global_store_dwordx4 v[148:149], v[142:145], off offset:256
	v_pk_mul_f32 v[146:147], v[74:75], v[140:141] op_sel_hi:[1,0]
	s_nop 0
	v_pk_mul_f32 v[144:145], v[76:77], v[140:141] op_sel_hi:[1,0]
	v_pk_mul_f32 v[142:143], v[78:79], v[140:141] op_sel_hi:[1,0]
	v_mul_f32_e32 v133, 0xbfb8aa3b, v144
	v_mul_f32_e32 v135, 0xbfb8aa3b, v145
	v_pk_mul_f32 v[144:145], v[72:73], v[140:141] op_sel_hi:[1,0]
	v_mul_f32_e32 v137, 0xbfb8aa3b, v142
	v_mul_f32_e32 v142, 0xbfb8aa3b, v145
	v_mul_f32_e32 v139, 0xbfb8aa3b, v143
	v_exp_f32_e32 v142, v142
	v_mul_f32_e32 v143, 0xbfb8aa3b, v146
	v_mul_f32_e32 v141, 0xbfb8aa3b, v144
	v_exp_f32_e32 v143, v143
	v_mul_f32_e32 v144, 0xbfb8aa3b, v147
	v_exp_f32_e32 v141, v141
	v_exp_f32_e32 v144, v144
	v_exp_f32_e32 v133, v133
	v_exp_f32_e32 v135, v135
	v_exp_f32_e32 v137, v137
	v_exp_f32_e32 v139, v139
	v_add_f32_e32 v142, 1.0, v142
	v_rcp_f32_e32 v145, v142
	v_add_f32_e32 v142, 1.0, v143
	v_add_f32_e32 v141, 1.0, v141
	v_rcp_f32_e32 v146, v142
	v_add_f32_e32 v142, 1.0, v144
	v_add_f32_e32 v133, 1.0, v133
	v_add_f32_e32 v135, 1.0, v135
	v_add_f32_e32 v137, 1.0, v137
	v_add_f32_e32 v139, 1.0, v139
	v_rcp_f32_e32 v141, v141
	v_rcp_f32_e32 v147, v142
	v_rcp_f32_e32 v133, v133
	v_rcp_f32_e32 v135, v135
	v_rcp_f32_e32 v137, v137
	v_rcp_f32_e32 v139, v139
	v_cvt_pk_bf16_f32 v144, v141, v145
	v_cvt_pk_bf16_f32 v145, v146, v147
	v_add_co_u32_e32 v146, vcc, s67, v130
	v_cvt_pk_bf16_f32 v142, v133, v135
	v_cvt_pk_bf16_f32 v143, v137, v139
	v_addc_co_u32_e32 v147, vcc, 0, v131, vcc
	global_store_dwordx4 v[146:147], v[142:145], off
	v_pk_mul_f32 v[148:149], v[66:67], v[140:141] op_sel_hi:[1,0]
	s_nop 0
	v_pk_mul_f32 v[142:143], v[70:71], v[140:141] op_sel_hi:[1,0]
	v_pk_mul_f32 v[144:145], v[68:69], v[140:141] op_sel_hi:[1,0]
	v_pk_mul_f32 v[140:141], v[64:65], v[140:141] op_sel_hi:[1,0]
	v_mul_f32_e32 v137, 0xbfb8aa3b, v142
	v_mul_f32_e32 v140, 0xbfb8aa3b, v140
	v_exp_f32_e32 v140, v140
	v_mul_f32_e32 v141, 0xbfb8aa3b, v141
	v_exp_f32_e32 v141, v141
	v_mul_f32_e32 v133, 0xbfb8aa3b, v144
	v_add_f32_e32 v140, 1.0, v140
	v_rcp_f32_e32 v142, v140
	v_add_f32_e32 v140, 1.0, v141
	v_mul_f32_e32 v141, 0xbfb8aa3b, v148
	v_mul_f32_e32 v135, 0xbfb8aa3b, v145
	v_mul_f32_e32 v139, 0xbfb8aa3b, v143
	v_exp_f32_e32 v141, v141
	v_mul_f32_e32 v143, 0xbfb8aa3b, v149
	v_exp_f32_e32 v133, v133
	v_exp_f32_e32 v135, v135
	v_exp_f32_e32 v137, v137
	v_exp_f32_e32 v139, v139
	v_exp_f32_e32 v143, v143
; DI unsigned pk_bf16(float lo, float hi) { f32x2 v = {lo, hi}; return __builtin_bit_cast(unsigned, __builtin_convertvector(v, bf16v2)); }
; DI float fast_sigmoid(float x) { return __builtin_amdgcn_rcpf(1.0f + __expf(-x)); }
;     DI void operator()(AccRef acc, const Unit& u, int wr, int wc, int fr, int fq) const {
;     ...
;         for (int ai = 0; ai < 2; ++ai)
; #pragma unroll
;             for (int m = 0; m < 4; ++m)
; #pragma unroll
;                 for (int bj = 0; bj < 2; ++bj) {
;                     const float rs = rsc.r[ai][m];
;                     const f32x4 r0 = acc[ai][bj][m][0] * rs, r1 = acc[ai][bj][m][1] * rs;
;                     u32x4 w;
;                     w.x = pk_bf16(fast_sigmoid(r0[0]), fast_sigmoid(r0[1])); w.y = pk_bf16(fast_sigmoid(r0[2]), fast_sigmoid(r0[3]));
;                     w.z = pk_bf16(fast_sigmoid(r1[0]), fast_sigmoid(r1[1])); w.w = pk_bf16(fast_sigmoid(r1[2]), fast_sigmoid(r1[3]));
;                     *(u32x4*)(Gp + (ai * 128 + m * 16) * 256 + bj * 128) = w;
	v_rcp_f32_e32 v144, v140
	v_add_f32_e32 v140, 1.0, v141
	v_add_f32_e32 v133, 1.0, v133
	v_add_f32_e32 v135, 1.0, v135
	v_add_f32_e32 v137, 1.0, v137
	v_add_f32_e32 v139, 1.0, v139
	v_rcp_f32_e32 v145, v140
	v_add_f32_e32 v140, 1.0, v143
	v_rcp_f32_e32 v133, v133
	v_rcp_f32_e32 v135, v135
	v_rcp_f32_e32 v137, v137
	v_rcp_f32_e32 v139, v139
	v_rcp_f32_e32 v143, v140
	v_cvt_pk_bf16_f32 v140, v133, v135
	v_cvt_pk_bf16_f32 v142, v142, v144
	v_cvt_pk_bf16_f32 v141, v137, v139
	v_cvt_pk_bf16_f32 v143, v145, v143
	global_store_dwordx4 v[146:147], v[140:143], off offset:256
	v_pk_mul_f32 v[144:145], v[58:59], v[138:139] op_sel_hi:[1,0]
	s_nop 0
	v_pk_mul_f32 v[142:143], v[60:61], v[138:139] op_sel_hi:[1,0]
	v_pk_mul_f32 v[140:141], v[62:63], v[138:139] op_sel_hi:[1,0]
	v_mul_f32_e32 v133, 0xbfb8aa3b, v142
	v_mul_f32_e32 v135, 0xbfb8aa3b, v143
	v_pk_mul_f32 v[142:143], v[56:57], v[138:139] op_sel_hi:[1,0]
	v_mul_f32_e32 v137, 0xbfb8aa3b, v140
	v_mul_f32_e32 v140, 0xbfb8aa3b, v142
	v_mul_f32_e32 v139, 0xbfb8aa3b, v141
	v_exp_f32_e32 v140, v140
	v_mul_f32_e32 v141, 0xbfb8aa3b, v143
	v_exp_f32_e32 v141, v141
	v_mul_f32_e32 v143, 0xbfb8aa3b, v145
	v_add_f32_e32 v140, 1.0, v140
	v_rcp_f32_e32 v142, v140
	v_add_f32_e32 v140, 1.0, v141
	v_mul_f32_e32 v141, 0xbfb8aa3b, v144
	v_exp_f32_e32 v141, v141
	v_exp_f32_e32 v133, v133
	v_exp_f32_e32 v135, v135
	v_exp_f32_e32 v137, v137
	v_exp_f32_e32 v139, v139
	v_exp_f32_e32 v143, v143
	v_rcp_f32_e32 v144, v140
	v_add_f32_e32 v140, 1.0, v141
	v_add_f32_e32 v133, 1.0, v133
	v_add_f32_e32 v135, 1.0, v135
	v_add_f32_e32 v137, 1.0, v137
	v_add_f32_e32 v139, 1.0, v139
	v_rcp_f32_e32 v145, v140
	v_add_f32_e32 v140, 1.0, v143
	v_rcp_f32_e32 v133, v133
	v_rcp_f32_e32 v135, v135
	v_rcp_f32_e32 v137, v137
	v_rcp_f32_e32 v139, v139
	v_rcp_f32_e32 v143, v140
	v_cvt_pk_bf16_f32 v142, v142, v144
	v_add_co_u32_e32 v144, vcc, s62, v130
	v_cvt_pk_bf16_f32 v140, v133, v135
	v_cvt_pk_bf16_f32 v141, v137, v139
	v_cvt_pk_bf16_f32 v143, v145, v143
	v_addc_co_u32_e32 v145, vcc, 0, v131, vcc
	global_store_dwordx4 v[144:145], v[140:143], off
	v_pk_mul_f32 v[146:147], v[50:51], v[138:139] op_sel_hi:[1,0]
	s_nop 0
	v_pk_mul_f32 v[140:141], v[54:55], v[138:139] op_sel_hi:[1,0]
	v_pk_mul_f32 v[142:143], v[52:53], v[138:139] op_sel_hi:[1,0]
	v_pk_mul_f32 v[138:139], v[48:49], v[138:139] op_sel_hi:[1,0]
	v_mul_f32_e32 v137, 0xbfb8aa3b, v140
	v_mul_f32_e32 v138, 0xbfb8aa3b, v138
	v_exp_f32_e32 v138, v138
	v_mul_f32_e32 v139, 0xbfb8aa3b, v139
	v_exp_f32_e32 v139, v139
	v_mul_f32_e32 v140, 0xbfb8aa3b, v141
	v_add_f32_e32 v138, 1.0, v138
	v_rcp_f32_e32 v141, v138
	v_add_f32_e32 v138, 1.0, v139
	v_mul_f32_e32 v139, 0xbfb8aa3b, v146
	v_mul_f32_e32 v133, 0xbfb8aa3b, v142
	v_mul_f32_e32 v135, 0xbfb8aa3b, v143
	v_exp_f32_e32 v139, v139
	v_mul_f32_e32 v142, 0xbfb8aa3b, v147
	v_exp_f32_e32 v133, v133
	v_exp_f32_e32 v135, v135
	v_exp_f32_e32 v137, v137
	v_exp_f32_e32 v140, v140
	v_exp_f32_e32 v142, v142
	v_rcp_f32_e32 v143, v138
	v_add_f32_e32 v138, 1.0, v139
	v_add_f32_e32 v133, 1.0, v133
	v_add_f32_e32 v135, 1.0, v135
	v_add_f32_e32 v137, 1.0, v137
	v_add_f32_e32 v140, 1.0, v140
	v_rcp_f32_e32 v146, v138
	v_add_f32_e32 v138, 1.0, v142
	v_rcp_f32_e32 v133, v133
	v_rcp_f32_e32 v135, v135
	v_rcp_f32_e32 v137, v137
	v_rcp_f32_e32 v140, v140
	v_rcp_f32_e32 v142, v138
	v_cvt_pk_bf16_f32 v138, v133, v135
	v_cvt_pk_bf16_f32 v139, v137, v140
	v_cvt_pk_bf16_f32 v140, v141, v143
	v_cvt_pk_bf16_f32 v141, v146, v142
	global_store_dwordx4 v[144:145], v[138:141], off offset:256
	v_pk_mul_f32 v[142:143], v[42:43], v[136:137] op_sel_hi:[1,0]
	s_nop 0
	v_pk_mul_f32 v[138:139], v[46:47], v[136:137] op_sel_hi:[1,0]
	v_pk_mul_f32 v[140:141], v[44:45], v[136:137] op_sel_hi:[1,0]
	s_nop 0
	v_mul_f32_e32 v133, 0xbfb8aa3b, v140
	v_mul_f32_e32 v135, 0xbfb8aa3b, v141
	v_pk_mul_f32 v[140:141], v[40:41], v[136:137] op_sel_hi:[1,0]
	v_mul_f32_e32 v137, 0xbfb8aa3b, v138
	v_mul_f32_e32 v138, 0xbfb8aa3b, v139
	v_exp_f32_e32 v138, v138
	v_mul_f32_e32 v139, 0xbfb8aa3b, v140
	v_exp_f32_e32 v139, v139
	v_mul_f32_e32 v140, 0xbfb8aa3b, v141
	v_exp_f32_e32 v140, v140
	v_add_f32_e32 v138, 1.0, v138
	v_rcp_f32_e32 v141, v138
	v_add_f32_e32 v138, 1.0, v139
	v_mul_f32_e32 v139, 0xbfb8aa3b, v142
	v_rcp_f32_e32 v144, v138
	v_add_f32_e32 v138, 1.0, v140
	v_exp_f32_e32 v139, v139
	v_mul_f32_e32 v140, 0xbfb8aa3b, v143
	v_exp_f32_e32 v133, v133
	v_exp_f32_e32 v135, v135
	v_exp_f32_e32 v137, v137
	v_exp_f32_e32 v140, v140
	v_rcp_f32_e32 v142, v138
	v_add_f32_e32 v138, 1.0, v139
	v_add_f32_e32 v133, 1.0, v133
	v_add_f32_e32 v135, 1.0, v135
	v_add_f32_e32 v137, 1.0, v137
	v_rcp_f32_e32 v143, v138
	v_add_f32_e32 v138, 1.0, v140
	v_rcp_f32_e32 v133, v133
	v_rcp_f32_e32 v135, v135
	v_rcp_f32_e32 v137, v137
	v_rcp_f32_e32 v145, v138
	v_cvt_pk_bf16_f32 v140, v144, v142
	v_add_co_u32_e32 v142, vcc, s63, v130
	v_cvt_pk_bf16_f32 v138, v133, v135
	v_cvt_pk_bf16_f32 v139, v137, v141
	v_cvt_pk_bf16_f32 v141, v143, v145
	v_addc_co_u32_e32 v143, vcc, 0, v131, vcc
	global_store_dwordx4 v[142:143], v[138:141], off
	v_pk_mul_f32 v[144:145], v[34:35], v[136:137] op_sel_hi:[1,0]
	s_nop 0
	v_pk_mul_f32 v[138:139], v[38:39], v[136:137] op_sel_hi:[1,0]
	v_pk_mul_f32 v[140:141], v[36:37], v[136:137] op_sel_hi:[1,0]
	v_pk_mul_f32 v[136:137], v[32:33], v[136:137] op_sel_hi:[1,0]
	v_mul_f32_e32 v133, 0xbfb8aa3b, v140
	v_mul_f32_e32 v136, 0xbfb8aa3b, v136
	v_exp_f32_e32 v136, v136
	v_mul_f32_e32 v137, 0xbfb8aa3b, v137
	v_exp_f32_e32 v137, v137
	v_mul_f32_e32 v135, 0xbfb8aa3b, v141
	v_add_f32_e32 v136, 1.0, v136
	v_rcp_f32_e32 v140, v136
	v_add_f32_e32 v136, 1.0, v137
	v_mul_f32_e32 v137, 0xbfb8aa3b, v144
	v_mul_f32_e32 v138, 0xbfb8aa3b, v138
; DI unsigned pk_bf16(float lo, float hi) { f32x2 v = {lo, hi}; return __builtin_bit_cast(unsigned, __builtin_convertvector(v, bf16v2)); }
; DI float fast_sigmoid(float x) { return __builtin_amdgcn_rcpf(1.0f + __expf(-x)); }
;     DI void operator()(AccRef acc, const Unit& u, int wr, int wc, int fr, int fq) const {
;     ...
;         for (int ai = 0; ai < 2; ++ai)
; #pragma unroll
;             for (int m = 0; m < 4; ++m)
; #pragma unroll
;                 for (int bj = 0; bj < 2; ++bj) {
;                     const float rs = rsc.r[ai][m];
;                     const f32x4 r0 = acc[ai][bj][m][0] * rs, r1 = acc[ai][bj][m][1] * rs;
;                     u32x4 w;
;                     w.x = pk_bf16(fast_sigmoid(r0[0]), fast_sigmoid(r0[1])); w.y = pk_bf16(fast_sigmoid(r0[2]), fast_sigmoid(r0[3]));
;                     w.z = pk_bf16(fast_sigmoid(r1[0]), fast_sigmoid(r1[1])); w.w = pk_bf16(fast_sigmoid(r1[2]), fast_sigmoid(r1[3]));
;                     *(u32x4*)(Gp + (ai * 128 + m * 16) * 256 + bj * 128) = w;
	v_mul_f32_e32 v139, 0xbfb8aa3b, v139
	v_exp_f32_e32 v137, v137
	v_mul_f32_e32 v141, 0xbfb8aa3b, v145
	v_exp_f32_e32 v133, v133
	v_exp_f32_e32 v135, v135
	v_exp_f32_e32 v138, v138
	v_exp_f32_e32 v139, v139
	v_exp_f32_e32 v141, v141
	v_rcp_f32_e32 v144, v136
	v_add_f32_e32 v136, 1.0, v137
	v_add_f32_e32 v133, 1.0, v133
	v_add_f32_e32 v135, 1.0, v135
	v_add_f32_e32 v138, 1.0, v138
	v_add_f32_e32 v139, 1.0, v139
	v_rcp_f32_e32 v145, v136
	v_add_f32_e32 v136, 1.0, v141
	v_rcp_f32_e32 v133, v133
	v_rcp_f32_e32 v135, v135
	v_rcp_f32_e32 v138, v138
	v_rcp_f32_e32 v139, v139
	v_rcp_f32_e32 v141, v136
	v_cvt_pk_bf16_f32 v136, v133, v135
	v_cvt_pk_bf16_f32 v137, v138, v139
	v_cvt_pk_bf16_f32 v138, v140, v144
	v_cvt_pk_bf16_f32 v139, v145, v141
	global_store_dwordx4 v[142:143], v[136:139], off offset:256
	v_pk_mul_f32 v[140:141], v[26:27], v[134:135] op_sel_hi:[1,0]
	s_nop 0
	v_pk_mul_f32 v[136:137], v[30:31], v[134:135] op_sel_hi:[1,0]
	v_pk_mul_f32 v[138:139], v[28:29], v[134:135] op_sel_hi:[1,0]
	v_mul_f32_e32 v136, 0xbfb8aa3b, v136
	v_mul_f32_e32 v135, 0xbfb8aa3b, v139
	v_exp_f32_e32 v135, v135
	v_exp_f32_e32 v136, v136
	v_mul_f32_e32 v137, 0xbfb8aa3b, v137
	v_exp_f32_e32 v137, v137
	v_mul_f32_e32 v133, 0xbfb8aa3b, v138
	v_pk_mul_f32 v[138:139], v[24:25], v[134:135] op_sel_hi:[1,0]
	v_add_f32_e32 v136, 1.0, v136
	v_rcp_f32_e32 v142, v136
	v_add_f32_e32 v136, 1.0, v137
	v_mul_f32_e32 v137, 0xbfb8aa3b, v138
	v_exp_f32_e32 v137, v137
	v_mul_f32_e32 v138, 0xbfb8aa3b, v139
	v_exp_f32_e32 v138, v138
	v_rcp_f32_e32 v139, v136
	v_add_f32_e32 v136, 1.0, v137
	v_mul_f32_e32 v137, 0xbfb8aa3b, v140
	v_rcp_f32_e32 v143, v136
	v_add_f32_e32 v136, 1.0, v138
	v_exp_f32_e32 v137, v137
	v_mul_f32_e32 v138, 0xbfb8aa3b, v141
	v_exp_f32_e32 v133, v133
	v_exp_f32_e32 v138, v138
	v_rcp_f32_e32 v140, v136
	v_add_f32_e32 v136, 1.0, v137
	v_add_f32_e32 v133, 1.0, v133
	v_add_f32_e32 v135, 1.0, v135
	v_rcp_f32_e32 v141, v136
	v_add_f32_e32 v136, 1.0, v138
	v_rcp_f32_e32 v133, v133
	v_rcp_f32_e32 v135, v135
	v_rcp_f32_e32 v144, v136
	v_cvt_pk_bf16_f32 v138, v143, v140
	v_add_co_u32_e32 v140, vcc, s64, v130
	v_cvt_pk_bf16_f32 v136, v133, v135
	v_cvt_pk_bf16_f32 v137, v142, v139
	v_cvt_pk_bf16_f32 v139, v141, v144
	v_addc_co_u32_e32 v141, vcc, 0, v131, vcc
	global_store_dwordx4 v[140:141], v[136:139], off
	v_pk_mul_f32 v[142:143], v[18:19], v[134:135] op_sel_hi:[1,0]
	s_nop 0
	v_pk_mul_f32 v[138:139], v[20:21], v[134:135] op_sel_hi:[1,0]
	v_pk_mul_f32 v[136:137], v[22:23], v[134:135] op_sel_hi:[1,0]
	v_mul_f32_e32 v135, 0xbfb8aa3b, v139
	v_mul_f32_e32 v133, 0xbfb8aa3b, v138
	v_exp_f32_e32 v138, v135
	v_pk_mul_f32 v[134:135], v[16:17], v[134:135] op_sel_hi:[1,0]
	v_mul_f32_e32 v136, 0xbfb8aa3b, v136
	v_mul_f32_e32 v134, 0xbfb8aa3b, v134
	v_exp_f32_e32 v134, v134
	v_mul_f32_e32 v135, 0xbfb8aa3b, v135
	v_exp_f32_e32 v135, v135
	v_mul_f32_e32 v137, 0xbfb8aa3b, v137
	v_add_f32_e32 v134, 1.0, v134
	v_rcp_f32_e32 v139, v134
	v_add_f32_e32 v134, 1.0, v135
	v_mul_f32_e32 v135, 0xbfb8aa3b, v142
	v_exp_f32_e32 v135, v135
	v_mul_f32_e32 v142, 0xbfb8aa3b, v143
	v_exp_f32_e32 v133, v133
	v_exp_f32_e32 v136, v136
	v_exp_f32_e32 v137, v137
	v_exp_f32_e32 v142, v142
	v_rcp_f32_e32 v143, v134
	v_add_f32_e32 v134, 1.0, v135
	v_add_f32_e32 v133, 1.0, v133
	v_add_f32_e32 v138, 1.0, v138
	v_add_f32_e32 v136, 1.0, v136
	v_add_f32_e32 v137, 1.0, v137
	v_rcp_f32_e32 v144, v134
	v_add_f32_e32 v134, 1.0, v142
	v_rcp_f32_e32 v133, v133
	v_rcp_f32_e32 v138, v138
	v_rcp_f32_e32 v136, v136
	v_rcp_f32_e32 v137, v137
	v_rcp_f32_e32 v142, v134
	v_cvt_pk_bf16_f32 v134, v133, v138
	v_cvt_pk_bf16_f32 v135, v136, v137
	v_cvt_pk_bf16_f32 v136, v139, v143
	v_cvt_pk_bf16_f32 v137, v144, v142
	global_store_dwordx4 v[140:141], v[134:137], off offset:256
	v_pk_mul_f32 v[138:139], v[10:11], v[132:133] op_sel_hi:[1,0]
	s_nop 0
	v_pk_mul_f32 v[134:135], v[14:15], v[132:133] op_sel_hi:[1,0]
	v_pk_mul_f32 v[136:137], v[12:13], v[132:133] op_sel_hi:[1,0]
	v_mul_f32_e32 v134, 0xbfb8aa3b, v134
	v_mul_f32_e32 v133, 0xbfb8aa3b, v136
	v_exp_f32_e32 v133, v133
	v_exp_f32_e32 v134, v134
	v_mul_f32_e32 v135, 0xbfb8aa3b, v135
	v_exp_f32_e32 v135, v135
	v_mul_f32_e32 v136, 0xbfb8aa3b, v137
	v_exp_f32_e32 v140, v136
	v_pk_mul_f32 v[136:137], v[8:9], v[132:133] op_sel_hi:[1,0]
	v_add_f32_e32 v134, 1.0, v134
	v_rcp_f32_e32 v141, v134
	v_add_f32_e32 v134, 1.0, v135
	v_mul_f32_e32 v135, 0xbfb8aa3b, v136
	v_exp_f32_e32 v135, v135
	v_mul_f32_e32 v136, 0xbfb8aa3b, v137
	v_exp_f32_e32 v136, v136
	v_rcp_f32_e32 v137, v134
	v_add_f32_e32 v134, 1.0, v135
	v_mul_f32_e32 v135, 0xbfb8aa3b, v138
	v_rcp_f32_e32 v142, v134
	v_add_f32_e32 v134, 1.0, v136
	v_exp_f32_e32 v135, v135
	v_mul_f32_e32 v136, 0xbfb8aa3b, v139
	v_exp_f32_e32 v136, v136
	v_rcp_f32_e32 v138, v134
	v_add_f32_e32 v134, 1.0, v135
	v_add_f32_e32 v133, 1.0, v133
	v_rcp_f32_e32 v139, v134
	v_add_f32_e32 v134, 1.0, v136
	v_rcp_f32_e32 v133, v133
	v_rcp_f32_e32 v143, v134
	v_add_f32_e32 v140, 1.0, v140
	v_rcp_f32_e32 v140, v140
	v_cvt_pk_bf16_f32 v136, v142, v138
	v_add_co_u32_e32 v138, vcc, s65, v130
	v_cvt_pk_bf16_f32 v135, v141, v137
	v_cvt_pk_bf16_f32 v137, v139, v143
	v_addc_co_u32_e32 v139, vcc, 0, v131, vcc
	v_pk_mul_f32 v[130:131], v[6:7], v[132:133] op_sel_hi:[1,0]
	v_cvt_pk_bf16_f32 v134, v133, v140
	v_mul_f32_e32 v130, 0xbfb8aa3b, v130
	v_exp_f32_e32 v130, v130
	v_mul_f32_e32 v131, 0xbfb8aa3b, v131
	global_store_dwordx4 v[138:139], v[134:137], off
	v_exp_f32_e32 v131, v131
	v_add_f32_e32 v130, 1.0, v130
	v_pk_mul_f32 v[134:135], v[4:5], v[132:133] op_sel_hi:[1,0]
	v_pk_mul_f32 v[136:137], v[2:3], v[132:133] op_sel_hi:[1,0]
	v_mul_f32_e32 v133, 0xbfb8aa3b, v134
	v_exp_f32_e32 v134, v133
	v_mul_f32_e32 v133, 0xbfb8aa3b, v135
	v_exp_f32_e32 v135, v133
	v_pk_mul_f32 v[132:133], v[0:1], v[132:133] op_sel_hi:[1,0]
	v_rcp_f32_e32 v140, v130
	v_add_f32_e32 v130, 1.0, v131
	v_mul_f32_e32 v131, 0xbfb8aa3b, v132
	v_exp_f32_e32 v131, v131
	v_mul_f32_e32 v132, 0xbfb8aa3b, v133
	v_exp_f32_e32 v132, v132
	v_rcp_f32_e32 v133, v130
	v_add_f32_e32 v130, 1.0, v131
	v_mul_f32_e32 v131, 0xbfb8aa3b, v136
	v_rcp_f32_e32 v141, v130
	v_add_f32_e32 v130, 1.0, v132
	v_exp_f32_e32 v131, v131
	v_mul_f32_e32 v132, 0xbfb8aa3b, v137
	v_exp_f32_e32 v132, v132
	v_rcp_f32_e32 v136, v130
	v_add_f32_e32 v130, 1.0, v131
	v_add_f32_e32 v134, 1.0, v134
	v_add_f32_e32 v135, 1.0, v135
	v_rcp_f32_e32 v137, v130
	v_add_f32_e32 v130, 1.0, v132
	v_rcp_f32_e32 v134, v134
	v_rcp_f32_e32 v135, v135
	v_rcp_f32_e32 v142, v130
	v_cvt_pk_bf16_f32 v131, v140, v133
	v_cvt_pk_bf16_f32 v132, v141, v136
	v_cvt_pk_bf16_f32 v130, v134, v135
	v_cvt_pk_bf16_f32 v133, v137, v142
	global_store_dwordx4 v[138:139], v[130:133], off offset:256

; #define PG8_STAGE(bufoff, gbase, voff) do { _Pragma("unroll") for (int _i = 0; _i < 2; ++_i) \
;         __builtin_amdgcn_global_load_lds((const unsigned*)((const char*)(gbase) + (voff)[_i]), (LAS unsigned*)(lds + (bufoff) + ldsw + _i * 8192), 16, 0, 0); } while (0)
; #define PG8_LDA(dst, b, h) do { _Pragma("unroll") for (int m = 0; m < 4; ++m) _Pragma("unroll") for (int k = 0; k < 2; ++k) dst[m][k] = *(const LAS bf16x8*)(lds + PG8_SA(b, h) + aoff + m * 2048 + k * 1024); } while (0)
; #define PG8_LDB(dst, b, h) do { _Pragma("unroll") for (int n = 0; n < 2; ++n) _Pragma("unroll") for (int k = 0; k < 2; ++k) dst[n][k] = *(const LAS bf16x8*)(lds + PG8_SB(b, h) + boff + n * 2048 + k * 1024); } while (0)
; #define PG8_MMA(ai, bj, At, Bt) do { __builtin_amdgcn_s_setprio(1); _Pragma("unroll") for (int m = 0; m < 4; ++m) _Pragma("unroll") for (int n = 0; n < 2; ++n) _Pragma("unroll") for (int k = 0; k < 2; ++k) \
;         acc[ai][bj][m][n] = __builtin_amdgcn_mfma_f32_16x16x32_bf16(Bt[n][k], At[m][k], acc[ai][bj][m][n], 0, 0, 0); __builtin_amdgcn_s_setprio(0); } while (0)
; #define PG8_WAIT_L(n) asm volatile("s_waitcnt lgkmcnt(" #n ")" ::: "memory")
; #define PG8_BAR __builtin_amdgcn_s_barrier()
; #define PG8_SCHED __builtin_amdgcn_sched_barrier(0)
; #define PG8_STAGE(bufoff, gbase, voff) do { _Pragma("unroll") for (int _i = 0; _i < 2; ++_i) \
;         __builtin_amdgcn_global_load_lds((const unsigned*)((const char*)(gbase) + (voff)[_i]), (LAS unsigned*)(lds + (bufoff) + ldsw + _i * 8192), 16, 0, 0); } while (0)
; template <class Epi0, class Epi1>
; DI void gemm_phase_dual(LAS unsigned char* lds, const Gemm g, const Gemm g1, const StaticOrder S, const Epi0 E0, const Epi1 E1) {
;     ...
;             const char* a2 = last ? nA : cA + (size_t)(t + 2) * kstep; const char* b2 = last ? nB : cB + (size_t)(t + 2) * kstep;
;             const char* a3 = a2 + kstep; const char* b3 = b2 + kstep;
;             PG8_LDB(B0, 0, 0); PG8_SCHED; PG8_LDA(At, 0, 0); PG8_STAGE(PG8_SA(1, 1), a1 + hstep, voffA);
;             PG8_WAIT_L(8); PG8_BAR; PG8_WAIT_L(0); PG8_MMA(0, 0, At, B0); PG8_BAR; PG8_SCHED;
;             PG8_LDB(B1, 0, 1); PG8_STAGE(PG8_SB(0, 0), b2, voffB);
;             PG8_BAR; PG8_WAIT_L(0); PG8_MMA(0, 1, At, B1); PG8_BAR;
;             PG8_LDA(At, 0, 1); PG8_STAGE(PG8_SA(0, 0), a2, voffA);
;             PG8_BAR; PG8_WAIT_L(0); PG8_MMA(1, 0, At, B0); PG8_BAR; PG8_SCHED;
.LBB0_708:
	ds_read_b128 v[156:159], v179
	ds_read_b128 v[160:163], v179 offset:1024
	ds_read_b128 v[164:167], v179 offset:2048
	ds_read_b128 v[168:171], v179 offset:3072
	s_add_u32 s40, s38, 0xfffc0080
	s_addc_u32 s41, s39, -1
	s_cmp_eq_u32 s69, 12
	s_cselect_b32 s43, s6, s41
	s_cselect_b32 s42, s7, s40
	s_cselect_b32 s41, s17, s68
	s_cselect_b32 s40, s19, s67
	v_lshl_add_u64 v[210:211], s[38:39], 0, v[148:149]
	s_add_i32 m0, s25, 0xc000
	ds_read_b128 v[172:175], v180
	ds_read_b128 v[182:185], v180 offset:1024
	ds_read_b128 v[186:189], v180 offset:2048
	ds_read_b128 v[190:193], v180 offset:3072
	ds_read_b128 v[194:197], v180 offset:4096
	ds_read_b128 v[198:201], v180 offset:5120
	ds_read_b128 v[202:205], v180 offset:6144
	ds_read_b128 v[206:209], v180 offset:7168
	global_load_lds_dwordx4 v[210:211], off
	v_lshl_add_u64 v[210:211], s[38:39], 0, v[150:151]
	s_add_i32 m0, s25, 0xe000
	s_nop 0
	global_load_lds_dwordx4 v[210:211], off
	s_waitcnt lgkmcnt(8)
	s_barrier
	s_waitcnt lgkmcnt(0)
	s_setprio 1
	s_waitcnt lgkmcnt(0)
	v_mfma_f32_16x16x32_bf16 v[124:127], v[156:159], v[172:175], v[124:127]
	v_mfma_f32_16x16x32_bf16 v[120:123], v[164:167], v[172:175], v[120:123]
	v_mfma_f32_16x16x32_bf16 v[108:111], v[156:159], v[186:189], v[108:111]
	v_mfma_f32_16x16x32_bf16 v[104:107], v[164:167], v[186:189], v[104:107]
	v_mfma_f32_16x16x32_bf16 v[92:95], v[156:159], v[194:197], v[92:95]
	v_mfma_f32_16x16x32_bf16 v[88:91], v[164:167], v[194:197], v[88:91]
	v_mfma_f32_16x16x32_bf16 v[84:87], v[156:159], v[202:205], v[84:87]
	v_mfma_f32_16x16x32_bf16 v[80:83], v[164:167], v[202:205], v[80:83]
	v_mfma_f32_16x16x32_bf16 v[124:127], v[160:163], v[182:185], v[124:127]
	v_mfma_f32_16x16x32_bf16 v[120:123], v[168:171], v[182:185], v[120:123]
	v_mfma_f32_16x16x32_bf16 v[108:111], v[160:163], v[190:193], v[108:111]
	v_mfma_f32_16x16x32_bf16 v[104:107], v[168:171], v[190:193], v[104:107]
	v_mfma_f32_16x16x32_bf16 v[92:95], v[160:163], v[198:201], v[92:95]
	v_mfma_f32_16x16x32_bf16 v[88:91], v[168:171], v[198:201], v[88:91]
	v_mfma_f32_16x16x32_bf16 v[84:87], v[160:163], v[206:209], v[84:87]
	v_mfma_f32_16x16x32_bf16 v[80:83], v[168:171], v[206:209], v[80:83]
	s_setprio 0
	s_barrier
	s_add_i32 s76, s52, s44
	v_lshl_add_u64 v[228:229], s[40:41], 0, v[130:131]
	s_mov_b32 m0, s76
	ds_read_b128 v[210:213], v181
	ds_read_b128 v[214:217], v181 offset:1024
	ds_read_b128 v[218:221], v181 offset:2048
	ds_read_b128 v[224:227], v181 offset:3072
	global_load_lds_dwordx4 v[228:229], off
	v_lshl_add_u64 v[230:231], s[40:41], 0, v[134:135]
	s_add_i32 m0, s76, 0x2000
	s_nop 0
	global_load_lds_dwordx4 v[230:231], off
	s_barrier
	s_waitcnt lgkmcnt(0)
	s_setprio 1
	s_waitcnt lgkmcnt(0)
	v_mfma_f32_16x16x32_bf16 v[116:119], v[210:213], v[172:175], v[116:119]
	v_mfma_f32_16x16x32_bf16 v[112:115], v[218:221], v[172:175], v[112:115]
	v_mfma_f32_16x16x32_bf16 v[100:103], v[210:213], v[186:189], v[100:103]
	v_mfma_f32_16x16x32_bf16 v[96:99], v[218:221], v[186:189], v[96:99]
	v_mfma_f32_16x16x32_bf16 v[76:79], v[210:213], v[194:197], v[76:79]
	v_mfma_f32_16x16x32_bf16 v[72:75], v[218:221], v[194:197], v[72:75]
	v_mfma_f32_16x16x32_bf16 v[68:71], v[210:213], v[202:205], v[68:71]
	v_mfma_f32_16x16x32_bf16 v[64:67], v[218:221], v[202:205], v[64:67]
	v_mfma_f32_16x16x32_bf16 v[116:119], v[214:217], v[182:185], v[116:119]
	v_mfma_f32_16x16x32_bf16 v[112:115], v[224:227], v[182:185], v[112:115]
	v_mfma_f32_16x16x32_bf16 v[100:103], v[214:217], v[190:193], v[100:103]
	v_mfma_f32_16x16x32_bf16 v[96:99], v[224:227], v[190:193], v[96:99]
	v_mfma_f32_16x16x32_bf16 v[76:79], v[214:217], v[198:201], v[76:79]
	v_mfma_f32_16x16x32_bf16 v[72:75], v[224:227], v[198:201], v[72:75]
	v_mfma_f32_16x16x32_bf16 v[68:71], v[214:217], v[206:209], v[68:71]
	v_mfma_f32_16x16x32_bf16 v[64:67], v[224:227], v[206:209], v[64:67]
	s_setprio 0
	s_mov_b32 m0, s25
	v_lshl_add_u64 v[232:233], s[42:43], 0, v[128:129]
	s_barrier
	ds_read_b128 v[172:175], v180 offset:16384
	ds_read_b128 v[182:185], v180 offset:17408
	ds_read_b128 v[186:189], v180 offset:18432
	ds_read_b128 v[190:193], v180 offset:19456
	ds_read_b128 v[194:197], v180 offset:20480
	ds_read_b128 v[198:201], v180 offset:21504
	ds_read_b128 v[202:205], v180 offset:22528
	ds_read_b128 v[206:209], v180 offset:23552
	global_load_lds_dwordx4 v[232:233], off
	v_lshl_add_u64 v[234:235], s[42:43], 0, v[132:133]
	s_mov_b32 m0, s45
	s_nop 0
	global_load_lds_dwordx4 v[234:235], off
	s_barrier
	s_waitcnt lgkmcnt(0)
	s_setprio 1
	s_waitcnt lgkmcnt(0)
	v_mfma_f32_16x16x32_bf16 v[60:63], v[156:159], v[172:175], v[60:63]
	v_mfma_f32_16x16x32_bf16 v[56:59], v[164:167], v[172:175], v[56:59]
	v_mfma_f32_16x16x32_bf16 v[52:55], v[156:159], v[186:189], v[52:55]
	v_mfma_f32_16x16x32_bf16 v[48:51], v[164:167], v[186:189], v[48:51]
	v_mfma_f32_16x16x32_bf16 v[28:31], v[156:159], v[194:197], v[28:31]
	v_mfma_f32_16x16x32_bf16 v[24:27], v[164:167], v[194:197], v[24:27]
	v_mfma_f32_16x16x32_bf16 v[20:23], v[156:159], v[202:205], v[20:23]
	v_mfma_f32_16x16x32_bf16 v[16:19], v[164:167], v[202:205], v[16:19]
	v_mfma_f32_16x16x32_bf16 v[60:63], v[160:163], v[182:185], v[60:63]
	v_mfma_f32_16x16x32_bf16 v[56:59], v[168:171], v[182:185], v[56:59]
	v_mfma_f32_16x16x32_bf16 v[52:55], v[160:163], v[190:193], v[52:55]
	v_mfma_f32_16x16x32_bf16 v[48:51], v[168:171], v[190:193], v[48:51]
	v_mfma_f32_16x16x32_bf16 v[28:31], v[160:163], v[198:201], v[28:31]
	v_mfma_f32_16x16x32_bf16 v[24:27], v[168:171], v[198:201], v[24:27]
	v_mfma_f32_16x16x32_bf16 v[20:23], v[160:163], v[206:209], v[20:23]
	v_mfma_f32_16x16x32_bf16 v[16:19], v[168:171], v[206:209], v[16:19]
	s_setprio 0
	s_barrier
; #define PG8_STAGE(bufoff, gbase, voff) do { _Pragma("unroll") for (int _i = 0; _i < 2; ++_i) \
;         __builtin_amdgcn_global_load_lds((const unsigned*)((const char*)(gbase) + (voff)[_i]), (LAS unsigned*)(lds + (bufoff) + ldsw + _i * 8192), 16, 0, 0); } while (0)
; #define PG8_LDA(dst, b, h) do { _Pragma("unroll") for (int m = 0; m < 4; ++m) _Pragma("unroll") for (int k = 0; k < 2; ++k) dst[m][k] = *(const LAS bf16x8*)(lds + PG8_SA(b, h) + aoff + m * 2048 + k * 1024); } while (0)
; #define PG8_LDB(dst, b, h) do { _Pragma("unroll") for (int n = 0; n < 2; ++n) _Pragma("unroll") for (int k = 0; k < 2; ++k) dst[n][k] = *(const LAS bf16x8*)(lds + PG8_SB(b, h) + boff + n * 2048 + k * 1024); } while (0)
; #define PG8_MMA(ai, bj, At, Bt) do { __builtin_amdgcn_s_setprio(1); _Pragma("unroll") for (int m = 0; m < 4; ++m) _Pragma("unroll") for (int n = 0; n < 2; ++n) _Pragma("unroll") for (int k = 0; k < 2; ++k) \
;         acc[ai][bj][m][n] = __builtin_amdgcn_mfma_f32_16x16x32_bf16(Bt[n][k], At[m][k], acc[ai][bj][m][n], 0, 0, 0); __builtin_amdgcn_s_setprio(0); } while (0)
; #define PG8_WAIT_V(n) asm volatile("s_waitcnt vmcnt(" #n ")" ::: "memory")
; #define PG8_WAIT_L(n) asm volatile("s_waitcnt lgkmcnt(" #n ")" ::: "memory")
; #define PG8_BAR __builtin_amdgcn_s_barrier()
; #define PG8_SCHED __builtin_amdgcn_sched_barrier(0)
; #define PG8_STAGE(bufoff, gbase, voff) do { _Pragma("unroll") for (int _i = 0; _i < 2; ++_i) \
;         __builtin_amdgcn_global_load_lds((const unsigned*)((const char*)(gbase) + (voff)[_i]), (LAS unsigned*)(lds + (bufoff) + ldsw + _i * 8192), 16, 0, 0); } while (0)
; #define PG8_WAIT_V(n) asm volatile("s_waitcnt vmcnt(" #n ")" ::: "memory")
; template <class Epi0, class Epi1>
; DI void gemm_phase_dual(LAS unsigned char* lds, const Gemm g, const Gemm g1, const StaticOrder S, const Epi0 E0, const Epi1 E1) {
;     ...
;             PG8_STAGE(PG8_SB(0, 1), b2 + hstep, voffB);
;             PG8_WAIT_V(6); PG8_BAR; PG8_MMA(1, 1, At, B1); PG8_BAR;
;             PG8_LDB(B0, 1, 0); PG8_SCHED; PG8_LDA(At, 1, 0); PG8_STAGE(PG8_SA(0, 1), a2 + hstep, voffA);
;             PG8_WAIT_L(8); PG8_BAR; PG8_WAIT_L(0); PG8_MMA(0, 0, At, B0); PG8_BAR; PG8_SCHED;
;             PG8_LDB(B1, 1, 1); PG8_STAGE(PG8_SB(1, 0), b3, voffB);
;             PG8_BAR; PG8_WAIT_L(0); PG8_MMA(0, 1, At, B1); PG8_BAR;
;             PG8_LDA(At, 1, 1); PG8_STAGE(PG8_SA(1, 0), a3, voffA);
	s_add_u32 s76, s40, 0x40000
	s_addc_u32 s77, s41, 0
	s_add_i32 s78, s53, s44
	v_lshl_add_u64 v[156:157], s[76:77], 0, v[130:131]
	s_mov_b32 m0, s78
	s_nop 0
	global_load_lds_dwordx4 v[156:157], off
	v_lshl_add_u64 v[156:157], s[76:77], 0, v[134:135]
	s_add_i32 m0, s78, 0x2000
	s_nop 0
	global_load_lds_dwordx4 v[156:157], off
	s_waitcnt vmcnt(6)
	s_barrier
	s_setprio 1
	v_mfma_f32_16x16x32_bf16 v[44:47], v[210:213], v[172:175], v[44:47]
	v_mfma_f32_16x16x32_bf16 v[40:43], v[218:221], v[172:175], v[40:43]
	v_mfma_f32_16x16x32_bf16 v[36:39], v[210:213], v[186:189], v[36:39]
	v_mfma_f32_16x16x32_bf16 v[32:35], v[218:221], v[186:189], v[32:35]
	v_mfma_f32_16x16x32_bf16 v[12:15], v[210:213], v[194:197], v[12:15]
	v_mfma_f32_16x16x32_bf16 v[8:11], v[218:221], v[194:197], v[8:11]
	v_mfma_f32_16x16x32_bf16 v[4:7], v[210:213], v[202:205], v[4:7]
	v_mfma_f32_16x16x32_bf16 v[0:3], v[218:221], v[202:205], v[0:3]
	v_mfma_f32_16x16x32_bf16 v[44:47], v[214:217], v[182:185], v[44:47]
	v_mfma_f32_16x16x32_bf16 v[40:43], v[224:227], v[182:185], v[40:43]
	v_mfma_f32_16x16x32_bf16 v[36:39], v[214:217], v[190:193], v[36:39]
	v_mfma_f32_16x16x32_bf16 v[32:35], v[224:227], v[190:193], v[32:35]
	v_mfma_f32_16x16x32_bf16 v[12:15], v[214:217], v[198:201], v[12:15]
	v_mfma_f32_16x16x32_bf16 v[8:11], v[224:227], v[198:201], v[8:11]
	v_mfma_f32_16x16x32_bf16 v[4:7], v[214:217], v[206:209], v[4:7]
	v_mfma_f32_16x16x32_bf16 v[0:3], v[224:227], v[206:209], v[0:3]
	s_setprio 0
	s_add_i32 s76, 0, 0x18000
	v_add_u32_e32 v168, s76, v177
	s_barrier
	ds_read_b128 v[156:159], v168
	ds_read_b128 v[160:163], v168 offset:1024
	ds_read_b128 v[164:167], v168 offset:2048
	ds_read_b128 v[168:171], v168 offset:3072
	s_add_u32 s42, s42, 0x40000
	s_addc_u32 s43, s43, 0
	s_mov_b32 m0, s46
	v_lshl_add_u64 v[210:211], s[42:43], 0, v[128:129]
	ds_read_b128 v[172:175], v180 offset:32768
	ds_read_b128 v[182:185], v180 offset:33792
	ds_read_b128 v[186:189], v180 offset:34816
	ds_read_b128 v[190:193], v180 offset:35840
	ds_read_b128 v[194:197], v180 offset:36864
	ds_read_b128 v[198:201], v180 offset:37888
	ds_read_b128 v[202:205], v180 offset:38912
	ds_read_b128 v[206:209], v180 offset:39936
	global_load_lds_dwordx4 v[210:211], off
	v_lshl_add_u64 v[210:211], s[42:43], 0, v[132:133]
	s_mov_b32 m0, s47
	s_nop 0
	global_load_lds_dwordx4 v[210:211], off
	s_waitcnt lgkmcnt(8)
	s_barrier
	s_waitcnt lgkmcnt(0)
	s_setprio 1
	s_waitcnt lgkmcnt(0)
	v_mfma_f32_16x16x32_bf16 v[124:127], v[156:159], v[172:175], v[124:127]
	v_mfma_f32_16x16x32_bf16 v[120:123], v[164:167], v[172:175], v[120:123]
	v_mfma_f32_16x16x32_bf16 v[108:111], v[156:159], v[186:189], v[108:111]
	v_mfma_f32_16x16x32_bf16 v[104:107], v[164:167], v[186:189], v[104:107]
	v_mfma_f32_16x16x32_bf16 v[92:95], v[156:159], v[194:197], v[92:95]
	v_mfma_f32_16x16x32_bf16 v[88:91], v[164:167], v[194:197], v[88:91]
	v_mfma_f32_16x16x32_bf16 v[84:87], v[156:159], v[202:205], v[84:87]
	v_mfma_f32_16x16x32_bf16 v[80:83], v[164:167], v[202:205], v[80:83]
	v_mfma_f32_16x16x32_bf16 v[124:127], v[160:163], v[182:185], v[124:127]
	v_mfma_f32_16x16x32_bf16 v[120:123], v[168:171], v[182:185], v[120:123]
	v_mfma_f32_16x16x32_bf16 v[108:111], v[160:163], v[190:193], v[108:111]
	v_mfma_f32_16x16x32_bf16 v[104:107], v[168:171], v[190:193], v[104:107]
	v_mfma_f32_16x16x32_bf16 v[92:95], v[160:163], v[198:201], v[92:95]
	v_mfma_f32_16x16x32_bf16 v[88:91], v[168:171], v[198:201], v[88:91]
	v_mfma_f32_16x16x32_bf16 v[84:87], v[160:163], v[206:209], v[84:87]
	v_mfma_f32_16x16x32_bf16 v[80:83], v[168:171], v[206:209], v[80:83]
	s_setprio 0
	s_barrier
	s_add_i32 s42, 0, 0x1c000
	s_add_i32 s43, s76, s44
	v_add_u32_e32 v224, s42, v177
	v_lshl_add_u64 v[228:229], v[228:229], 0, s[8:9]
	s_mov_b32 m0, s43
	ds_read_b128 v[210:213], v224
	ds_read_b128 v[214:217], v224 offset:1024
	ds_read_b128 v[218:221], v224 offset:2048
	ds_read_b128 v[224:227], v224 offset:3072
	global_load_lds_dwordx4 v[228:229], off
	v_lshl_add_u64 v[228:229], v[230:231], 0, s[8:9]
	s_add_i32 m0, s43, 0x2000
	s_nop 0
	global_load_lds_dwordx4 v[228:229], off
	s_barrier
	s_waitcnt lgkmcnt(0)
	s_setprio 1
	s_waitcnt lgkmcnt(0)
	v_mfma_f32_16x16x32_bf16 v[116:119], v[210:213], v[172:175], v[116:119]
	v_mfma_f32_16x16x32_bf16 v[112:115], v[218:221], v[172:175], v[112:115]
	v_mfma_f32_16x16x32_bf16 v[100:103], v[210:213], v[186:189], v[100:103]
	v_mfma_f32_16x16x32_bf16 v[96:99], v[218:221], v[186:189], v[96:99]
	v_mfma_f32_16x16x32_bf16 v[76:79], v[210:213], v[194:197], v[76:79]
	v_mfma_f32_16x16x32_bf16 v[72:75], v[218:221], v[194:197], v[72:75]
	v_mfma_f32_16x16x32_bf16 v[68:71], v[210:213], v[202:205], v[68:71]
	v_mfma_f32_16x16x32_bf16 v[64:67], v[218:221], v[202:205], v[64:67]
	v_mfma_f32_16x16x32_bf16 v[116:119], v[214:217], v[182:185], v[116:119]
	v_mfma_f32_16x16x32_bf16 v[112:115], v[224:227], v[182:185], v[112:115]
	v_mfma_f32_16x16x32_bf16 v[100:103], v[214:217], v[190:193], v[100:103]
	v_mfma_f32_16x16x32_bf16 v[96:99], v[224:227], v[190:193], v[96:99]
	v_mfma_f32_16x16x32_bf16 v[76:79], v[214:217], v[198:201], v[76:79]
	v_mfma_f32_16x16x32_bf16 v[72:75], v[224:227], v[198:201], v[72:75]
	v_mfma_f32_16x16x32_bf16 v[68:71], v[214:217], v[206:209], v[68:71]
	v_mfma_f32_16x16x32_bf16 v[64:67], v[224:227], v[206:209], v[64:67]
	s_setprio 0
	s_mov_b32 m0, s59
	v_lshl_add_u64 v[228:229], v[232:233], 0, s[8:9]
	s_barrier
	ds_read_b128 v[172:175], v180 offset:49152
	ds_read_b128 v[182:185], v180 offset:50176
	ds_read_b128 v[186:189], v180 offset:51200
	ds_read_b128 v[190:193], v180 offset:52224
	ds_read_b128 v[194:197], v180 offset:53248
	ds_read_b128 v[198:201], v180 offset:54272
	ds_read_b128 v[202:205], v180 offset:55296
	ds_read_b128 v[206:209], v180 offset:56320
	global_load_lds_dwordx4 v[228:229], off
	v_lshl_add_u64 v[228:229], v[234:235], 0, s[8:9]
	s_mov_b32 m0, s60
	s_nop 0
	global_load_lds_dwordx4 v[228:229], off
	s_barrier
; #define PG8_STAGE(bufoff, gbase, voff) do { _Pragma("unroll") for (int _i = 0; _i < 2; ++_i) \
;         __builtin_amdgcn_global_load_lds((const unsigned*)((const char*)(gbase) + (voff)[_i]), (LAS unsigned*)(lds + (bufoff) + ldsw + _i * 8192), 16, 0, 0); } while (0)
; #define PG8_MMA(ai, bj, At, Bt) do { __builtin_amdgcn_s_setprio(1); _Pragma("unroll") for (int m = 0; m < 4; ++m) _Pragma("unroll") for (int n = 0; n < 2; ++n) _Pragma("unroll") for (int k = 0; k < 2; ++k) \
;         acc[ai][bj][m][n] = __builtin_amdgcn_mfma_f32_16x16x32_bf16(Bt[n][k], At[m][k], acc[ai][bj][m][n], 0, 0, 0); __builtin_amdgcn_s_setprio(0); } while (0)
; #define PG8_WAIT_V(n) asm volatile("s_waitcnt vmcnt(" #n ")" ::: "memory")
; #define PG8_WAIT_L(n) asm volatile("s_waitcnt lgkmcnt(" #n ")" ::: "memory")
; #define PG8_BAR __builtin_amdgcn_s_barrier()
; #define PG8_SCHED __builtin_amdgcn_sched_barrier(0)
; #define PG8_BAR __builtin_amdgcn_s_barrier()
; template <class Epi0, class Epi1>
; DI void gemm_phase_dual(LAS unsigned char* lds, const Gemm g, const Gemm g1, const StaticOrder S, const Epi0 E0, const Epi1 E1) {
;     ...
;             PG8_BAR; PG8_WAIT_L(0); PG8_MMA(1, 0, At, B0); PG8_BAR; PG8_SCHED;
;             PG8_STAGE(PG8_SB(1, 1), b3 + hstep, voffB);
;             PG8_WAIT_V(6); PG8_BAR; PG8_MMA(1, 1, At, B1); PG8_BAR;
;         }
;         if (ui & 1) E1(acc, cur, wr, wc, fr, fq); else E0(acc, cur, wr, wc, fr, fq);
;         if (!has_next) break;
; #pragma unroll
;     DI void operator()(AccRef acc, const Unit& u, int wr, int wc, int fr, int fq) const {
;         const int row0 = u.pm * 256 + wr * 64 + fr, col0 = u.pn * 256 + wc * 32 + 8 * fq;
; #pragma unroll
;         for (int ai = 0; ai < 2; ++ai)
; #pragma unroll
;             for (int mh = 0; mh < 2; ++mh) {
;                 u32x4 gv[2][2], mv[2][2];
; #pragma unroll
;                 for (int mm = 0; mm < 2; ++mm)
; #pragma unroll
;                     for (int bj = 0; bj < 2; ++bj) {
;                         const size_t row = (size_t)(row0 + ai * 128 + (mh * 2 + mm) * 16); const int col = col0 + bj * 128;
;                         gv[mm][bj] = *(const u32x4*)(gab + (size_t)(u.pm * 8 + SECOND * 4 + u.pn) * 65536 + (wr * 64 + fr + ai * 128 + (mh * 2 + mm) * 16) * 256 + wc * 32 + 8 * fq + bj * 128);
;                         if (SECOND) mv[mm][bj] = *(const u32x4*)(mrg + row * 1024 + col);
;                     }
	s_waitcnt lgkmcnt(0)
	s_setprio 1
	s_waitcnt lgkmcnt(0)
	v_mfma_f32_16x16x32_bf16 v[60:63], v[156:159], v[172:175], v[60:63]
	v_mfma_f32_16x16x32_bf16 v[56:59], v[164:167], v[172:175], v[56:59]
	v_mfma_f32_16x16x32_bf16 v[52:55], v[156:159], v[186:189], v[52:55]
	v_mfma_f32_16x16x32_bf16 v[48:51], v[164:167], v[186:189], v[48:51]
	v_mfma_f32_16x16x32_bf16 v[28:31], v[156:159], v[194:197], v[28:31]
	v_mfma_f32_16x16x32_bf16 v[24:27], v[164:167], v[194:197], v[24:27]
	v_mfma_f32_16x16x32_bf16 v[20:23], v[156:159], v[202:205], v[20:23]
	v_mfma_f32_16x16x32_bf16 v[16:19], v[164:167], v[202:205], v[16:19]
	v_mfma_f32_16x16x32_bf16 v[60:63], v[160:163], v[182:185], v[60:63]
	v_mfma_f32_16x16x32_bf16 v[56:59], v[168:171], v[182:185], v[56:59]
	v_mfma_f32_16x16x32_bf16 v[52:55], v[160:163], v[190:193], v[52:55]
	v_mfma_f32_16x16x32_bf16 v[48:51], v[168:171], v[190:193], v[48:51]
	v_mfma_f32_16x16x32_bf16 v[28:31], v[160:163], v[198:201], v[28:31]
	v_mfma_f32_16x16x32_bf16 v[24:27], v[168:171], v[198:201], v[24:27]
	v_mfma_f32_16x16x32_bf16 v[20:23], v[160:163], v[206:209], v[20:23]
	v_mfma_f32_16x16x32_bf16 v[16:19], v[168:171], v[206:209], v[16:19]
	s_setprio 0
	s_barrier
	s_add_u32 s40, s40, 0x40080
	s_addc_u32 s41, s41, 0
	s_add_i32 s42, s42, s44
	v_lshl_add_u64 v[156:157], s[40:41], 0, v[130:131]
	s_mov_b32 m0, s42
	s_nop 0
	global_load_lds_dwordx4 v[156:157], off
	v_lshl_add_u64 v[156:157], s[40:41], 0, v[134:135]
	s_add_i32 m0, s42, 0x2000
	s_nop 0
	global_load_lds_dwordx4 v[156:157], off
	s_waitcnt vmcnt(6)
	s_barrier
	s_setprio 1
	v_mfma_f32_16x16x32_bf16 v[44:47], v[210:213], v[172:175], v[44:47]
	v_mfma_f32_16x16x32_bf16 v[40:43], v[218:221], v[172:175], v[40:43]
	v_mfma_f32_16x16x32_bf16 v[36:39], v[210:213], v[186:189], v[36:39]
	v_mfma_f32_16x16x32_bf16 v[32:35], v[218:221], v[186:189], v[32:35]
	v_mfma_f32_16x16x32_bf16 v[12:15], v[210:213], v[194:197], v[12:15]
	v_mfma_f32_16x16x32_bf16 v[8:11], v[218:221], v[194:197], v[8:11]
	v_mfma_f32_16x16x32_bf16 v[4:7], v[210:213], v[202:205], v[4:7]
	v_mfma_f32_16x16x32_bf16 v[0:3], v[218:221], v[202:205], v[0:3]
	v_mfma_f32_16x16x32_bf16 v[44:47], v[214:217], v[182:185], v[44:47]
	v_mfma_f32_16x16x32_bf16 v[40:43], v[224:227], v[182:185], v[40:43]
	v_mfma_f32_16x16x32_bf16 v[36:39], v[214:217], v[190:193], v[36:39]
	v_mfma_f32_16x16x32_bf16 v[32:35], v[224:227], v[190:193], v[32:35]
	v_mfma_f32_16x16x32_bf16 v[12:15], v[214:217], v[198:201], v[12:15]
	v_mfma_f32_16x16x32_bf16 v[8:11], v[224:227], v[198:201], v[8:11]
	v_mfma_f32_16x16x32_bf16 v[4:7], v[214:217], v[206:209], v[4:7]
	v_mfma_f32_16x16x32_bf16 v[0:3], v[224:227], v[206:209], v[0:3]
	s_setprio 0
	s_add_i32 s69, s69, 2
	s_add_u32 s38, s38, 0x100
	s_addc_u32 s39, s39, 0
	s_add_u32 s67, s67, 0x100
	s_addc_u32 s68, s68, 0
	s_cmp_gt_u32 s69, 13
	s_barrier
	s_cbranch_scc0 .LBB0_708
	v_lshl_add_u32 v164, s24, 8, v176
	s_lshl_b32 s17, s66, 8
	v_or_b32_e32 v162, s17, v178
	v_or_b32_e32 v160, 16, v164
	s_mov_b64 s[6:7], -1
	s_and_b64 vcc, exec, s[28:29]
	v_ashrrev_i32_e32 v165, 31, v164
	v_ashrrev_i32_e32 v163, 31, v162
	v_ashrrev_i32_e32 v161, 31, v160
	v_or_b32_e32 v158, 32, v164
	v_or_b32_e32 v156, 48, v164
	s_cbranch_vccz .LBB0_711
	s_lshl_b32 s6, s24, 3
	s_add_i32 s6, s66, s6
	s_add_i32 s6, s6, 4
	v_lshlrev_b64 v[168:169], 11, v[160:161]
	s_ashr_i32 s7, s6, 31
	v_lshlrev_b64 v[166:167], 11, v[164:165]
	v_lshlrev_b64 v[170:171], 1, v[162:163]
	v_lshl_add_u64 v[168:169], s[36:37], 0, v[168:169]
	s_lshl_b64 s[6:7], s[6:7], 17
	v_lshl_add_u64 v[166:167], s[36:37], 0, v[166:167]
	v_lshl_add_u64 v[174:175], v[168:169], 0, v[170:171]
	v_lshl_add_u64 v[168:169], v[136:137], 0, s[6:7]
	v_lshl_add_u64 v[166:167], v[166:167], 0, v[170:171]
	v_lshl_add_u64 v[172:173], v[138:139], 1, v[168:169]
	global_load_dwordx4 v[182:185], v[166:167], off
	global_load_dwordx4 v[186:189], v[166:167], off offset:256
	global_load_dwordx4 v[190:193], v[174:175], off
	global_load_dwordx4 v[194:197], v[172:173], off
	global_load_dwordx4 v[198:201], v[172:173], off offset:256
	v_add_co_u32_e32 v206, vcc, s48, v172
	v_ashrrev_i32_e32 v159, 31, v158
	s_nop 0
	v_addc_co_u32_e32 v207, vcc, 0, v173, vcc
	global_load_dwordx4 v[202:205], v[206:207], off
	s_nop 0
	global_load_dwordx4 v[206:209], v[206:207], off offset:256
	s_nop 0
	global_load_dwordx4 v[210:213], v[174:175], off offset:256
	v_ashrrev_i32_e32 v157, 31, v156
	s_mov_b64 s[6:7], 0
	s_waitcnt vmcnt(0)
; DI unsigned pk_bf16(float lo, float hi) { f32x2 v = {lo, hi}; return __builtin_bit_cast(unsigned, __builtin_convertvector(v, bf16v2)); }
; DI float bf_lo(unsigned w) { return __uint_as_float(w << 16); }
; DI float bf_hi(unsigned w) { return __uint_as_float(w & 0xffff0000u); }
;     DI void operator()(AccRef acc, const Unit& u, int wr, int wc, int fr, int fq) const {
;     ...
;                 for (int mm = 0; mm < 2; ++mm)
; #pragma unroll
;                     for (int bj = 0; bj < 2; ++bj) {
;                         const size_t row = (size_t)(row0 + ai * 128 + (mh * 2 + mm) * 16); const int col = col0 + bj * 128;
;                         gv[mm][bj] = *(const u32x4*)(gab + (size_t)(u.pm * 8 + SECOND * 4 + u.pn) * 65536 + (wr * 64 + fr + ai * 128 + (mh * 2 + mm) * 16) * 256 + wc * 32 + 8 * fq + bj * 128);
;                         if (SECOND) mv[mm][bj] = *(const u32x4*)(mrg + row * 1024 + col);
;                     }
; #pragma unroll
;                 for (int mm = 0; mm < 2; ++mm)
; #pragma unroll
;                     for (int bj = 0; bj < 2; ++bj) {
;                         const int m = mh * 2 + mm;
;                         const size_t row = (size_t)(row0 + ai * 128 + m * 16); const int col = col0 + bj * 128;
;                         const u32x4 gt = gv[mm][bj];
;                         const f32x4 r0 = acc[ai][bj][m][0], r1 = acc[ai][bj][m][1];
;                         float v[8] = {bf_lo(gt.x) * r0[0], bf_hi(gt.x) * r0[1], bf_lo(gt.y) * r0[2], bf_hi(gt.y) * r0[3], bf_lo(gt.z) * r1[0], bf_hi(gt.z) * r1[1], bf_lo(gt.w) * r1[2], bf_hi(gt.w) * r1[3]};
;                         if (SECOND) { const u32x4 o = mv[mm][bj]; v[0] += bf_lo(o.x); v[1] += bf_hi(o.x); v[2] += bf_lo(o.y); v[3] += bf_hi(o.y); v[4] += bf_lo(o.z); v[5] += bf_hi(o.z); v[6] += bf_lo(o.w); v[7] += bf_hi(o.w); }
;                         u32x4 w; w.x = pk_bf16(v[0], v[1]); w.y = pk_bf16(v[2], v[3]); w.z = pk_bf16(v[4], v[5]); w.w = pk_bf16(v[6], v[7]);
;                         *(u32x4*)(mrg + row * 1024 + col) = w;
	v_lshlrev_b32_e32 v214, 16, v182
	v_and_b32_e32 v215, 0xffff0000, v182
	v_lshlrev_b32_e32 v182, 16, v183
	v_and_b32_e32 v183, 0xffff0000, v183
	v_lshlrev_b32_e32 v216, 16, v184
	v_and_b32_e32 v217, 0xffff0000, v184
	v_lshlrev_b32_e32 v184, 16, v185
	v_and_b32_e32 v185, 0xffff0000, v185
	v_lshlrev_b32_e32 v228, 16, v194
	v_and_b32_e32 v229, 0xffff0000, v194
	v_lshlrev_b32_e32 v194, 16, v195
	v_and_b32_e32 v195, 0xffff0000, v195
	v_lshlrev_b32_e32 v230, 16, v196
	v_and_b32_e32 v231, 0xffff0000, v196
	v_lshlrev_b32_e32 v196, 16, v197
	v_and_b32_e32 v197, 0xffff0000, v197
	v_lshlrev_b32_e32 v218, 16, v186
	v_and_b32_e32 v219, 0xffff0000, v186
	v_lshlrev_b32_e32 v186, 16, v187
	v_and_b32_e32 v187, 0xffff0000, v187
	v_lshlrev_b32_e32 v220, 16, v188
	v_and_b32_e32 v221, 0xffff0000, v188
	v_lshlrev_b32_e32 v188, 16, v189
	v_and_b32_e32 v189, 0xffff0000, v189
	v_lshlrev_b32_e32 v232, 16, v198
	v_and_b32_e32 v233, 0xffff0000, v198
	v_lshlrev_b32_e32 v198, 16, v199
	v_and_b32_e32 v199, 0xffff0000, v199
	v_lshlrev_b32_e32 v234, 16, v200
	v_and_b32_e32 v235, 0xffff0000, v200
	v_lshlrev_b32_e32 v200, 16, v201
	v_and_b32_e32 v201, 0xffff0000, v201
	v_pk_fma_f32 v[214:215], v[124:125], v[228:229], v[214:215]
	v_pk_fma_f32 v[194:195], v[126:127], v[194:195], v[182:183]
	v_pk_fma_f32 v[216:217], v[120:121], v[230:231], v[216:217]
	v_pk_fma_f32 v[196:197], v[122:123], v[196:197], v[184:185]
	v_pk_fma_f32 v[218:219], v[116:117], v[232:233], v[218:219]
	v_pk_fma_f32 v[198:199], v[118:119], v[198:199], v[186:187]
	v_pk_fma_f32 v[220:221], v[112:113], v[234:235], v[220:221]
	v_pk_fma_f32 v[200:201], v[114:115], v[200:201], v[188:189]
	v_cvt_pk_bf16_f32 v182, v214, v215
	v_cvt_pk_bf16_f32 v183, v194, v195
	v_cvt_pk_bf16_f32 v184, v216, v217
	v_cvt_pk_bf16_f32 v185, v196, v197
	v_lshlrev_b32_e32 v224, 16, v190
	v_and_b32_e32 v225, 0xffff0000, v190
	v_lshlrev_b32_e32 v190, 16, v191
	v_and_b32_e32 v191, 0xffff0000, v191
	v_lshlrev_b32_e32 v226, 16, v192
	v_and_b32_e32 v227, 0xffff0000, v192
	v_lshlrev_b32_e32 v228, 16, v202
	v_and_b32_e32 v229, 0xffff0000, v202
	v_lshlrev_b32_e32 v202, 16, v203
	v_and_b32_e32 v203, 0xffff0000, v203
	v_lshlrev_b32_e32 v230, 16, v204
	v_and_b32_e32 v231, 0xffff0000, v204
	v_cvt_pk_bf16_f32 v186, v218, v219
	v_cvt_pk_bf16_f32 v187, v198, v199
	v_cvt_pk_bf16_f32 v188, v220, v221
	v_cvt_pk_bf16_f32 v189, v200, v201
	global_store_dwordx4 v[166:167], v[182:185], off
	global_store_dwordx4 v[166:167], v[186:189], off offset:256
	v_pk_fma_f32 v[194:195], v[108:109], v[228:229], v[224:225]
	v_lshlrev_b32_e32 v182, 16, v205
	v_and_b32_e32 v183, 0xffff0000, v205
	v_lshlrev_b32_e32 v184, 16, v193
	v_and_b32_e32 v185, 0xffff0000, v193
	v_pk_fma_f32 v[190:191], v[110:111], v[202:203], v[190:191]
	v_pk_fma_f32 v[196:197], v[104:105], v[230:231], v[226:227]
	v_pk_fma_f32 v[186:187], v[106:107], v[182:183], v[184:185]
	v_cvt_pk_bf16_f32 v182, v194, v195
	v_cvt_pk_bf16_f32 v183, v190, v191
	v_cvt_pk_bf16_f32 v184, v196, v197
	v_cvt_pk_bf16_f32 v185, v186, v187
	global_store_dwordx4 v[174:175], v[182:185], off
	v_lshlrev_b32_e32 v186, 16, v211
	v_and_b32_e32 v187, 0xffff0000, v211
	v_lshlrev_b32_e32 v182, 16, v206
	v_and_b32_e32 v183, 0xffff0000, v206
	v_lshlrev_b32_e32 v184, 16, v210
	v_and_b32_e32 v185, 0xffff0000, v210
	v_pk_fma_f32 v[182:183], v[100:101], v[182:183], v[184:185]
	v_lshlrev_b32_e32 v184, 16, v207
	v_and_b32_e32 v185, 0xffff0000, v207
	v_pk_fma_f32 v[184:185], v[102:103], v[184:185], v[186:187]
	v_lshlrev_b32_e32 v186, 16, v208
	v_and_b32_e32 v187, 0xffff0000, v208
	v_lshlrev_b32_e32 v188, 16, v212
	v_and_b32_e32 v189, 0xffff0000, v212
	v_pk_fma_f32 v[190:191], v[96:97], v[186:187], v[188:189]
	v_lshlrev_b32_e32 v186, 16, v209
	v_and_b32_e32 v187, 0xffff0000, v209
	v_lshlrev_b32_e32 v188, 16, v213
	v_and_b32_e32 v189, 0xffff0000, v213
	v_cvt_pk_bf16_f32 v182, v182, v183
	v_cvt_pk_bf16_f32 v183, v184, v185
	v_lshlrev_b64 v[184:185], 11, v[158:159]
	v_pk_fma_f32 v[192:193], v[98:99], v[186:187], v[188:189]
	v_lshl_add_u64 v[184:185], s[36:37], 0, v[184:185]
	v_lshl_add_u64 v[210:211], v[184:185], 0, v[170:171]
	v_cvt_pk_bf16_f32 v184, v190, v191
	v_cvt_pk_bf16_f32 v185, v192, v193
	global_load_dwordx4 v[186:189], v[210:211], off
	s_waitcnt vmcnt(0)
	v_lshlrev_b32_e32 v214, 16, v188
	global_store_dwordx4 v[174:175], v[182:185], off offset:256
	v_add_co_u32_e32 v174, vcc, s49, v172
	v_and_b32_e32 v215, 0xffff0000, v188
	s_nop 0
	v_addc_co_u32_e32 v175, vcc, 0, v173, vcc
	global_load_dwordx4 v[182:185], v[174:175], off
	global_load_dwordx4 v[190:193], v[174:175], off offset:256
	global_load_dwordx4 v[194:197], v[210:211], off offset:256
	v_add_co_u32_e32 v202, vcc, s50, v172
	v_lshlrev_b64 v[174:175], 11, v[156:157]
	s_nop 0
	v_addc_co_u32_e32 v203, vcc, 0, v173, vcc
	v_lshl_add_u64 v[198:199], s[36:37], 0, v[174:175]
	global_load_dwordx4 v[172:175], v[202:203], off
	v_lshl_add_u64 v[212:213], v[198:199], 0, v[170:171]
	global_load_dwordx4 v[198:201], v[212:213], off
	s_nop 0
	global_load_dwordx4 v[202:205], v[202:203], off offset:256
	s_nop 0
	global_load_dwordx4 v[206:209], v[212:213], off offset:256
	v_lshlrev_b32_e32 v170, 16, v186
	v_and_b32_e32 v171, 0xffff0000, v186
	v_lshlrev_b32_e32 v186, 16, v187
	v_and_b32_e32 v187, 0xffff0000, v187
	v_lshlrev_b32_e32 v188, 16, v189
	v_and_b32_e32 v189, 0xffff0000, v189
	s_waitcnt vmcnt(0)
; DI unsigned pk_bf16(float lo, float hi) { f32x2 v = {lo, hi}; return __builtin_bit_cast(unsigned, __builtin_convertvector(v, bf16v2)); }
; DI float bf_lo(unsigned w) { return __uint_as_float(w << 16); }
; DI float bf_hi(unsigned w) { return __uint_as_float(w & 0xffff0000u); }
;     DI void operator()(AccRef acc, const Unit& u, int wr, int wc, int fr, int fq) const {
;     ...
;                 for (int mm = 0; mm < 2; ++mm)
; #pragma unroll
;                     for (int bj = 0; bj < 2; ++bj) {
;                         const size_t row = (size_t)(row0 + ai * 128 + (mh * 2 + mm) * 16); const int col = col0 + bj * 128;
;                         gv[mm][bj] = *(const u32x4*)(gab + (size_t)(u.pm * 8 + SECOND * 4 + u.pn) * 65536 + (wr * 64 + fr + ai * 128 + (mh * 2 + mm) * 16) * 256 + wc * 32 + 8 * fq + bj * 128);
;                         if (SECOND) mv[mm][bj] = *(const u32x4*)(mrg + row * 1024 + col);
;                     }
; #pragma unroll
;                 for (int mm = 0; mm < 2; ++mm)
; #pragma unroll
;                     for (int bj = 0; bj < 2; ++bj) {
;                         const int m = mh * 2 + mm;
;                         const size_t row = (size_t)(row0 + ai * 128 + m * 16); const int col = col0 + bj * 128;
;                         const u32x4 gt = gv[mm][bj];
;                         const f32x4 r0 = acc[ai][bj][m][0], r1 = acc[ai][bj][m][1];
;                         float v[8] = {bf_lo(gt.x) * r0[0], bf_hi(gt.x) * r0[1], bf_lo(gt.y) * r0[2], bf_hi(gt.y) * r0[3], bf_lo(gt.z) * r1[0], bf_hi(gt.z) * r1[1], bf_lo(gt.w) * r1[2], bf_hi(gt.w) * r1[3]};
;                         if (SECOND) { const u32x4 o = mv[mm][bj]; v[0] += bf_lo(o.x); v[1] += bf_hi(o.x); v[2] += bf_lo(o.y); v[3] += bf_hi(o.y); v[4] += bf_lo(o.z); v[5] += bf_hi(o.z); v[6] += bf_lo(o.w); v[7] += bf_hi(o.w); }
;                         u32x4 w; w.x = pk_bf16(v[0], v[1]); w.y = pk_bf16(v[2], v[3]); w.z = pk_bf16(v[4], v[5]); w.w = pk_bf16(v[6], v[7]);
;                         *(u32x4*)(mrg + row * 1024 + col) = w;
	v_lshlrev_b32_e32 v216, 16, v182
	v_and_b32_e32 v217, 0xffff0000, v182
	v_lshlrev_b32_e32 v182, 16, v183
	v_and_b32_e32 v183, 0xffff0000, v183
	v_lshlrev_b32_e32 v218, 16, v184
	v_and_b32_e32 v219, 0xffff0000, v184
	v_lshlrev_b32_e32 v184, 16, v185
	v_and_b32_e32 v185, 0xffff0000, v185
	v_pk_fma_f32 v[170:171], v[92:93], v[216:217], v[170:171]
	v_pk_fma_f32 v[186:187], v[94:95], v[182:183], v[186:187]
	v_pk_fma_f32 v[214:215], v[88:89], v[218:219], v[214:215]
	v_pk_fma_f32 v[188:189], v[90:91], v[184:185], v[188:189]
	v_cvt_pk_bf16_f32 v182, v170, v171
	v_cvt_pk_bf16_f32 v183, v186, v187
	v_cvt_pk_bf16_f32 v184, v214, v215
	v_cvt_pk_bf16_f32 v185, v188, v189
	global_store_dwordx4 v[210:211], v[182:185], off
	v_lshlrev_b32_e32 v186, 16, v196
	v_and_b32_e32 v187, 0xffff0000, v196
	v_lshlrev_b32_e32 v182, 16, v191
	v_and_b32_e32 v183, 0xffff0000, v191
	v_lshlrev_b32_e32 v184, 16, v195
	v_and_b32_e32 v185, 0xffff0000, v195
	v_pk_fma_f32 v[184:185], v[78:79], v[182:183], v[184:185]
	v_lshlrev_b32_e32 v182, 16, v192
	v_and_b32_e32 v183, 0xffff0000, v192
	v_lshlrev_b32_e32 v220, 16, v190
	v_and_b32_e32 v221, 0xffff0000, v190
	v_lshlrev_b32_e32 v170, 16, v194
	v_and_b32_e32 v171, 0xffff0000, v194
	v_pk_fma_f32 v[186:187], v[72:73], v[182:183], v[186:187]
	v_lshlrev_b32_e32 v182, 16, v193
	v_and_b32_e32 v183, 0xffff0000, v193
	v_lshlrev_b32_e32 v188, 16, v197
	v_and_b32_e32 v189, 0xffff0000, v197
	v_pk_fma_f32 v[170:171], v[76:77], v[220:221], v[170:171]
	v_pk_fma_f32 v[188:189], v[74:75], v[182:183], v[188:189]
	v_cvt_pk_bf16_f32 v182, v170, v171
	v_cvt_pk_bf16_f32 v183, v184, v185
	v_cvt_pk_bf16_f32 v184, v186, v187
	v_cvt_pk_bf16_f32 v185, v188, v189
	global_store_dwordx4 v[210:211], v[182:185], off offset:256
	v_lshlrev_b32_e32 v170, 16, v172
	v_and_b32_e32 v171, 0xffff0000, v172
	v_lshlrev_b32_e32 v182, 16, v198
	v_and_b32_e32 v183, 0xffff0000, v198
	v_pk_fma_f32 v[170:171], v[84:85], v[170:171], v[182:183]
	v_lshlrev_b32_e32 v172, 16, v173
	v_and_b32_e32 v173, 0xffff0000, v173
	v_lshlrev_b32_e32 v182, 16, v199
	v_and_b32_e32 v183, 0xffff0000, v199
	v_pk_fma_f32 v[172:173], v[86:87], v[172:173], v[182:183]
	v_lshlrev_b32_e32 v182, 16, v174
	v_and_b32_e32 v183, 0xffff0000, v174
	v_lshlrev_b32_e32 v184, 16, v200
	v_and_b32_e32 v185, 0xffff0000, v200
	v_pk_fma_f32 v[182:183], v[80:81], v[182:183], v[184:185]
	v_lshlrev_b32_e32 v174, 16, v175
	v_and_b32_e32 v175, 0xffff0000, v175
	v_lshlrev_b32_e32 v184, 16, v201
	v_and_b32_e32 v185, 0xffff0000, v201
	v_pk_fma_f32 v[174:175], v[82:83], v[174:175], v[184:185]
	v_cvt_pk_bf16_f32 v170, v170, v171
	v_cvt_pk_bf16_f32 v171, v172, v173
	v_cvt_pk_bf16_f32 v172, v182, v183
	v_cvt_pk_bf16_f32 v173, v174, v175
	global_store_dwordx4 v[212:213], v[170:173], off
	v_lshlrev_b32_e32 v174, 16, v207
	v_and_b32_e32 v175, 0xffff0000, v207
	v_lshlrev_b32_e32 v170, 16, v202
	v_and_b32_e32 v171, 0xffff0000, v202
	v_lshlrev_b32_e32 v172, 16, v206
	v_and_b32_e32 v173, 0xffff0000, v206
	v_pk_fma_f32 v[170:171], v[68:69], v[170:171], v[172:173]
	v_lshlrev_b32_e32 v172, 16, v203
	v_and_b32_e32 v173, 0xffff0000, v203
	v_pk_fma_f32 v[172:173], v[70:71], v[172:173], v[174:175]
	v_lshlrev_b32_e32 v174, 16, v204
	v_and_b32_e32 v175, 0xffff0000, v204
	v_lshlrev_b32_e32 v182, 16, v208
	v_and_b32_e32 v183, 0xffff0000, v208
	v_pk_fma_f32 v[174:175], v[64:65], v[174:175], v[182:183]
	v_lshlrev_b32_e32 v182, 16, v205
	v_and_b32_e32 v183, 0xffff0000, v205
	v_lshlrev_b32_e32 v184, 16, v209
	v_and_b32_e32 v185, 0xffff0000, v209
	v_pk_fma_f32 v[182:183], v[66:67], v[182:183], v[184:185]
	v_cvt_pk_bf16_f32 v170, v170, v171
	v_cvt_pk_bf16_f32 v171, v172, v173
	v_cvt_pk_bf16_f32 v172, v174, v175
	v_cvt_pk_bf16_f32 v173, v182, v183
	global_store_dwordx4 v[212:213], v[170:173], off offset:256
	v_lshl_add_u64 v[174:175], v[140:141], 1, v[168:169]
	v_add_co_u32_e32 v210, vcc, s61, v166
	global_load_dwordx4 v[170:173], v[174:175], off
	s_nop 0
	v_addc_co_u32_e32 v211, vcc, 0, v167, vcc
	global_load_dwordx4 v[182:185], v[210:211], off
	global_load_dwordx4 v[186:189], v[174:175], off offset:256
	v_lshl_add_u64 v[174:175], v[166:167], 0, s[0:1]
	global_load_dwordx4 v[190:193], v[174:175], off offset:256
	v_lshl_add_u64 v[202:203], v[142:143], 1, v[168:169]
	v_add_co_u32_e32 v212, vcc, s62, v166
	global_load_dwordx4 v[194:197], v[202:203], off
	s_nop 0
	v_addc_co_u32_e32 v213, vcc, 0, v167, vcc
	global_load_dwordx4 v[198:201], v[212:213], off
	s_nop 0
	global_load_dwordx4 v[202:205], v[202:203], off offset:256
	v_lshl_add_u64 v[214:215], v[166:167], 0, s[10:11]
	global_load_dwordx4 v[206:209], v[214:215], off offset:256
	s_waitcnt vmcnt(0)
; DI unsigned pk_bf16(float lo, float hi) { f32x2 v = {lo, hi}; return __builtin_bit_cast(unsigned, __builtin_convertvector(v, bf16v2)); }
; DI float bf_lo(unsigned w) { return __uint_as_float(w << 16); }
; DI float bf_hi(unsigned w) { return __uint_as_float(w & 0xffff0000u); }
;     DI void operator()(AccRef acc, const Unit& u, int wr, int wc, int fr, int fq) const {
;     ...
;                 for (int mm = 0; mm < 2; ++mm)
; #pragma unroll
;                     for (int bj = 0; bj < 2; ++bj) {
;                         const size_t row = (size_t)(row0 + ai * 128 + (mh * 2 + mm) * 16); const int col = col0 + bj * 128;
;                         gv[mm][bj] = *(const u32x4*)(gab + (size_t)(u.pm * 8 + SECOND * 4 + u.pn) * 65536 + (wr * 64 + fr + ai * 128 + (mh * 2 + mm) * 16) * 256 + wc * 32 + 8 * fq + bj * 128);
;                         if (SECOND) mv[mm][bj] = *(const u32x4*)(mrg + row * 1024 + col);
;                     }
; #pragma unroll
;                 for (int mm = 0; mm < 2; ++mm)
; #pragma unroll
;                     for (int bj = 0; bj < 2; ++bj) {
;                         const int m = mh * 2 + mm;
;                         const size_t row = (size_t)(row0 + ai * 128 + m * 16); const int col = col0 + bj * 128;
;                         const u32x4 gt = gv[mm][bj];
;                         const f32x4 r0 = acc[ai][bj][m][0], r1 = acc[ai][bj][m][1];
;                         float v[8] = {bf_lo(gt.x) * r0[0], bf_hi(gt.x) * r0[1], bf_lo(gt.y) * r0[2], bf_hi(gt.y) * r0[3], bf_lo(gt.z) * r1[0], bf_hi(gt.z) * r1[1], bf_lo(gt.w) * r1[2], bf_hi(gt.w) * r1[3]};
;                         if (SECOND) { const u32x4 o = mv[mm][bj]; v[0] += bf_lo(o.x); v[1] += bf_hi(o.x); v[2] += bf_lo(o.y); v[3] += bf_hi(o.y); v[4] += bf_lo(o.z); v[5] += bf_hi(o.z); v[6] += bf_lo(o.w); v[7] += bf_hi(o.w); }
;                         u32x4 w; w.x = pk_bf16(v[0], v[1]); w.y = pk_bf16(v[2], v[3]); w.z = pk_bf16(v[4], v[5]); w.w = pk_bf16(v[6], v[7]);
;                         *(u32x4*)(mrg + row * 1024 + col) = w;
	v_lshlrev_b32_e32 v216, 16, v170
	v_and_b32_e32 v217, 0xffff0000, v170
	v_lshlrev_b32_e32 v218, 16, v182
	v_and_b32_e32 v219, 0xffff0000, v182
	v_lshlrev_b32_e32 v170, 16, v171
	v_and_b32_e32 v171, 0xffff0000, v171
	v_lshlrev_b32_e32 v182, 16, v183
	v_and_b32_e32 v183, 0xffff0000, v183
	v_pk_fma_f32 v[216:217], v[60:61], v[216:217], v[218:219]
	v_pk_fma_f32 v[182:183], v[62:63], v[170:171], v[182:183]
	v_lshlrev_b32_e32 v170, 16, v172
	v_and_b32_e32 v171, 0xffff0000, v172
	v_lshlrev_b32_e32 v218, 16, v184
	v_and_b32_e32 v219, 0xffff0000, v184
	v_pk_fma_f32 v[218:219], v[56:57], v[170:171], v[218:219]
	v_lshlrev_b32_e32 v170, 16, v173
	v_and_b32_e32 v171, 0xffff0000, v173
	v_lshlrev_b32_e32 v172, 16, v185
	v_and_b32_e32 v173, 0xffff0000, v185
	v_pk_fma_f32 v[184:185], v[58:59], v[170:171], v[172:173]
	v_cvt_pk_bf16_f32 v170, v216, v217
	v_cvt_pk_bf16_f32 v171, v182, v183
	v_cvt_pk_bf16_f32 v172, v218, v219
	v_cvt_pk_bf16_f32 v173, v184, v185
	global_store_dwordx4 v[210:211], v[170:173], off
	v_lshlrev_b32_e32 v182, 16, v191
	v_and_b32_e32 v183, 0xffff0000, v191
	v_lshlrev_b32_e32 v170, 16, v186
	v_and_b32_e32 v171, 0xffff0000, v186
	v_lshlrev_b32_e32 v172, 16, v190
	v_and_b32_e32 v173, 0xffff0000, v190
	v_pk_fma_f32 v[170:171], v[44:45], v[170:171], v[172:173]
	v_lshlrev_b32_e32 v172, 16, v187
	v_and_b32_e32 v173, 0xffff0000, v187
	v_pk_fma_f32 v[172:173], v[46:47], v[172:173], v[182:183]
	v_lshlrev_b32_e32 v182, 16, v188
	v_and_b32_e32 v183, 0xffff0000, v188
	v_lshlrev_b32_e32 v184, 16, v192
	v_and_b32_e32 v185, 0xffff0000, v192
	v_pk_fma_f32 v[182:183], v[40:41], v[182:183], v[184:185]
	v_lshlrev_b32_e32 v184, 16, v189
	v_and_b32_e32 v185, 0xffff0000, v189
	v_lshlrev_b32_e32 v186, 16, v193
	v_and_b32_e32 v187, 0xffff0000, v193
	v_pk_fma_f32 v[184:185], v[42:43], v[184:185], v[186:187]
	v_cvt_pk_bf16_f32 v170, v170, v171
	v_cvt_pk_bf16_f32 v171, v172, v173
	v_cvt_pk_bf16_f32 v172, v182, v183
	v_cvt_pk_bf16_f32 v173, v184, v185
	global_store_dwordx4 v[174:175], v[170:173], off offset:256
	v_lshlrev_b32_e32 v174, 16, v199
	v_and_b32_e32 v175, 0xffff0000, v199
	v_lshlrev_b32_e32 v170, 16, v194
	v_and_b32_e32 v171, 0xffff0000, v194
	v_lshlrev_b32_e32 v172, 16, v198
	v_and_b32_e32 v173, 0xffff0000, v198
	v_pk_fma_f32 v[170:171], v[52:53], v[170:171], v[172:173]
	v_lshlrev_b32_e32 v172, 16, v195
	v_and_b32_e32 v173, 0xffff0000, v195
	v_pk_fma_f32 v[172:173], v[54:55], v[172:173], v[174:175]
	v_lshlrev_b32_e32 v174, 16, v196
	v_and_b32_e32 v175, 0xffff0000, v196
	v_lshlrev_b32_e32 v182, 16, v200
	v_and_b32_e32 v183, 0xffff0000, v200
	v_pk_fma_f32 v[174:175], v[48:49], v[174:175], v[182:183]
	v_lshlrev_b32_e32 v182, 16, v197
	v_and_b32_e32 v183, 0xffff0000, v197
	v_lshlrev_b32_e32 v184, 16, v201
	v_and_b32_e32 v185, 0xffff0000, v201
	v_pk_fma_f32 v[182:183], v[50:51], v[182:183], v[184:185]
	v_cvt_pk_bf16_f32 v170, v170, v171
	v_cvt_pk_bf16_f32 v171, v172, v173
	v_cvt_pk_bf16_f32 v172, v174, v175
	v_cvt_pk_bf16_f32 v173, v182, v183
	global_store_dwordx4 v[212:213], v[170:173], off
	v_lshlrev_b32_e32 v174, 16, v207
	v_and_b32_e32 v175, 0xffff0000, v207
	v_lshlrev_b32_e32 v170, 16, v202
	v_and_b32_e32 v171, 0xffff0000, v202
	v_lshlrev_b32_e32 v172, 16, v206
	v_and_b32_e32 v173, 0xffff0000, v206
	v_pk_fma_f32 v[170:171], v[36:37], v[170:171], v[172:173]
	v_lshlrev_b32_e32 v172, 16, v203
	v_and_b32_e32 v173, 0xffff0000, v203
	v_pk_fma_f32 v[172:173], v[38:39], v[172:173], v[174:175]
	v_lshlrev_b32_e32 v174, 16, v204
	v_and_b32_e32 v175, 0xffff0000, v204
	v_lshlrev_b32_e32 v182, 16, v208
	v_and_b32_e32 v183, 0xffff0000, v208
	v_pk_fma_f32 v[174:175], v[32:33], v[174:175], v[182:183]
	v_lshlrev_b32_e32 v182, 16, v205
	v_and_b32_e32 v183, 0xffff0000, v205
	v_lshlrev_b32_e32 v184, 16, v209
	v_and_b32_e32 v185, 0xffff0000, v209
	v_pk_fma_f32 v[182:183], v[34:35], v[182:183], v[184:185]
	v_cvt_pk_bf16_f32 v170, v170, v171
	v_cvt_pk_bf16_f32 v171, v172, v173
	v_cvt_pk_bf16_f32 v172, v174, v175
	v_cvt_pk_bf16_f32 v173, v182, v183
	global_store_dwordx4 v[214:215], v[170:173], off offset:256
	v_lshl_add_u64 v[174:175], v[144:145], 1, v[168:169]
	v_add_co_u32_e32 v206, vcc, s63, v166
	global_load_dwordx4 v[170:173], v[174:175], off
	s_nop 0
	v_addc_co_u32_e32 v207, vcc, 0, v167, vcc
	global_load_dwordx4 v[182:185], v[206:207], off
	global_load_dwordx4 v[186:189], v[174:175], off offset:256
	v_lshl_add_u64 v[174:175], v[166:167], 0, s[12:13]
	global_load_dwordx4 v[190:193], v[174:175], off offset:256
	v_lshl_add_u64 v[168:169], v[146:147], 1, v[168:169]
	v_add_co_u32_e32 v208, vcc, s64, v166
	global_load_dwordx4 v[194:197], v[168:169], off
	s_nop 0
	v_addc_co_u32_e32 v209, vcc, 0, v167, vcc
	global_load_dwordx4 v[198:201], v[208:209], off
	global_load_dwordx4 v[202:205], v[168:169], off offset:256
	v_lshl_add_u64 v[210:211], v[166:167], 0, s[14:15]
	global_load_dwordx4 v[166:169], v[210:211], off offset:256
	s_waitcnt vmcnt(0)
; DI unsigned pk_bf16(float lo, float hi) { f32x2 v = {lo, hi}; return __builtin_bit_cast(unsigned, __builtin_convertvector(v, bf16v2)); }
; DI float bf_lo(unsigned w) { return __uint_as_float(w << 16); }
; DI float bf_hi(unsigned w) { return __uint_as_float(w & 0xffff0000u); }
;     DI void operator()(AccRef acc, const Unit& u, int wr, int wc, int fr, int fq) const {
;     ...
;                 for (int mm = 0; mm < 2; ++mm)
; #pragma unroll
;                     for (int bj = 0; bj < 2; ++bj) {
;                         const size_t row = (size_t)(row0 + ai * 128 + (mh * 2 + mm) * 16); const int col = col0 + bj * 128;
;                         gv[mm][bj] = *(const u32x4*)(gab + (size_t)(u.pm * 8 + SECOND * 4 + u.pn) * 65536 + (wr * 64 + fr + ai * 128 + (mh * 2 + mm) * 16) * 256 + wc * 32 + 8 * fq + bj * 128);
;                         if (SECOND) mv[mm][bj] = *(const u32x4*)(mrg + row * 1024 + col);
;                     }
; #pragma unroll
;                 for (int mm = 0; mm < 2; ++mm)
; #pragma unroll
;                     for (int bj = 0; bj < 2; ++bj) {
;                         const int m = mh * 2 + mm;
;                         const size_t row = (size_t)(row0 + ai * 128 + m * 16); const int col = col0 + bj * 128;
;                         const u32x4 gt = gv[mm][bj];
;                         const f32x4 r0 = acc[ai][bj][m][0], r1 = acc[ai][bj][m][1];
;                         float v[8] = {bf_lo(gt.x) * r0[0], bf_hi(gt.x) * r0[1], bf_lo(gt.y) * r0[2], bf_hi(gt.y) * r0[3], bf_lo(gt.z) * r1[0], bf_hi(gt.z) * r1[1], bf_lo(gt.w) * r1[2], bf_hi(gt.w) * r1[3]};
;                         if (SECOND) { const u32x4 o = mv[mm][bj]; v[0] += bf_lo(o.x); v[1] += bf_hi(o.x); v[2] += bf_lo(o.y); v[3] += bf_hi(o.y); v[4] += bf_lo(o.z); v[5] += bf_hi(o.z); v[6] += bf_lo(o.w); v[7] += bf_hi(o.w); }
;                         u32x4 w; w.x = pk_bf16(v[0], v[1]); w.y = pk_bf16(v[2], v[3]); w.z = pk_bf16(v[4], v[5]); w.w = pk_bf16(v[6], v[7]);
;                         *(u32x4*)(mrg + row * 1024 + col) = w;
	v_lshlrev_b32_e32 v212, 16, v170
	v_and_b32_e32 v213, 0xffff0000, v170
	v_lshlrev_b32_e32 v214, 16, v182
	v_and_b32_e32 v215, 0xffff0000, v182
	v_lshlrev_b32_e32 v170, 16, v171
	v_and_b32_e32 v171, 0xffff0000, v171
	v_lshlrev_b32_e32 v182, 16, v183
	v_and_b32_e32 v183, 0xffff0000, v183
	v_pk_fma_f32 v[212:213], v[28:29], v[212:213], v[214:215]
	v_pk_fma_f32 v[182:183], v[30:31], v[170:171], v[182:183]
	v_lshlrev_b32_e32 v170, 16, v172
	v_and_b32_e32 v171, 0xffff0000, v172
	v_lshlrev_b32_e32 v214, 16, v184
	v_and_b32_e32 v215, 0xffff0000, v184
	v_pk_fma_f32 v[214:215], v[24:25], v[170:171], v[214:215]
	v_lshlrev_b32_e32 v170, 16, v173
	v_and_b32_e32 v171, 0xffff0000, v173
	v_lshlrev_b32_e32 v172, 16, v185
	v_and_b32_e32 v173, 0xffff0000, v185
	v_pk_fma_f32 v[184:185], v[26:27], v[170:171], v[172:173]
	v_cvt_pk_bf16_f32 v170, v212, v213
	v_cvt_pk_bf16_f32 v171, v182, v183
	v_cvt_pk_bf16_f32 v172, v214, v215
	v_cvt_pk_bf16_f32 v173, v184, v185
	global_store_dwordx4 v[206:207], v[170:173], off
	v_lshlrev_b32_e32 v182, 16, v191
	v_and_b32_e32 v183, 0xffff0000, v191
	v_lshlrev_b32_e32 v170, 16, v186
	v_and_b32_e32 v171, 0xffff0000, v186
	v_lshlrev_b32_e32 v172, 16, v190
	v_and_b32_e32 v173, 0xffff0000, v190
	v_pk_fma_f32 v[170:171], v[12:13], v[170:171], v[172:173]
	v_lshlrev_b32_e32 v172, 16, v187
	v_and_b32_e32 v173, 0xffff0000, v187
	v_pk_fma_f32 v[172:173], v[14:15], v[172:173], v[182:183]
	v_lshlrev_b32_e32 v182, 16, v188
	v_and_b32_e32 v183, 0xffff0000, v188
	v_lshlrev_b32_e32 v184, 16, v192
	v_and_b32_e32 v185, 0xffff0000, v192
	v_pk_fma_f32 v[182:183], v[8:9], v[182:183], v[184:185]
	v_lshlrev_b32_e32 v184, 16, v189
	v_and_b32_e32 v185, 0xffff0000, v189
	v_lshlrev_b32_e32 v186, 16, v193
	v_and_b32_e32 v187, 0xffff0000, v193
	v_pk_fma_f32 v[184:185], v[10:11], v[184:185], v[186:187]
	v_cvt_pk_bf16_f32 v170, v170, v171
	v_cvt_pk_bf16_f32 v171, v172, v173
	v_cvt_pk_bf16_f32 v172, v182, v183
	v_cvt_pk_bf16_f32 v173, v184, v185
	global_store_dwordx4 v[174:175], v[170:173], off offset:256
	v_lshlrev_b32_e32 v174, 16, v199
	v_and_b32_e32 v175, 0xffff0000, v199
	v_lshlrev_b32_e32 v170, 16, v194
	v_and_b32_e32 v171, 0xffff0000, v194
	v_lshlrev_b32_e32 v172, 16, v198
	v_and_b32_e32 v173, 0xffff0000, v198
	v_pk_fma_f32 v[170:171], v[20:21], v[170:171], v[172:173]
	v_lshlrev_b32_e32 v172, 16, v195
	v_and_b32_e32 v173, 0xffff0000, v195
	v_pk_fma_f32 v[172:173], v[22:23], v[172:173], v[174:175]
	v_lshlrev_b32_e32 v174, 16, v196
	v_and_b32_e32 v175, 0xffff0000, v196
	v_lshlrev_b32_e32 v182, 16, v200
	v_and_b32_e32 v183, 0xffff0000, v200
	v_pk_fma_f32 v[174:175], v[16:17], v[174:175], v[182:183]
	v_lshlrev_b32_e32 v182, 16, v197
	v_and_b32_e32 v183, 0xffff0000, v197
	v_lshlrev_b32_e32 v184, 16, v201
	v_and_b32_e32 v185, 0xffff0000, v201
	v_pk_fma_f32 v[182:183], v[18:19], v[182:183], v[184:185]
	v_cvt_pk_bf16_f32 v170, v170, v171
	v_cvt_pk_bf16_f32 v171, v172, v173
	v_cvt_pk_bf16_f32 v172, v174, v175
	v_cvt_pk_bf16_f32 v173, v182, v183
	global_store_dwordx4 v[208:209], v[170:173], off
	v_lshlrev_b32_e32 v174, 16, v168
	v_and_b32_e32 v175, 0xffff0000, v168
	v_lshlrev_b32_e32 v170, 16, v202
	v_and_b32_e32 v171, 0xffff0000, v202
	v_lshlrev_b32_e32 v172, 16, v166
	v_and_b32_e32 v173, 0xffff0000, v166
	v_pk_fma_f32 v[170:171], v[4:5], v[170:171], v[172:173]
	v_lshlrev_b32_e32 v172, 16, v203
	v_and_b32_e32 v173, 0xffff0000, v203
	v_lshlrev_b32_e32 v166, 16, v167
	v_and_b32_e32 v167, 0xffff0000, v167
	v_pk_fma_f32 v[172:173], v[6:7], v[172:173], v[166:167]
	v_lshlrev_b32_e32 v166, 16, v204
	v_and_b32_e32 v167, 0xffff0000, v204
	v_pk_fma_f32 v[174:175], v[0:1], v[166:167], v[174:175]
	v_lshlrev_b32_e32 v166, 16, v205
	v_and_b32_e32 v167, 0xffff0000, v205
	v_lshlrev_b32_e32 v168, 16, v169
	v_and_b32_e32 v169, 0xffff0000, v169
	v_pk_fma_f32 v[182:183], v[2:3], v[166:167], v[168:169]
	v_cvt_pk_bf16_f32 v166, v170, v171
	v_cvt_pk_bf16_f32 v167, v172, v173
	v_cvt_pk_bf16_f32 v168, v174, v175
	v_cvt_pk_bf16_f32 v169, v182, v183
	global_store_dwordx4 v[210:211], v[166:169], off offset:256

; #define PG8_STAGE(bufoff, gbase, voff) do { _Pragma("unroll") for (int _i = 0; _i < 2; ++_i) \
;         __builtin_amdgcn_global_load_lds((const unsigned*)((const char*)(gbase) + (voff)[_i]), (LAS unsigned*)(lds + (bufoff) + ldsw + _i * 8192), 16, 0, 0); } while (0)
; #define PG8_LDA(dst, b, h) do { _Pragma("unroll") for (int m = 0; m < 4; ++m) _Pragma("unroll") for (int k = 0; k < 2; ++k) dst[m][k] = *(const LAS bf16x8*)(lds + PG8_SA(b, h) + aoff + m * 2048 + k * 1024); } while (0)
; #define PG8_LDB(dst, b, h) do { _Pragma("unroll") for (int n = 0; n < 2; ++n) _Pragma("unroll") for (int k = 0; k < 2; ++k) dst[n][k] = *(const LAS bf16x8*)(lds + PG8_SB(b, h) + boff + n * 2048 + k * 1024); } while (0)
; #define PG8_MMA(ai, bj, At, Bt) do { __builtin_amdgcn_s_setprio(1); _Pragma("unroll") for (int m = 0; m < 4; ++m) _Pragma("unroll") for (int n = 0; n < 2; ++n) _Pragma("unroll") for (int k = 0; k < 2; ++k) \
;         acc[ai][bj][m][n] = __builtin_amdgcn_mfma_f32_16x16x32_bf16(Bt[n][k], At[m][k], acc[ai][bj][m][n], 0, 0, 0); __builtin_amdgcn_s_setprio(0); } while (0)
; #define PG8_WAIT_L(n) asm volatile("s_waitcnt lgkmcnt(" #n ")" ::: "memory")
; #define PG8_BAR __builtin_amdgcn_s_barrier()
; #define PG8_SCHED __builtin_amdgcn_sched_barrier(0)
; #define PG8_WAIT_L(n) asm volatile("s_waitcnt lgkmcnt(" #n ")" ::: "memory")
; #define PG8_BAR __builtin_amdgcn_s_barrier()
; template <class Epi>
; DI void gemm_phase(LAS unsigned char* lds, const Gemm g, const StaticOrder S, const Epi E) {
;     ...
;         for (int t = 0; t < nt; t += 2) {
;             const bool last = (t == nt - 2);
;             const char* a1 = cA + (size_t)(t + 1) * kstep;
;             const char* a2 = last ? nA : cA + (size_t)(t + 2) * kstep; const char* b2 = last ? nB : cB + (size_t)(t + 2) * kstep;
;             const char* a3 = a2 + kstep; const char* b3 = b2 + kstep;
;             PG8_LDB(B0, 0, 0); PG8_SCHED; PG8_LDA(At, 0, 0); PG8_STAGE(PG8_SA(1, 1), a1 + hstep, voffA);
;             PG8_WAIT_L(8); PG8_BAR; PG8_WAIT_L(0); PG8_MMA(0, 0, At, B0); PG8_BAR; PG8_SCHED;
;             PG8_LDB(B1, 0, 1); PG8_STAGE(PG8_SB(0, 0), b2, voffB);
;             PG8_BAR; PG8_WAIT_L(0); PG8_MMA(0, 1, At, B1); PG8_BAR;
;             PG8_LDA(At, 0, 1); PG8_STAGE(PG8_SA(0, 0), a2, voffA);
;             PG8_BAR; PG8_WAIT_L(0); PG8_MMA(1, 0, At, B0); PG8_BAR; PG8_SCHED;
.LBB0_786:
	ds_read_b128 v[128:131], v187
	ds_read_b128 v[132:135], v187 offset:1024
	ds_read_b128 v[136:139], v187 offset:2048
	ds_read_b128 v[140:143], v187 offset:3072
	s_add_u32 s28, s24, 0xfffc0080
	s_addc_u32 s29, s25, -1
	s_cmp_eq_u32 s52, 12
	s_cselect_b32 s39, s6, s29
	s_cselect_b32 s38, s7, s28
	s_cselect_b32 s29, s11, s51
	s_cselect_b32 s28, s13, s50
	v_lshl_add_u64 v[200:201], s[24:25], 0, v[160:161]
	s_add_i32 m0, s19, 0xc000
	ds_read_b128 v[144:147], v188
	ds_read_b128 v[148:151], v188 offset:1024
	ds_read_b128 v[168:171], v188 offset:2048
	ds_read_b128 v[172:175], v188 offset:3072
	ds_read_b128 v[176:179], v188 offset:4096
	ds_read_b128 v[180:183], v188 offset:5120
	ds_read_b128 v[192:195], v188 offset:6144
	ds_read_b128 v[196:199], v188 offset:7168
	global_load_lds_dwordx4 v[200:201], off
	v_lshl_add_u64 v[200:201], s[24:25], 0, v[162:163]
	s_add_i32 m0, s19, 0xe000
	s_nop 0
	global_load_lds_dwordx4 v[200:201], off
	s_waitcnt lgkmcnt(8)
	s_barrier
	s_waitcnt lgkmcnt(0)
	s_setprio 1
	s_waitcnt lgkmcnt(0)
	v_mfma_f32_16x16x32_bf16 v[124:127], v[128:131], v[144:147], v[124:127]
	v_mfma_f32_16x16x32_bf16 v[120:123], v[136:139], v[144:147], v[120:123]
	v_mfma_f32_16x16x32_bf16 v[108:111], v[128:131], v[168:171], v[108:111]
	v_mfma_f32_16x16x32_bf16 v[104:107], v[136:139], v[168:171], v[104:107]
	v_mfma_f32_16x16x32_bf16 v[92:95], v[128:131], v[176:179], v[92:95]
	v_mfma_f32_16x16x32_bf16 v[88:91], v[136:139], v[176:179], v[88:91]
	v_mfma_f32_16x16x32_bf16 v[76:79], v[128:131], v[192:195], v[76:79]
	v_mfma_f32_16x16x32_bf16 v[72:75], v[136:139], v[192:195], v[72:75]
	v_mfma_f32_16x16x32_bf16 v[124:127], v[132:135], v[148:151], v[124:127]
	v_mfma_f32_16x16x32_bf16 v[120:123], v[140:143], v[148:151], v[120:123]
	v_mfma_f32_16x16x32_bf16 v[108:111], v[132:135], v[172:175], v[108:111]
	v_mfma_f32_16x16x32_bf16 v[104:107], v[140:143], v[172:175], v[104:107]
	v_mfma_f32_16x16x32_bf16 v[92:95], v[132:135], v[180:183], v[92:95]
	v_mfma_f32_16x16x32_bf16 v[88:91], v[140:143], v[180:183], v[88:91]
	v_mfma_f32_16x16x32_bf16 v[76:79], v[132:135], v[196:199], v[76:79]
	v_mfma_f32_16x16x32_bf16 v[72:75], v[140:143], v[196:199], v[72:75]
	s_setprio 0
	s_barrier
	s_add_i32 s53, s48, s40
	v_lshl_add_u64 v[216:217], s[28:29], 0, v[154:155]
	s_mov_b32 m0, s53
	ds_read_b128 v[200:203], v189
	ds_read_b128 v[204:207], v189 offset:1024
	ds_read_b128 v[208:211], v189 offset:2048
	ds_read_b128 v[212:215], v189 offset:3072
	global_load_lds_dwordx4 v[216:217], off
	v_lshl_add_u64 v[218:219], s[28:29], 0, v[158:159]
	s_add_i32 m0, s53, 0x2000
	s_nop 0
	global_load_lds_dwordx4 v[218:219], off
	s_barrier
	s_waitcnt lgkmcnt(0)
	s_setprio 1
	s_waitcnt lgkmcnt(0)
	v_mfma_f32_16x16x32_bf16 v[116:119], v[200:203], v[144:147], v[116:119]
	v_mfma_f32_16x16x32_bf16 v[112:115], v[208:211], v[144:147], v[112:115]
	v_mfma_f32_16x16x32_bf16 v[100:103], v[200:203], v[168:171], v[100:103]
	v_mfma_f32_16x16x32_bf16 v[96:99], v[208:211], v[168:171], v[96:99]
	v_mfma_f32_16x16x32_bf16 v[84:87], v[200:203], v[176:179], v[84:87]
	v_mfma_f32_16x16x32_bf16 v[80:83], v[208:211], v[176:179], v[80:83]
	v_mfma_f32_16x16x32_bf16 v[68:71], v[200:203], v[192:195], v[68:71]
	v_mfma_f32_16x16x32_bf16 v[64:67], v[208:211], v[192:195], v[64:67]
	v_mfma_f32_16x16x32_bf16 v[116:119], v[204:207], v[148:151], v[116:119]
	v_mfma_f32_16x16x32_bf16 v[112:115], v[212:215], v[148:151], v[112:115]
	v_mfma_f32_16x16x32_bf16 v[100:103], v[204:207], v[172:175], v[100:103]
	v_mfma_f32_16x16x32_bf16 v[96:99], v[212:215], v[172:175], v[96:99]
	v_mfma_f32_16x16x32_bf16 v[84:87], v[204:207], v[180:183], v[84:87]
	v_mfma_f32_16x16x32_bf16 v[80:83], v[212:215], v[180:183], v[80:83]
	v_mfma_f32_16x16x32_bf16 v[68:71], v[204:207], v[196:199], v[68:71]
	v_mfma_f32_16x16x32_bf16 v[64:67], v[212:215], v[196:199], v[64:67]
	s_setprio 0
	s_mov_b32 m0, s19
	v_lshl_add_u64 v[220:221], s[38:39], 0, v[152:153]
	s_barrier
	ds_read_b128 v[144:147], v188 offset:16384
	ds_read_b128 v[148:151], v188 offset:17408
	ds_read_b128 v[168:171], v188 offset:18432
	ds_read_b128 v[172:175], v188 offset:19456
	ds_read_b128 v[176:179], v188 offset:20480
	ds_read_b128 v[180:183], v188 offset:21504
	ds_read_b128 v[192:195], v188 offset:22528
	ds_read_b128 v[196:199], v188 offset:23552
	global_load_lds_dwordx4 v[220:221], off
	v_lshl_add_u64 v[224:225], s[38:39], 0, v[156:157]
	s_mov_b32 m0, s23
	s_nop 0
	global_load_lds_dwordx4 v[224:225], off
	s_barrier
	s_waitcnt lgkmcnt(0)
	s_setprio 1
	s_waitcnt lgkmcnt(0)
	v_mfma_f32_16x16x32_bf16 v[60:63], v[128:131], v[144:147], v[60:63]
	v_mfma_f32_16x16x32_bf16 v[56:59], v[136:139], v[144:147], v[56:59]
	v_mfma_f32_16x16x32_bf16 v[44:47], v[128:131], v[168:171], v[44:47]
	v_mfma_f32_16x16x32_bf16 v[40:43], v[136:139], v[168:171], v[40:43]
	v_mfma_f32_16x16x32_bf16 v[28:31], v[128:131], v[176:179], v[28:31]
	v_mfma_f32_16x16x32_bf16 v[24:27], v[136:139], v[176:179], v[24:27]
	v_mfma_f32_16x16x32_bf16 v[12:15], v[128:131], v[192:195], v[12:15]
	v_mfma_f32_16x16x32_bf16 v[8:11], v[136:139], v[192:195], v[8:11]
	v_mfma_f32_16x16x32_bf16 v[60:63], v[132:135], v[148:151], v[60:63]
	v_mfma_f32_16x16x32_bf16 v[56:59], v[140:143], v[148:151], v[56:59]
	v_mfma_f32_16x16x32_bf16 v[44:47], v[132:135], v[172:175], v[44:47]
	v_mfma_f32_16x16x32_bf16 v[40:43], v[140:143], v[172:175], v[40:43]
	v_mfma_f32_16x16x32_bf16 v[28:31], v[132:135], v[180:183], v[28:31]
	v_mfma_f32_16x16x32_bf16 v[24:27], v[140:143], v[180:183], v[24:27]
	v_mfma_f32_16x16x32_bf16 v[12:15], v[132:135], v[196:199], v[12:15]
	v_mfma_f32_16x16x32_bf16 v[8:11], v[140:143], v[196:199], v[8:11]
	s_setprio 0
	s_barrier
; #define PG8_STAGE(bufoff, gbase, voff) do { _Pragma("unroll") for (int _i = 0; _i < 2; ++_i) \
;         __builtin_amdgcn_global_load_lds((const unsigned*)((const char*)(gbase) + (voff)[_i]), (LAS unsigned*)(lds + (bufoff) + ldsw + _i * 8192), 16, 0, 0); } while (0)
; #define PG8_LDA(dst, b, h) do { _Pragma("unroll") for (int m = 0; m < 4; ++m) _Pragma("unroll") for (int k = 0; k < 2; ++k) dst[m][k] = *(const LAS bf16x8*)(lds + PG8_SA(b, h) + aoff + m * 2048 + k * 1024); } while (0)
; #define PG8_LDB(dst, b, h) do { _Pragma("unroll") for (int n = 0; n < 2; ++n) _Pragma("unroll") for (int k = 0; k < 2; ++k) dst[n][k] = *(const LAS bf16x8*)(lds + PG8_SB(b, h) + boff + n * 2048 + k * 1024); } while (0)
; #define PG8_MMA(ai, bj, At, Bt) do { __builtin_amdgcn_s_setprio(1); _Pragma("unroll") for (int m = 0; m < 4; ++m) _Pragma("unroll") for (int n = 0; n < 2; ++n) _Pragma("unroll") for (int k = 0; k < 2; ++k) \
;         acc[ai][bj][m][n] = __builtin_amdgcn_mfma_f32_16x16x32_bf16(Bt[n][k], At[m][k], acc[ai][bj][m][n], 0, 0, 0); __builtin_amdgcn_s_setprio(0); } while (0)
; #define PG8_WAIT_V(n) asm volatile("s_waitcnt vmcnt(" #n ")" ::: "memory")
; #define PG8_WAIT_L(n) asm volatile("s_waitcnt lgkmcnt(" #n ")" ::: "memory")
; #define PG8_BAR __builtin_amdgcn_s_barrier()
; #define PG8_SCHED __builtin_amdgcn_sched_barrier(0)
; #define PG8_STAGE(bufoff, gbase, voff) do { _Pragma("unroll") for (int _i = 0; _i < 2; ++_i) \
;         __builtin_amdgcn_global_load_lds((const unsigned*)((const char*)(gbase) + (voff)[_i]), (LAS unsigned*)(lds + (bufoff) + ldsw + _i * 8192), 16, 0, 0); } while (0)
; #define PG8_WAIT_V(n) asm volatile("s_waitcnt vmcnt(" #n ")" ::: "memory")
; #define PG8_BAR __builtin_amdgcn_s_barrier()
; template <class Epi>
; DI void gemm_phase(LAS unsigned char* lds, const Gemm g, const StaticOrder S, const Epi E) {
;     ...
;             PG8_STAGE(PG8_SB(0, 1), b2 + hstep, voffB);
;             PG8_WAIT_V(6); PG8_BAR; PG8_MMA(1, 1, At, B1); PG8_BAR;
;             PG8_LDB(B0, 1, 0); PG8_SCHED; PG8_LDA(At, 1, 0); PG8_STAGE(PG8_SA(0, 1), a2 + hstep, voffA);
;             PG8_WAIT_L(8); PG8_BAR; PG8_WAIT_L(0); PG8_MMA(0, 0, At, B0); PG8_BAR; PG8_SCHED;
;             PG8_LDB(B1, 1, 1); PG8_STAGE(PG8_SB(1, 0), b3, voffB);
;             PG8_BAR; PG8_WAIT_L(0); PG8_MMA(0, 1, At, B1); PG8_BAR;
;             PG8_LDA(At, 1, 1); PG8_STAGE(PG8_SA(1, 0), a3, voffA);
	s_add_u32 s58, s28, 0x40000
	s_addc_u32 s59, s29, 0
	s_add_i32 s53, s49, s40
	v_lshl_add_u64 v[128:129], s[58:59], 0, v[154:155]
	s_mov_b32 m0, s53
	s_nop 0
	global_load_lds_dwordx4 v[128:129], off
	v_lshl_add_u64 v[128:129], s[58:59], 0, v[158:159]
	s_add_i32 m0, s53, 0x2000
	s_nop 0
	global_load_lds_dwordx4 v[128:129], off
	s_waitcnt vmcnt(6)
	s_barrier
	s_setprio 1
	v_mfma_f32_16x16x32_bf16 v[52:55], v[200:203], v[144:147], v[52:55]
	v_mfma_f32_16x16x32_bf16 v[48:51], v[208:211], v[144:147], v[48:51]
	v_mfma_f32_16x16x32_bf16 v[36:39], v[200:203], v[168:171], v[36:39]
	v_mfma_f32_16x16x32_bf16 v[32:35], v[208:211], v[168:171], v[32:35]
	v_mfma_f32_16x16x32_bf16 v[20:23], v[200:203], v[176:179], v[20:23]
	v_mfma_f32_16x16x32_bf16 v[16:19], v[208:211], v[176:179], v[16:19]
	v_mfma_f32_16x16x32_bf16 v[4:7], v[200:203], v[192:195], v[4:7]
	v_mfma_f32_16x16x32_bf16 v[0:3], v[208:211], v[192:195], v[0:3]
	v_mfma_f32_16x16x32_bf16 v[52:55], v[204:207], v[148:151], v[52:55]
	v_mfma_f32_16x16x32_bf16 v[48:51], v[212:215], v[148:151], v[48:51]
	v_mfma_f32_16x16x32_bf16 v[36:39], v[204:207], v[172:175], v[36:39]
	v_mfma_f32_16x16x32_bf16 v[32:35], v[212:215], v[172:175], v[32:35]
	v_mfma_f32_16x16x32_bf16 v[20:23], v[204:207], v[180:183], v[20:23]
	v_mfma_f32_16x16x32_bf16 v[16:19], v[212:215], v[180:183], v[16:19]
	v_mfma_f32_16x16x32_bf16 v[4:7], v[204:207], v[196:199], v[4:7]
	v_mfma_f32_16x16x32_bf16 v[0:3], v[212:215], v[196:199], v[0:3]
	s_setprio 0
	s_add_i32 s53, 0, 0x18000
	v_add_u32_e32 v140, s53, v185
	s_barrier
	ds_read_b128 v[128:131], v140
	ds_read_b128 v[132:135], v140 offset:1024
	ds_read_b128 v[136:139], v140 offset:2048
	ds_read_b128 v[140:143], v140 offset:3072
	s_add_u32 s38, s38, 0x40000
	s_addc_u32 s39, s39, 0
	s_mov_b32 m0, s41
	v_lshl_add_u64 v[200:201], s[38:39], 0, v[152:153]
	ds_read_b128 v[144:147], v188 offset:32768
	ds_read_b128 v[148:151], v188 offset:33792
	ds_read_b128 v[168:171], v188 offset:34816
	ds_read_b128 v[172:175], v188 offset:35840
	ds_read_b128 v[176:179], v188 offset:36864
	ds_read_b128 v[180:183], v188 offset:37888
	ds_read_b128 v[192:195], v188 offset:38912
	ds_read_b128 v[196:199], v188 offset:39936
	global_load_lds_dwordx4 v[200:201], off
	v_lshl_add_u64 v[200:201], s[38:39], 0, v[156:157]
	s_mov_b32 m0, s42
	s_nop 0
	global_load_lds_dwordx4 v[200:201], off
	s_waitcnt lgkmcnt(8)
	s_barrier
	s_waitcnt lgkmcnt(0)
	s_setprio 1
	s_waitcnt lgkmcnt(0)
	v_mfma_f32_16x16x32_bf16 v[124:127], v[128:131], v[144:147], v[124:127]
	v_mfma_f32_16x16x32_bf16 v[120:123], v[136:139], v[144:147], v[120:123]
	v_mfma_f32_16x16x32_bf16 v[108:111], v[128:131], v[168:171], v[108:111]
	v_mfma_f32_16x16x32_bf16 v[104:107], v[136:139], v[168:171], v[104:107]
	v_mfma_f32_16x16x32_bf16 v[92:95], v[128:131], v[176:179], v[92:95]
	v_mfma_f32_16x16x32_bf16 v[88:91], v[136:139], v[176:179], v[88:91]
	v_mfma_f32_16x16x32_bf16 v[76:79], v[128:131], v[192:195], v[76:79]
	v_mfma_f32_16x16x32_bf16 v[72:75], v[136:139], v[192:195], v[72:75]
	v_mfma_f32_16x16x32_bf16 v[124:127], v[132:135], v[148:151], v[124:127]
	v_mfma_f32_16x16x32_bf16 v[120:123], v[140:143], v[148:151], v[120:123]
	v_mfma_f32_16x16x32_bf16 v[108:111], v[132:135], v[172:175], v[108:111]
	v_mfma_f32_16x16x32_bf16 v[104:107], v[140:143], v[172:175], v[104:107]
	v_mfma_f32_16x16x32_bf16 v[92:95], v[132:135], v[180:183], v[92:95]
	v_mfma_f32_16x16x32_bf16 v[88:91], v[140:143], v[180:183], v[88:91]
	v_mfma_f32_16x16x32_bf16 v[76:79], v[132:135], v[196:199], v[76:79]
	v_mfma_f32_16x16x32_bf16 v[72:75], v[140:143], v[196:199], v[72:75]
	s_setprio 0
	s_barrier
	s_add_i32 s38, 0, 0x1c000
	s_add_i32 s39, s53, s40
	v_add_u32_e32 v191, s38, v185
	v_lshl_add_u64 v[216:217], v[216:217], 0, s[8:9]
	s_mov_b32 m0, s39
	ds_read_b128 v[200:203], v191
	ds_read_b128 v[204:207], v191 offset:1024
	ds_read_b128 v[208:211], v191 offset:2048
	ds_read_b128 v[212:215], v191 offset:3072
	global_load_lds_dwordx4 v[216:217], off
	v_lshl_add_u64 v[216:217], v[218:219], 0, s[8:9]
	s_add_i32 m0, s39, 0x2000
	s_nop 0
	global_load_lds_dwordx4 v[216:217], off
	s_barrier
	s_waitcnt lgkmcnt(0)
	s_setprio 1
	s_waitcnt lgkmcnt(0)
	v_mfma_f32_16x16x32_bf16 v[116:119], v[200:203], v[144:147], v[116:119]
	v_mfma_f32_16x16x32_bf16 v[112:115], v[208:211], v[144:147], v[112:115]
	v_mfma_f32_16x16x32_bf16 v[100:103], v[200:203], v[168:171], v[100:103]
	v_mfma_f32_16x16x32_bf16 v[96:99], v[208:211], v[168:171], v[96:99]
	v_mfma_f32_16x16x32_bf16 v[84:87], v[200:203], v[176:179], v[84:87]
	v_mfma_f32_16x16x32_bf16 v[80:83], v[208:211], v[176:179], v[80:83]
	v_mfma_f32_16x16x32_bf16 v[68:71], v[200:203], v[192:195], v[68:71]
	v_mfma_f32_16x16x32_bf16 v[64:67], v[208:211], v[192:195], v[64:67]
	v_mfma_f32_16x16x32_bf16 v[116:119], v[204:207], v[148:151], v[116:119]
	v_mfma_f32_16x16x32_bf16 v[112:115], v[212:215], v[148:151], v[112:115]
	v_mfma_f32_16x16x32_bf16 v[100:103], v[204:207], v[172:175], v[100:103]
	v_mfma_f32_16x16x32_bf16 v[96:99], v[212:215], v[172:175], v[96:99]
	v_mfma_f32_16x16x32_bf16 v[84:87], v[204:207], v[180:183], v[84:87]
	v_mfma_f32_16x16x32_bf16 v[80:83], v[212:215], v[180:183], v[80:83]
	v_mfma_f32_16x16x32_bf16 v[68:71], v[204:207], v[196:199], v[68:71]
	v_mfma_f32_16x16x32_bf16 v[64:67], v[212:215], v[196:199], v[64:67]
	s_setprio 0
	s_mov_b32 m0, s44
	v_lshl_add_u64 v[216:217], v[220:221], 0, s[8:9]
	s_barrier
	ds_read_b128 v[144:147], v188 offset:49152
	ds_read_b128 v[148:151], v188 offset:50176
	ds_read_b128 v[168:171], v188 offset:51200
	ds_read_b128 v[172:175], v188 offset:52224
	ds_read_b128 v[176:179], v188 offset:53248
	ds_read_b128 v[180:183], v188 offset:54272
	ds_read_b128 v[192:195], v188 offset:55296
	ds_read_b128 v[196:199], v188 offset:56320
	global_load_lds_dwordx4 v[216:217], off
	v_lshl_add_u64 v[216:217], v[224:225], 0, s[8:9]
	s_mov_b32 m0, s45
	s_nop 0
	global_load_lds_dwordx4 v[216:217], off
	s_barrier
; DI unsigned pk_bf16(float lo, float hi) { f32x2 v = {lo, hi}; return __builtin_bit_cast(unsigned, __builtin_convertvector(v, bf16v2)); }
; DI f32x4 bf_lo4(u32x4 w) { f32x4 r; r[0] = bf_lo(w.x); r[1] = bf_hi(w.x); r[2] = bf_lo(w.y); r[3] = bf_hi(w.y); return r; }
; DI f32x4 bf_hi4(u32x4 w) { f32x4 r; r[0] = bf_lo(w.z); r[1] = bf_hi(w.z); r[2] = bf_lo(w.w); r[3] = bf_hi(w.w); return r; }
; #define PG8_WAIT_V(n) asm volatile("s_waitcnt vmcnt(" #n ")" ::: "memory")
; template <class Epi>
; DI void gemm_phase(LAS unsigned char* lds, const Gemm g, const StaticOrder S, const Epi E) {
;     ...
;             PG8_BAR; PG8_WAIT_L(0); PG8_MMA(1, 0, At, B0); PG8_BAR; PG8_SCHED;
;             PG8_STAGE(PG8_SB(1, 1), b3 + hstep, voffB);
;             PG8_WAIT_V(6); PG8_BAR; PG8_MMA(1, 1, At, B1); PG8_BAR;
;     DI void operator()(AccRef acc, const Unit& u, int wr, int wc, int fr, int fq) const {
;     ...
;         for (int ai = 0; ai < 2; ++ai) {
;             f32x4 bv[4][2][2];
; #pragma unroll
;             for (int m = 0; m < 4; ++m)
; #pragma unroll
;                 for (int bj = 0; bj < 2; ++bj) {
;                     const size_t o = (size_t)(row0 + ai * 128 + m * 16) * DM + col0 + bj * 128;
;                     if (BASEF32) { bv[m][bj][0] = *(const f32x4*)(basef + o); bv[m][bj][1] = *(const f32x4*)(basef + o + 4); }
;                     else { const u32x4 h = *(const u32x4*)(xnb + o); bv[m][bj][0] = bf_lo4(h); bv[m][bj][1] = bf_hi4(h); }
;                 }
; #pragma unroll
;             for (int m = 0; m < 4; ++m) {
;                 const int row = row0 + ai * 128 + m * 16;
;                 float q = 0.f;
; #pragma unroll
;                 for (int bj = 0; bj < 2; ++bj) {
;                     const size_t o = (size_t)row * DM + col0 + bj * 128;
;                     const f32x4 r0 = bv[m][bj][0] + scale * acc[ai][bj][m][0], r1 = bv[m][bj][1] + scale * acc[ai][bj][m][1];
;                     u32x4 w; w.x = pk_bf16(r0[0], r0[1]); w.y = pk_bf16(r0[2], r0[3]); w.z = pk_bf16(r1[0], r1[1]); w.w = pk_bf16(r1[2], r1[3]);
;                     *(u32x4*)(xnb + o) = w;
;                     if (STATS) q += r0[0] * r0[0] + r0[1] * r0[1] + r0[2] * r0[2] + r0[3] * r0[3] + r1[0] * r1[0] + r1[1] * r1[1] + r1[2] * r1[2] + r1[3] * r1[3];
;                 }
;                 if (STATS) { q += __shfl_xor(q, 16); q += __shfl_xor(q, 32); if (fq == 0) atomicAdd(ss + row, q); }
	s_waitcnt lgkmcnt(0)
	s_setprio 1
	s_waitcnt lgkmcnt(0)
	v_mfma_f32_16x16x32_bf16 v[60:63], v[128:131], v[144:147], v[60:63]
	v_mfma_f32_16x16x32_bf16 v[56:59], v[136:139], v[144:147], v[56:59]
	v_mfma_f32_16x16x32_bf16 v[44:47], v[128:131], v[168:171], v[44:47]
	v_mfma_f32_16x16x32_bf16 v[40:43], v[136:139], v[168:171], v[40:43]
	v_mfma_f32_16x16x32_bf16 v[28:31], v[128:131], v[176:179], v[28:31]
	v_mfma_f32_16x16x32_bf16 v[24:27], v[136:139], v[176:179], v[24:27]
	v_mfma_f32_16x16x32_bf16 v[12:15], v[128:131], v[192:195], v[12:15]
	v_mfma_f32_16x16x32_bf16 v[8:11], v[136:139], v[192:195], v[8:11]
	v_mfma_f32_16x16x32_bf16 v[60:63], v[132:135], v[148:151], v[60:63]
	v_mfma_f32_16x16x32_bf16 v[56:59], v[140:143], v[148:151], v[56:59]
	v_mfma_f32_16x16x32_bf16 v[44:47], v[132:135], v[172:175], v[44:47]
	v_mfma_f32_16x16x32_bf16 v[40:43], v[140:143], v[172:175], v[40:43]
	v_mfma_f32_16x16x32_bf16 v[28:31], v[132:135], v[180:183], v[28:31]
	v_mfma_f32_16x16x32_bf16 v[24:27], v[140:143], v[180:183], v[24:27]
	v_mfma_f32_16x16x32_bf16 v[12:15], v[132:135], v[196:199], v[12:15]
	v_mfma_f32_16x16x32_bf16 v[8:11], v[140:143], v[196:199], v[8:11]
	s_setprio 0
	s_barrier
	s_add_u32 s28, s28, 0x40080
	s_addc_u32 s29, s29, 0
	s_add_i32 s38, s38, s40
	v_lshl_add_u64 v[128:129], s[28:29], 0, v[154:155]
	s_mov_b32 m0, s38
	s_nop 0
	global_load_lds_dwordx4 v[128:129], off
	v_lshl_add_u64 v[128:129], s[28:29], 0, v[158:159]
	s_add_i32 m0, s38, 0x2000
	s_nop 0
	global_load_lds_dwordx4 v[128:129], off
	s_waitcnt vmcnt(6)
	s_barrier
	s_setprio 1
	v_mfma_f32_16x16x32_bf16 v[52:55], v[200:203], v[144:147], v[52:55]
	v_mfma_f32_16x16x32_bf16 v[48:51], v[208:211], v[144:147], v[48:51]
	v_mfma_f32_16x16x32_bf16 v[36:39], v[200:203], v[168:171], v[36:39]
	v_mfma_f32_16x16x32_bf16 v[32:35], v[208:211], v[168:171], v[32:35]
	v_mfma_f32_16x16x32_bf16 v[20:23], v[200:203], v[176:179], v[20:23]
	v_mfma_f32_16x16x32_bf16 v[16:19], v[208:211], v[176:179], v[16:19]
	v_mfma_f32_16x16x32_bf16 v[4:7], v[200:203], v[192:195], v[4:7]
	v_mfma_f32_16x16x32_bf16 v[0:3], v[208:211], v[192:195], v[0:3]
	v_mfma_f32_16x16x32_bf16 v[52:55], v[204:207], v[148:151], v[52:55]
	v_mfma_f32_16x16x32_bf16 v[48:51], v[212:215], v[148:151], v[48:51]
	v_mfma_f32_16x16x32_bf16 v[36:39], v[204:207], v[172:175], v[36:39]
	v_mfma_f32_16x16x32_bf16 v[32:35], v[212:215], v[172:175], v[32:35]
	v_mfma_f32_16x16x32_bf16 v[20:23], v[204:207], v[180:183], v[20:23]
	v_mfma_f32_16x16x32_bf16 v[16:19], v[212:215], v[180:183], v[16:19]
	v_mfma_f32_16x16x32_bf16 v[4:7], v[204:207], v[196:199], v[4:7]
	v_mfma_f32_16x16x32_bf16 v[0:3], v[212:215], v[196:199], v[0:3]
	s_setprio 0
	s_add_i32 s52, s52, 2
	s_add_u32 s24, s24, 0x100
	s_addc_u32 s25, s25, 0
	s_add_u32 s50, s50, 0x100
	s_addc_u32 s51, s51, 0
	s_cmp_gt_u32 s52, 13
	s_barrier
	s_cbranch_scc0 .LBB0_786
	v_lshl_add_u32 v170, s18, 8, v184
	v_lshl_or_b32 v128, s22, 8, v186
	v_ashrrev_i32_e32 v129, 31, v128
	v_ashrrev_i32_e32 v171, 31, v170
	v_lshl_add_u64 v[168:169], v[128:129], 1, s[56:57]
	v_lshlrev_b64 v[128:129], 11, v[170:171]
	v_lshl_add_u64 v[202:203], v[168:169], 0, v[128:129]
	global_load_dwordx4 v[194:197], v[202:203], off
	global_load_dwordx4 v[198:201], v[202:203], off offset:256
	v_or_b32_e32 v180, 16, v170
	v_or_b32_e32 v176, 32, v170
	v_or_b32_e32 v172, 48, v170
	v_ashrrev_i32_e32 v181, 31, v180
	v_ashrrev_i32_e32 v177, 31, v176
	v_ashrrev_i32_e32 v173, 31, v172
	v_lshlrev_b64 v[128:129], 11, v[180:181]
	v_lshlrev_b64 v[130:131], 11, v[176:177]
	v_lshlrev_b64 v[132:133], 11, v[172:173]
	v_lshl_add_u64 v[182:183], v[168:169], 0, v[128:129]
	v_lshl_add_u64 v[178:179], v[168:169], 0, v[130:131]
	v_lshl_add_u64 v[174:175], v[168:169], 0, v[132:133]
	global_load_dwordx4 v[148:151], v[182:183], off
	global_load_dwordx4 v[144:147], v[182:183], off offset:256
	global_load_dwordx4 v[140:143], v[178:179], off
	global_load_dwordx4 v[136:139], v[178:179], off offset:256
	global_load_dwordx4 v[132:135], v[174:175], off
	global_load_dwordx4 v[128:131], v[174:175], off offset:256
	v_and_b32_e32 v192, 64, v190
	v_xor_b32_e32 v191, 16, v190
	v_add_u32_e32 v192, 64, v192
	v_cmp_lt_i32_e32 vcc, v191, v192
	v_xor_b32_e32 v193, 32, v190
	s_waitcnt vmcnt(0)
	v_lshlrev_b32_e32 v204, 16, v194
	v_and_b32_e32 v205, 0xffff0000, v194
	v_lshlrev_b32_e32 v208, 16, v198
	v_and_b32_e32 v209, 0xffff0000, v198
	v_lshlrev_b32_e32 v194, 16, v195
	v_and_b32_e32 v195, 0xffff0000, v195
	v_lshlrev_b32_e32 v210, 16, v200
	v_and_b32_e32 v211, 0xffff0000, v200
	v_lshlrev_b32_e32 v200, 16, v201
	v_and_b32_e32 v201, 0xffff0000, v201
	v_pk_add_f32 v[124:125], v[124:125], v[204:205]
	v_pk_add_f32 v[116:117], v[116:117], v[208:209]
	v_lshlrev_b32_e32 v198, 16, v199
	v_and_b32_e32 v199, 0xffff0000, v199
	v_pk_add_f32 v[126:127], v[126:127], v[194:195]
	v_pk_add_f32 v[194:195], v[114:115], v[200:201]
	v_mul_f32_e32 v114, v125, v125
	v_mul_f32_e32 v115, v117, v117
	v_pk_add_f32 v[118:119], v[118:119], v[198:199]
	v_fmac_f32_e32 v114, v124, v124
	v_fmac_f32_e32 v115, v116, v116
	v_lshlrev_b32_e32 v206, 16, v196
	v_and_b32_e32 v207, 0xffff0000, v196
	v_lshlrev_b32_e32 v196, 16, v197
	v_and_b32_e32 v197, 0xffff0000, v197
	v_fmac_f32_e32 v114, v126, v126
	v_fmac_f32_e32 v115, v118, v118
	v_pk_add_f32 v[122:123], v[122:123], v[196:197]
	v_pk_add_f32 v[120:121], v[120:121], v[206:207]
	v_pk_add_f32 v[196:197], v[112:113], v[210:211]
	v_fmac_f32_e32 v114, v127, v127
	v_fmac_f32_e32 v115, v119, v119
	v_fmac_f32_e32 v114, v120, v120
	v_fmac_f32_e32 v115, v196, v196
	v_fmac_f32_e32 v114, v121, v121
	v_fmac_f32_e32 v115, v197, v197
	v_fmac_f32_e32 v114, v122, v122
	v_fmac_f32_e32 v115, v194, v194
	v_cndmask_b32_e32 v191, v190, v191, vcc
	v_fmac_f32_e32 v114, v123, v123
	v_fmac_f32_e32 v115, v195, v195
	v_cmp_lt_i32_e32 vcc, v193, v192
	v_lshlrev_b32_e32 v192, 2, v191
	v_cvt_pk_bf16_f32 v112, v124, v125
	v_add_f32_e32 v124, v114, v115
	ds_bpermute_b32 v125, v192, v124
	v_cndmask_b32_e32 v193, v190, v193, vcc
	v_cvt_pk_bf16_f32 v113, v126, v127
	v_cvt_pk_bf16_f32 v114, v120, v121
	v_cvt_pk_bf16_f32 v115, v122, v123
	v_lshlrev_b32_e32 v191, 2, v193
	global_store_dwordx4 v[202:203], v[112:115], off
	s_waitcnt lgkmcnt(0)
	s_nop 0
	v_add_f32_e32 v112, v124, v125
	ds_bpermute_b32 v113, v191, v112
	v_cvt_pk_bf16_f32 v114, v116, v117
	v_cvt_pk_bf16_f32 v115, v118, v119
	v_cvt_pk_bf16_f32 v116, v196, v197
	v_cvt_pk_bf16_f32 v117, v194, v195
	global_store_dwordx4 v[202:203], v[114:117], off offset:256
	s_and_saveexec_b64 s[6:7], s[0:1]
	s_cbranch_execz .LBB0_789
	s_waitcnt lgkmcnt(0)
	v_add_f32_e32 v114, v112, v113
	v_lshl_add_u64 v[112:113], v[170:171], 2, s[20:21]
	global_atomic_add_f32 v[112:113], v114, off

; #define PG8_STAGE(bufoff, gbase, voff) do { _Pragma("unroll") for (int _i = 0; _i < 2; ++_i) \
;         __builtin_amdgcn_global_load_lds((const unsigned*)((const char*)(gbase) + (voff)[_i]), (LAS unsigned*)(lds + (bufoff) + ldsw + _i * 8192), 16, 0, 0); } while (0)
; #define PG8_LDA(dst, b, h) do { _Pragma("unroll") for (int m = 0; m < 4; ++m) _Pragma("unroll") for (int k = 0; k < 2; ++k) dst[m][k] = *(const LAS bf16x8*)(lds + PG8_SA(b, h) + aoff + m * 2048 + k * 1024); } while (0)
; #define PG8_LDB(dst, b, h) do { _Pragma("unroll") for (int n = 0; n < 2; ++n) _Pragma("unroll") for (int k = 0; k < 2; ++k) dst[n][k] = *(const LAS bf16x8*)(lds + PG8_SB(b, h) + boff + n * 2048 + k * 1024); } while (0)
; #define PG8_MMA(ai, bj, At, Bt) do { __builtin_amdgcn_s_setprio(1); _Pragma("unroll") for (int m = 0; m < 4; ++m) _Pragma("unroll") for (int n = 0; n < 2; ++n) _Pragma("unroll") for (int k = 0; k < 2; ++k) \
;         acc[ai][bj][m][n] = __builtin_amdgcn_mfma_f32_16x16x32_bf16(Bt[n][k], At[m][k], acc[ai][bj][m][n], 0, 0, 0); __builtin_amdgcn_s_setprio(0); } while (0)
; #define PG8_WAIT_L(n) asm volatile("s_waitcnt lgkmcnt(" #n ")" ::: "memory")
; #define PG8_BAR __builtin_amdgcn_s_barrier()
; #define PG8_SCHED __builtin_amdgcn_sched_barrier(0)
; #define PG8_WAIT_L(n) asm volatile("s_waitcnt lgkmcnt(" #n ")" ::: "memory")
; #define PG8_BAR __builtin_amdgcn_s_barrier()
; template <class Epi>
; DI void gemm_phase(LAS unsigned char* lds, const Gemm g, const StaticOrder S, const Epi E) {
;     ...
;         for (int t = 0; t < nt; t += 2) {
;             const bool last = (t == nt - 2);
;             const char* a1 = cA + (size_t)(t + 1) * kstep;
;             const char* a2 = last ? nA : cA + (size_t)(t + 2) * kstep; const char* b2 = last ? nB : cB + (size_t)(t + 2) * kstep;
;             const char* a3 = a2 + kstep; const char* b3 = b2 + kstep;
;             PG8_LDB(B0, 0, 0); PG8_SCHED; PG8_LDA(At, 0, 0); PG8_STAGE(PG8_SA(1, 1), a1 + hstep, voffA);
;             PG8_WAIT_L(8); PG8_BAR; PG8_WAIT_L(0); PG8_MMA(0, 0, At, B0); PG8_BAR; PG8_SCHED;
;             PG8_LDB(B1, 0, 1); PG8_STAGE(PG8_SB(0, 0), b2, voffB);
;             PG8_BAR; PG8_WAIT_L(0); PG8_MMA(0, 1, At, B1); PG8_BAR;
;             PG8_LDA(At, 0, 1); PG8_STAGE(PG8_SA(0, 0), a2, voffA);
;             PG8_BAR; PG8_WAIT_L(0); PG8_MMA(1, 0, At, B0); PG8_BAR; PG8_SCHED;
.LBB0_865:
	ds_read_b128 v[144:147], v155
	ds_read_b128 v[160:163], v155 offset:1024
	ds_read_b128 v[164:167], v155 offset:2048
	ds_read_b128 v[168:171], v155 offset:3072
	s_add_u32 s10, s8, 0xfffc0080
	s_addc_u32 s11, s9, -1
	s_cmp_eq_u32 s25, 12
	s_cselect_b32 s13, s14, s11
	s_cselect_b32 s12, s15, s10
	s_cselect_b32 s11, s16, s19
	s_cselect_b32 s10, s17, s18
	v_lshl_add_u64 v[204:205], s[8:9], 0, v[136:137]
	s_add_i32 m0, s40, 0xc000
	ds_read_b128 v[172:175], v157
	ds_read_b128 v[176:179], v157 offset:1024
	ds_read_b128 v[180:183], v157 offset:2048
	ds_read_b128 v[184:187], v157 offset:3072
	ds_read_b128 v[188:191], v157 offset:4096
	ds_read_b128 v[192:195], v157 offset:5120
	ds_read_b128 v[196:199], v157 offset:6144
	ds_read_b128 v[200:203], v157 offset:7168
	global_load_lds_dwordx4 v[204:205], off
	v_lshl_add_u64 v[204:205], s[8:9], 0, v[138:139]
	s_add_i32 m0, s40, 0xe000
	s_nop 0
	global_load_lds_dwordx4 v[204:205], off
	s_waitcnt lgkmcnt(8)
	s_barrier
	s_waitcnt lgkmcnt(0)
	s_setprio 1
	s_waitcnt lgkmcnt(0)
	v_mfma_f32_16x16x32_bf16 v[124:127], v[144:147], v[172:175], v[124:127]
	v_mfma_f32_16x16x32_bf16 v[120:123], v[164:167], v[172:175], v[120:123]
	v_mfma_f32_16x16x32_bf16 v[108:111], v[144:147], v[180:183], v[108:111]
	v_mfma_f32_16x16x32_bf16 v[104:107], v[164:167], v[180:183], v[104:107]
	v_mfma_f32_16x16x32_bf16 v[92:95], v[144:147], v[188:191], v[92:95]
	v_mfma_f32_16x16x32_bf16 v[88:91], v[164:167], v[188:191], v[88:91]
	v_mfma_f32_16x16x32_bf16 v[76:79], v[144:147], v[196:199], v[76:79]
	v_mfma_f32_16x16x32_bf16 v[72:75], v[164:167], v[196:199], v[72:75]
	v_mfma_f32_16x16x32_bf16 v[124:127], v[160:163], v[176:179], v[124:127]
	v_mfma_f32_16x16x32_bf16 v[120:123], v[168:171], v[176:179], v[120:123]
	v_mfma_f32_16x16x32_bf16 v[108:111], v[160:163], v[184:187], v[108:111]
	v_mfma_f32_16x16x32_bf16 v[104:107], v[168:171], v[184:187], v[104:107]
	v_mfma_f32_16x16x32_bf16 v[92:95], v[160:163], v[192:195], v[92:95]
	v_mfma_f32_16x16x32_bf16 v[88:91], v[168:171], v[192:195], v[88:91]
	v_mfma_f32_16x16x32_bf16 v[76:79], v[160:163], v[200:203], v[76:79]
	v_mfma_f32_16x16x32_bf16 v[72:75], v[168:171], v[200:203], v[72:75]
	s_setprio 0
	s_barrier
	s_add_i32 s29, s49, s34
	v_lshl_add_u64 v[220:221], s[10:11], 0, v[132:133]
	s_mov_b32 m0, s29
	ds_read_b128 v[204:207], v158
	ds_read_b128 v[208:211], v158 offset:1024
	ds_read_b128 v[212:215], v158 offset:2048
	ds_read_b128 v[216:219], v158 offset:3072
	global_load_lds_dwordx4 v[220:221], off
	v_lshl_add_u64 v[224:225], s[10:11], 0, v[128:129]
	s_add_i32 m0, s29, 0x2000
	s_nop 0
	global_load_lds_dwordx4 v[224:225], off
	s_barrier
	s_waitcnt lgkmcnt(0)
	s_setprio 1
	s_waitcnt lgkmcnt(0)
	v_mfma_f32_16x16x32_bf16 v[116:119], v[204:207], v[172:175], v[116:119]
	v_mfma_f32_16x16x32_bf16 v[112:115], v[212:215], v[172:175], v[112:115]
	v_mfma_f32_16x16x32_bf16 v[100:103], v[204:207], v[180:183], v[100:103]
	v_mfma_f32_16x16x32_bf16 v[96:99], v[212:215], v[180:183], v[96:99]
	v_mfma_f32_16x16x32_bf16 v[84:87], v[204:207], v[188:191], v[84:87]
	v_mfma_f32_16x16x32_bf16 v[80:83], v[212:215], v[188:191], v[80:83]
	v_mfma_f32_16x16x32_bf16 v[68:71], v[204:207], v[196:199], v[68:71]
	v_mfma_f32_16x16x32_bf16 v[64:67], v[212:215], v[196:199], v[64:67]
	v_mfma_f32_16x16x32_bf16 v[116:119], v[208:211], v[176:179], v[116:119]
	v_mfma_f32_16x16x32_bf16 v[112:115], v[216:219], v[176:179], v[112:115]
	v_mfma_f32_16x16x32_bf16 v[100:103], v[208:211], v[184:187], v[100:103]
	v_mfma_f32_16x16x32_bf16 v[96:99], v[216:219], v[184:187], v[96:99]
	v_mfma_f32_16x16x32_bf16 v[84:87], v[208:211], v[192:195], v[84:87]
	v_mfma_f32_16x16x32_bf16 v[80:83], v[216:219], v[192:195], v[80:83]
	v_mfma_f32_16x16x32_bf16 v[68:71], v[208:211], v[200:203], v[68:71]
	v_mfma_f32_16x16x32_bf16 v[64:67], v[216:219], v[200:203], v[64:67]
	s_setprio 0
	s_mov_b32 m0, s40
	v_lshl_add_u64 v[226:227], s[12:13], 0, v[134:135]
	s_barrier
	ds_read_b128 v[172:175], v157 offset:16384
	ds_read_b128 v[176:179], v157 offset:17408
	ds_read_b128 v[180:183], v157 offset:18432
	ds_read_b128 v[184:187], v157 offset:19456
	ds_read_b128 v[188:191], v157 offset:20480
	ds_read_b128 v[192:195], v157 offset:21504
	ds_read_b128 v[196:199], v157 offset:22528
	ds_read_b128 v[200:203], v157 offset:23552
	global_load_lds_dwordx4 v[226:227], off
	v_lshl_add_u64 v[228:229], s[12:13], 0, v[130:131]
	s_mov_b32 m0, s41
	s_nop 0
	global_load_lds_dwordx4 v[228:229], off
	s_barrier
	s_waitcnt lgkmcnt(0)
	s_setprio 1
	s_waitcnt lgkmcnt(0)
	v_mfma_f32_16x16x32_bf16 v[60:63], v[144:147], v[172:175], v[60:63]
	v_mfma_f32_16x16x32_bf16 v[56:59], v[164:167], v[172:175], v[56:59]
	v_mfma_f32_16x16x32_bf16 v[44:47], v[144:147], v[180:183], v[44:47]
	v_mfma_f32_16x16x32_bf16 v[40:43], v[164:167], v[180:183], v[40:43]
	v_mfma_f32_16x16x32_bf16 v[28:31], v[144:147], v[188:191], v[28:31]
	v_mfma_f32_16x16x32_bf16 v[24:27], v[164:167], v[188:191], v[24:27]
	v_mfma_f32_16x16x32_bf16 v[12:15], v[144:147], v[196:199], v[12:15]
	v_mfma_f32_16x16x32_bf16 v[8:11], v[164:167], v[196:199], v[8:11]
	v_mfma_f32_16x16x32_bf16 v[60:63], v[160:163], v[176:179], v[60:63]
	v_mfma_f32_16x16x32_bf16 v[56:59], v[168:171], v[176:179], v[56:59]
	v_mfma_f32_16x16x32_bf16 v[44:47], v[160:163], v[184:187], v[44:47]
	v_mfma_f32_16x16x32_bf16 v[40:43], v[168:171], v[184:187], v[40:43]
	v_mfma_f32_16x16x32_bf16 v[28:31], v[160:163], v[192:195], v[28:31]
	v_mfma_f32_16x16x32_bf16 v[24:27], v[168:171], v[192:195], v[24:27]
	v_mfma_f32_16x16x32_bf16 v[12:15], v[160:163], v[200:203], v[12:15]
	v_mfma_f32_16x16x32_bf16 v[8:11], v[168:171], v[200:203], v[8:11]
	s_setprio 0
	s_barrier
; #define PG8_STAGE(bufoff, gbase, voff) do { _Pragma("unroll") for (int _i = 0; _i < 2; ++_i) \
;         __builtin_amdgcn_global_load_lds((const unsigned*)((const char*)(gbase) + (voff)[_i]), (LAS unsigned*)(lds + (bufoff) + ldsw + _i * 8192), 16, 0, 0); } while (0)
; #define PG8_LDA(dst, b, h) do { _Pragma("unroll") for (int m = 0; m < 4; ++m) _Pragma("unroll") for (int k = 0; k < 2; ++k) dst[m][k] = *(const LAS bf16x8*)(lds + PG8_SA(b, h) + aoff + m * 2048 + k * 1024); } while (0)
; #define PG8_LDB(dst, b, h) do { _Pragma("unroll") for (int n = 0; n < 2; ++n) _Pragma("unroll") for (int k = 0; k < 2; ++k) dst[n][k] = *(const LAS bf16x8*)(lds + PG8_SB(b, h) + boff + n * 2048 + k * 1024); } while (0)
; #define PG8_MMA(ai, bj, At, Bt) do { __builtin_amdgcn_s_setprio(1); _Pragma("unroll") for (int m = 0; m < 4; ++m) _Pragma("unroll") for (int n = 0; n < 2; ++n) _Pragma("unroll") for (int k = 0; k < 2; ++k) \
;         acc[ai][bj][m][n] = __builtin_amdgcn_mfma_f32_16x16x32_bf16(Bt[n][k], At[m][k], acc[ai][bj][m][n], 0, 0, 0); __builtin_amdgcn_s_setprio(0); } while (0)
; #define PG8_WAIT_V(n) asm volatile("s_waitcnt vmcnt(" #n ")" ::: "memory")
; #define PG8_WAIT_L(n) asm volatile("s_waitcnt lgkmcnt(" #n ")" ::: "memory")
; #define PG8_BAR __builtin_amdgcn_s_barrier()
; #define PG8_SCHED __builtin_amdgcn_sched_barrier(0)
; #define PG8_STAGE(bufoff, gbase, voff) do { _Pragma("unroll") for (int _i = 0; _i < 2; ++_i) \
;         __builtin_amdgcn_global_load_lds((const unsigned*)((const char*)(gbase) + (voff)[_i]), (LAS unsigned*)(lds + (bufoff) + ldsw + _i * 8192), 16, 0, 0); } while (0)
; #define PG8_WAIT_V(n) asm volatile("s_waitcnt vmcnt(" #n ")" ::: "memory")
; #define PG8_BAR __builtin_amdgcn_s_barrier()
; template <class Epi>
; DI void gemm_phase(LAS unsigned char* lds, const Gemm g, const StaticOrder S, const Epi E) {
;     ...
;             PG8_STAGE(PG8_SB(0, 1), b2 + hstep, voffB);
;             PG8_WAIT_V(6); PG8_BAR; PG8_MMA(1, 1, At, B1); PG8_BAR;
;             PG8_LDB(B0, 1, 0); PG8_SCHED; PG8_LDA(At, 1, 0); PG8_STAGE(PG8_SA(0, 1), a2 + hstep, voffA);
;             PG8_WAIT_L(8); PG8_BAR; PG8_WAIT_L(0); PG8_MMA(0, 0, At, B0); PG8_BAR; PG8_SCHED;
;             PG8_LDB(B1, 1, 1); PG8_STAGE(PG8_SB(1, 0), b3, voffB);
;             PG8_BAR; PG8_WAIT_L(0); PG8_MMA(0, 1, At, B1); PG8_BAR;
;             PG8_LDA(At, 1, 1); PG8_STAGE(PG8_SA(1, 0), a3, voffA);
	s_add_u32 s58, s10, 0x40000
	s_addc_u32 s59, s11, 0
	s_add_i32 s29, s50, s34
	v_lshl_add_u64 v[144:145], s[58:59], 0, v[132:133]
	s_mov_b32 m0, s29
	s_nop 0
	global_load_lds_dwordx4 v[144:145], off
	v_lshl_add_u64 v[144:145], s[58:59], 0, v[128:129]
	s_add_i32 m0, s29, 0x2000
	s_nop 0
	global_load_lds_dwordx4 v[144:145], off
	s_waitcnt vmcnt(6)
	s_barrier
	s_setprio 1
	v_mfma_f32_16x16x32_bf16 v[52:55], v[204:207], v[172:175], v[52:55]
	v_mfma_f32_16x16x32_bf16 v[48:51], v[212:215], v[172:175], v[48:51]
	v_mfma_f32_16x16x32_bf16 v[36:39], v[204:207], v[180:183], v[36:39]
	v_mfma_f32_16x16x32_bf16 v[32:35], v[212:215], v[180:183], v[32:35]
	v_mfma_f32_16x16x32_bf16 v[20:23], v[204:207], v[188:191], v[20:23]
	v_mfma_f32_16x16x32_bf16 v[16:19], v[212:215], v[188:191], v[16:19]
	v_mfma_f32_16x16x32_bf16 v[4:7], v[204:207], v[196:199], v[4:7]
	v_mfma_f32_16x16x32_bf16 v[0:3], v[212:215], v[196:199], v[0:3]
	v_mfma_f32_16x16x32_bf16 v[52:55], v[208:211], v[176:179], v[52:55]
	v_mfma_f32_16x16x32_bf16 v[48:51], v[216:219], v[176:179], v[48:51]
	v_mfma_f32_16x16x32_bf16 v[36:39], v[208:211], v[184:187], v[36:39]
	v_mfma_f32_16x16x32_bf16 v[32:35], v[216:219], v[184:187], v[32:35]
	v_mfma_f32_16x16x32_bf16 v[20:23], v[208:211], v[192:195], v[20:23]
	v_mfma_f32_16x16x32_bf16 v[16:19], v[216:219], v[192:195], v[16:19]
	v_mfma_f32_16x16x32_bf16 v[4:7], v[208:211], v[200:203], v[4:7]
	v_mfma_f32_16x16x32_bf16 v[0:3], v[216:219], v[200:203], v[0:3]
	s_setprio 0
	s_add_i32 s29, 0, 0x18000
	v_add_u32_e32 v148, s29, v151
	s_barrier
	ds_read_b128 v[144:147], v148
	ds_read_b128 v[160:163], v148 offset:1024
	ds_read_b128 v[164:167], v148 offset:2048
	ds_read_b128 v[168:171], v148 offset:3072
	s_add_u32 s12, s12, 0x40000
	s_addc_u32 s13, s13, 0
	s_mov_b32 m0, s42
	v_lshl_add_u64 v[204:205], s[12:13], 0, v[134:135]
	ds_read_b128 v[172:175], v157 offset:32768
	ds_read_b128 v[176:179], v157 offset:33792
	ds_read_b128 v[180:183], v157 offset:34816
	ds_read_b128 v[184:187], v157 offset:35840
	ds_read_b128 v[188:191], v157 offset:36864
	ds_read_b128 v[192:195], v157 offset:37888
	ds_read_b128 v[196:199], v157 offset:38912
	ds_read_b128 v[200:203], v157 offset:39936
	global_load_lds_dwordx4 v[204:205], off
	v_lshl_add_u64 v[204:205], s[12:13], 0, v[130:131]
	s_mov_b32 m0, s43
	s_nop 0
	global_load_lds_dwordx4 v[204:205], off
	s_waitcnt lgkmcnt(8)
	s_barrier
	s_waitcnt lgkmcnt(0)
	s_setprio 1
	s_waitcnt lgkmcnt(0)
	v_mfma_f32_16x16x32_bf16 v[124:127], v[144:147], v[172:175], v[124:127]
	v_mfma_f32_16x16x32_bf16 v[120:123], v[164:167], v[172:175], v[120:123]
	v_mfma_f32_16x16x32_bf16 v[108:111], v[144:147], v[180:183], v[108:111]
	v_mfma_f32_16x16x32_bf16 v[104:107], v[164:167], v[180:183], v[104:107]
	v_mfma_f32_16x16x32_bf16 v[92:95], v[144:147], v[188:191], v[92:95]
	v_mfma_f32_16x16x32_bf16 v[88:91], v[164:167], v[188:191], v[88:91]
	v_mfma_f32_16x16x32_bf16 v[76:79], v[144:147], v[196:199], v[76:79]
	v_mfma_f32_16x16x32_bf16 v[72:75], v[164:167], v[196:199], v[72:75]
	v_mfma_f32_16x16x32_bf16 v[124:127], v[160:163], v[176:179], v[124:127]
	v_mfma_f32_16x16x32_bf16 v[120:123], v[168:171], v[176:179], v[120:123]
	v_mfma_f32_16x16x32_bf16 v[108:111], v[160:163], v[184:187], v[108:111]
	v_mfma_f32_16x16x32_bf16 v[104:107], v[168:171], v[184:187], v[104:107]
	v_mfma_f32_16x16x32_bf16 v[92:95], v[160:163], v[192:195], v[92:95]
	v_mfma_f32_16x16x32_bf16 v[88:91], v[168:171], v[192:195], v[88:91]
	v_mfma_f32_16x16x32_bf16 v[76:79], v[160:163], v[200:203], v[76:79]
	v_mfma_f32_16x16x32_bf16 v[72:75], v[168:171], v[200:203], v[72:75]
	s_setprio 0
	s_barrier
	s_add_i32 s12, 0, 0x1c000
	s_add_i32 s13, s29, s34
	v_add_u32_e32 v148, s12, v151
	v_lshl_add_u64 v[220:221], v[220:221], 0, s[22:23]
	s_mov_b32 m0, s13
	ds_read_b128 v[204:207], v148
	ds_read_b128 v[208:211], v148 offset:1024
	ds_read_b128 v[212:215], v148 offset:2048
	ds_read_b128 v[216:219], v148 offset:3072
	global_load_lds_dwordx4 v[220:221], off
	v_lshl_add_u64 v[220:221], v[224:225], 0, s[22:23]
	s_add_i32 m0, s13, 0x2000
	s_nop 0
	global_load_lds_dwordx4 v[220:221], off
	s_barrier
	s_waitcnt lgkmcnt(0)
	s_setprio 1
	s_waitcnt lgkmcnt(0)
	v_mfma_f32_16x16x32_bf16 v[116:119], v[204:207], v[172:175], v[116:119]
	v_mfma_f32_16x16x32_bf16 v[112:115], v[212:215], v[172:175], v[112:115]
	v_mfma_f32_16x16x32_bf16 v[100:103], v[204:207], v[180:183], v[100:103]
	v_mfma_f32_16x16x32_bf16 v[96:99], v[212:215], v[180:183], v[96:99]
	v_mfma_f32_16x16x32_bf16 v[84:87], v[204:207], v[188:191], v[84:87]
	v_mfma_f32_16x16x32_bf16 v[80:83], v[212:215], v[188:191], v[80:83]
	v_mfma_f32_16x16x32_bf16 v[68:71], v[204:207], v[196:199], v[68:71]
	v_mfma_f32_16x16x32_bf16 v[64:67], v[212:215], v[196:199], v[64:67]
	v_mfma_f32_16x16x32_bf16 v[116:119], v[208:211], v[176:179], v[116:119]
	v_mfma_f32_16x16x32_bf16 v[112:115], v[216:219], v[176:179], v[112:115]
	v_mfma_f32_16x16x32_bf16 v[100:103], v[208:211], v[184:187], v[100:103]
	v_mfma_f32_16x16x32_bf16 v[96:99], v[216:219], v[184:187], v[96:99]
	v_mfma_f32_16x16x32_bf16 v[84:87], v[208:211], v[192:195], v[84:87]
	v_mfma_f32_16x16x32_bf16 v[80:83], v[216:219], v[192:195], v[80:83]
	v_mfma_f32_16x16x32_bf16 v[68:71], v[208:211], v[200:203], v[68:71]
	v_mfma_f32_16x16x32_bf16 v[64:67], v[216:219], v[200:203], v[64:67]
	s_setprio 0
	s_mov_b32 m0, s45
	v_lshl_add_u64 v[220:221], v[226:227], 0, s[22:23]
	s_barrier
	ds_read_b128 v[172:175], v157 offset:49152
	ds_read_b128 v[176:179], v157 offset:50176
	ds_read_b128 v[180:183], v157 offset:51200
	ds_read_b128 v[184:187], v157 offset:52224
	ds_read_b128 v[188:191], v157 offset:53248
	ds_read_b128 v[192:195], v157 offset:54272
	ds_read_b128 v[196:199], v157 offset:55296
	ds_read_b128 v[200:203], v157 offset:56320
	global_load_lds_dwordx4 v[220:221], off
	v_lshl_add_u64 v[220:221], v[228:229], 0, s[22:23]
	s_mov_b32 m0, s46
	s_nop 0
	global_load_lds_dwordx4 v[220:221], off
	s_barrier
; #define PG8_STAGE(bufoff, gbase, voff) do { _Pragma("unroll") for (int _i = 0; _i < 2; ++_i) \
;         __builtin_amdgcn_global_load_lds((const unsigned*)((const char*)(gbase) + (voff)[_i]), (LAS unsigned*)(lds + (bufoff) + ldsw + _i * 8192), 16, 0, 0); } while (0)
; #define PG8_MMA(ai, bj, At, Bt) do { __builtin_amdgcn_s_setprio(1); _Pragma("unroll") for (int m = 0; m < 4; ++m) _Pragma("unroll") for (int n = 0; n < 2; ++n) _Pragma("unroll") for (int k = 0; k < 2; ++k) \
;         acc[ai][bj][m][n] = __builtin_amdgcn_mfma_f32_16x16x32_bf16(Bt[n][k], At[m][k], acc[ai][bj][m][n], 0, 0, 0); __builtin_amdgcn_s_setprio(0); } while (0)
; #define PG8_WAIT_V(n) asm volatile("s_waitcnt vmcnt(" #n ")" ::: "memory")
; #define PG8_WAIT_L(n) asm volatile("s_waitcnt lgkmcnt(" #n ")" ::: "memory")
; #define PG8_BAR __builtin_amdgcn_s_barrier()
; #define PG8_SCHED __builtin_amdgcn_sched_barrier(0)
; #define PG8_STAGE(bufoff, gbase, voff) do { _Pragma("unroll") for (int _i = 0; _i < 2; ++_i) \
;         __builtin_amdgcn_global_load_lds((const unsigned*)((const char*)(gbase) + (voff)[_i]), (LAS unsigned*)(lds + (bufoff) + ldsw + _i * 8192), 16, 0, 0); } while (0)
; #define PG8_MMA(ai, bj, At, Bt) do { __builtin_amdgcn_s_setprio(1); _Pragma("unroll") for (int m = 0; m < 4; ++m) _Pragma("unroll") for (int n = 0; n < 2; ++n) _Pragma("unroll") for (int k = 0; k < 2; ++k) \
;         acc[ai][bj][m][n] = __builtin_amdgcn_mfma_f32_16x16x32_bf16(Bt[n][k], At[m][k], acc[ai][bj][m][n], 0, 0, 0); __builtin_amdgcn_s_setprio(0); } while (0)
; #define PG8_WAIT_V(n) asm volatile("s_waitcnt vmcnt(" #n ")" ::: "memory")
; DI RowScales load_rowscales(const float* ss, int row0) {
;     RowScales t;
; #pragma unroll
;     for (int ai = 0; ai < 2; ++ai)
; #pragma unroll
;         for (int m = 0; m < 4; ++m) t.r[ai][m] = ss[row0 + ai * 128 + m * 16];
; #pragma unroll
;     for (int ai = 0; ai < 2; ++ai)
; #pragma unroll
;         for (int m = 0; m < 4; ++m) t.r[ai][m] = rsqrtf(t.r[ai][m] * (1.0f / 1024.0f) + 1e-6f);
;     return t;
; template <class Epi>
; DI void gemm_phase(LAS unsigned char* lds, const Gemm g, const StaticOrder S, const Epi E) {
;     ...
;             PG8_BAR; PG8_WAIT_L(0); PG8_MMA(1, 0, At, B0); PG8_BAR; PG8_SCHED;
;             PG8_STAGE(PG8_SB(1, 1), b3 + hstep, voffB);
;             PG8_WAIT_V(6); PG8_BAR; PG8_MMA(1, 1, At, B1); PG8_BAR;
	s_waitcnt lgkmcnt(0)
	s_setprio 1
	s_waitcnt lgkmcnt(0)
	v_mfma_f32_16x16x32_bf16 v[60:63], v[144:147], v[172:175], v[60:63]
	v_mfma_f32_16x16x32_bf16 v[56:59], v[164:167], v[172:175], v[56:59]
	v_mfma_f32_16x16x32_bf16 v[44:47], v[144:147], v[180:183], v[44:47]
	v_mfma_f32_16x16x32_bf16 v[40:43], v[164:167], v[180:183], v[40:43]
	v_mfma_f32_16x16x32_bf16 v[28:31], v[144:147], v[188:191], v[28:31]
	v_mfma_f32_16x16x32_bf16 v[24:27], v[164:167], v[188:191], v[24:27]
	v_mfma_f32_16x16x32_bf16 v[12:15], v[144:147], v[196:199], v[12:15]
	v_mfma_f32_16x16x32_bf16 v[8:11], v[164:167], v[196:199], v[8:11]
	v_mfma_f32_16x16x32_bf16 v[60:63], v[160:163], v[176:179], v[60:63]
	v_mfma_f32_16x16x32_bf16 v[56:59], v[168:171], v[176:179], v[56:59]
	v_mfma_f32_16x16x32_bf16 v[44:47], v[160:163], v[184:187], v[44:47]
	v_mfma_f32_16x16x32_bf16 v[40:43], v[168:171], v[184:187], v[40:43]
	v_mfma_f32_16x16x32_bf16 v[28:31], v[160:163], v[192:195], v[28:31]
	v_mfma_f32_16x16x32_bf16 v[24:27], v[168:171], v[192:195], v[24:27]
	v_mfma_f32_16x16x32_bf16 v[12:15], v[160:163], v[200:203], v[12:15]
	v_mfma_f32_16x16x32_bf16 v[8:11], v[168:171], v[200:203], v[8:11]
	s_setprio 0
	s_barrier
	s_add_u32 s10, s10, 0x40080
	s_addc_u32 s11, s11, 0
	s_add_i32 s12, s12, s34
	v_lshl_add_u64 v[144:145], s[10:11], 0, v[132:133]
	s_mov_b32 m0, s12
	s_nop 0
	global_load_lds_dwordx4 v[144:145], off
	v_lshl_add_u64 v[144:145], s[10:11], 0, v[128:129]
	s_add_i32 m0, s12, 0x2000
	s_nop 0
	global_load_lds_dwordx4 v[144:145], off
	s_waitcnt vmcnt(6)
	s_barrier
	s_setprio 1
	v_mfma_f32_16x16x32_bf16 v[52:55], v[204:207], v[172:175], v[52:55]
	v_mfma_f32_16x16x32_bf16 v[48:51], v[212:215], v[172:175], v[48:51]
	v_mfma_f32_16x16x32_bf16 v[36:39], v[204:207], v[180:183], v[36:39]
	v_mfma_f32_16x16x32_bf16 v[32:35], v[212:215], v[180:183], v[32:35]
	v_mfma_f32_16x16x32_bf16 v[20:23], v[204:207], v[188:191], v[20:23]
	v_mfma_f32_16x16x32_bf16 v[16:19], v[212:215], v[188:191], v[16:19]
	v_mfma_f32_16x16x32_bf16 v[4:7], v[204:207], v[196:199], v[4:7]
	v_mfma_f32_16x16x32_bf16 v[0:3], v[212:215], v[196:199], v[0:3]
	v_mfma_f32_16x16x32_bf16 v[52:55], v[208:211], v[176:179], v[52:55]
	v_mfma_f32_16x16x32_bf16 v[48:51], v[216:219], v[176:179], v[48:51]
	v_mfma_f32_16x16x32_bf16 v[36:39], v[208:211], v[184:187], v[36:39]
	v_mfma_f32_16x16x32_bf16 v[32:35], v[216:219], v[184:187], v[32:35]
	v_mfma_f32_16x16x32_bf16 v[20:23], v[208:211], v[192:195], v[20:23]
	v_mfma_f32_16x16x32_bf16 v[16:19], v[216:219], v[192:195], v[16:19]
	v_mfma_f32_16x16x32_bf16 v[4:7], v[208:211], v[200:203], v[4:7]
	v_mfma_f32_16x16x32_bf16 v[0:3], v[216:219], v[200:203], v[0:3]
	s_setprio 0
	s_add_i32 s25, s25, 2
	s_add_u32 s8, s8, 0x100
	s_addc_u32 s9, s9, 0
	s_add_u32 s18, s18, 0x100
	s_addc_u32 s19, s19, 0
	s_cmp_gt_u32 s25, 13
	s_barrier
	s_cbranch_scc0 .LBB0_865
	v_lshl_add_u32 v146, s4, 8, v149
	v_ashrrev_i32_e32 v147, 31, v146
	v_lshl_add_u64 v[144:145], v[146:147], 2, s[20:21]
	global_load_dword v147, v[144:145], off
	global_load_dword v148, v[144:145], off offset:64
	global_load_dword v150, v[144:145], off offset:128
	global_load_dword v152, v[144:145], off offset:192
	global_load_dword v154, v[144:145], off offset:512
	global_load_dword v156, v[144:145], off offset:576
	global_load_dword v160, v[144:145], off offset:640
	global_load_dword v161, v[144:145], off offset:704
	v_lshl_or_b32 v144, s5, 7, v153
	v_ashrrev_i32_e32 v145, 31, v144
	v_lshl_add_u64 v[144:145], v[144:145], 1, s[54:55]
	s_waitcnt vmcnt(0)
	v_fmamk_f32 v147, v147, 0x3a800000, v159
	v_mul_f32_e32 v162, 0x4b800000, v147
	v_cmp_gt_f32_e32 vcc, s51, v147
	v_fmamk_f32 v152, v152, 0x3a800000, v159
	v_fmamk_f32 v154, v154, 0x3a800000, v159
	v_cndmask_b32_e32 v147, v147, v162, vcc
	v_mul_f32_e32 v165, 0x4b800000, v152
	v_fmamk_f32 v161, v161, 0x3a800000, v159
	v_mul_f32_e32 v166, 0x4b800000, v154
	v_mul_f32_e32 v169, 0x4b800000, v161
	v_cmp_gt_f32_e64 s[10:11], s51, v152
	v_cmp_gt_f32_e64 s[12:13], s51, v154
	v_cmp_gt_f32_e64 s[18:19], s51, v161
	v_rsq_f32_e32 v147, v147
	v_fmamk_f32 v156, v156, 0x3a800000, v159
	v_cndmask_b32_e64 v152, v152, v165, s[10:11]
	v_cndmask_b32_e64 v154, v154, v166, s[12:13]
	v_cndmask_b32_e64 v161, v161, v169, s[18:19]
	v_fmamk_f32 v148, v148, 0x3a800000, v159
	v_fmamk_f32 v160, v160, 0x3a800000, v159
	v_mul_f32_e32 v167, 0x4b800000, v156
	v_cmp_gt_f32_e64 s[14:15], s51, v156
	v_rsq_f32_e32 v152, v152
	v_rsq_f32_e32 v154, v154
	v_rsq_f32_e32 v161, v161
	v_mul_f32_e32 v163, 0x4b800000, v148
	v_mul_f32_e32 v168, 0x4b800000, v160
	v_cmp_gt_f32_e64 s[4:5], s51, v148
	v_cndmask_b32_e64 v156, v156, v167, s[14:15]
	v_cmp_gt_f32_e64 s[16:17], s51, v160
	v_fmamk_f32 v150, v150, 0x3a800000, v159
	v_cndmask_b32_e64 v148, v148, v163, s[4:5]
	v_cndmask_b32_e64 v160, v160, v168, s[16:17]
	v_rsq_f32_e32 v163, v156
	v_mul_f32_e32 v156, 0x45800000, v147
	v_mul_f32_e32 v164, 0x4b800000, v150
	v_cmp_gt_f32_e64 s[8:9], s51, v150
	v_rsq_f32_e32 v165, v160
	v_cndmask_b32_e32 v160, v147, v156, vcc
	v_cndmask_b32_e64 v150, v150, v164, s[8:9]
	v_rsq_f32_e32 v148, v148
	v_mul_f32_e32 v166, 0x45800000, v152
	v_mul_f32_e32 v167, 0x45800000, v154
	v_pk_mul_f32 v[126:127], v[126:127], v[160:161] op_sel_hi:[1,0]
	v_pk_mul_f32 v[124:125], v[124:125], v[160:161] op_sel_hi:[1,0]
	v_rsq_f32_e32 v150, v150
	v_cndmask_b32_e64 v156, v152, v166, s[10:11]
	v_cndmask_b32_e64 v154, v154, v167, s[12:13]
	v_pk_mul_f32 v[122:123], v[122:123], v[160:161] op_sel_hi:[1,0]
	v_pk_mul_f32 v[120:121], v[120:121], v[160:161] op_sel_hi:[1,0]
	v_pk_mul_f32 v[118:119], v[118:119], v[160:161] op_sel_hi:[1,0]
	v_pk_mul_f32 v[116:117], v[116:117], v[160:161] op_sel_hi:[1,0]
; DI unsigned pk_bf16(float lo, float hi) { f32x2 v = {lo, hi}; return __builtin_bit_cast(unsigned, __builtin_convertvector(v, bf16v2)); }
; DI float fast_silu(float x) { return x * fast_sigmoid(x); }
;     DI void operator()(AccRef acc, const Unit& u, int wr, int wc, int fr, int fq) const {
;     ...
; #pragma unroll
;         for (int ai = 0; ai < 2; ++ai)
; #pragma unroll
;             for (int m = 0; m < 4; ++m) {
;                 const int row = row0 + ai * 128 + m * 16;
;                 const float r = RS ? rsc.r[ai][m] : 1.0f;
;                 const f32x4 a0 = acc[ai][0][m][0] * r, a1 = acc[ai][0][m][1] * r, b0 = acc[ai][1][m][0] * r, b1 = acc[ai][1][m][1] * r;
;                 u32x4 w;
;                 w.x = pk_bf16(fast_silu(a0[0]) * b0[0], fast_silu(a0[1]) * b0[1]); w.y = pk_bf16(fast_silu(a0[2]) * b0[2], fast_silu(a0[3]) * b0[3]);
;                 w.z = pk_bf16(fast_silu(a1[0]) * b1[0], fast_silu(a1[1]) * b1[1]); w.w = pk_bf16(fast_silu(a1[2]) * b1[2], fast_silu(a1[3]) * b1[3]);
;                 *(u32x4*)(G + (size_t)row * DFF + col) = w;
	v_pk_mul_f32 v[166:167], v[114:115], v[160:161] op_sel_hi:[1,0]
	v_pk_mul_f32 v[114:115], v[112:113], v[160:161] op_sel_hi:[1,0]
	v_mul_f32_e32 v112, 0xbfb8aa3b, v124
	v_mul_f32_e32 v113, 0xbfb8aa3b, v125
	v_mul_f32_e32 v147, 0xbfb8aa3b, v126
	v_mul_f32_e32 v160, 0xbfb8aa3b, v127
	v_exp_f32_e32 v112, v112
	v_exp_f32_e32 v113, v113
	v_exp_f32_e32 v147, v147
	v_exp_f32_e32 v160, v160
	v_mul_f32_e32 v162, 0x45800000, v148
	v_mul_f32_e32 v170, 0x45800000, v161
	v_mul_f32_e32 v164, 0x45800000, v150
	v_mul_f32_e32 v169, 0x45800000, v165
	v_cndmask_b32_e64 v162, v148, v162, s[4:5]
	v_cndmask_b32_e64 v148, v161, v170, s[18:19]
	v_mul_f32_e32 v161, 0xbfb8aa3b, v120
	v_cndmask_b32_e64 v164, v150, v164, s[8:9]
	v_cndmask_b32_e64 v150, v165, v169, s[16:17]
	v_exp_f32_e32 v165, v161
	v_add_f32_e32 v112, 1.0, v112
	v_add_f32_e32 v113, 1.0, v113
	v_add_f32_e32 v147, 1.0, v147
	v_add_f32_e32 v161, 1.0, v160
	v_rcp_f32_e32 v112, v112
	v_rcp_f32_e32 v113, v113
	v_rcp_f32_e32 v160, v147
	v_rcp_f32_e32 v161, v161
	v_mul_f32_e32 v168, 0x45800000, v163
	v_pk_mul_f32 v[112:113], v[124:125], v[112:113]
	v_cndmask_b32_e64 v152, v163, v168, s[14:15]
	v_pk_mul_f32 v[124:125], v[126:127], v[160:161]
	v_mul_f32_e32 v163, 0xbfb8aa3b, v121
	v_pk_mul_f32 v[112:113], v[116:117], v[112:113]
	v_pk_mul_f32 v[116:117], v[118:119], v[124:125]
	v_exp_f32_e32 v163, v163
	v_cvt_pk_bf16_f32 v112, v112, v113
	v_cvt_pk_bf16_f32 v113, v116, v117
	v_mul_f32_e32 v117, 0xbfb8aa3b, v122
	v_mul_f32_e32 v118, 0xbfb8aa3b, v123
	v_exp_f32_e32 v117, v117
	v_exp_f32_e32 v118, v118
	v_add_f32_e32 v116, 1.0, v163
	v_add_f32_e32 v147, 1.0, v165
	v_rcp_f32_e32 v169, v116
	v_add_f32_e32 v116, 1.0, v117
	v_add_f32_e32 v117, 1.0, v118
	v_rcp_f32_e32 v168, v147
	v_rcp_f32_e32 v116, v116
	v_rcp_f32_e32 v117, v117
	v_pk_mul_f32 v[108:109], v[108:109], v[162:163] op_sel_hi:[1,0]
	v_pk_mul_f32 v[118:119], v[120:121], v[168:169]
	v_pk_mul_f32 v[110:111], v[110:111], v[162:163] op_sel_hi:[1,0]
	v_pk_mul_f32 v[116:117], v[122:123], v[116:117]
	v_pk_mul_f32 v[114:115], v[114:115], v[118:119]
	v_pk_mul_f32 v[116:117], v[166:167], v[116:117]
	v_cvt_pk_bf16_f32 v114, v114, v115
	v_cvt_pk_bf16_f32 v115, v116, v117
	v_mad_i64_i32 v[116:117], s[4:5], v146, s52, v[144:145]
	global_store_dwordx4 v[116:117], v[112:115], off
	v_pk_mul_f32 v[100:101], v[100:101], v[162:163] op_sel_hi:[1,0]
	v_pk_mul_f32 v[104:105], v[104:105], v[162:163] op_sel_hi:[1,0]
	v_pk_mul_f32 v[112:113], v[98:99], v[162:163] op_sel_hi:[1,0]
	v_mul_f32_e32 v98, 0xbfb8aa3b, v108
	v_exp_f32_e32 v114, v98
	v_mul_f32_e32 v98, 0xbfb8aa3b, v109
	v_exp_f32_e32 v115, v98
	v_pk_mul_f32 v[98:99], v[96:97], v[162:163] op_sel_hi:[1,0]
	v_add_f32_e32 v96, 1.0, v114
	v_mul_f32_e32 v114, 0xbfb8aa3b, v110
	v_add_f32_e32 v97, 1.0, v115
	v_mul_f32_e32 v115, 0xbfb8aa3b, v111
	v_exp_f32_e32 v114, v114
	v_exp_f32_e32 v115, v115
	v_rcp_f32_e32 v96, v96
	v_rcp_f32_e32 v97, v97
	v_add_f32_e32 v114, 1.0, v114
	v_add_f32_e32 v115, 1.0, v115
	v_rcp_f32_e32 v114, v114
	v_rcp_f32_e32 v115, v115
	v_pk_mul_f32 v[96:97], v[108:109], v[96:97]
	v_pk_mul_f32 v[102:103], v[102:103], v[162:163] op_sel_hi:[1,0]
	v_pk_mul_f32 v[96:97], v[100:101], v[96:97]
	v_pk_mul_f32 v[100:101], v[110:111], v[114:115]
	v_cvt_pk_bf16_f32 v96, v96, v97
	v_mul_f32_e32 v97, 0xbfb8aa3b, v104
	v_pk_mul_f32 v[100:101], v[102:103], v[100:101]
	v_exp_f32_e32 v102, v97
	v_mul_f32_e32 v97, 0xbfb8aa3b, v105
	v_exp_f32_e32 v103, v97
	v_pk_mul_f32 v[106:107], v[106:107], v[162:163] op_sel_hi:[1,0]
	v_cvt_pk_bf16_f32 v97, v100, v101
	v_add_f32_e32 v100, 1.0, v102
	v_add_f32_e32 v101, 1.0, v103
	v_mul_f32_e32 v102, 0xbfb8aa3b, v106
	v_mul_f32_e32 v103, 0xbfb8aa3b, v107
	v_exp_f32_e32 v102, v102
	v_exp_f32_e32 v103, v103
	v_rcp_f32_e32 v100, v100
	v_rcp_f32_e32 v101, v101
	v_add_f32_e32 v102, 1.0, v102
	v_add_f32_e32 v103, 1.0, v103
	v_rcp_f32_e32 v102, v102
	v_rcp_f32_e32 v103, v103
	v_pk_mul_f32 v[100:101], v[104:105], v[100:101]
	v_or_b32_e32 v116, 16, v146
	v_pk_mul_f32 v[98:99], v[98:99], v[100:101]
	v_pk_mul_f32 v[100:101], v[106:107], v[102:103]
	v_cvt_pk_bf16_f32 v98, v98, v99
	v_pk_mul_f32 v[100:101], v[112:113], v[100:101]
	v_pk_mul_f32 v[92:93], v[92:93], v[164:165] op_sel_hi:[1,0]
	v_cvt_pk_bf16_f32 v99, v100, v101
	v_mad_i64_i32 v[100:101], s[4:5], v116, s52, v[144:145]
	global_store_dwordx4 v[100:101], v[96:99], off
	v_pk_mul_f32 v[94:95], v[94:95], v[164:165] op_sel_hi:[1,0]
	v_pk_mul_f32 v[84:85], v[84:85], v[164:165] op_sel_hi:[1,0]
	v_pk_mul_f32 v[96:97], v[82:83], v[164:165] op_sel_hi:[1,0]
	v_mul_f32_e32 v82, 0xbfb8aa3b, v92
	v_exp_f32_e32 v98, v82
	v_mul_f32_e32 v82, 0xbfb8aa3b, v93
	v_exp_f32_e32 v99, v82
	v_pk_mul_f32 v[82:83], v[80:81], v[164:165] op_sel_hi:[1,0]
	v_add_f32_e32 v80, 1.0, v98
	v_mul_f32_e32 v98, 0xbfb8aa3b, v94
	v_add_f32_e32 v81, 1.0, v99
	v_mul_f32_e32 v99, 0xbfb8aa3b, v95
	v_exp_f32_e32 v98, v98
	v_exp_f32_e32 v99, v99
	v_rcp_f32_e32 v80, v80
	v_rcp_f32_e32 v81, v81
	v_add_f32_e32 v98, 1.0, v98
	v_add_f32_e32 v99, 1.0, v99
	v_rcp_f32_e32 v98, v98
	v_rcp_f32_e32 v99, v99
	v_pk_mul_f32 v[80:81], v[92:93], v[80:81]
	v_pk_mul_f32 v[88:89], v[88:89], v[164:165] op_sel_hi:[1,0]
	v_pk_mul_f32 v[80:81], v[84:85], v[80:81]
	v_pk_mul_f32 v[86:87], v[86:87], v[164:165] op_sel_hi:[1,0]
	v_cvt_pk_bf16_f32 v80, v80, v81
	v_pk_mul_f32 v[84:85], v[94:95], v[98:99]
	v_mul_f32_e32 v81, 0xbfb8aa3b, v88
	v_pk_mul_f32 v[84:85], v[86:87], v[84:85]
	v_exp_f32_e32 v86, v81
	v_mul_f32_e32 v81, 0xbfb8aa3b, v89
	v_exp_f32_e32 v87, v81
	v_pk_mul_f32 v[90:91], v[90:91], v[164:165] op_sel_hi:[1,0]
	v_cvt_pk_bf16_f32 v81, v84, v85
	v_add_f32_e32 v84, 1.0, v86
	v_add_f32_e32 v85, 1.0, v87
; DI unsigned pk_bf16(float lo, float hi) { f32x2 v = {lo, hi}; return __builtin_bit_cast(unsigned, __builtin_convertvector(v, bf16v2)); }
; DI float fast_silu(float x) { return x * fast_sigmoid(x); }
;     DI void operator()(AccRef acc, const Unit& u, int wr, int wc, int fr, int fq) const {
;     ...
; #pragma unroll
;         for (int ai = 0; ai < 2; ++ai)
; #pragma unroll
;             for (int m = 0; m < 4; ++m) {
;                 const int row = row0 + ai * 128 + m * 16;
;                 const float r = RS ? rsc.r[ai][m] : 1.0f;
;                 const f32x4 a0 = acc[ai][0][m][0] * r, a1 = acc[ai][0][m][1] * r, b0 = acc[ai][1][m][0] * r, b1 = acc[ai][1][m][1] * r;
;                 u32x4 w;
;                 w.x = pk_bf16(fast_silu(a0[0]) * b0[0], fast_silu(a0[1]) * b0[1]); w.y = pk_bf16(fast_silu(a0[2]) * b0[2], fast_silu(a0[3]) * b0[3]);
;                 w.z = pk_bf16(fast_silu(a1[0]) * b1[0], fast_silu(a1[1]) * b1[1]); w.w = pk_bf16(fast_silu(a1[2]) * b1[2], fast_silu(a1[3]) * b1[3]);
;                 *(u32x4*)(G + (size_t)row * DFF + col) = w;
	v_mul_f32_e32 v86, 0xbfb8aa3b, v90
	v_mul_f32_e32 v87, 0xbfb8aa3b, v91
	v_exp_f32_e32 v86, v86
	v_exp_f32_e32 v87, v87
	v_rcp_f32_e32 v84, v84
	v_rcp_f32_e32 v85, v85
	v_add_f32_e32 v86, 1.0, v86
	v_add_f32_e32 v87, 1.0, v87
	v_rcp_f32_e32 v86, v86
	v_rcp_f32_e32 v87, v87
	v_pk_mul_f32 v[84:85], v[88:89], v[84:85]
	v_or_b32_e32 v100, 32, v146
	v_pk_mul_f32 v[82:83], v[82:83], v[84:85]
	v_pk_mul_f32 v[84:85], v[90:91], v[86:87]
	v_cvt_pk_bf16_f32 v82, v82, v83
	v_pk_mul_f32 v[84:85], v[96:97], v[84:85]
	v_pk_mul_f32 v[76:77], v[76:77], v[156:157] op_sel_hi:[1,0]
	v_cvt_pk_bf16_f32 v83, v84, v85
	v_mad_i64_i32 v[84:85], s[4:5], v100, s52, v[144:145]
	global_store_dwordx4 v[84:85], v[80:83], off
	v_pk_mul_f32 v[78:79], v[78:79], v[156:157] op_sel_hi:[1,0]
	v_pk_mul_f32 v[68:69], v[68:69], v[156:157] op_sel_hi:[1,0]
	v_pk_mul_f32 v[80:81], v[66:67], v[156:157] op_sel_hi:[1,0]
	v_mul_f32_e32 v66, 0xbfb8aa3b, v76
	v_exp_f32_e32 v82, v66
	v_mul_f32_e32 v66, 0xbfb8aa3b, v77
	v_exp_f32_e32 v83, v66
	v_pk_mul_f32 v[66:67], v[64:65], v[156:157] op_sel_hi:[1,0]
	v_add_f32_e32 v64, 1.0, v82
	v_mul_f32_e32 v82, 0xbfb8aa3b, v78
	v_add_f32_e32 v65, 1.0, v83
	v_mul_f32_e32 v83, 0xbfb8aa3b, v79
	v_exp_f32_e32 v82, v82
	v_exp_f32_e32 v83, v83
	v_rcp_f32_e32 v64, v64
	v_rcp_f32_e32 v65, v65
	v_add_f32_e32 v82, 1.0, v82
	v_add_f32_e32 v83, 1.0, v83
	v_rcp_f32_e32 v82, v82
	v_rcp_f32_e32 v83, v83
	v_pk_mul_f32 v[64:65], v[76:77], v[64:65]
	v_pk_mul_f32 v[72:73], v[72:73], v[156:157] op_sel_hi:[1,0]
	v_pk_mul_f32 v[64:65], v[68:69], v[64:65]
	v_pk_mul_f32 v[70:71], v[70:71], v[156:157] op_sel_hi:[1,0]
	v_cvt_pk_bf16_f32 v64, v64, v65
	v_pk_mul_f32 v[68:69], v[78:79], v[82:83]
	v_mul_f32_e32 v65, 0xbfb8aa3b, v72
	v_pk_mul_f32 v[68:69], v[70:71], v[68:69]
	v_exp_f32_e32 v70, v65
	v_mul_f32_e32 v65, 0xbfb8aa3b, v73
	v_exp_f32_e32 v71, v65
	v_pk_mul_f32 v[74:75], v[74:75], v[156:157] op_sel_hi:[1,0]
	v_cvt_pk_bf16_f32 v65, v68, v69
	v_add_f32_e32 v68, 1.0, v70
	v_add_f32_e32 v69, 1.0, v71
	v_mul_f32_e32 v70, 0xbfb8aa3b, v74
	v_mul_f32_e32 v71, 0xbfb8aa3b, v75
	v_exp_f32_e32 v70, v70
	v_exp_f32_e32 v71, v71
	v_rcp_f32_e32 v68, v68
	v_rcp_f32_e32 v69, v69
	v_add_f32_e32 v70, 1.0, v70
	v_add_f32_e32 v71, 1.0, v71
	v_rcp_f32_e32 v70, v70
	v_rcp_f32_e32 v71, v71
	v_pk_mul_f32 v[68:69], v[72:73], v[68:69]
	v_or_b32_e32 v84, 48, v146
	v_pk_mul_f32 v[66:67], v[66:67], v[68:69]
	v_pk_mul_f32 v[68:69], v[74:75], v[70:71]
	v_cvt_pk_bf16_f32 v66, v66, v67
	v_pk_mul_f32 v[68:69], v[80:81], v[68:69]
	v_pk_mul_f32 v[60:61], v[60:61], v[154:155] op_sel_hi:[1,0]
	v_cvt_pk_bf16_f32 v67, v68, v69
	v_mad_i64_i32 v[68:69], s[4:5], v84, s52, v[144:145]
	global_store_dwordx4 v[68:69], v[64:67], off
	v_pk_mul_f32 v[62:63], v[62:63], v[154:155] op_sel_hi:[1,0]
	v_pk_mul_f32 v[52:53], v[52:53], v[154:155] op_sel_hi:[1,0]
	v_pk_mul_f32 v[64:65], v[50:51], v[154:155] op_sel_hi:[1,0]
	v_mul_f32_e32 v50, 0xbfb8aa3b, v60
	v_exp_f32_e32 v66, v50
	v_mul_f32_e32 v50, 0xbfb8aa3b, v61
	v_exp_f32_e32 v67, v50
	v_pk_mul_f32 v[50:51], v[48:49], v[154:155] op_sel_hi:[1,0]
	v_add_f32_e32 v48, 1.0, v66
	v_mul_f32_e32 v66, 0xbfb8aa3b, v62
	v_add_f32_e32 v49, 1.0, v67
	v_mul_f32_e32 v67, 0xbfb8aa3b, v63
	v_exp_f32_e32 v66, v66
	v_exp_f32_e32 v67, v67
	v_rcp_f32_e32 v48, v48
	v_rcp_f32_e32 v49, v49
	v_add_f32_e32 v66, 1.0, v66
	v_add_f32_e32 v67, 1.0, v67
	v_rcp_f32_e32 v66, v66
	v_rcp_f32_e32 v67, v67
	v_pk_mul_f32 v[48:49], v[60:61], v[48:49]
	v_pk_mul_f32 v[56:57], v[56:57], v[154:155] op_sel_hi:[1,0]
	v_pk_mul_f32 v[48:49], v[52:53], v[48:49]
	v_pk_mul_f32 v[54:55], v[54:55], v[154:155] op_sel_hi:[1,0]
	v_cvt_pk_bf16_f32 v48, v48, v49
	v_pk_mul_f32 v[52:53], v[62:63], v[66:67]
	v_mul_f32_e32 v49, 0xbfb8aa3b, v56
	v_pk_mul_f32 v[52:53], v[54:55], v[52:53]
	v_exp_f32_e32 v54, v49
	v_mul_f32_e32 v49, 0xbfb8aa3b, v57
	v_exp_f32_e32 v55, v49
	v_pk_mul_f32 v[58:59], v[58:59], v[154:155] op_sel_hi:[1,0]
	v_cvt_pk_bf16_f32 v49, v52, v53
	v_add_f32_e32 v52, 1.0, v54
	v_add_f32_e32 v53, 1.0, v55
	v_mul_f32_e32 v54, 0xbfb8aa3b, v58
	v_mul_f32_e32 v55, 0xbfb8aa3b, v59
	v_exp_f32_e32 v54, v54
	v_exp_f32_e32 v55, v55
	v_rcp_f32_e32 v52, v52
	v_rcp_f32_e32 v53, v53
	v_add_f32_e32 v54, 1.0, v54
	v_add_f32_e32 v55, 1.0, v55
	v_rcp_f32_e32 v54, v54
	v_rcp_f32_e32 v55, v55
	v_pk_mul_f32 v[52:53], v[56:57], v[52:53]
	v_add_u32_e32 v68, 0x80, v146
	v_pk_mul_f32 v[50:51], v[50:51], v[52:53]
	v_pk_mul_f32 v[52:53], v[58:59], v[54:55]
	v_cvt_pk_bf16_f32 v50, v50, v51
	v_pk_mul_f32 v[52:53], v[64:65], v[52:53]
	v_pk_mul_f32 v[44:45], v[44:45], v[152:153] op_sel_hi:[1,0]
	v_cvt_pk_bf16_f32 v51, v52, v53
	v_mad_i64_i32 v[52:53], s[4:5], v68, s52, v[144:145]
	global_store_dwordx4 v[52:53], v[48:51], off
	v_pk_mul_f32 v[46:47], v[46:47], v[152:153] op_sel_hi:[1,0]
	v_pk_mul_f32 v[36:37], v[36:37], v[152:153] op_sel_hi:[1,0]
	v_pk_mul_f32 v[48:49], v[34:35], v[152:153] op_sel_hi:[1,0]
	v_mul_f32_e32 v34, 0xbfb8aa3b, v44
	v_exp_f32_e32 v50, v34
	v_mul_f32_e32 v34, 0xbfb8aa3b, v45
	v_exp_f32_e32 v51, v34
	v_pk_mul_f32 v[34:35], v[32:33], v[152:153] op_sel_hi:[1,0]
	v_add_f32_e32 v32, 1.0, v50
	v_mul_f32_e32 v50, 0xbfb8aa3b, v46
	v_add_f32_e32 v33, 1.0, v51
	v_mul_f32_e32 v51, 0xbfb8aa3b, v47
	v_exp_f32_e32 v50, v50
	v_exp_f32_e32 v51, v51
	v_rcp_f32_e32 v32, v32
	v_rcp_f32_e32 v33, v33
	v_add_f32_e32 v50, 1.0, v50
	v_add_f32_e32 v51, 1.0, v51
	v_rcp_f32_e32 v50, v50
; DI unsigned pk_bf16(float lo, float hi) { f32x2 v = {lo, hi}; return __builtin_bit_cast(unsigned, __builtin_convertvector(v, bf16v2)); }
; DI float fast_silu(float x) { return x * fast_sigmoid(x); }
; #define PG8_WAIT_V(n) asm volatile("s_waitcnt vmcnt(" #n ")" ::: "memory")
; #define PG8_BAR __builtin_amdgcn_s_barrier()
; #define PG8_WAIT_V(n) asm volatile("s_waitcnt vmcnt(" #n ")" ::: "memory")
; #define PG8_BAR __builtin_amdgcn_s_barrier()
; template <class Epi>
; DI void gemm_phase(LAS unsigned char* lds, const Gemm g, const StaticOrder S, const Epi E) {
;     ...
;         if (!has_next) break;
; #pragma unroll
;         for (int a = 0; a < 2; ++a)
; #pragma unroll
;             for (int b = 0; b < 2; ++b)
; #pragma unroll
;                 for (int m = 0; m < 4; ++m)
; #pragma unroll
;                     for (int n = 0; n < 2; ++n) acc[a][b][m][n] = (f32x4){0.f, 0.f, 0.f, 0.f};
;         cur = nxt; cA = nA; cB = nB; ++ui;
;     }
;     PG8_WAIT_V(0);
;     if (wr == 0) PG8_BAR;
;     PG8_BAR;
;     DI void operator()(AccRef acc, const Unit& u, int wr, int wc, int fr, int fq) const {
;     ...
; #pragma unroll
;         for (int ai = 0; ai < 2; ++ai)
; #pragma unroll
;             for (int m = 0; m < 4; ++m) {
;                 const int row = row0 + ai * 128 + m * 16;
;                 const float r = RS ? rsc.r[ai][m] : 1.0f;
;                 const f32x4 a0 = acc[ai][0][m][0] * r, a1 = acc[ai][0][m][1] * r, b0 = acc[ai][1][m][0] * r, b1 = acc[ai][1][m][1] * r;
;                 u32x4 w;
;                 w.x = pk_bf16(fast_silu(a0[0]) * b0[0], fast_silu(a0[1]) * b0[1]); w.y = pk_bf16(fast_silu(a0[2]) * b0[2], fast_silu(a0[3]) * b0[3]);
;                 w.z = pk_bf16(fast_silu(a1[0]) * b1[0], fast_silu(a1[1]) * b1[1]); w.w = pk_bf16(fast_silu(a1[2]) * b1[2], fast_silu(a1[3]) * b1[3]);
;                 *(u32x4*)(G + (size_t)row * DFF + col) = w;
	v_rcp_f32_e32 v51, v51
	v_pk_mul_f32 v[32:33], v[44:45], v[32:33]
	v_pk_mul_f32 v[40:41], v[40:41], v[152:153] op_sel_hi:[1,0]
	v_pk_mul_f32 v[32:33], v[36:37], v[32:33]
	v_pk_mul_f32 v[38:39], v[38:39], v[152:153] op_sel_hi:[1,0]
	v_cvt_pk_bf16_f32 v32, v32, v33
	v_pk_mul_f32 v[36:37], v[46:47], v[50:51]
	v_mul_f32_e32 v33, 0xbfb8aa3b, v40
	v_pk_mul_f32 v[36:37], v[38:39], v[36:37]
	v_exp_f32_e32 v38, v33
	v_mul_f32_e32 v33, 0xbfb8aa3b, v41
	v_exp_f32_e32 v39, v33
	v_pk_mul_f32 v[42:43], v[42:43], v[152:153] op_sel_hi:[1,0]
	v_cvt_pk_bf16_f32 v33, v36, v37
	v_add_f32_e32 v36, 1.0, v38
	v_add_f32_e32 v37, 1.0, v39
	v_mul_f32_e32 v38, 0xbfb8aa3b, v42
	v_mul_f32_e32 v39, 0xbfb8aa3b, v43
	v_exp_f32_e32 v38, v38
	v_exp_f32_e32 v39, v39
	v_rcp_f32_e32 v36, v36
	v_rcp_f32_e32 v37, v37
	v_add_f32_e32 v38, 1.0, v38
	v_add_f32_e32 v39, 1.0, v39
	v_rcp_f32_e32 v38, v38
	v_rcp_f32_e32 v39, v39
	v_pk_mul_f32 v[36:37], v[40:41], v[36:37]
	v_add_u32_e32 v52, 0x90, v146
	v_pk_mul_f32 v[34:35], v[34:35], v[36:37]
	v_pk_mul_f32 v[36:37], v[42:43], v[38:39]
	v_cvt_pk_bf16_f32 v34, v34, v35
	v_pk_mul_f32 v[36:37], v[48:49], v[36:37]
	v_pk_mul_f32 v[28:29], v[28:29], v[150:151] op_sel_hi:[1,0]
	v_cvt_pk_bf16_f32 v35, v36, v37
	v_mad_i64_i32 v[36:37], s[4:5], v52, s52, v[144:145]
	global_store_dwordx4 v[36:37], v[32:35], off
	v_pk_mul_f32 v[30:31], v[30:31], v[150:151] op_sel_hi:[1,0]
	v_pk_mul_f32 v[20:21], v[20:21], v[150:151] op_sel_hi:[1,0]
	v_pk_mul_f32 v[32:33], v[18:19], v[150:151] op_sel_hi:[1,0]
	v_mul_f32_e32 v18, 0xbfb8aa3b, v28
	v_exp_f32_e32 v34, v18
	v_mul_f32_e32 v18, 0xbfb8aa3b, v29
	v_exp_f32_e32 v35, v18
	v_pk_mul_f32 v[18:19], v[16:17], v[150:151] op_sel_hi:[1,0]
	v_add_f32_e32 v16, 1.0, v34
	v_mul_f32_e32 v34, 0xbfb8aa3b, v30
	v_add_f32_e32 v17, 1.0, v35
	v_mul_f32_e32 v35, 0xbfb8aa3b, v31
	v_exp_f32_e32 v34, v34
	v_exp_f32_e32 v35, v35
	v_rcp_f32_e32 v16, v16
	v_rcp_f32_e32 v17, v17
	v_add_f32_e32 v34, 1.0, v34
	v_add_f32_e32 v35, 1.0, v35
	v_rcp_f32_e32 v34, v34
	v_rcp_f32_e32 v35, v35
	v_pk_mul_f32 v[16:17], v[28:29], v[16:17]
	v_pk_mul_f32 v[24:25], v[24:25], v[150:151] op_sel_hi:[1,0]
	v_pk_mul_f32 v[16:17], v[20:21], v[16:17]
	v_pk_mul_f32 v[22:23], v[22:23], v[150:151] op_sel_hi:[1,0]
	v_cvt_pk_bf16_f32 v16, v16, v17
	v_pk_mul_f32 v[20:21], v[30:31], v[34:35]
	v_mul_f32_e32 v17, 0xbfb8aa3b, v24
	v_pk_mul_f32 v[20:21], v[22:23], v[20:21]
	v_exp_f32_e32 v22, v17
	v_mul_f32_e32 v17, 0xbfb8aa3b, v25
	v_exp_f32_e32 v23, v17
	v_pk_mul_f32 v[26:27], v[26:27], v[150:151] op_sel_hi:[1,0]
	v_cvt_pk_bf16_f32 v17, v20, v21
	v_add_f32_e32 v20, 1.0, v22
	v_add_f32_e32 v21, 1.0, v23
	v_mul_f32_e32 v22, 0xbfb8aa3b, v26
	v_mul_f32_e32 v23, 0xbfb8aa3b, v27
	v_exp_f32_e32 v22, v22
	v_exp_f32_e32 v23, v23
	v_rcp_f32_e32 v20, v20
	v_rcp_f32_e32 v21, v21
	v_add_f32_e32 v22, 1.0, v22
	v_add_f32_e32 v23, 1.0, v23
	v_rcp_f32_e32 v22, v22
	v_rcp_f32_e32 v23, v23
	v_pk_mul_f32 v[20:21], v[24:25], v[20:21]
	v_add_u32_e32 v36, 0xa0, v146
	v_pk_mul_f32 v[18:19], v[18:19], v[20:21]
	v_pk_mul_f32 v[20:21], v[26:27], v[22:23]
	v_cvt_pk_bf16_f32 v18, v18, v19
	v_pk_mul_f32 v[20:21], v[32:33], v[20:21]
	v_pk_mul_f32 v[12:13], v[12:13], v[148:149] op_sel_hi:[1,0]
	v_cvt_pk_bf16_f32 v19, v20, v21
	v_mad_i64_i32 v[20:21], s[4:5], v36, s52, v[144:145]
	global_store_dwordx4 v[20:21], v[16:19], off
	v_pk_mul_f32 v[14:15], v[14:15], v[148:149] op_sel_hi:[1,0]
	v_pk_mul_f32 v[4:5], v[4:5], v[148:149] op_sel_hi:[1,0]
	v_pk_mul_f32 v[16:17], v[2:3], v[148:149] op_sel_hi:[1,0]
	v_mul_f32_e32 v2, 0xbfb8aa3b, v12
	v_exp_f32_e32 v18, v2
	v_mul_f32_e32 v2, 0xbfb8aa3b, v13
	v_exp_f32_e32 v19, v2
	v_pk_mul_f32 v[2:3], v[0:1], v[148:149] op_sel_hi:[1,0]
	v_add_f32_e32 v0, 1.0, v18
	v_mul_f32_e32 v18, 0xbfb8aa3b, v14
	v_add_f32_e32 v1, 1.0, v19
	v_mul_f32_e32 v19, 0xbfb8aa3b, v15
	v_exp_f32_e32 v18, v18
	v_exp_f32_e32 v19, v19
	v_rcp_f32_e32 v0, v0
	v_rcp_f32_e32 v1, v1
	v_add_f32_e32 v18, 1.0, v18
	v_add_f32_e32 v19, 1.0, v19
	v_rcp_f32_e32 v18, v18
	v_rcp_f32_e32 v19, v19
	v_pk_mul_f32 v[0:1], v[12:13], v[0:1]
	v_pk_mul_f32 v[8:9], v[8:9], v[148:149] op_sel_hi:[1,0]
	v_pk_mul_f32 v[0:1], v[4:5], v[0:1]
	v_pk_mul_f32 v[6:7], v[6:7], v[148:149] op_sel_hi:[1,0]
	v_cvt_pk_bf16_f32 v0, v0, v1
	v_pk_mul_f32 v[4:5], v[14:15], v[18:19]
	v_mul_f32_e32 v1, 0xbfb8aa3b, v8
	v_pk_mul_f32 v[4:5], v[6:7], v[4:5]
	v_exp_f32_e32 v6, v1
	v_mul_f32_e32 v1, 0xbfb8aa3b, v9
	v_exp_f32_e32 v7, v1
	v_pk_mul_f32 v[10:11], v[10:11], v[148:149] op_sel_hi:[1,0]
	v_cvt_pk_bf16_f32 v1, v4, v5
	v_add_f32_e32 v4, 1.0, v6
	v_add_f32_e32 v5, 1.0, v7
	v_mul_f32_e32 v6, 0xbfb8aa3b, v10
	v_mul_f32_e32 v7, 0xbfb8aa3b, v11
	v_exp_f32_e32 v6, v6
	v_exp_f32_e32 v7, v7
	v_rcp_f32_e32 v4, v4
	v_rcp_f32_e32 v5, v5
	v_add_f32_e32 v6, 1.0, v6
	v_add_f32_e32 v7, 1.0, v7
	v_rcp_f32_e32 v6, v6
	v_rcp_f32_e32 v7, v7
	v_pk_mul_f32 v[4:5], v[8:9], v[4:5]
	v_add_u32_e32 v20, 0xb0, v146
	v_pk_mul_f32 v[2:3], v[2:3], v[4:5]
	v_pk_mul_f32 v[4:5], v[10:11], v[6:7]
	v_cvt_pk_bf16_f32 v2, v2, v3
	v_pk_mul_f32 v[4:5], v[16:17], v[4:5]
	s_and_b64 vcc, exec, s[0:1]
	v_cvt_pk_bf16_f32 v3, v4, v5
	v_mad_i64_i32 v[4:5], s[4:5], v20, s52, v[144:145]
	s_mov_b32 s5, s24
	s_mov_b32 s4, s28
	s_mov_b64 s[10:11], s[38:39]
	s_mov_b64 s[8:9], s[36:37]
	global_store_dwordx4 v[4:5], v[0:3], off
	s_cbranch_vccz .LBB0_862
	s_waitcnt vmcnt(0)
	s_cmpk_gt_u32 s6, 0xff
	s_cbranch_scc1 .LBB0_869
	s_barrier

; #define PG8_STAGE(bufoff, gbase, voff) do { _Pragma("unroll") for (int _i = 0; _i < 2; ++_i) \
;         __builtin_amdgcn_global_load_lds((const unsigned*)((const char*)(gbase) + (voff)[_i]), (LAS unsigned*)(lds + (bufoff) + ldsw + _i * 8192), 16, 0, 0); } while (0)
; #define PG8_LDA(dst, b, h) do { _Pragma("unroll") for (int m = 0; m < 4; ++m) _Pragma("unroll") for (int k = 0; k < 2; ++k) dst[m][k] = *(const LAS bf16x8*)(lds + PG8_SA(b, h) + aoff + m * 2048 + k * 1024); } while (0)
; #define PG8_LDB(dst, b, h) do { _Pragma("unroll") for (int n = 0; n < 2; ++n) _Pragma("unroll") for (int k = 0; k < 2; ++k) dst[n][k] = *(const LAS bf16x8*)(lds + PG8_SB(b, h) + boff + n * 2048 + k * 1024); } while (0)
; #define PG8_MMA(ai, bj, At, Bt) do { __builtin_amdgcn_s_setprio(1); _Pragma("unroll") for (int m = 0; m < 4; ++m) _Pragma("unroll") for (int n = 0; n < 2; ++n) _Pragma("unroll") for (int k = 0; k < 2; ++k) \
;         acc[ai][bj][m][n] = __builtin_amdgcn_mfma_f32_16x16x32_bf16(Bt[n][k], At[m][k], acc[ai][bj][m][n], 0, 0, 0); __builtin_amdgcn_s_setprio(0); } while (0)
; #define PG8_WAIT_L(n) asm volatile("s_waitcnt lgkmcnt(" #n ")" ::: "memory")
; #define PG8_BAR __builtin_amdgcn_s_barrier()
; #define PG8_SCHED __builtin_amdgcn_sched_barrier(0)
; #define PG8_WAIT_L(n) asm volatile("s_waitcnt lgkmcnt(" #n ")" ::: "memory")
; #define PG8_BAR __builtin_amdgcn_s_barrier()
; template <class Epi>
; DI void gemm_phase(LAS unsigned char* lds, const Gemm g, const StaticOrder S, const Epi E) {
;     ...
;         for (int t = 0; t < nt; t += 2) {
;             const bool last = (t == nt - 2);
;             const char* a1 = cA + (size_t)(t + 1) * kstep;
;             const char* a2 = last ? nA : cA + (size_t)(t + 2) * kstep; const char* b2 = last ? nB : cB + (size_t)(t + 2) * kstep;
;             const char* a3 = a2 + kstep; const char* b3 = b2 + kstep;
;             PG8_LDB(B0, 0, 0); PG8_SCHED; PG8_LDA(At, 0, 0); PG8_STAGE(PG8_SA(1, 1), a1 + hstep, voffA);
;             PG8_WAIT_L(8); PG8_BAR; PG8_WAIT_L(0); PG8_MMA(0, 0, At, B0); PG8_BAR; PG8_SCHED;
;             PG8_LDB(B1, 0, 1); PG8_STAGE(PG8_SB(0, 0), b2, voffB);
;             PG8_BAR; PG8_WAIT_L(0); PG8_MMA(0, 1, At, B1); PG8_BAR;
;             PG8_LDA(At, 0, 1); PG8_STAGE(PG8_SA(0, 0), a2, voffA);
;             PG8_BAR; PG8_WAIT_L(0); PG8_MMA(1, 0, At, B0); PG8_BAR; PG8_SCHED;
.LBB0_941:
	ds_read_b128 v[144:147], v199
	ds_read_b128 v[148:151], v199 offset:1024
	ds_read_b128 v[152:155], v199 offset:2048
	ds_read_b128 v[156:159], v199 offset:3072
	s_add_u32 s22, s20, 0x100
	s_addc_u32 s23, s21, 0
	s_cmp_eq_u32 s58, 40
	s_cselect_b32 s27, s9, s23
	s_cselect_b32 s26, s8, s22
	s_cselect_b32 s25, s5, s53
	s_cselect_b32 s24, s4, s52
	v_lshl_add_u64 v[192:193], s[20:21], 0, v[136:137]
	s_add_i32 m0, s33, 0xc000
	ds_read_b128 v[160:163], v200
	ds_read_b128 v[164:167], v200 offset:1024
	ds_read_b128 v[168:171], v200 offset:2048
	ds_read_b128 v[172:175], v200 offset:3072
	ds_read_b128 v[176:179], v200 offset:4096
	ds_read_b128 v[180:183], v200 offset:5120
	ds_read_b128 v[184:187], v200 offset:6144
	ds_read_b128 v[188:191], v200 offset:7168
	global_load_lds_dwordx4 v[192:193], off
	v_lshl_add_u64 v[192:193], s[20:21], 0, v[138:139]
	s_add_i32 m0, s33, 0xe000
	s_nop 0
	global_load_lds_dwordx4 v[192:193], off
	s_waitcnt lgkmcnt(8)
	s_barrier
	s_waitcnt lgkmcnt(0)
	s_setprio 1
	s_waitcnt lgkmcnt(0)
	v_mfma_f32_16x16x32_bf16 v[124:127], v[144:147], v[160:163], v[124:127]
	v_mfma_f32_16x16x32_bf16 v[120:123], v[152:155], v[160:163], v[120:123]
	v_mfma_f32_16x16x32_bf16 v[108:111], v[144:147], v[168:171], v[108:111]
	v_mfma_f32_16x16x32_bf16 v[104:107], v[152:155], v[168:171], v[104:107]
	v_mfma_f32_16x16x32_bf16 v[92:95], v[144:147], v[176:179], v[92:95]
	v_mfma_f32_16x16x32_bf16 v[88:91], v[152:155], v[176:179], v[88:91]
	v_mfma_f32_16x16x32_bf16 v[84:87], v[144:147], v[184:187], v[84:87]
	v_mfma_f32_16x16x32_bf16 v[76:79], v[152:155], v[184:187], v[76:79]
	v_mfma_f32_16x16x32_bf16 v[124:127], v[148:151], v[164:167], v[124:127]
	v_mfma_f32_16x16x32_bf16 v[120:123], v[156:159], v[164:167], v[120:123]
	v_mfma_f32_16x16x32_bf16 v[108:111], v[148:151], v[172:175], v[108:111]
	v_mfma_f32_16x16x32_bf16 v[104:107], v[156:159], v[172:175], v[104:107]
	v_mfma_f32_16x16x32_bf16 v[92:95], v[148:151], v[180:183], v[92:95]
	v_mfma_f32_16x16x32_bf16 v[88:91], v[156:159], v[180:183], v[88:91]
	v_mfma_f32_16x16x32_bf16 v[84:87], v[148:151], v[188:191], v[84:87]
	v_mfma_f32_16x16x32_bf16 v[76:79], v[156:159], v[188:191], v[76:79]
	s_setprio 0
	s_barrier
	s_add_i32 s20, s42, s29
	v_lshl_add_u64 v[214:215], s[24:25], 0, v[130:131]
	s_mov_b32 m0, s20
	ds_read_b128 v[192:195], v201
	ds_read_b128 v[202:205], v201 offset:1024
	ds_read_b128 v[206:209], v201 offset:2048
	ds_read_b128 v[210:213], v201 offset:3072
	global_load_lds_dwordx4 v[214:215], off
	v_lshl_add_u64 v[216:217], s[24:25], 0, v[134:135]
	s_add_i32 m0, s20, 0x2000
	s_nop 0
	global_load_lds_dwordx4 v[216:217], off
	s_barrier
	s_waitcnt lgkmcnt(0)
	s_setprio 1
	s_waitcnt lgkmcnt(0)
	v_mfma_f32_16x16x32_bf16 v[116:119], v[192:195], v[160:163], v[116:119]
	v_mfma_f32_16x16x32_bf16 v[112:115], v[206:209], v[160:163], v[112:115]
	v_mfma_f32_16x16x32_bf16 v[100:103], v[192:195], v[168:171], v[100:103]
	v_mfma_f32_16x16x32_bf16 v[96:99], v[206:209], v[168:171], v[96:99]
	v_mfma_f32_16x16x32_bf16 v[80:83], v[192:195], v[176:179], v[80:83]
	v_mfma_f32_16x16x32_bf16 v[72:75], v[206:209], v[176:179], v[72:75]
	v_mfma_f32_16x16x32_bf16 v[68:71], v[192:195], v[184:187], v[68:71]
	v_mfma_f32_16x16x32_bf16 v[64:67], v[206:209], v[184:187], v[64:67]
	v_mfma_f32_16x16x32_bf16 v[116:119], v[202:205], v[164:167], v[116:119]
	v_mfma_f32_16x16x32_bf16 v[112:115], v[210:213], v[164:167], v[112:115]
	v_mfma_f32_16x16x32_bf16 v[100:103], v[202:205], v[172:175], v[100:103]
	v_mfma_f32_16x16x32_bf16 v[96:99], v[210:213], v[172:175], v[96:99]
	v_mfma_f32_16x16x32_bf16 v[80:83], v[202:205], v[180:183], v[80:83]
	v_mfma_f32_16x16x32_bf16 v[72:75], v[210:213], v[180:183], v[72:75]
	v_mfma_f32_16x16x32_bf16 v[68:71], v[202:205], v[188:191], v[68:71]
	v_mfma_f32_16x16x32_bf16 v[64:67], v[210:213], v[188:191], v[64:67]
	s_setprio 0
	s_mov_b32 m0, s33
	v_lshl_add_u64 v[218:219], s[26:27], 0, v[128:129]
	s_barrier
	ds_read_b128 v[160:163], v200 offset:16384
	ds_read_b128 v[164:167], v200 offset:17408
	ds_read_b128 v[168:171], v200 offset:18432
	ds_read_b128 v[172:175], v200 offset:19456
	ds_read_b128 v[176:179], v200 offset:20480
	ds_read_b128 v[180:183], v200 offset:21504
	ds_read_b128 v[184:187], v200 offset:22528
	ds_read_b128 v[188:191], v200 offset:23552
	global_load_lds_dwordx4 v[218:219], off
	v_lshl_add_u64 v[220:221], s[26:27], 0, v[132:133]
	s_mov_b32 m0, s34
	s_nop 0
	global_load_lds_dwordx4 v[220:221], off
	s_barrier
	s_waitcnt lgkmcnt(0)
	s_setprio 1
	s_waitcnt lgkmcnt(0)
	v_mfma_f32_16x16x32_bf16 v[60:63], v[144:147], v[160:163], v[60:63]
	v_mfma_f32_16x16x32_bf16 v[56:59], v[152:155], v[160:163], v[56:59]
	v_mfma_f32_16x16x32_bf16 v[48:51], v[144:147], v[168:171], v[48:51]
	v_mfma_f32_16x16x32_bf16 v[40:43], v[152:155], v[168:171], v[40:43]
	v_mfma_f32_16x16x32_bf16 v[32:35], v[144:147], v[176:179], v[32:35]
	v_mfma_f32_16x16x32_bf16 v[24:27], v[152:155], v[176:179], v[24:27]
	v_mfma_f32_16x16x32_bf16 v[16:19], v[144:147], v[184:187], v[16:19]
	v_mfma_f32_16x16x32_bf16 v[8:11], v[152:155], v[184:187], v[8:11]
	v_mfma_f32_16x16x32_bf16 v[60:63], v[148:151], v[164:167], v[60:63]
	v_mfma_f32_16x16x32_bf16 v[56:59], v[156:159], v[164:167], v[56:59]
	v_mfma_f32_16x16x32_bf16 v[48:51], v[148:151], v[172:175], v[48:51]
	v_mfma_f32_16x16x32_bf16 v[40:43], v[156:159], v[172:175], v[40:43]
	v_mfma_f32_16x16x32_bf16 v[32:35], v[148:151], v[180:183], v[32:35]
	v_mfma_f32_16x16x32_bf16 v[24:27], v[156:159], v[180:183], v[24:27]
	v_mfma_f32_16x16x32_bf16 v[16:19], v[148:151], v[188:191], v[16:19]
	v_mfma_f32_16x16x32_bf16 v[8:11], v[156:159], v[188:191], v[8:11]
	s_setprio 0
	s_barrier
; #define PG8_STAGE(bufoff, gbase, voff) do { _Pragma("unroll") for (int _i = 0; _i < 2; ++_i) \
;         __builtin_amdgcn_global_load_lds((const unsigned*)((const char*)(gbase) + (voff)[_i]), (LAS unsigned*)(lds + (bufoff) + ldsw + _i * 8192), 16, 0, 0); } while (0)
; #define PG8_LDA(dst, b, h) do { _Pragma("unroll") for (int m = 0; m < 4; ++m) _Pragma("unroll") for (int k = 0; k < 2; ++k) dst[m][k] = *(const LAS bf16x8*)(lds + PG8_SA(b, h) + aoff + m * 2048 + k * 1024); } while (0)
; #define PG8_LDB(dst, b, h) do { _Pragma("unroll") for (int n = 0; n < 2; ++n) _Pragma("unroll") for (int k = 0; k < 2; ++k) dst[n][k] = *(const LAS bf16x8*)(lds + PG8_SB(b, h) + boff + n * 2048 + k * 1024); } while (0)
; #define PG8_MMA(ai, bj, At, Bt) do { __builtin_amdgcn_s_setprio(1); _Pragma("unroll") for (int m = 0; m < 4; ++m) _Pragma("unroll") for (int n = 0; n < 2; ++n) _Pragma("unroll") for (int k = 0; k < 2; ++k) \
;         acc[ai][bj][m][n] = __builtin_amdgcn_mfma_f32_16x16x32_bf16(Bt[n][k], At[m][k], acc[ai][bj][m][n], 0, 0, 0); __builtin_amdgcn_s_setprio(0); } while (0)
; #define PG8_WAIT_V(n) asm volatile("s_waitcnt vmcnt(" #n ")" ::: "memory")
; #define PG8_WAIT_L(n) asm volatile("s_waitcnt lgkmcnt(" #n ")" ::: "memory")
; #define PG8_BAR __builtin_amdgcn_s_barrier()
; #define PG8_SCHED __builtin_amdgcn_sched_barrier(0)
; #define PG8_STAGE(bufoff, gbase, voff) do { _Pragma("unroll") for (int _i = 0; _i < 2; ++_i) \
;         __builtin_amdgcn_global_load_lds((const unsigned*)((const char*)(gbase) + (voff)[_i]), (LAS unsigned*)(lds + (bufoff) + ldsw + _i * 8192), 16, 0, 0); } while (0)
; #define PG8_WAIT_V(n) asm volatile("s_waitcnt vmcnt(" #n ")" ::: "memory")
; #define PG8_BAR __builtin_amdgcn_s_barrier()
; template <class Epi>
; DI void gemm_phase(LAS unsigned char* lds, const Gemm g, const StaticOrder S, const Epi E) {
;     ...
;             PG8_STAGE(PG8_SB(0, 1), b2 + hstep, voffB);
;             PG8_WAIT_V(6); PG8_BAR; PG8_MMA(1, 1, At, B1); PG8_BAR;
;             PG8_LDB(B0, 1, 0); PG8_SCHED; PG8_LDA(At, 1, 0); PG8_STAGE(PG8_SA(0, 1), a2 + hstep, voffA);
;             PG8_WAIT_L(8); PG8_BAR; PG8_WAIT_L(0); PG8_MMA(0, 0, At, B0); PG8_BAR; PG8_SCHED;
;             PG8_LDB(B1, 1, 1); PG8_STAGE(PG8_SB(1, 0), b3, voffB);
;             PG8_BAR; PG8_WAIT_L(0); PG8_MMA(0, 1, At, B1); PG8_BAR;
;             PG8_LDA(At, 1, 1); PG8_STAGE(PG8_SA(1, 0), a3, voffA);
	s_add_u32 s20, s24, 0xb0000
	s_addc_u32 s21, s25, 0
	s_add_i32 s59, s43, s29
	v_lshl_add_u64 v[144:145], s[20:21], 0, v[130:131]
	s_mov_b32 m0, s59
	s_nop 0
	global_load_lds_dwordx4 v[144:145], off
	v_lshl_add_u64 v[144:145], s[20:21], 0, v[134:135]
	s_add_i32 m0, s59, 0x2000
	s_nop 0
	global_load_lds_dwordx4 v[144:145], off
	s_waitcnt vmcnt(6)
	s_barrier
	s_setprio 1
	v_mfma_f32_16x16x32_bf16 v[52:55], v[192:195], v[160:163], v[52:55]
	v_mfma_f32_16x16x32_bf16 v[44:47], v[206:209], v[160:163], v[44:47]
	v_mfma_f32_16x16x32_bf16 v[36:39], v[192:195], v[168:171], v[36:39]
	v_mfma_f32_16x16x32_bf16 v[28:31], v[206:209], v[168:171], v[28:31]
	v_mfma_f32_16x16x32_bf16 v[20:23], v[192:195], v[176:179], v[20:23]
	v_mfma_f32_16x16x32_bf16 v[12:15], v[206:209], v[176:179], v[12:15]
	v_mfma_f32_16x16x32_bf16 v[4:7], v[192:195], v[184:187], v[4:7]
	v_mfma_f32_16x16x32_bf16 v[0:3], v[206:209], v[184:187], v[0:3]
	v_mfma_f32_16x16x32_bf16 v[52:55], v[202:205], v[164:167], v[52:55]
	v_mfma_f32_16x16x32_bf16 v[44:47], v[210:213], v[164:167], v[44:47]
	v_mfma_f32_16x16x32_bf16 v[36:39], v[202:205], v[172:175], v[36:39]
	v_mfma_f32_16x16x32_bf16 v[28:31], v[210:213], v[172:175], v[28:31]
	v_mfma_f32_16x16x32_bf16 v[20:23], v[202:205], v[180:183], v[20:23]
	v_mfma_f32_16x16x32_bf16 v[12:15], v[210:213], v[180:183], v[12:15]
	v_mfma_f32_16x16x32_bf16 v[4:7], v[202:205], v[188:191], v[4:7]
	v_mfma_f32_16x16x32_bf16 v[0:3], v[210:213], v[188:191], v[0:3]
	s_setprio 0
	s_add_i32 s59, 0, 0x18000
	v_add_u32_e32 v156, s59, v197
	s_barrier
	ds_read_b128 v[144:147], v156
	ds_read_b128 v[148:151], v156 offset:1024
	ds_read_b128 v[152:155], v156 offset:2048
	ds_read_b128 v[156:159], v156 offset:3072
	s_add_u32 s20, s26, 0xb0000
	s_addc_u32 s21, s27, 0
	s_mov_b32 m0, s35
	v_lshl_add_u64 v[192:193], s[20:21], 0, v[128:129]
	ds_read_b128 v[160:163], v200 offset:32768
	ds_read_b128 v[164:167], v200 offset:33792
	ds_read_b128 v[168:171], v200 offset:34816
	ds_read_b128 v[172:175], v200 offset:35840
	ds_read_b128 v[176:179], v200 offset:36864
	ds_read_b128 v[180:183], v200 offset:37888
	ds_read_b128 v[184:187], v200 offset:38912
	ds_read_b128 v[188:191], v200 offset:39936
	global_load_lds_dwordx4 v[192:193], off
	v_lshl_add_u64 v[192:193], s[20:21], 0, v[132:133]
	s_mov_b32 m0, s36
	s_nop 0
	global_load_lds_dwordx4 v[192:193], off
	s_waitcnt lgkmcnt(8)
	s_barrier
	s_waitcnt lgkmcnt(0)
	s_setprio 1
	s_waitcnt lgkmcnt(0)
	v_mfma_f32_16x16x32_bf16 v[124:127], v[144:147], v[160:163], v[124:127]
	v_mfma_f32_16x16x32_bf16 v[120:123], v[152:155], v[160:163], v[120:123]
	v_mfma_f32_16x16x32_bf16 v[108:111], v[144:147], v[168:171], v[108:111]
	v_mfma_f32_16x16x32_bf16 v[104:107], v[152:155], v[168:171], v[104:107]
	v_mfma_f32_16x16x32_bf16 v[92:95], v[144:147], v[176:179], v[92:95]
	v_mfma_f32_16x16x32_bf16 v[88:91], v[152:155], v[176:179], v[88:91]
	v_mfma_f32_16x16x32_bf16 v[84:87], v[144:147], v[184:187], v[84:87]
	v_mfma_f32_16x16x32_bf16 v[76:79], v[152:155], v[184:187], v[76:79]
	v_mfma_f32_16x16x32_bf16 v[124:127], v[148:151], v[164:167], v[124:127]
	v_mfma_f32_16x16x32_bf16 v[120:123], v[156:159], v[164:167], v[120:123]
	v_mfma_f32_16x16x32_bf16 v[108:111], v[148:151], v[172:175], v[108:111]
	v_mfma_f32_16x16x32_bf16 v[104:107], v[156:159], v[172:175], v[104:107]
	v_mfma_f32_16x16x32_bf16 v[92:95], v[148:151], v[180:183], v[92:95]
	v_mfma_f32_16x16x32_bf16 v[88:91], v[156:159], v[180:183], v[88:91]
	v_mfma_f32_16x16x32_bf16 v[84:87], v[148:151], v[188:191], v[84:87]
	v_mfma_f32_16x16x32_bf16 v[76:79], v[156:159], v[188:191], v[76:79]
	s_setprio 0
	s_barrier
	s_add_i32 s26, 0, 0x1c000
	s_add_i32 s20, s59, s29
	v_add_u32_e32 v210, s26, v197
	v_lshl_add_u64 v[214:215], v[214:215], 0, s[10:11]
	s_mov_b32 m0, s20
	ds_read_b128 v[192:195], v210
	ds_read_b128 v[202:205], v210 offset:1024
	ds_read_b128 v[206:209], v210 offset:2048
	ds_read_b128 v[210:213], v210 offset:3072
	global_load_lds_dwordx4 v[214:215], off
	v_lshl_add_u64 v[214:215], v[216:217], 0, s[10:11]
	s_add_i32 m0, s20, 0x2000
	s_nop 0
	global_load_lds_dwordx4 v[214:215], off
	s_barrier
	s_waitcnt lgkmcnt(0)
	s_setprio 1
	s_waitcnt lgkmcnt(0)
	v_mfma_f32_16x16x32_bf16 v[116:119], v[192:195], v[160:163], v[116:119]
	v_mfma_f32_16x16x32_bf16 v[112:115], v[206:209], v[160:163], v[112:115]
	v_mfma_f32_16x16x32_bf16 v[100:103], v[192:195], v[168:171], v[100:103]
	v_mfma_f32_16x16x32_bf16 v[96:99], v[206:209], v[168:171], v[96:99]
	v_mfma_f32_16x16x32_bf16 v[80:83], v[192:195], v[176:179], v[80:83]
	v_mfma_f32_16x16x32_bf16 v[72:75], v[206:209], v[176:179], v[72:75]
	v_mfma_f32_16x16x32_bf16 v[68:71], v[192:195], v[184:187], v[68:71]
	v_mfma_f32_16x16x32_bf16 v[64:67], v[206:209], v[184:187], v[64:67]
	v_mfma_f32_16x16x32_bf16 v[116:119], v[202:205], v[164:167], v[116:119]
	v_mfma_f32_16x16x32_bf16 v[112:115], v[210:213], v[164:167], v[112:115]
	v_mfma_f32_16x16x32_bf16 v[100:103], v[202:205], v[172:175], v[100:103]
	v_mfma_f32_16x16x32_bf16 v[96:99], v[210:213], v[172:175], v[96:99]
	v_mfma_f32_16x16x32_bf16 v[80:83], v[202:205], v[180:183], v[80:83]
	v_mfma_f32_16x16x32_bf16 v[72:75], v[210:213], v[180:183], v[72:75]
	v_mfma_f32_16x16x32_bf16 v[68:71], v[202:205], v[188:191], v[68:71]
	v_mfma_f32_16x16x32_bf16 v[64:67], v[210:213], v[188:191], v[64:67]
	s_setprio 0
	s_mov_b32 m0, s38
	v_lshl_add_u64 v[214:215], v[218:219], 0, s[10:11]
	s_barrier
	ds_read_b128 v[160:163], v200 offset:49152
	ds_read_b128 v[164:167], v200 offset:50176
	ds_read_b128 v[168:171], v200 offset:51200
	ds_read_b128 v[172:175], v200 offset:52224
	ds_read_b128 v[176:179], v200 offset:53248
	ds_read_b128 v[180:183], v200 offset:54272
	ds_read_b128 v[184:187], v200 offset:55296
	ds_read_b128 v[188:191], v200 offset:56320
	global_load_lds_dwordx4 v[214:215], off
	v_lshl_add_u64 v[214:215], v[220:221], 0, s[10:11]
	s_mov_b32 m0, s39
	s_nop 0
	global_load_lds_dwordx4 v[214:215], off
	s_barrier
; DI f32x4 bf_lo4(u32x4 w) { f32x4 r; r[0] = bf_lo(w.x); r[1] = bf_hi(w.x); r[2] = bf_lo(w.y); r[3] = bf_hi(w.y); return r; }
; DI f32x4 bf_hi4(u32x4 w) { f32x4 r; r[0] = bf_lo(w.z); r[1] = bf_hi(w.z); r[2] = bf_lo(w.w); r[3] = bf_hi(w.w); return r; }
; #define PG8_STAGE(bufoff, gbase, voff) do { _Pragma("unroll") for (int _i = 0; _i < 2; ++_i) \
;         __builtin_amdgcn_global_load_lds((const unsigned*)((const char*)(gbase) + (voff)[_i]), (LAS unsigned*)(lds + (bufoff) + ldsw + _i * 8192), 16, 0, 0); } while (0)
; #define PG8_LDA(dst, b, h) do { _Pragma("unroll") for (int m = 0; m < 4; ++m) _Pragma("unroll") for (int k = 0; k < 2; ++k) dst[m][k] = *(const LAS bf16x8*)(lds + PG8_SA(b, h) + aoff + m * 2048 + k * 1024); } while (0)
; #define PG8_LDB(dst, b, h) do { _Pragma("unroll") for (int n = 0; n < 2; ++n) _Pragma("unroll") for (int k = 0; k < 2; ++k) dst[n][k] = *(const LAS bf16x8*)(lds + PG8_SB(b, h) + boff + n * 2048 + k * 1024); } while (0)
; #define PG8_WAIT_V(n) asm volatile("s_waitcnt vmcnt(" #n ")" ::: "memory")
; #define PG8_WAIT_L(n) asm volatile("s_waitcnt lgkmcnt(" #n ")" ::: "memory")
; #define PG8_BAR __builtin_amdgcn_s_barrier()
; template <class Epi>
; DI void gemm_phase(LAS unsigned char* lds, const Gemm g, const StaticOrder S, const Epi E) {
;     ...
;             PG8_LDB(B1, 1, 1); PG8_STAGE(PG8_SB(1, 0), b3, voffB);
;             PG8_BAR; PG8_WAIT_L(0); PG8_MMA(0, 1, At, B1); PG8_BAR;
;             PG8_LDA(At, 1, 1); PG8_STAGE(PG8_SA(1, 0), a3, voffA);
;             PG8_BAR; PG8_WAIT_L(0); PG8_MMA(1, 0, At, B0); PG8_BAR; PG8_SCHED;
;             PG8_STAGE(PG8_SB(1, 1), b3 + hstep, voffB);
;             PG8_WAIT_V(6); PG8_BAR; PG8_MMA(1, 1, At, B1); PG8_BAR;
;     DI void operator()(AccRef acc, const Unit& u, int wr, int wc, int fr, int fq) const {
;     ...
; #pragma unroll
;         for (int ai = 0; ai < 2; ++ai) {
;             f32x4 bv[4][2][2];
; #pragma unroll
;             for (int m = 0; m < 4; ++m)
; #pragma unroll
;                 for (int bj = 0; bj < 2; ++bj) {
;                     const size_t o = (size_t)(row0 + ai * 128 + m * 16) * DM + col0 + bj * 128;
;                     if (BASEF32) { bv[m][bj][0] = *(const f32x4*)(basef + o); bv[m][bj][1] = *(const f32x4*)(basef + o + 4); }
;                     else { const u32x4 h = *(const u32x4*)(xnb + o); bv[m][bj][0] = bf_lo4(h); bv[m][bj][1] = bf_hi4(h); }
;                 }
	s_waitcnt lgkmcnt(0)
	s_setprio 1
	s_waitcnt lgkmcnt(0)
	v_mfma_f32_16x16x32_bf16 v[60:63], v[144:147], v[160:163], v[60:63]
	v_mfma_f32_16x16x32_bf16 v[56:59], v[152:155], v[160:163], v[56:59]
	v_mfma_f32_16x16x32_bf16 v[48:51], v[144:147], v[168:171], v[48:51]
	v_mfma_f32_16x16x32_bf16 v[40:43], v[152:155], v[168:171], v[40:43]
	v_mfma_f32_16x16x32_bf16 v[32:35], v[144:147], v[176:179], v[32:35]
	v_mfma_f32_16x16x32_bf16 v[24:27], v[152:155], v[176:179], v[24:27]
	v_mfma_f32_16x16x32_bf16 v[16:19], v[144:147], v[184:187], v[16:19]
	v_mfma_f32_16x16x32_bf16 v[8:11], v[152:155], v[184:187], v[8:11]
	v_mfma_f32_16x16x32_bf16 v[60:63], v[148:151], v[164:167], v[60:63]
	v_mfma_f32_16x16x32_bf16 v[56:59], v[156:159], v[164:167], v[56:59]
	v_mfma_f32_16x16x32_bf16 v[48:51], v[148:151], v[172:175], v[48:51]
	v_mfma_f32_16x16x32_bf16 v[40:43], v[156:159], v[172:175], v[40:43]
	v_mfma_f32_16x16x32_bf16 v[32:35], v[148:151], v[180:183], v[32:35]
	v_mfma_f32_16x16x32_bf16 v[24:27], v[156:159], v[180:183], v[24:27]
	v_mfma_f32_16x16x32_bf16 v[16:19], v[148:151], v[188:191], v[16:19]
	v_mfma_f32_16x16x32_bf16 v[8:11], v[156:159], v[188:191], v[8:11]
	s_setprio 0
	s_barrier
	s_add_u32 s20, s24, 0xb0080
	s_addc_u32 s21, s25, 0
	s_add_i32 s24, s26, s29
	v_lshl_add_u64 v[144:145], s[20:21], 0, v[130:131]
	s_mov_b32 m0, s24
	s_nop 0
	global_load_lds_dwordx4 v[144:145], off
	v_lshl_add_u64 v[144:145], s[20:21], 0, v[134:135]
	s_add_i32 m0, s24, 0x2000
	s_nop 0
	global_load_lds_dwordx4 v[144:145], off
	s_waitcnt vmcnt(6)
	s_barrier
	s_setprio 1
	v_mfma_f32_16x16x32_bf16 v[52:55], v[192:195], v[160:163], v[52:55]
	v_mfma_f32_16x16x32_bf16 v[44:47], v[206:209], v[160:163], v[44:47]
	v_mfma_f32_16x16x32_bf16 v[36:39], v[192:195], v[168:171], v[36:39]
	v_mfma_f32_16x16x32_bf16 v[28:31], v[206:209], v[168:171], v[28:31]
	v_mfma_f32_16x16x32_bf16 v[20:23], v[192:195], v[176:179], v[20:23]
	v_mfma_f32_16x16x32_bf16 v[12:15], v[206:209], v[176:179], v[12:15]
	v_mfma_f32_16x16x32_bf16 v[4:7], v[192:195], v[184:187], v[4:7]
	v_mfma_f32_16x16x32_bf16 v[0:3], v[206:209], v[184:187], v[0:3]
	v_mfma_f32_16x16x32_bf16 v[52:55], v[202:205], v[164:167], v[52:55]
	v_mfma_f32_16x16x32_bf16 v[44:47], v[210:213], v[164:167], v[44:47]
	v_mfma_f32_16x16x32_bf16 v[36:39], v[202:205], v[172:175], v[36:39]
	v_mfma_f32_16x16x32_bf16 v[28:31], v[210:213], v[172:175], v[28:31]
	v_mfma_f32_16x16x32_bf16 v[20:23], v[202:205], v[180:183], v[20:23]
	v_mfma_f32_16x16x32_bf16 v[12:15], v[210:213], v[180:183], v[12:15]
	v_mfma_f32_16x16x32_bf16 v[4:7], v[202:205], v[188:191], v[4:7]
	v_mfma_f32_16x16x32_bf16 v[0:3], v[210:213], v[188:191], v[0:3]
	s_setprio 0
	s_add_i32 s58, s58, 2
	s_add_u32 s52, s52, 0x100
	s_addc_u32 s53, s53, 0
	s_cmp_gt_u32 s58, 41
	s_mov_b64 s[20:21], s[22:23]
	s_barrier
	s_cbranch_scc0 .LBB0_941
	v_lshl_add_u32 v148, s50, 8, v196
	v_lshl_or_b32 v144, s51, 8, v198
	v_or_b32_e32 v146, 16, v148
	v_ashrrev_i32_e32 v145, 31, v144
	v_ashrrev_i32_e32 v147, 31, v146
	v_lshl_add_u64 v[176:177], v[144:145], 1, s[56:57]
	v_ashrrev_i32_e32 v149, 31, v148
	v_lshlrev_b64 v[146:147], 11, v[146:147]
	v_lshlrev_b64 v[144:145], 11, v[148:149]
	v_lshl_add_u64 v[150:151], v[176:177], 0, v[146:147]
	v_or_b32_e32 v146, 32, v148
	v_or_b32_e32 v148, 48, v148
	v_ashrrev_i32_e32 v147, 31, v146
	v_ashrrev_i32_e32 v149, 31, v148
	v_lshl_add_u64 v[144:145], v[176:177], 0, v[144:145]
	v_lshlrev_b64 v[146:147], 11, v[146:147]
	v_lshlrev_b64 v[148:149], 11, v[148:149]
	global_load_dwordx4 v[152:155], v[144:145], off
	global_load_dwordx4 v[156:159], v[144:145], off offset:256
	v_lshl_add_u64 v[146:147], v[176:177], 0, v[146:147]
	v_lshl_add_u64 v[148:149], v[176:177], 0, v[148:149]
	global_load_dwordx4 v[160:163], v[150:151], off
	global_load_dwordx4 v[164:167], v[150:151], off offset:256
	global_load_dwordx4 v[168:171], v[146:147], off
	global_load_dwordx4 v[172:175], v[146:147], off offset:256
	global_load_dwordx4 v[202:205], v[148:149], off
	global_load_dwordx4 v[206:209], v[148:149], off offset:256
	s_mov_b32 s51, s48
	s_mov_b32 s50, s49
	s_mov_b64 s[22:23], s[4:5]
	s_mov_b64 s[20:21], s[8:9]
	s_waitcnt vmcnt(0)
	v_lshlrev_b32_e32 v214, 16, v154
	v_and_b32_e32 v215, 0xffff0000, v154
	v_lshlrev_b32_e32 v216, 16, v155
	v_and_b32_e32 v217, 0xffff0000, v155
	v_lshlrev_b32_e32 v210, 16, v152
	v_and_b32_e32 v211, 0xffff0000, v152
	v_lshlrev_b32_e32 v212, 16, v153
	v_and_b32_e32 v213, 0xffff0000, v153
	v_lshlrev_b32_e32 v194, 16, v162
	v_and_b32_e32 v195, 0xffff0000, v162
	v_lshlrev_b32_e32 v230, 16, v163
	v_and_b32_e32 v231, 0xffff0000, v163
	v_lshlrev_b32_e32 v154, 16, v202
	v_and_b32_e32 v155, 0xffff0000, v202
	v_lshlrev_b32_e32 v162, 16, v203
	v_and_b32_e32 v163, 0xffff0000, v203
	v_pk_fma_f32 v[202:203], v[122:123], 0.5, v[216:217] op_sel_hi:[1,0,1]
	v_pk_fma_f32 v[122:123], v[120:121], 0.5, v[214:215] op_sel_hi:[1,0,1]
	v_lshlrev_b32_e32 v218, 16, v156
	v_and_b32_e32 v219, 0xffff0000, v156
	v_lshlrev_b32_e32 v220, 16, v157
	v_and_b32_e32 v221, 0xffff0000, v157
	v_pk_fma_f32 v[126:127], v[126:127], 0.5, v[212:213] op_sel_hi:[1,0,1]
	v_pk_fma_f32 v[124:125], v[124:125], 0.5, v[210:211] op_sel_hi:[1,0,1]
	v_cvt_pk_bf16_f32 v122, v122, v123
	v_cvt_pk_bf16_f32 v123, v202, v203
	v_add_co_u32_e32 v202, vcc, s44, v144
	v_lshlrev_b32_e32 v224, 16, v158
	v_and_b32_e32 v225, 0xffff0000, v158
	v_lshlrev_b32_e32 v226, 16, v159
	v_and_b32_e32 v227, 0xffff0000, v159
	v_cvt_pk_bf16_f32 v120, v124, v125
	v_cvt_pk_bf16_f32 v121, v126, v127
	v_pk_fma_f32 v[118:119], v[118:119], 0.5, v[220:221] op_sel_hi:[1,0,1]
	v_pk_fma_f32 v[116:117], v[116:117], 0.5, v[218:219] op_sel_hi:[1,0,1]
	v_addc_co_u32_e32 v203, vcc, 0, v145, vcc
; DI unsigned pk_bf16(float lo, float hi) { f32x2 v = {lo, hi}; return __builtin_bit_cast(unsigned, __builtin_convertvector(v, bf16v2)); }
;     DI void operator()(AccRef acc, const Unit& u, int wr, int wc, int fr, int fq) const {
;     ...
;             for (int m = 0; m < 4; ++m) {
;                 const int row = row0 + ai * 128 + m * 16;
;                 float q = 0.f;
; #pragma unroll
;                 for (int bj = 0; bj < 2; ++bj) {
;                     const size_t o = (size_t)row * DM + col0 + bj * 128;
;                     const f32x4 r0 = bv[m][bj][0] + scale * acc[ai][bj][m][0], r1 = bv[m][bj][1] + scale * acc[ai][bj][m][1];
;                     u32x4 w; w.x = pk_bf16(r0[0], r0[1]); w.y = pk_bf16(r0[2], r0[3]); w.z = pk_bf16(r1[0], r1[1]); w.w = pk_bf16(r1[2], r1[3]);
;                     *(u32x4*)(xnb + o) = w;
;                     if (STATS) q += r0[0] * r0[0] + r0[1] * r0[1] + r0[2] * r0[2] + r0[3] * r0[3] + r1[0] * r1[0] + r1[1] * r1[1] + r1[2] * r1[2] + r1[3] * r1[3];
	v_lshlrev_b32_e32 v192, 16, v160
	v_and_b32_e32 v193, 0xffff0000, v160
	global_store_dwordx4 v[144:145], v[120:123], off
	v_pk_fma_f32 v[108:109], v[108:109], 0.5, v[192:193] op_sel_hi:[1,0,1]
	v_lshl_add_u64 v[192:193], v[144:145], 0, s[12:13]
	v_pk_fma_f32 v[120:121], v[114:115], 0.5, v[226:227] op_sel_hi:[1,0,1]
	v_pk_fma_f32 v[114:115], v[112:113], 0.5, v[224:225] op_sel_hi:[1,0,1]
	v_cvt_pk_bf16_f32 v112, v116, v117
	v_cvt_pk_bf16_f32 v113, v118, v119
	global_load_dwordx4 v[116:119], v[202:203], off
	v_cvt_pk_bf16_f32 v114, v114, v115
	v_cvt_pk_bf16_f32 v115, v120, v121
	v_lshlrev_b32_e32 v228, 16, v161
	v_and_b32_e32 v229, 0xffff0000, v161
	global_store_dwordx4 v[144:145], v[112:115], off offset:256
	v_pk_fma_f32 v[120:121], v[106:107], 0.5, v[230:231] op_sel_hi:[1,0,1]
	v_pk_fma_f32 v[110:111], v[110:111], 0.5, v[228:229] op_sel_hi:[1,0,1]
	v_pk_fma_f32 v[112:113], v[104:105], 0.5, v[194:195] op_sel_hi:[1,0,1]
	global_load_dwordx4 v[104:107], v[192:193], off offset:256
	v_add_co_u32_e32 v194, vcc, s45, v144
	v_lshlrev_b32_e32 v184, 16, v164
	s_nop 0
	v_addc_co_u32_e32 v195, vcc, 0, v145, vcc
	v_and_b32_e32 v185, 0xffff0000, v164
	v_lshlrev_b32_e32 v188, 16, v165
	v_and_b32_e32 v189, 0xffff0000, v165
	v_lshlrev_b32_e32 v186, 16, v166
	v_and_b32_e32 v187, 0xffff0000, v166
	v_lshlrev_b32_e32 v190, 16, v167
	v_and_b32_e32 v191, 0xffff0000, v167
	v_cvt_pk_bf16_f32 v108, v108, v109
	v_cvt_pk_bf16_f32 v109, v110, v111
	v_cvt_pk_bf16_f32 v110, v112, v113
	global_load_dwordx4 v[112:115], v[194:195], off
	v_cvt_pk_bf16_f32 v111, v120, v121
	global_store_dwordx4 v[150:151], v[108:111], off
	v_pk_fma_f32 v[124:125], v[98:99], 0.5, v[190:191] op_sel_hi:[1,0,1]
	v_pk_fma_f32 v[96:97], v[96:97], 0.5, v[186:187] op_sel_hi:[1,0,1]
	v_pk_fma_f32 v[110:111], v[102:103], 0.5, v[188:189] op_sel_hi:[1,0,1]
	v_pk_fma_f32 v[108:109], v[100:101], 0.5, v[184:185] op_sel_hi:[1,0,1]
	v_lshl_add_u64 v[98:99], v[144:145], 0, s[14:15]
	global_load_dwordx4 v[100:103], v[98:99], off offset:256
	v_cvt_pk_bf16_f32 v108, v108, v109
	v_cvt_pk_bf16_f32 v109, v110, v111
	v_cvt_pk_bf16_f32 v110, v96, v97
	v_add_co_u32_e32 v96, vcc, s46, v144
	v_lshlrev_b32_e32 v176, 16, v168
	s_nop 0
	v_addc_co_u32_e32 v97, vcc, 0, v145, vcc
	v_and_b32_e32 v177, 0xffff0000, v168
	v_lshlrev_b32_e32 v180, 16, v169
	v_and_b32_e32 v181, 0xffff0000, v169
	v_lshlrev_b32_e32 v178, 16, v170
	v_and_b32_e32 v179, 0xffff0000, v170
	v_lshlrev_b32_e32 v182, 16, v171
	v_and_b32_e32 v183, 0xffff0000, v171
	global_load_dwordx4 v[120:123], v[96:97], off
	v_cvt_pk_bf16_f32 v111, v124, v125
	global_store_dwordx4 v[150:151], v[108:111], off offset:256
	v_pk_fma_f32 v[150:151], v[90:91], 0.5, v[182:183] op_sel_hi:[1,0,1]
	v_pk_fma_f32 v[88:89], v[88:89], 0.5, v[178:179] op_sel_hi:[1,0,1]
	v_pk_fma_f32 v[110:111], v[94:95], 0.5, v[180:181] op_sel_hi:[1,0,1]
	v_pk_fma_f32 v[108:109], v[92:93], 0.5, v[176:177] op_sel_hi:[1,0,1]
	v_lshl_add_u64 v[90:91], v[144:145], 0, s[16:17]
	global_load_dwordx4 v[92:95], v[90:91], off offset:256
	v_cvt_pk_bf16_f32 v108, v108, v109
	v_cvt_pk_bf16_f32 v109, v110, v111
	v_cvt_pk_bf16_f32 v110, v88, v89
	v_add_co_u32_e32 v88, vcc, s47, v144
	v_lshlrev_b32_e32 v170, 16, v174
	s_nop 0
	v_addc_co_u32_e32 v89, vcc, 0, v145, vcc
	v_and_b32_e32 v171, 0xffff0000, v174
	global_load_dwordx4 v[124:127], v[88:89], off
	v_lshlrev_b32_e32 v168, 16, v172
	v_and_b32_e32 v169, 0xffff0000, v172
	v_lshlrev_b32_e32 v172, 16, v173
	v_and_b32_e32 v173, 0xffff0000, v173
	v_cvt_pk_bf16_f32 v111, v150, v151
	v_pk_fma_f32 v[150:151], v[72:73], 0.5, v[170:171] op_sel_hi:[1,0,1]
	v_lshl_add_u64 v[72:73], v[144:145], 0, s[18:19]
	global_store_dwordx4 v[146:147], v[108:111], off
	v_lshlrev_b32_e32 v174, 16, v175
	v_and_b32_e32 v175, 0xffff0000, v175
	v_pk_fma_f32 v[110:111], v[82:83], 0.5, v[172:173] op_sel_hi:[1,0,1]
	v_pk_fma_f32 v[108:109], v[80:81], 0.5, v[168:169] op_sel_hi:[1,0,1]
	global_load_dwordx4 v[80:83], v[72:73], off offset:256
	v_lshlrev_b32_e32 v160, 16, v204
	v_and_b32_e32 v161, 0xffff0000, v204
	v_lshlrev_b32_e32 v166, 16, v205
	v_and_b32_e32 v167, 0xffff0000, v205
	v_pk_fma_f32 v[74:75], v[74:75], 0.5, v[174:175] op_sel_hi:[1,0,1]
	v_cvt_pk_bf16_f32 v108, v108, v109
	v_cvt_pk_bf16_f32 v109, v110, v111
	v_cvt_pk_bf16_f32 v111, v74, v75
	v_pk_fma_f32 v[86:87], v[86:87], 0.5, v[162:163] op_sel_hi:[1,0,1]
	v_pk_fma_f32 v[74:75], v[84:85], 0.5, v[154:155] op_sel_hi:[1,0,1]
	v_pk_fma_f32 v[78:79], v[78:79], 0.5, v[166:167] op_sel_hi:[1,0,1]
	v_pk_fma_f32 v[76:77], v[76:77], 0.5, v[160:161] op_sel_hi:[1,0,1]
	v_lshlrev_b32_e32 v152, 16, v206
	v_and_b32_e32 v153, 0xffff0000, v206
	v_lshlrev_b32_e32 v158, 16, v207
	v_and_b32_e32 v159, 0xffff0000, v207
	v_lshlrev_b32_e32 v156, 16, v208
	v_and_b32_e32 v157, 0xffff0000, v208
	v_lshlrev_b32_e32 v164, 16, v209
	v_and_b32_e32 v165, 0xffff0000, v209
	v_cvt_pk_bf16_f32 v74, v74, v75
	v_cvt_pk_bf16_f32 v75, v86, v87
	v_cvt_pk_bf16_f32 v76, v76, v77
	v_cvt_pk_bf16_f32 v77, v78, v79
	global_store_dwordx4 v[148:149], v[74:77], off
	v_pk_fma_f32 v[70:71], v[70:71], 0.5, v[158:159] op_sel_hi:[1,0,1]
	v_pk_fma_f32 v[68:69], v[68:69], 0.5, v[152:153] op_sel_hi:[1,0,1]
	v_pk_fma_f32 v[74:75], v[66:67], 0.5, v[164:165] op_sel_hi:[1,0,1]
	v_pk_fma_f32 v[66:67], v[64:65], 0.5, v[156:157] op_sel_hi:[1,0,1]
	v_cvt_pk_bf16_f32 v64, v68, v69
	v_cvt_pk_bf16_f32 v65, v70, v71
	v_cvt_pk_bf16_f32 v66, v66, v67
	v_cvt_pk_bf16_f32 v67, v74, v75
	global_store_dwordx4 v[148:149], v[64:67], off offset:256
	s_waitcnt vmcnt(0)
; DI unsigned pk_bf16(float lo, float hi) { f32x2 v = {lo, hi}; return __builtin_bit_cast(unsigned, __builtin_convertvector(v, bf16v2)); }
; #define PG8_WAIT_V(n) asm volatile("s_waitcnt vmcnt(" #n ")" ::: "memory")
; #define PG8_BAR __builtin_amdgcn_s_barrier()
; #define PG8_WAIT_V(n) asm volatile("s_waitcnt vmcnt(" #n ")" ::: "memory")
; #define PG8_BAR __builtin_amdgcn_s_barrier()
; template <class Epi>
; DI void gemm_phase(LAS unsigned char* lds, const Gemm g, const StaticOrder S, const Epi E) {
;     ...
;         E(acc, cur, wr, wc, fr, fq);
;         if (!has_next) break;
; #pragma unroll
;         for (int a = 0; a < 2; ++a)
; #pragma unroll
;             for (int b = 0; b < 2; ++b)
; #pragma unroll
;                 for (int m = 0; m < 4; ++m)
; #pragma unroll
;                     for (int n = 0; n < 2; ++n) acc[a][b][m][n] = (f32x4){0.f, 0.f, 0.f, 0.f};
;         cur = nxt; cA = nA; cB = nB; ++ui;
;     }
;     PG8_WAIT_V(0);
;     if (wr == 0) PG8_BAR;
;     PG8_BAR;
;     DI void operator()(AccRef acc, const Unit& u, int wr, int wc, int fr, int fq) const {
;     ...
;                 for (int bj = 0; bj < 2; ++bj) {
;                     const size_t o = (size_t)row * DM + col0 + bj * 128;
;                     const f32x4 r0 = bv[m][bj][0] + scale * acc[ai][bj][m][0], r1 = bv[m][bj][1] + scale * acc[ai][bj][m][1];
;                     u32x4 w; w.x = pk_bf16(r0[0], r0[1]); w.y = pk_bf16(r0[2], r0[3]); w.z = pk_bf16(r1[0], r1[1]); w.w = pk_bf16(r1[2], r1[3]);
;                     *(u32x4*)(xnb + o) = w;
	v_lshlrev_b32_e32 v68, 16, v118
	v_and_b32_e32 v69, 0xffff0000, v118
	v_lshlrev_b32_e32 v64, 16, v116
	v_and_b32_e32 v65, 0xffff0000, v116
	v_lshlrev_b32_e32 v66, 16, v117
	v_and_b32_e32 v67, 0xffff0000, v117
	v_lshlrev_b32_e32 v70, 16, v119
	v_and_b32_e32 v71, 0xffff0000, v119
	v_pk_fma_f32 v[62:63], v[62:63], 0.5, v[66:67] op_sel_hi:[1,0,1]
	v_pk_fma_f32 v[60:61], v[60:61], 0.5, v[64:65] op_sel_hi:[1,0,1]
	v_pk_fma_f32 v[64:65], v[58:59], 0.5, v[70:71] op_sel_hi:[1,0,1]
	v_pk_fma_f32 v[58:59], v[56:57], 0.5, v[68:69] op_sel_hi:[1,0,1]
	v_lshlrev_b32_e32 v74, 16, v104
	v_and_b32_e32 v75, 0xffff0000, v104
	v_lshlrev_b32_e32 v76, 16, v105
	v_and_b32_e32 v77, 0xffff0000, v105
	v_lshlrev_b32_e32 v78, 16, v106
	v_and_b32_e32 v79, 0xffff0000, v106
	v_lshlrev_b32_e32 v84, 16, v107
	v_and_b32_e32 v85, 0xffff0000, v107
	v_cvt_pk_bf16_f32 v56, v60, v61
	v_cvt_pk_bf16_f32 v57, v62, v63
	v_cvt_pk_bf16_f32 v58, v58, v59
	v_cvt_pk_bf16_f32 v59, v64, v65
	v_cvt_pk_bf16_f32 v110, v150, v151
	global_store_dwordx4 v[202:203], v[56:59], off
	v_pk_fma_f32 v[54:55], v[54:55], 0.5, v[76:77] op_sel_hi:[1,0,1]
	v_pk_fma_f32 v[52:53], v[52:53], 0.5, v[74:75] op_sel_hi:[1,0,1]
	v_pk_fma_f32 v[56:57], v[46:47], 0.5, v[84:85] op_sel_hi:[1,0,1]
	v_pk_fma_f32 v[46:47], v[44:45], 0.5, v[78:79] op_sel_hi:[1,0,1]
	global_store_dwordx4 v[146:147], v[108:111], off offset:256
	v_lshlrev_b32_e32 v86, 16, v112
	v_and_b32_e32 v87, 0xffff0000, v112
	v_lshlrev_b32_e32 v104, 16, v113
	v_and_b32_e32 v105, 0xffff0000, v113
	v_lshlrev_b32_e32 v106, 16, v114
	v_and_b32_e32 v107, 0xffff0000, v114
	v_lshlrev_b32_e32 v108, 16, v115
	v_and_b32_e32 v109, 0xffff0000, v115
	v_cvt_pk_bf16_f32 v44, v52, v53
	v_cvt_pk_bf16_f32 v45, v54, v55
	v_cvt_pk_bf16_f32 v46, v46, v47
	v_cvt_pk_bf16_f32 v47, v56, v57
	global_store_dwordx4 v[192:193], v[44:47], off offset:256
	v_lshlrev_b32_e32 v110, 16, v100
	v_and_b32_e32 v111, 0xffff0000, v100
	v_pk_fma_f32 v[44:45], v[50:51], 0.5, v[104:105] op_sel_hi:[1,0,1]
	v_pk_fma_f32 v[46:47], v[48:49], 0.5, v[86:87] op_sel_hi:[1,0,1]
	v_pk_fma_f32 v[48:49], v[42:43], 0.5, v[108:109] op_sel_hi:[1,0,1]
	v_pk_fma_f32 v[42:43], v[40:41], 0.5, v[106:107] op_sel_hi:[1,0,1]
	v_lshlrev_b32_e32 v100, 16, v101
	v_and_b32_e32 v101, 0xffff0000, v101
	v_lshlrev_b32_e32 v112, 16, v102
	v_and_b32_e32 v113, 0xffff0000, v102
	v_lshlrev_b32_e32 v102, 16, v103
	v_and_b32_e32 v103, 0xffff0000, v103
	v_cvt_pk_bf16_f32 v40, v46, v47
	v_cvt_pk_bf16_f32 v41, v44, v45
	v_cvt_pk_bf16_f32 v42, v42, v43
	v_cvt_pk_bf16_f32 v43, v48, v49
	global_store_dwordx4 v[194:195], v[40:43], off
	v_pk_fma_f32 v[38:39], v[38:39], 0.5, v[100:101] op_sel_hi:[1,0,1]
	v_pk_fma_f32 v[36:37], v[36:37], 0.5, v[110:111] op_sel_hi:[1,0,1]
	v_pk_fma_f32 v[40:41], v[30:31], 0.5, v[102:103] op_sel_hi:[1,0,1]
	v_pk_fma_f32 v[30:31], v[28:29], 0.5, v[112:113] op_sel_hi:[1,0,1]
	v_lshlrev_b32_e32 v114, 16, v120
	v_and_b32_e32 v115, 0xffff0000, v120
	v_lshlrev_b32_e32 v116, 16, v121
	v_and_b32_e32 v117, 0xffff0000, v121
	v_lshlrev_b32_e32 v118, 16, v122
	v_and_b32_e32 v119, 0xffff0000, v122
	v_lshlrev_b32_e32 v120, 16, v123
	v_and_b32_e32 v121, 0xffff0000, v123
	v_cvt_pk_bf16_f32 v28, v36, v37
	v_cvt_pk_bf16_f32 v29, v38, v39
	v_cvt_pk_bf16_f32 v30, v30, v31
	v_cvt_pk_bf16_f32 v31, v40, v41
	global_store_dwordx4 v[98:99], v[28:31], off offset:256
	v_lshlrev_b32_e32 v122, 16, v92
	v_and_b32_e32 v123, 0xffff0000, v92
	v_pk_fma_f32 v[28:29], v[34:35], 0.5, v[116:117] op_sel_hi:[1,0,1]
	v_pk_fma_f32 v[30:31], v[32:33], 0.5, v[114:115] op_sel_hi:[1,0,1]
	v_pk_fma_f32 v[32:33], v[26:27], 0.5, v[120:121] op_sel_hi:[1,0,1]
	v_pk_fma_f32 v[26:27], v[24:25], 0.5, v[118:119] op_sel_hi:[1,0,1]
	v_lshlrev_b32_e32 v92, 16, v93
	v_and_b32_e32 v93, 0xffff0000, v93
	v_lshlrev_b32_e32 v144, 16, v94
	v_and_b32_e32 v145, 0xffff0000, v94
	v_lshlrev_b32_e32 v94, 16, v95
	v_and_b32_e32 v95, 0xffff0000, v95
	v_cvt_pk_bf16_f32 v24, v30, v31
	v_cvt_pk_bf16_f32 v25, v28, v29
	v_cvt_pk_bf16_f32 v26, v26, v27
	v_cvt_pk_bf16_f32 v27, v32, v33
	global_store_dwordx4 v[96:97], v[24:27], off
	v_pk_fma_f32 v[22:23], v[22:23], 0.5, v[92:93] op_sel_hi:[1,0,1]
	v_pk_fma_f32 v[20:21], v[20:21], 0.5, v[122:123] op_sel_hi:[1,0,1]
	v_pk_fma_f32 v[24:25], v[14:15], 0.5, v[94:95] op_sel_hi:[1,0,1]
	v_pk_fma_f32 v[14:15], v[12:13], 0.5, v[144:145] op_sel_hi:[1,0,1]
	v_lshlrev_b32_e32 v146, 16, v124
	v_and_b32_e32 v147, 0xffff0000, v124
	v_lshlrev_b32_e32 v124, 16, v125
	v_and_b32_e32 v125, 0xffff0000, v125
	v_lshlrev_b32_e32 v148, 16, v126
	v_and_b32_e32 v149, 0xffff0000, v126
	v_lshlrev_b32_e32 v126, 16, v127
	v_and_b32_e32 v127, 0xffff0000, v127
	v_cvt_pk_bf16_f32 v12, v20, v21
	v_cvt_pk_bf16_f32 v13, v22, v23
	v_cvt_pk_bf16_f32 v14, v14, v15
	v_cvt_pk_bf16_f32 v15, v24, v25
	global_store_dwordx4 v[90:91], v[12:15], off offset:256
	v_lshlrev_b32_e32 v150, 16, v80
	v_and_b32_e32 v151, 0xffff0000, v80
	v_pk_fma_f32 v[12:13], v[18:19], 0.5, v[124:125] op_sel_hi:[1,0,1]
	v_pk_fma_f32 v[14:15], v[16:17], 0.5, v[146:147] op_sel_hi:[1,0,1]
	v_pk_fma_f32 v[16:17], v[10:11], 0.5, v[126:127] op_sel_hi:[1,0,1]
	v_pk_fma_f32 v[10:11], v[8:9], 0.5, v[148:149] op_sel_hi:[1,0,1]
	v_lshlrev_b32_e32 v80, 16, v81
	v_and_b32_e32 v81, 0xffff0000, v81
	v_lshlrev_b32_e32 v152, 16, v82
	v_and_b32_e32 v153, 0xffff0000, v82
	v_lshlrev_b32_e32 v82, 16, v83
	v_and_b32_e32 v83, 0xffff0000, v83
	v_cvt_pk_bf16_f32 v8, v14, v15
	v_cvt_pk_bf16_f32 v9, v12, v13
	v_cvt_pk_bf16_f32 v10, v10, v11
	v_cvt_pk_bf16_f32 v11, v16, v17
	global_store_dwordx4 v[88:89], v[8:11], off
	v_pk_fma_f32 v[6:7], v[6:7], 0.5, v[80:81] op_sel_hi:[1,0,1]
	v_pk_fma_f32 v[4:5], v[4:5], 0.5, v[150:151] op_sel_hi:[1,0,1]
	v_pk_fma_f32 v[8:9], v[2:3], 0.5, v[82:83] op_sel_hi:[1,0,1]
	v_pk_fma_f32 v[2:3], v[0:1], 0.5, v[152:153] op_sel_hi:[1,0,1]
	v_cvt_pk_bf16_f32 v0, v4, v5
	v_cvt_pk_bf16_f32 v1, v6, v7
	v_cvt_pk_bf16_f32 v2, v2, v3
	v_cvt_pk_bf16_f32 v3, v8, v9
	s_and_b64 vcc, exec, s[0:1]
	global_store_dwordx4 v[72:73], v[0:3], off offset:256
	s_cbranch_vccz .LBB0_930
	s_waitcnt vmcnt(0)
	s_cmpk_gt_u32 s6, 0xff
	s_cbranch_scc1 .LBB0_945
	s_barrier

; DI int opaque_tid() { int t = threadIdx.x; asm volatile("" : "+v"(t)); return t; }
; DI f32x4 bf_lo4(u32x4 w) { f32x4 r; r[0] = bf_lo(w.x); r[1] = bf_hi(w.x); r[2] = bf_lo(w.y); r[3] = bf_hi(w.y); return r; }
; DI f32x4 bf_hi4(u32x4 w) { f32x4 r; r[0] = bf_lo(w.z); r[1] = bf_hi(w.z); r[2] = bf_lo(w.w); r[3] = bf_hi(w.w); return r; }
; DI void final_norm_phase(const bf16_t* src, const float* w, float* dst) {
;     const int tid_ = opaque_tid(), lane = tid_ & 63, wid = tid_ >> 6;
;     f32x4 wv[2][2];
; #pragma unroll
;     for (int j = 0; j < 2; ++j) { wv[j][0] = *(const f32x4*)(w + j * 512 + lane * 8); wv[j][1] = *(const f32x4*)(w + j * 512 + lane * 8 + 4); }
;     for (int row = (blockIdx.x * 8 + wid) * 2; row < NTOK; row += gridDim.x * 16) {
;         u32x4 hv[2][2];
; #pragma unroll
;         for (int r = 0; r < 2; ++r)
; #pragma unroll
;             for (int j = 0; j < 2; ++j) hv[r][j] = *(const u32x4*)(src + (size_t)(row + r) * DM + j * 512 + lane * 8);
;         float ss[2] = {0.f, 0.f};
;         f32x4 v[2][2][2];
; #pragma unroll
;         for (int r = 0; r < 2; ++r)
; #pragma unroll
;             for (int j = 0; j < 2; ++j) {
;                 v[r][j][0] = bf_lo4(hv[r][j]); v[r][j][1] = bf_hi4(hv[r][j]);
; #pragma unroll
;                 for (int e = 0; e < 4; ++e) ss[r] += v[r][j][0][e] * v[r][j][0][e] + v[r][j][1][e] * v[r][j][1][e];
;             }
; #pragma unroll
.LBB0_998:
	s_or_b64 exec, exec, s[0:1]
	s_waitcnt lgkmcnt(0)
	s_barrier
	v_readlane_b32 s0, v243, 7
	v_ashrrev_i32_e32 v0, 5, v222
	v_and_b32_e32 v0, -2, v0
	v_add_u32_e32 v16, s0, v0
	s_mov_b32 s0, 0x10000
	v_cmp_gt_i32_e32 vcc, s0, v16
	s_and_saveexec_b64 s[0:1], vcc
	s_cbranch_execz .LBB0_1001
	v_lshlrev_b32_e32 v0, 3, v222
	v_and_b32_e32 v17, 0x1f8, v0
	v_lshlrev_b32_e32 v20, 2, v17
	global_load_dwordx4 v[0:3], v20, s[70:71] offset:16
	global_load_dwordx4 v[4:7], v20, s[70:71]
	global_load_dwordx4 v[8:11], v20, s[70:71] offset:2064
	global_load_dwordx4 v[12:15], v20, s[70:71] offset:2048
	v_lshlrev_b32_e32 v18, 1, v17
	v_mbcnt_hi_u32_b32 v17, -1, v223
	v_and_b32_e32 v22, 64, v17
	v_add_u32_e32 v22, 64, v22
	v_xor_b32_e32 v23, 32, v17
	v_cmp_lt_i32_e32 vcc, v23, v22
	v_xor_b32_e32 v24, 16, v17
	v_mov_b32_e32 v21, 0
	v_cndmask_b32_e32 v23, v17, v23, vcc
	v_cmp_lt_i32_e32 vcc, v24, v22
	v_mov_b32_e32 v19, v21
	v_lshl_add_u64 v[18:19], s[56:57], 0, v[18:19]
	v_cndmask_b32_e32 v24, v17, v24, vcc
	v_lshlrev_b32_e32 v48, 2, v24
	v_xor_b32_e32 v24, 8, v17
	v_cmp_lt_i32_e32 vcc, v24, v22
	v_lshl_add_u64 v[20:21], s[72:73], 0, v[20:21]
	s_lshl_b32 s5, s30, 4
	v_cndmask_b32_e32 v24, v17, v24, vcc
	v_lshlrev_b32_e32 v49, 2, v24
	v_xor_b32_e32 v24, 4, v17
	v_cmp_lt_i32_e32 vcc, v24, v22
	v_lshlrev_b32_e32 v23, 2, v23
	s_mov_b64 s[2:3], 0
	v_cndmask_b32_e32 v24, v17, v24, vcc
	v_lshlrev_b32_e32 v50, 2, v24
	v_xor_b32_e32 v24, 2, v17
	v_cmp_lt_i32_e32 vcc, v24, v22
	s_mov_b32 s4, 0x3a800000
	s_mov_b32 s6, 0x800000
	v_cndmask_b32_e32 v24, v17, v24, vcc
	v_lshlrev_b32_e32 v51, 2, v24
	v_xor_b32_e32 v24, 1, v17
	v_cmp_lt_i32_e32 vcc, v24, v22
	s_mov_b32 s7, 0xffff
	v_mov_b32_e32 v22, 0x358637bd
	v_cndmask_b32_e32 v17, v17, v24, vcc
	v_lshlrev_b32_e32 v52, 2, v17
	v_mov_b32_e32 v116, v16
	v_ashrrev_i32_e32 v117, 31, v116
	v_lshlrev_b64 v[118:119], 11, v[116:117]
	v_lshl_add_u64 v[118:119], v[18:19], 0, v[118:119]
	global_load_dwordx4 v[100:103], v[118:119], off offset:1024
	global_load_dwordx4 v[104:107], v[118:119], off
	global_load_dwordx4 v[108:111], v[118:119], off offset:3072
	global_load_dwordx4 v[112:115], v[118:119], off offset:2048
	s_waitcnt vmcnt(0)
.LBB0_1000:
	s_waitcnt vmcnt(8)
	v_ashrrev_i32_e32 v17, 31, v16
	v_add_u32_e32 v66, 1, v16
	v_ashrrev_i32_e32 v67, 31, v66
	v_add_u32_e32 v116, s5, v16
	v_ashrrev_i32_e32 v117, 31, v116
	v_lshlrev_b64 v[118:119], 11, v[116:117]
	v_lshl_add_u64 v[118:119], v[18:19], 0, v[118:119]
	v_mov_b32_e32 v24, v100
	v_mov_b32_e32 v25, v101
	v_mov_b32_e32 v26, v102
	v_mov_b32_e32 v27, v103
	v_mov_b32_e32 v54, v104
	v_mov_b32_e32 v55, v105
	v_mov_b32_e32 v56, v106
	v_mov_b32_e32 v57, v107
	v_mov_b32_e32 v58, v108
	v_mov_b32_e32 v59, v109
	v_mov_b32_e32 v60, v110
	v_mov_b32_e32 v61, v111
	v_mov_b32_e32 v62, v112
	v_mov_b32_e32 v63, v113
	v_mov_b32_e32 v64, v114
	v_mov_b32_e32 v65, v115
	global_load_dwordx4 v[100:103], v[118:119], off offset:1024
	global_load_dwordx4 v[104:107], v[118:119], off
	global_load_dwordx4 v[108:111], v[118:119], off offset:3072
	global_load_dwordx4 v[112:115], v[118:119], off offset:2048
	v_lshlrev_b64 v[66:67], 12, v[66:67]
	v_and_b32_e32 v44, 0xffff0000, v24
	v_lshlrev_b32_e32 v29, 16, v56
	v_and_b32_e32 v33, 0xffff0000, v56
	v_lshlrev_b32_e32 v45, 16, v24
	v_lshlrev_b32_e32 v28, 16, v64
	v_and_b32_e32 v32, 0xffff0000, v64
	v_and_b32_e32 v46, 0xffff0000, v26
	v_lshlrev_b32_e32 v47, 16, v26
	v_and_b32_e32 v68, 0xffff0000, v25
	v_lshlrev_b32_e32 v69, 16, v25
	v_and_b32_e32 v70, 0xffff0000, v27
	v_lshlrev_b32_e32 v71, 16, v27
	v_lshlrev_b32_e32 v31, 16, v54
	v_and_b32_e32 v35, 0xffff0000, v54
	v_lshlrev_b32_e32 v37, 16, v57
	v_and_b32_e32 v24, 0xffff0000, v60
	v_lshlrev_b32_e32 v25, 16, v60
	v_lshlrev_b32_e32 v30, 16, v62
	v_and_b32_e32 v34, 0xffff0000, v62
	v_lshlrev_b32_e32 v36, 16, v65
	v_and_b32_e32 v40, 0xffff0000, v65
	v_and_b32_e32 v60, 0xffff0000, v61
	v_lshlrev_b32_e32 v61, 16, v61
	v_pk_mul_f32 v[64:65], v[28:29], v[28:29]
	v_pk_mul_f32 v[72:73], v[32:33], v[32:33]
	v_lshlrev_b32_e32 v39, 16, v55
	v_and_b32_e32 v43, 0xffff0000, v55
	v_and_b32_e32 v41, 0xffff0000, v57
	v_pk_mul_f32 v[54:55], v[46:47], v[46:47]
	v_pk_mul_f32 v[56:57], v[70:71], v[70:71]
	v_and_b32_e32 v26, 0xffff0000, v58
	v_lshlrev_b32_e32 v27, 16, v58
	v_lshlrev_b32_e32 v38, 16, v63
	v_and_b32_e32 v42, 0xffff0000, v63
	v_and_b32_e32 v58, 0xffff0000, v59
	v_lshlrev_b32_e32 v59, 16, v59
	v_pk_mul_f32 v[62:63], v[24:25], v[24:25]
	v_pk_mul_f32 v[74:75], v[36:37], v[36:37]
	v_pk_mul_f32 v[78:79], v[60:61], v[60:61]
	v_pk_fma_f32 v[64:65], v[30:31], v[30:31], v[64:65]
	v_pk_fma_f32 v[72:73], v[34:35], v[34:35], v[72:73]
	v_pk_fma_f32 v[54:55], v[44:45], v[44:45], v[54:55]
	v_pk_fma_f32 v[56:57], v[68:69], v[68:69], v[56:57]
	v_pk_mul_f32 v[76:77], v[40:41], v[40:41]
	v_pk_fma_f32 v[62:63], v[26:27], v[26:27], v[62:63]
	v_pk_fma_f32 v[74:75], v[38:39], v[38:39], v[74:75]
	v_pk_fma_f32 v[78:79], v[58:59], v[58:59], v[78:79]
	v_pk_add_f32 v[64:65], v[64:65], v[72:73]
	v_pk_fma_f32 v[76:77], v[42:43], v[42:43], v[76:77]
	v_mov_b32_e32 v81, v55
	v_mov_b32_e32 v55, v57
	v_mov_b32_e32 v80, v63
	v_mov_b32_e32 v63, v54
	v_mov_b32_e32 v54, v79
	v_mov_b32_e32 v79, v56
	v_pk_add_f32 v[56:57], v[74:75], v[64:65]
	v_mov_b32_e32 v74, v29
	v_pk_add_f32 v[56:57], v[76:77], v[56:57]
	v_mov_b32_e32 v75, v33
	v_pk_add_f32 v[56:57], v[80:81], v[56:57]
	v_pk_mov_b32 v[64:65], v[70:71], v[70:71] op_sel:[1,0]
	v_pk_add_f32 v[56:57], v[62:63], v[56:57]
	v_lshlrev_b64 v[62:63], 12, v[16:17]
	v_pk_add_f32 v[54:55], v[54:55], v[56:57]
	v_lshl_add_u64 v[72:73], v[20:21], 0, v[62:63]
	v_pk_add_f32 v[54:55], v[78:79], v[54:55]
	ds_bpermute_b32 v57, v23, v55
	ds_bpermute_b32 v56, v23, v54
	v_mov_b32_e32 v78, v45
	v_mov_b32_e32 v79, v44
	v_mov_b32_e32 v44, v47
	v_mov_b32_e32 v45, v46
	s_waitcnt lgkmcnt(0)
; DI void final_norm_phase(const bf16_t* src, const float* w, float* dst) {
;     ...
;         for (int o = 32; o >= 1; o >>= 1) { ss[0] += __shfl_xor(ss[0], o); ss[1] += __shfl_xor(ss[1], o); }
; #pragma unroll
;         for (int r = 0; r < 2; ++r) {
;             const float rs = rsqrtf(ss[r] * (1.0f / 1024.0f) + 1e-6f);
; #pragma unroll
;             for (int j = 0; j < 2; ++j) {
;                 *(f32x4*)(dst + (size_t)(row + r) * DM + j * 512 + lane * 8) = v[r][j][0] * rs * wv[j][0];
;                 *(f32x4*)(dst + (size_t)(row + r) * DM + j * 512 + lane * 8 + 4) = v[r][j][1] * rs * wv[j][1];
;             }
;         }
;     }
	v_pk_add_f32 v[54:55], v[54:55], v[56:57]
	ds_bpermute_b32 v57, v48, v55
	ds_bpermute_b32 v56, v48, v54
	v_pk_mov_b32 v[62:63], v[68:69], v[68:69] op_sel:[1,0]
	v_mov_b32_e32 v68, v31
	v_mov_b32_e32 v69, v35
	v_mov_b32_e32 v70, v39
	s_waitcnt lgkmcnt(0)
	v_pk_add_f32 v[54:55], v[54:55], v[56:57]
	ds_bpermute_b32 v57, v49, v55
	ds_bpermute_b32 v56, v49, v54
	v_mov_b32_e32 v71, v43
	v_mov_b32_e32 v76, v37
	v_mov_b32_e32 v77, v41
	v_mov_b32_e32 v37, v40
	s_waitcnt lgkmcnt(0)
	v_pk_add_f32 v[54:55], v[54:55], v[56:57]
	ds_bpermute_b32 v57, v50, v55
	ds_bpermute_b32 v56, v50, v54
	v_pk_mov_b32 v[80:81], v[58:59], v[58:59] op_sel:[1,0]
	v_pk_mov_b32 v[82:83], v[60:61], v[60:61] op_sel:[1,0]
	v_mov_b32_e32 v39, v42
	v_add_u32_e32 v16, s5, v16
	s_waitcnt lgkmcnt(0)
	v_pk_add_f32 v[54:55], v[54:55], v[56:57]
	ds_bpermute_b32 v57, v51, v55
	ds_bpermute_b32 v56, v51, v54
	s_waitcnt lgkmcnt(0)
	v_pk_add_f32 v[54:55], v[54:55], v[56:57]
	ds_bpermute_b32 v57, v52, v55
	ds_bpermute_b32 v56, v52, v54
	s_waitcnt lgkmcnt(0)
	v_pk_add_f32 v[46:47], v[54:55], v[56:57]
	s_nop 0
	v_pk_fma_f32 v[46:47], v[46:47], s[4:5], v[22:23] op_sel_hi:[1,0,0]
	s_nop 0
	v_mul_f32_e32 v17, 0x4b800000, v47
	v_mul_f32_e32 v29, 0x4b800000, v46
	v_cmp_gt_f32_e32 vcc, s6, v47
	v_cmp_gt_f32_e64 s[0:1], s6, v46
	s_nop 0
	v_cndmask_b32_e32 v17, v47, v17, vcc
	v_cndmask_b32_e64 v29, v46, v29, s[0:1]
	v_rsq_f32_e32 v17, v17
	v_rsq_f32_e32 v29, v29
	v_mul_f32_e32 v31, 0x45800000, v17
	v_mul_f32_e32 v33, 0x45800000, v29
	v_cndmask_b32_e32 v46, v17, v31, vcc
	v_cndmask_b32_e64 v84, v29, v33, s[0:1]
	v_mov_b32_e32 v31, v34
	v_pk_mul_f32 v[54:55], v[46:47], v[68:69] op_sel_hi:[0,1]
	v_pk_mul_f32 v[56:57], v[46:47], v[70:71] op_sel_hi:[0,1]
	v_pk_mul_f32 v[30:31], v[84:85], v[30:31] op_sel_hi:[0,1]
	v_mov_b32_e32 v29, v32
	v_pk_mul_f32 v[58:59], v[46:47], v[74:75] op_sel_hi:[0,1]
	v_pk_mul_f32 v[60:61], v[46:47], v[76:77] op_sel_hi:[0,1]
	v_pk_mul_f32 v[68:69], v[46:47], v[78:79] op_sel_hi:[0,1]
	v_pk_mul_f32 v[62:63], v[46:47], v[62:63] op_sel_hi:[0,1]
	v_pk_mul_f32 v[70:71], v[46:47], v[44:45] op_sel_hi:[0,1]
	v_pk_mul_f32 v[64:65], v[46:47], v[64:65] op_sel_hi:[0,1]
	v_pk_mul_f32 v[46:47], v[6:7], v[56:57]
	v_pk_mul_f32 v[44:45], v[4:5], v[54:55]
	v_pk_mul_f32 v[42:43], v[4:5], v[30:31]
	v_pk_mul_f32 v[28:29], v[84:85], v[28:29] op_sel_hi:[0,1]
	v_pk_mul_f32 v[30:31], v[84:85], v[36:37] op_sel_hi:[0,1]
	v_pk_mul_f32 v[56:57], v[2:3], v[60:61]
	v_pk_mul_f32 v[54:55], v[0:1], v[58:59]
	v_pk_mul_f32 v[60:61], v[14:15], v[62:63]
	v_pk_mul_f32 v[58:59], v[12:13], v[68:69]
	v_pk_mul_f32 v[64:65], v[10:11], v[64:65]
	v_pk_mul_f32 v[62:63], v[8:9], v[70:71]
	global_store_dwordx4 v[72:73], v[44:47], off
	global_store_dwordx4 v[72:73], v[54:57], off offset:16
	global_store_dwordx4 v[72:73], v[58:61], off offset:2048
	global_store_dwordx4 v[72:73], v[62:65], off offset:2064
	v_lshl_add_u64 v[46:47], v[20:21], 0, v[66:67]
	v_pk_mul_f32 v[30:31], v[2:3], v[30:31]
	v_pk_mul_f32 v[28:29], v[0:1], v[28:29]
	global_store_dwordx4 v[46:47], v[28:31], off offset:16
	v_pk_mul_f32 v[34:35], v[84:85], v[38:39] op_sel_hi:[0,1]
	v_cmp_lt_i32_e32 vcc, s7, v16
	v_mov_b32_e32 v28, v27
	v_mov_b32_e32 v29, v26
	v_pk_mul_f32 v[26:27], v[84:85], v[28:29] op_sel_hi:[0,1]
	v_pk_mul_f32 v[28:29], v[84:85], v[80:81] op_sel_hi:[0,1]
	v_pk_mul_f32 v[28:29], v[14:15], v[28:29]
	v_pk_mul_f32 v[26:27], v[12:13], v[26:27]
	global_store_dwordx4 v[46:47], v[26:29], off offset:2048
	v_pk_mul_f32 v[44:45], v[6:7], v[34:35]
	s_or_b64 s[2:3], vcc, s[2:3]
	v_mov_b32_e32 v26, v25
	v_mov_b32_e32 v27, v24
	v_pk_mul_f32 v[24:25], v[84:85], v[26:27] op_sel_hi:[0,1]
	v_pk_mul_f32 v[26:27], v[84:85], v[82:83] op_sel_hi:[0,1]
	v_pk_mul_f32 v[26:27], v[10:11], v[26:27]
	v_pk_mul_f32 v[24:25], v[8:9], v[24:25]
	global_store_dwordx4 v[46:47], v[42:45], off
	global_store_dwordx4 v[46:47], v[24:27], off offset:2064
	s_andn2_b64 exec, exec, s[2:3]
	s_cbranch_execnz .LBB0_1000
